# SB loop: moved compiler vmcnt(0) from before first MFMA to loop bottom so next-tile prefetch overlaps compute; GEMM epilogues: IEEE div/sqrt expansions replaced by v_rcp/v_sqrt (f32) + dead code remov
# speedup vs baseline: 1.0079x; 1.0079x over previous
;     DI void operator()(const f32x4 (&acc)[2][2][4][2], const pg8::Unit& u, int wr, int wc, int fr, int fq) const {
;     ...
;                 if (part) { const f32x4* pq = (const f32x4*)(part + (size_t)row * 16); const f32x4 t4 = (pq[0] + pq[1]) + (pq[2] + pq[3]); rs = 1.0f / sqrtf(((t4.x + t4.y) + (t4.z + t4.w)) * (1.f / DM) + NORM_EPS); }
;                 f32x4 c0 = {1.f, 1.f, 1.f, 1.f}, c1 = c0, s0 = {0.f, 0.f, 0.f, 0.f}, s1 = s0;
;                 if (do_rope && mine) { const float* cs = rope + (size_t)row * 16; c0 = *(const f32x4*)cs; c1 = *(const f32x4*)(cs + 4); s0 = *(const f32x4*)(cs + 8) * sgn; s1 = *(const f32x4*)(cs + 12) * sgn; }
; #pragma unroll
;                 for (int bj = 0; bj < 2; ++bj) {
;                     f32x4 v0 = acc[ai][bj][m][0] * rs, v1 = acc[ai][bj][m][1] * rs;
;                     if (act == 2) {
; #pragma unroll
;                         for (int k = 0; k < 4; ++k) { const float a = fmaxf(v0[k], 0.f), b = fmaxf(v1[k], 0.f); v0[k] = a * a; v1[k] = b * b; }
;                     }
;                     if (do_rope) {
;                         f32x4 p0, p1;
; #pragma unroll
;                         for (int k = 0; k < 4; ++k) { p0[k] = __shfl_xor(v0[k], 16); p1[k] = __shfl_xor(v1[k], 16); }
;                         v0 = v0 * c0 + p0 * s0; v1 = v1 * c1 + p1 * s1;
.LBB0_168:
	s_or_b64 exec, exec, s[8:9]
	s_waitcnt vmcnt(0)
	v_pk_add_f32 v[146:147], v[150:151], v[146:147]
	v_pk_add_f32 v[144:145], v[148:149], v[144:145]
	v_pk_add_f32 v[136:137], v[140:141], v[136:137]
	v_pk_add_f32 v[138:139], v[142:143], v[138:139]
	v_pk_add_f32 v[136:137], v[144:145], v[136:137]
	v_pk_add_f32 v[138:139], v[146:147], v[138:139]
	v_add_f32_e32 v136, v136, v137
	v_add_f32_e32 v137, v138, v139
	v_add_f32_e32 v136, v136, v137
	v_fmamk_f32 v136, v136, 0x3a800000, v204
	v_mul_f32_e32 v137, 0x4f800000, v136
	v_cmp_gt_f32_e32 vcc, s70, v136
	s_nop 1
	v_cndmask_b32_e32 v136, v136, v137, vcc
	v_sqrt_f32_e32 v137, v136
	s_nop 0
	s_nop 0
	v_mov_b32_e32 v138, v137
	s_nop 1
	v_mov_b32_e32 v137, v138
	v_mul_f32_e32 v138, 0x37800000, v137
	v_cndmask_b32_e32 v137, v137, v138, vcc
	v_cmp_class_f32_e32 vcc, v136, v205
	s_nop 1
	v_cndmask_b32_e32 v136, v137, v136, vcc
	v_div_scale_f32 v139, vcc, 1.0, v136, 1.0
	v_rcp_f32_e32 v137, v136
	s_nop 0
	v_mul_f32_e32 v138, 1.0, v137
	v_cndmask_b32_e64 v136, 0, 1, s[44:45]
	v_pk_mul_f32 v[126:127], v[126:127], v[138:139] op_sel_hi:[1,0]
	v_pk_mul_f32 v[124:125], v[124:125], v[138:139] op_sel_hi:[1,0]
	v_pk_mul_f32 v[122:123], v[122:123], v[138:139] op_sel_hi:[1,0]
	v_cmp_ne_u32_e64 s[8:9], 1, v136
	s_andn2_b64 vcc, exec, s[44:45]
	v_pk_mul_f32 v[140:141], v[120:121], v[138:139] op_sel_hi:[1,0]
	s_cbranch_vccnz .LBB0_170
	v_and_b32_e32 v121, 64, v206
	v_xor_b32_e32 v120, 16, v206
	v_add_u32_e32 v121, 64, v121
	v_cmp_lt_i32_e32 vcc, v120, v121
	s_nop 1
	v_cndmask_b32_e32 v120, v206, v120, vcc
	v_lshlrev_b32_e32 v139, 2, v120
	ds_bpermute_b32 v120, v139, v124
	ds_bpermute_b32 v121, v139, v125
	ds_bpermute_b32 v136, v139, v140
	ds_bpermute_b32 v142, v139, v126
	ds_bpermute_b32 v143, v139, v127
	ds_bpermute_b32 v137, v139, v141
	ds_bpermute_b32 v144, v139, v122
	ds_bpermute_b32 v145, v139, v123
	s_waitcnt lgkmcnt(6)
	v_pk_mul_f32 v[120:121], v[178:179], v[120:121]
	s_waitcnt lgkmcnt(3)
	v_pk_mul_f32 v[142:143], v[180:181], v[142:143]
	v_pk_fma_f32 v[124:125], v[124:125], v[132:133], v[120:121]
	s_waitcnt lgkmcnt(2)
	v_pk_mul_f32 v[120:121], v[176:177], v[136:137]
	s_waitcnt lgkmcnt(0)
	v_pk_mul_f32 v[136:137], v[174:175], v[144:145]
	v_pk_fma_f32 v[126:127], v[126:127], v[134:135], v[142:143]
	v_pk_fma_f32 v[122:123], v[122:123], v[130:131], v[136:137]
	v_pk_fma_f32 v[140:141], v[140:141], v[128:129], v[120:121]

;     DI void operator()(const f32x4 (&acc)[2][2][4][2], const pg8::Unit& u, int wr, int wc, int fr, int fq) const {
;     ...
;                 if (part) { const f32x4* pq = (const f32x4*)(part + (size_t)row * 16); const f32x4 t4 = (pq[0] + pq[1]) + (pq[2] + pq[3]); rs = 1.0f / sqrtf(((t4.x + t4.y) + (t4.z + t4.w)) * (1.f / DM) + NORM_EPS); }
;                 f32x4 c0 = {1.f, 1.f, 1.f, 1.f}, c1 = c0, s0 = {0.f, 0.f, 0.f, 0.f}, s1 = s0;
;                 if (do_rope && mine) { const float* cs = rope + (size_t)row * 16; c0 = *(const f32x4*)cs; c1 = *(const f32x4*)(cs + 4); s0 = *(const f32x4*)(cs + 8) * sgn; s1 = *(const f32x4*)(cs + 12) * sgn; }
; #pragma unroll
;                 for (int bj = 0; bj < 2; ++bj) {
;                     f32x4 v0 = acc[ai][bj][m][0] * rs, v1 = acc[ai][bj][m][1] * rs;
;                     if (act == 2) {
; #pragma unroll
;                         for (int k = 0; k < 4; ++k) { const float a = fmaxf(v0[k], 0.f), b = fmaxf(v1[k], 0.f); v0[k] = a * a; v1[k] = b * b; }
;                     }
;                     if (do_rope) {
;                         f32x4 p0, p1;
; #pragma unroll
;                         for (int k = 0; k < 4; ++k) { p0[k] = __shfl_xor(v0[k], 16); p1[k] = __shfl_xor(v1[k], 16); }
;                         v0 = v0 * c0 + p0 * s0; v1 = v1 * c1 + p1 * s1;
.LBB0_174:
	s_or_b64 exec, exec, s[10:11]
	s_waitcnt vmcnt(0)
	v_pk_add_f32 v[130:131], v[134:135], v[130:131]
	v_pk_add_f32 v[128:129], v[132:133], v[128:129]
	v_pk_add_f32 v[120:121], v[124:125], v[120:121]
	v_pk_add_f32 v[122:123], v[126:127], v[122:123]
	v_pk_add_f32 v[120:121], v[128:129], v[120:121]
	v_pk_add_f32 v[122:123], v[130:131], v[122:123]
	v_add_f32_e32 v120, v120, v121
	v_add_f32_e32 v121, v122, v123
	v_add_f32_e32 v120, v120, v121
	v_fmamk_f32 v120, v120, 0x3a800000, v204
	v_mul_f32_e32 v121, 0x4f800000, v120
	v_cmp_gt_f32_e32 vcc, s70, v120
	s_nop 1
	v_cndmask_b32_e32 v120, v120, v121, vcc
	v_sqrt_f32_e32 v121, v120
	s_nop 0
	s_nop 0
	v_mov_b32_e32 v122, v121
	s_nop 1
	v_mov_b32_e32 v121, v122
	v_mul_f32_e32 v122, 0x37800000, v121
	v_cndmask_b32_e32 v121, v121, v122, vcc
	v_cmp_class_f32_e32 vcc, v120, v205
	s_nop 1
	v_cndmask_b32_e32 v120, v121, v120, vcc
	v_div_scale_f32 v121, s[10:11], v120, v120, 1.0
	v_rcp_f32_e32 v122, v121
	s_nop 0
	v_fma_f32 v123, -v121, v122, 1.0
	v_fmac_f32_e32 v122, v123, v122
	v_div_scale_f32 v123, vcc, 1.0, v120, 1.0
	v_mul_f32_e32 v124, v123, v122
	v_fma_f32 v125, -v121, v124, v123
	v_fmac_f32_e32 v124, v125, v122
	v_rcp_f32_e32 v121, v120
	s_nop 0
	v_mul_f32_e32 v120, 1.0, v121
	v_pk_mul_f32 v[110:111], v[110:111], v[120:121] op_sel_hi:[1,0]
	v_pk_mul_f32 v[108:109], v[108:109], v[120:121] op_sel_hi:[1,0]
	v_pk_mul_f32 v[106:107], v[106:107], v[120:121] op_sel_hi:[1,0]
	s_and_b64 vcc, exec, s[8:9]
	v_pk_mul_f32 v[122:123], v[104:105], v[120:121] op_sel_hi:[1,0]
	s_cbranch_vccnz .LBB0_176
	v_and_b32_e32 v105, 64, v206
	v_xor_b32_e32 v104, 16, v206
	v_add_u32_e32 v105, 64, v105
	v_cmp_lt_i32_e32 vcc, v104, v105
	s_nop 1
	v_cndmask_b32_e32 v104, v206, v104, vcc
	v_lshlrev_b32_e32 v121, 2, v104
	ds_bpermute_b32 v104, v121, v108
	ds_bpermute_b32 v105, v121, v109
	ds_bpermute_b32 v124, v121, v122
	ds_bpermute_b32 v126, v121, v110
	ds_bpermute_b32 v127, v121, v111
	ds_bpermute_b32 v125, v121, v123
	ds_bpermute_b32 v128, v121, v106
	ds_bpermute_b32 v129, v121, v107
	s_waitcnt lgkmcnt(6)
	v_pk_mul_f32 v[104:105], v[142:143], v[104:105]
	s_waitcnt lgkmcnt(3)
	v_pk_mul_f32 v[126:127], v[144:145], v[126:127]
	v_pk_fma_f32 v[108:109], v[108:109], v[116:117], v[104:105]
	s_waitcnt lgkmcnt(2)
	v_pk_mul_f32 v[104:105], v[140:141], v[124:125]
	s_waitcnt lgkmcnt(0)
	v_pk_mul_f32 v[124:125], v[138:139], v[128:129]
	v_pk_fma_f32 v[110:111], v[110:111], v[118:119], v[126:127]
	v_pk_fma_f32 v[106:107], v[106:107], v[114:115], v[124:125]
	v_pk_fma_f32 v[122:123], v[122:123], v[112:113], v[104:105]

;     DI void operator()(const f32x4 (&acc)[2][2][4][2], const pg8::Unit& u, int wr, int wc, int fr, int fq) const {
;     ...
;                 if (part) { const f32x4* pq = (const f32x4*)(part + (size_t)row * 16); const f32x4 t4 = (pq[0] + pq[1]) + (pq[2] + pq[3]); rs = 1.0f / sqrtf(((t4.x + t4.y) + (t4.z + t4.w)) * (1.f / DM) + NORM_EPS); }
;                 f32x4 c0 = {1.f, 1.f, 1.f, 1.f}, c1 = c0, s0 = {0.f, 0.f, 0.f, 0.f}, s1 = s0;
;                 if (do_rope && mine) { const float* cs = rope + (size_t)row * 16; c0 = *(const f32x4*)cs; c1 = *(const f32x4*)(cs + 4); s0 = *(const f32x4*)(cs + 8) * sgn; s1 = *(const f32x4*)(cs + 12) * sgn; }
; #pragma unroll
;                 for (int bj = 0; bj < 2; ++bj) {
;                     f32x4 v0 = acc[ai][bj][m][0] * rs, v1 = acc[ai][bj][m][1] * rs;
;                     if (act == 2) {
; #pragma unroll
;                         for (int k = 0; k < 4; ++k) { const float a = fmaxf(v0[k], 0.f), b = fmaxf(v1[k], 0.f); v0[k] = a * a; v1[k] = b * b; }
;                     }
;                     if (do_rope) {
;                         f32x4 p0, p1;
; #pragma unroll
;                         for (int k = 0; k < 4; ++k) { p0[k] = __shfl_xor(v0[k], 16); p1[k] = __shfl_xor(v1[k], 16); }
;                         v0 = v0 * c0 + p0 * s0; v1 = v1 * c1 + p1 * s1;
.LBB0_180:
	s_or_b64 exec, exec, s[10:11]
	s_waitcnt vmcnt(0)
	v_pk_add_f32 v[114:115], v[118:119], v[114:115]
	v_pk_add_f32 v[112:113], v[116:117], v[112:113]
	v_pk_add_f32 v[104:105], v[108:109], v[104:105]
	v_pk_add_f32 v[106:107], v[110:111], v[106:107]
	v_pk_add_f32 v[104:105], v[112:113], v[104:105]
	v_pk_add_f32 v[106:107], v[114:115], v[106:107]
	v_add_f32_e32 v104, v104, v105
	v_add_f32_e32 v105, v106, v107
	v_add_f32_e32 v104, v104, v105
	v_fmamk_f32 v104, v104, 0x3a800000, v204
	v_mul_f32_e32 v105, 0x4f800000, v104
	v_cmp_gt_f32_e32 vcc, s70, v104
	s_nop 1
	v_cndmask_b32_e32 v104, v104, v105, vcc
	v_sqrt_f32_e32 v105, v104
	s_nop 0
	s_nop 0
	v_mov_b32_e32 v106, v105
	s_nop 1
	v_mov_b32_e32 v105, v106
	v_mul_f32_e32 v106, 0x37800000, v105
	v_cndmask_b32_e32 v105, v105, v106, vcc
	v_cmp_class_f32_e32 vcc, v104, v205
	s_nop 1
	v_cndmask_b32_e32 v104, v105, v104, vcc
	v_div_scale_f32 v105, s[10:11], v104, v104, 1.0
	v_rcp_f32_e32 v106, v105
	s_nop 0
	v_fma_f32 v107, -v105, v106, 1.0
	v_fmac_f32_e32 v106, v107, v106
	v_div_scale_f32 v107, vcc, 1.0, v104, 1.0
	v_mul_f32_e32 v108, v107, v106
	v_fma_f32 v109, -v105, v108, v107
	v_fmac_f32_e32 v108, v109, v106
	v_rcp_f32_e32 v105, v104
	s_nop 0
	v_mul_f32_e32 v104, 1.0, v105
	v_pk_mul_f32 v[94:95], v[94:95], v[104:105] op_sel_hi:[1,0]
	v_pk_mul_f32 v[92:93], v[92:93], v[104:105] op_sel_hi:[1,0]
	v_pk_mul_f32 v[90:91], v[90:91], v[104:105] op_sel_hi:[1,0]
	s_and_b64 vcc, exec, s[8:9]
	v_pk_mul_f32 v[106:107], v[88:89], v[104:105] op_sel_hi:[1,0]
	s_cbranch_vccnz .LBB0_182
	v_and_b32_e32 v89, 64, v206
	v_xor_b32_e32 v88, 16, v206
	v_add_u32_e32 v89, 64, v89
	v_cmp_lt_i32_e32 vcc, v88, v89
	s_nop 1
	v_cndmask_b32_e32 v88, v206, v88, vcc
	v_lshlrev_b32_e32 v105, 2, v88
	ds_bpermute_b32 v88, v105, v92
	ds_bpermute_b32 v89, v105, v93
	ds_bpermute_b32 v108, v105, v106
	ds_bpermute_b32 v110, v105, v94
	ds_bpermute_b32 v111, v105, v95
	ds_bpermute_b32 v109, v105, v107
	ds_bpermute_b32 v112, v105, v90
	ds_bpermute_b32 v113, v105, v91
	s_waitcnt lgkmcnt(6)
	v_pk_mul_f32 v[88:89], v[124:125], v[88:89]
	s_waitcnt lgkmcnt(3)
	v_pk_mul_f32 v[110:111], v[126:127], v[110:111]
	v_pk_fma_f32 v[92:93], v[92:93], v[100:101], v[88:89]
	s_waitcnt lgkmcnt(2)
	v_pk_mul_f32 v[88:89], v[122:123], v[108:109]
	s_waitcnt lgkmcnt(0)
	v_pk_mul_f32 v[108:109], v[120:121], v[112:113]
	v_pk_fma_f32 v[94:95], v[94:95], v[102:103], v[110:111]
	v_pk_fma_f32 v[90:91], v[90:91], v[98:99], v[108:109]
	v_pk_fma_f32 v[106:107], v[106:107], v[96:97], v[88:89]

;     DI void operator()(const f32x4 (&acc)[2][2][4][2], const pg8::Unit& u, int wr, int wc, int fr, int fq) const {
;     ...
;                 if (part) { const f32x4* pq = (const f32x4*)(part + (size_t)row * 16); const f32x4 t4 = (pq[0] + pq[1]) + (pq[2] + pq[3]); rs = 1.0f / sqrtf(((t4.x + t4.y) + (t4.z + t4.w)) * (1.f / DM) + NORM_EPS); }
;                 f32x4 c0 = {1.f, 1.f, 1.f, 1.f}, c1 = c0, s0 = {0.f, 0.f, 0.f, 0.f}, s1 = s0;
;                 if (do_rope && mine) { const float* cs = rope + (size_t)row * 16; c0 = *(const f32x4*)cs; c1 = *(const f32x4*)(cs + 4); s0 = *(const f32x4*)(cs + 8) * sgn; s1 = *(const f32x4*)(cs + 12) * sgn; }
; #pragma unroll
;                 for (int bj = 0; bj < 2; ++bj) {
;                     f32x4 v0 = acc[ai][bj][m][0] * rs, v1 = acc[ai][bj][m][1] * rs;
;                     if (act == 2) {
; #pragma unroll
;                         for (int k = 0; k < 4; ++k) { const float a = fmaxf(v0[k], 0.f), b = fmaxf(v1[k], 0.f); v0[k] = a * a; v1[k] = b * b; }
;                     }
;                     if (do_rope) {
;                         f32x4 p0, p1;
; #pragma unroll
;                         for (int k = 0; k < 4; ++k) { p0[k] = __shfl_xor(v0[k], 16); p1[k] = __shfl_xor(v1[k], 16); }
;                         v0 = v0 * c0 + p0 * s0; v1 = v1 * c1 + p1 * s1;
.LBB0_186:
	s_or_b64 exec, exec, s[10:11]
	s_waitcnt vmcnt(0)
	v_pk_add_f32 v[98:99], v[102:103], v[98:99]
	v_pk_add_f32 v[96:97], v[100:101], v[96:97]
	v_pk_add_f32 v[88:89], v[92:93], v[88:89]
	v_pk_add_f32 v[90:91], v[94:95], v[90:91]
	v_pk_add_f32 v[88:89], v[96:97], v[88:89]
	v_pk_add_f32 v[90:91], v[98:99], v[90:91]
	v_add_f32_e32 v88, v88, v89
	v_add_f32_e32 v89, v90, v91
	v_add_f32_e32 v88, v88, v89
	v_fmamk_f32 v88, v88, 0x3a800000, v204
	v_mul_f32_e32 v89, 0x4f800000, v88
	v_cmp_gt_f32_e32 vcc, s70, v88
	s_nop 1
	v_cndmask_b32_e32 v88, v88, v89, vcc
	v_sqrt_f32_e32 v89, v88
	s_nop 0
	s_nop 0
	v_mov_b32_e32 v90, v89
	s_nop 1
	v_mov_b32_e32 v89, v90
	v_mul_f32_e32 v90, 0x37800000, v89
	v_cndmask_b32_e32 v89, v89, v90, vcc
	v_cmp_class_f32_e32 vcc, v88, v205
	s_nop 1
	v_cndmask_b32_e32 v88, v89, v88, vcc
	v_div_scale_f32 v89, s[10:11], v88, v88, 1.0
	v_rcp_f32_e32 v90, v89
	s_nop 0
	v_fma_f32 v91, -v89, v90, 1.0
	v_fmac_f32_e32 v90, v91, v90
	v_div_scale_f32 v91, vcc, 1.0, v88, 1.0
	v_mul_f32_e32 v92, v91, v90
	v_fma_f32 v93, -v89, v92, v91
	v_fmac_f32_e32 v92, v93, v90
	v_rcp_f32_e32 v89, v88
	s_nop 0
	v_mul_f32_e32 v88, 1.0, v89
	v_pk_mul_f32 v[78:79], v[78:79], v[88:89] op_sel_hi:[1,0]
	v_pk_mul_f32 v[76:77], v[76:77], v[88:89] op_sel_hi:[1,0]
	v_pk_mul_f32 v[74:75], v[74:75], v[88:89] op_sel_hi:[1,0]
	s_and_b64 vcc, exec, s[8:9]
	v_pk_mul_f32 v[90:91], v[72:73], v[88:89] op_sel_hi:[1,0]
	s_cbranch_vccnz .LBB0_188
	v_and_b32_e32 v73, 64, v206
	v_xor_b32_e32 v72, 16, v206
	v_add_u32_e32 v73, 64, v73
	v_cmp_lt_i32_e32 vcc, v72, v73
	s_nop 1
	v_cndmask_b32_e32 v72, v206, v72, vcc
	v_lshlrev_b32_e32 v89, 2, v72
	ds_bpermute_b32 v72, v89, v76
	ds_bpermute_b32 v73, v89, v77
	ds_bpermute_b32 v92, v89, v90
	ds_bpermute_b32 v94, v89, v78
	ds_bpermute_b32 v95, v89, v79
	ds_bpermute_b32 v93, v89, v91
	ds_bpermute_b32 v96, v89, v74
	ds_bpermute_b32 v97, v89, v75
	s_waitcnt lgkmcnt(6)
	v_pk_mul_f32 v[72:73], v[108:109], v[72:73]
	s_waitcnt lgkmcnt(3)
	v_pk_mul_f32 v[94:95], v[110:111], v[94:95]
	v_pk_fma_f32 v[76:77], v[76:77], v[84:85], v[72:73]
	s_waitcnt lgkmcnt(2)
	v_pk_mul_f32 v[72:73], v[106:107], v[92:93]
	s_waitcnt lgkmcnt(0)
	v_pk_mul_f32 v[92:93], v[104:105], v[96:97]
	v_pk_fma_f32 v[78:79], v[78:79], v[86:87], v[94:95]
	v_pk_fma_f32 v[74:75], v[74:75], v[82:83], v[92:93]
	v_pk_fma_f32 v[90:91], v[90:91], v[80:81], v[72:73]

;     DI void operator()(const f32x4 (&acc)[2][2][4][2], const pg8::Unit& u, int wr, int wc, int fr, int fq) const {
;     ...
;                 if (part) { const f32x4* pq = (const f32x4*)(part + (size_t)row * 16); const f32x4 t4 = (pq[0] + pq[1]) + (pq[2] + pq[3]); rs = 1.0f / sqrtf(((t4.x + t4.y) + (t4.z + t4.w)) * (1.f / DM) + NORM_EPS); }
;                 f32x4 c0 = {1.f, 1.f, 1.f, 1.f}, c1 = c0, s0 = {0.f, 0.f, 0.f, 0.f}, s1 = s0;
;                 if (do_rope && mine) { const float* cs = rope + (size_t)row * 16; c0 = *(const f32x4*)cs; c1 = *(const f32x4*)(cs + 4); s0 = *(const f32x4*)(cs + 8) * sgn; s1 = *(const f32x4*)(cs + 12) * sgn; }
; #pragma unroll
;                 for (int bj = 0; bj < 2; ++bj) {
;                     f32x4 v0 = acc[ai][bj][m][0] * rs, v1 = acc[ai][bj][m][1] * rs;
;                     if (act == 2) {
; #pragma unroll
;                         for (int k = 0; k < 4; ++k) { const float a = fmaxf(v0[k], 0.f), b = fmaxf(v1[k], 0.f); v0[k] = a * a; v1[k] = b * b; }
;                     }
;                     if (do_rope) {
;                         f32x4 p0, p1;
; #pragma unroll
;                         for (int k = 0; k < 4; ++k) { p0[k] = __shfl_xor(v0[k], 16); p1[k] = __shfl_xor(v1[k], 16); }
;                         v0 = v0 * c0 + p0 * s0; v1 = v1 * c1 + p1 * s1;
.LBB0_192:
	s_or_b64 exec, exec, s[10:11]
	s_waitcnt vmcnt(0)
	v_pk_add_f32 v[82:83], v[86:87], v[82:83]
	v_pk_add_f32 v[80:81], v[84:85], v[80:81]
	v_pk_add_f32 v[72:73], v[76:77], v[72:73]
	v_pk_add_f32 v[74:75], v[78:79], v[74:75]
	v_pk_add_f32 v[72:73], v[80:81], v[72:73]
	v_pk_add_f32 v[74:75], v[82:83], v[74:75]
	v_add_f32_e32 v72, v72, v73
	v_add_f32_e32 v73, v74, v75
	v_add_f32_e32 v72, v72, v73
	v_fmamk_f32 v72, v72, 0x3a800000, v204
	v_mul_f32_e32 v73, 0x4f800000, v72
	v_cmp_gt_f32_e32 vcc, s70, v72
	s_nop 1
	v_cndmask_b32_e32 v72, v72, v73, vcc
	v_sqrt_f32_e32 v73, v72
	s_nop 0
	s_nop 0
	v_mov_b32_e32 v74, v73
	s_nop 1
	v_mov_b32_e32 v73, v74
	v_mul_f32_e32 v74, 0x37800000, v73
	v_cndmask_b32_e32 v73, v73, v74, vcc
	v_cmp_class_f32_e32 vcc, v72, v205
	s_nop 1
	v_cndmask_b32_e32 v72, v73, v72, vcc
	v_div_scale_f32 v73, s[10:11], v72, v72, 1.0
	v_rcp_f32_e32 v74, v73
	s_nop 0
	v_fma_f32 v75, -v73, v74, 1.0
	v_fmac_f32_e32 v74, v75, v74
	v_div_scale_f32 v75, vcc, 1.0, v72, 1.0
	v_mul_f32_e32 v76, v75, v74
	v_fma_f32 v77, -v73, v76, v75
	v_fmac_f32_e32 v76, v77, v74
	v_rcp_f32_e32 v73, v72
	s_nop 0
	v_mul_f32_e32 v72, 1.0, v73
	v_pk_mul_f32 v[62:63], v[62:63], v[72:73] op_sel_hi:[1,0]
	v_pk_mul_f32 v[60:61], v[60:61], v[72:73] op_sel_hi:[1,0]
	v_pk_mul_f32 v[58:59], v[58:59], v[72:73] op_sel_hi:[1,0]
	s_and_b64 vcc, exec, s[8:9]
	v_pk_mul_f32 v[74:75], v[56:57], v[72:73] op_sel_hi:[1,0]
	s_cbranch_vccnz .LBB0_194
	v_and_b32_e32 v57, 64, v206
	v_xor_b32_e32 v56, 16, v206
	v_add_u32_e32 v57, 64, v57
	v_cmp_lt_i32_e32 vcc, v56, v57
	s_nop 1
	v_cndmask_b32_e32 v56, v206, v56, vcc
	v_lshlrev_b32_e32 v73, 2, v56
	ds_bpermute_b32 v56, v73, v60
	ds_bpermute_b32 v57, v73, v61
	ds_bpermute_b32 v76, v73, v74
	ds_bpermute_b32 v78, v73, v62
	ds_bpermute_b32 v79, v73, v63
	ds_bpermute_b32 v77, v73, v75
	ds_bpermute_b32 v80, v73, v58
	ds_bpermute_b32 v81, v73, v59
	s_waitcnt lgkmcnt(6)
	v_pk_mul_f32 v[56:57], v[92:93], v[56:57]
	s_waitcnt lgkmcnt(3)
	v_pk_mul_f32 v[78:79], v[94:95], v[78:79]
	v_pk_fma_f32 v[60:61], v[60:61], v[68:69], v[56:57]
	s_waitcnt lgkmcnt(2)
	v_pk_mul_f32 v[56:57], v[90:91], v[76:77]
	s_waitcnt lgkmcnt(0)
	v_pk_mul_f32 v[76:77], v[88:89], v[80:81]
	v_pk_fma_f32 v[62:63], v[62:63], v[70:71], v[78:79]
	v_pk_fma_f32 v[58:59], v[58:59], v[66:67], v[76:77]
	v_pk_fma_f32 v[74:75], v[74:75], v[64:65], v[56:57]

;     DI void operator()(const f32x4 (&acc)[2][2][4][2], const pg8::Unit& u, int wr, int wc, int fr, int fq) const {
;     ...
;                 if (part) { const f32x4* pq = (const f32x4*)(part + (size_t)row * 16); const f32x4 t4 = (pq[0] + pq[1]) + (pq[2] + pq[3]); rs = 1.0f / sqrtf(((t4.x + t4.y) + (t4.z + t4.w)) * (1.f / DM) + NORM_EPS); }
;                 f32x4 c0 = {1.f, 1.f, 1.f, 1.f}, c1 = c0, s0 = {0.f, 0.f, 0.f, 0.f}, s1 = s0;
;                 if (do_rope && mine) { const float* cs = rope + (size_t)row * 16; c0 = *(const f32x4*)cs; c1 = *(const f32x4*)(cs + 4); s0 = *(const f32x4*)(cs + 8) * sgn; s1 = *(const f32x4*)(cs + 12) * sgn; }
; #pragma unroll
;                 for (int bj = 0; bj < 2; ++bj) {
;                     f32x4 v0 = acc[ai][bj][m][0] * rs, v1 = acc[ai][bj][m][1] * rs;
;                     if (act == 2) {
; #pragma unroll
;                         for (int k = 0; k < 4; ++k) { const float a = fmaxf(v0[k], 0.f), b = fmaxf(v1[k], 0.f); v0[k] = a * a; v1[k] = b * b; }
;                     }
;                     if (do_rope) {
;                         f32x4 p0, p1;
; #pragma unroll
;                         for (int k = 0; k < 4; ++k) { p0[k] = __shfl_xor(v0[k], 16); p1[k] = __shfl_xor(v1[k], 16); }
;                         v0 = v0 * c0 + p0 * s0; v1 = v1 * c1 + p1 * s1;
.LBB0_198:
	s_or_b64 exec, exec, s[10:11]
	s_waitcnt vmcnt(0)
	v_pk_add_f32 v[66:67], v[70:71], v[66:67]
	v_pk_add_f32 v[64:65], v[68:69], v[64:65]
	v_pk_add_f32 v[56:57], v[60:61], v[56:57]
	v_pk_add_f32 v[58:59], v[62:63], v[58:59]
	v_pk_add_f32 v[56:57], v[64:65], v[56:57]
	v_pk_add_f32 v[58:59], v[66:67], v[58:59]
	v_add_f32_e32 v56, v56, v57
	v_add_f32_e32 v57, v58, v59
	v_add_f32_e32 v56, v56, v57
	v_fmamk_f32 v56, v56, 0x3a800000, v204
	v_mul_f32_e32 v57, 0x4f800000, v56
	v_cmp_gt_f32_e32 vcc, s70, v56
	s_nop 1
	v_cndmask_b32_e32 v56, v56, v57, vcc
	v_sqrt_f32_e32 v57, v56
	s_nop 0
	s_nop 0
	v_mov_b32_e32 v58, v57
	s_nop 1
	v_mov_b32_e32 v57, v58
	v_mul_f32_e32 v58, 0x37800000, v57
	v_cndmask_b32_e32 v57, v57, v58, vcc
	v_cmp_class_f32_e32 vcc, v56, v205
	s_nop 1
	v_cndmask_b32_e32 v56, v57, v56, vcc
	v_div_scale_f32 v57, s[10:11], v56, v56, 1.0
	v_rcp_f32_e32 v58, v57
	s_nop 0
	v_fma_f32 v59, -v57, v58, 1.0
	v_fmac_f32_e32 v58, v59, v58
	v_div_scale_f32 v59, vcc, 1.0, v56, 1.0
	v_mul_f32_e32 v60, v59, v58
	v_fma_f32 v61, -v57, v60, v59
	v_fmac_f32_e32 v60, v61, v58
	v_rcp_f32_e32 v57, v56
	s_nop 0
	v_mul_f32_e32 v56, 1.0, v57
	v_pk_mul_f32 v[46:47], v[46:47], v[56:57] op_sel_hi:[1,0]
	v_pk_mul_f32 v[44:45], v[44:45], v[56:57] op_sel_hi:[1,0]
	v_pk_mul_f32 v[42:43], v[42:43], v[56:57] op_sel_hi:[1,0]
	s_and_b64 vcc, exec, s[8:9]
	v_pk_mul_f32 v[58:59], v[40:41], v[56:57] op_sel_hi:[1,0]
	s_cbranch_vccnz .LBB0_200
	v_and_b32_e32 v41, 64, v206
	v_xor_b32_e32 v40, 16, v206
	v_add_u32_e32 v41, 64, v41
	v_cmp_lt_i32_e32 vcc, v40, v41
	s_nop 1
	v_cndmask_b32_e32 v40, v206, v40, vcc
	v_lshlrev_b32_e32 v57, 2, v40
	ds_bpermute_b32 v40, v57, v44
	ds_bpermute_b32 v41, v57, v45
	ds_bpermute_b32 v60, v57, v58
	ds_bpermute_b32 v62, v57, v46
	ds_bpermute_b32 v63, v57, v47
	ds_bpermute_b32 v61, v57, v59
	ds_bpermute_b32 v64, v57, v42
	ds_bpermute_b32 v65, v57, v43
	s_waitcnt lgkmcnt(6)
	v_pk_mul_f32 v[40:41], v[76:77], v[40:41]
	s_waitcnt lgkmcnt(3)
	v_pk_mul_f32 v[62:63], v[78:79], v[62:63]
	v_pk_fma_f32 v[44:45], v[44:45], v[52:53], v[40:41]
	s_waitcnt lgkmcnt(2)
	v_pk_mul_f32 v[40:41], v[74:75], v[60:61]
	s_waitcnt lgkmcnt(0)
	v_pk_mul_f32 v[60:61], v[72:73], v[64:65]
	v_pk_fma_f32 v[46:47], v[46:47], v[54:55], v[62:63]
	v_pk_fma_f32 v[42:43], v[42:43], v[50:51], v[60:61]
	v_pk_fma_f32 v[58:59], v[58:59], v[48:49], v[40:41]

;     DI void operator()(const f32x4 (&acc)[2][2][4][2], const pg8::Unit& u, int wr, int wc, int fr, int fq) const {
;     ...
;                 if (part) { const f32x4* pq = (const f32x4*)(part + (size_t)row * 16); const f32x4 t4 = (pq[0] + pq[1]) + (pq[2] + pq[3]); rs = 1.0f / sqrtf(((t4.x + t4.y) + (t4.z + t4.w)) * (1.f / DM) + NORM_EPS); }
;                 f32x4 c0 = {1.f, 1.f, 1.f, 1.f}, c1 = c0, s0 = {0.f, 0.f, 0.f, 0.f}, s1 = s0;
;                 if (do_rope && mine) { const float* cs = rope + (size_t)row * 16; c0 = *(const f32x4*)cs; c1 = *(const f32x4*)(cs + 4); s0 = *(const f32x4*)(cs + 8) * sgn; s1 = *(const f32x4*)(cs + 12) * sgn; }
; #pragma unroll
;                 for (int bj = 0; bj < 2; ++bj) {
;                     f32x4 v0 = acc[ai][bj][m][0] * rs, v1 = acc[ai][bj][m][1] * rs;
;                     if (act == 2) {
; #pragma unroll
;                         for (int k = 0; k < 4; ++k) { const float a = fmaxf(v0[k], 0.f), b = fmaxf(v1[k], 0.f); v0[k] = a * a; v1[k] = b * b; }
;                     }
;                     if (do_rope) {
;                         f32x4 p0, p1;
; #pragma unroll
;                         for (int k = 0; k < 4; ++k) { p0[k] = __shfl_xor(v0[k], 16); p1[k] = __shfl_xor(v1[k], 16); }
;                         v0 = v0 * c0 + p0 * s0; v1 = v1 * c1 + p1 * s1;
.LBB0_204:
	s_or_b64 exec, exec, s[10:11]
	s_waitcnt vmcnt(0)
	v_pk_add_f32 v[50:51], v[54:55], v[50:51]
	v_pk_add_f32 v[48:49], v[52:53], v[48:49]
	v_pk_add_f32 v[40:41], v[44:45], v[40:41]
	v_pk_add_f32 v[42:43], v[46:47], v[42:43]
	v_pk_add_f32 v[40:41], v[48:49], v[40:41]
	v_pk_add_f32 v[42:43], v[50:51], v[42:43]
	v_add_f32_e32 v40, v40, v41
	v_add_f32_e32 v41, v42, v43
	v_add_f32_e32 v40, v40, v41
	v_fmamk_f32 v40, v40, 0x3a800000, v204
	v_mul_f32_e32 v41, 0x4f800000, v40
	v_cmp_gt_f32_e32 vcc, s70, v40
	s_nop 1
	v_cndmask_b32_e32 v40, v40, v41, vcc
	v_sqrt_f32_e32 v41, v40
	s_nop 0
	s_nop 0
	v_mov_b32_e32 v42, v41
	s_nop 1
	v_mov_b32_e32 v41, v42
	v_mul_f32_e32 v42, 0x37800000, v41
	v_cndmask_b32_e32 v41, v41, v42, vcc
	v_cmp_class_f32_e32 vcc, v40, v205
	s_nop 1
	v_cndmask_b32_e32 v40, v41, v40, vcc
	v_div_scale_f32 v41, s[10:11], v40, v40, 1.0
	v_rcp_f32_e32 v42, v41
	s_nop 0
	v_fma_f32 v43, -v41, v42, 1.0
	v_fmac_f32_e32 v42, v43, v42
	v_div_scale_f32 v43, vcc, 1.0, v40, 1.0
	v_mul_f32_e32 v44, v43, v42
	v_fma_f32 v45, -v41, v44, v43
	v_fmac_f32_e32 v44, v45, v42
	v_rcp_f32_e32 v41, v40
	s_nop 0
	v_mul_f32_e32 v40, 1.0, v41
	v_pk_mul_f32 v[30:31], v[30:31], v[40:41] op_sel_hi:[1,0]
	v_pk_mul_f32 v[28:29], v[28:29], v[40:41] op_sel_hi:[1,0]
	v_pk_mul_f32 v[26:27], v[26:27], v[40:41] op_sel_hi:[1,0]
	s_and_b64 vcc, exec, s[8:9]
	v_pk_mul_f32 v[42:43], v[24:25], v[40:41] op_sel_hi:[1,0]
	s_cbranch_vccnz .LBB0_206
	v_and_b32_e32 v25, 64, v206
	v_xor_b32_e32 v24, 16, v206
	v_add_u32_e32 v25, 64, v25
	v_cmp_lt_i32_e32 vcc, v24, v25
	s_nop 1
	v_cndmask_b32_e32 v24, v206, v24, vcc
	v_lshlrev_b32_e32 v41, 2, v24
	ds_bpermute_b32 v24, v41, v28
	ds_bpermute_b32 v25, v41, v29
	ds_bpermute_b32 v44, v41, v42
	ds_bpermute_b32 v46, v41, v30
	ds_bpermute_b32 v47, v41, v31
	ds_bpermute_b32 v45, v41, v43
	ds_bpermute_b32 v48, v41, v26
	ds_bpermute_b32 v49, v41, v27
	s_waitcnt lgkmcnt(6)
	v_pk_mul_f32 v[24:25], v[60:61], v[24:25]
	s_waitcnt lgkmcnt(3)
	v_pk_mul_f32 v[46:47], v[62:63], v[46:47]
	v_pk_fma_f32 v[28:29], v[28:29], v[36:37], v[24:25]
	s_waitcnt lgkmcnt(2)
	v_pk_mul_f32 v[24:25], v[58:59], v[44:45]
	s_waitcnt lgkmcnt(0)
	v_pk_mul_f32 v[44:45], v[56:57], v[48:49]
	v_pk_fma_f32 v[30:31], v[30:31], v[38:39], v[46:47]
	v_pk_fma_f32 v[26:27], v[26:27], v[34:35], v[44:45]
	v_pk_fma_f32 v[42:43], v[42:43], v[32:33], v[24:25]

;     DI void operator()(const f32x4 (&acc)[2][2][4][2], const pg8::Unit& u, int wr, int wc, int fr, int fq) const {
;     ...
;                 if (part) { const f32x4* pq = (const f32x4*)(part + (size_t)row * 16); const f32x4 t4 = (pq[0] + pq[1]) + (pq[2] + pq[3]); rs = 1.0f / sqrtf(((t4.x + t4.y) + (t4.z + t4.w)) * (1.f / DM) + NORM_EPS); }
;                 f32x4 c0 = {1.f, 1.f, 1.f, 1.f}, c1 = c0, s0 = {0.f, 0.f, 0.f, 0.f}, s1 = s0;
;                 if (do_rope && mine) { const float* cs = rope + (size_t)row * 16; c0 = *(const f32x4*)cs; c1 = *(const f32x4*)(cs + 4); s0 = *(const f32x4*)(cs + 8) * sgn; s1 = *(const f32x4*)(cs + 12) * sgn; }
; #pragma unroll
;                 for (int bj = 0; bj < 2; ++bj) {
;                     f32x4 v0 = acc[ai][bj][m][0] * rs, v1 = acc[ai][bj][m][1] * rs;
;                     if (act == 2) {
; #pragma unroll
;                         for (int k = 0; k < 4; ++k) { const float a = fmaxf(v0[k], 0.f), b = fmaxf(v1[k], 0.f); v0[k] = a * a; v1[k] = b * b; }
;                     }
;                     if (do_rope) {
;                         f32x4 p0, p1;
; #pragma unroll
;                         for (int k = 0; k < 4; ++k) { p0[k] = __shfl_xor(v0[k], 16); p1[k] = __shfl_xor(v1[k], 16); }
;                         v0 = v0 * c0 + p0 * s0; v1 = v1 * c1 + p1 * s1;
.LBB0_210:
	s_or_b64 exec, exec, s[10:11]
	s_waitcnt vmcnt(0)
	v_pk_add_f32 v[34:35], v[38:39], v[34:35]
	v_pk_add_f32 v[32:33], v[36:37], v[32:33]
	v_pk_add_f32 v[24:25], v[28:29], v[24:25]
	v_pk_add_f32 v[26:27], v[30:31], v[26:27]
	v_pk_add_f32 v[24:25], v[32:33], v[24:25]
	v_pk_add_f32 v[26:27], v[34:35], v[26:27]
	v_add_f32_e32 v24, v24, v25
	v_add_f32_e32 v25, v26, v27
	v_add_f32_e32 v24, v24, v25
	v_fmamk_f32 v24, v24, 0x3a800000, v204
	v_mul_f32_e32 v25, 0x4f800000, v24
	v_cmp_gt_f32_e32 vcc, s70, v24
	s_nop 1
	v_cndmask_b32_e32 v24, v24, v25, vcc
	v_sqrt_f32_e32 v25, v24
	s_nop 0
	s_nop 0
	v_mov_b32_e32 v26, v25
	s_nop 1
	v_mov_b32_e32 v25, v26
	v_mul_f32_e32 v26, 0x37800000, v25
	v_cndmask_b32_e32 v25, v25, v26, vcc
	v_cmp_class_f32_e32 vcc, v24, v205
	s_nop 1
	v_cndmask_b32_e32 v24, v25, v24, vcc
	v_div_scale_f32 v25, s[10:11], v24, v24, 1.0
	v_rcp_f32_e32 v26, v25
	s_nop 0
	v_fma_f32 v27, -v25, v26, 1.0
	v_fmac_f32_e32 v26, v27, v26
	v_div_scale_f32 v27, vcc, 1.0, v24, 1.0
	v_mul_f32_e32 v28, v27, v26
	v_fma_f32 v29, -v25, v28, v27
	v_fmac_f32_e32 v28, v29, v26
	v_rcp_f32_e32 v25, v24
	s_nop 0
	v_mul_f32_e32 v24, 1.0, v25
	v_pk_mul_f32 v[14:15], v[14:15], v[24:25] op_sel_hi:[1,0]
	v_pk_mul_f32 v[12:13], v[12:13], v[24:25] op_sel_hi:[1,0]
	v_pk_mul_f32 v[10:11], v[10:11], v[24:25] op_sel_hi:[1,0]
	s_and_b64 vcc, exec, s[8:9]
	v_pk_mul_f32 v[26:27], v[8:9], v[24:25] op_sel_hi:[1,0]
	s_cbranch_vccnz .LBB0_212
	v_and_b32_e32 v9, 64, v206
	v_xor_b32_e32 v8, 16, v206
	v_add_u32_e32 v9, 64, v9
	v_cmp_lt_i32_e32 vcc, v8, v9
	s_nop 1
	v_cndmask_b32_e32 v8, v206, v8, vcc
	v_lshlrev_b32_e32 v25, 2, v8
	ds_bpermute_b32 v8, v25, v12
	ds_bpermute_b32 v9, v25, v13
	ds_bpermute_b32 v28, v25, v26
	ds_bpermute_b32 v30, v25, v14
	ds_bpermute_b32 v31, v25, v15
	ds_bpermute_b32 v29, v25, v27
	ds_bpermute_b32 v32, v25, v10
	ds_bpermute_b32 v33, v25, v11
	s_waitcnt lgkmcnt(6)
	v_pk_mul_f32 v[8:9], v[44:45], v[8:9]
	s_waitcnt lgkmcnt(3)
	v_pk_mul_f32 v[30:31], v[46:47], v[30:31]
	v_pk_fma_f32 v[12:13], v[12:13], v[20:21], v[8:9]
	s_waitcnt lgkmcnt(2)
	v_pk_mul_f32 v[8:9], v[42:43], v[28:29]
	s_waitcnt lgkmcnt(0)
	v_pk_mul_f32 v[28:29], v[40:41], v[32:33]
	v_pk_fma_f32 v[14:15], v[14:15], v[22:23], v[30:31]
	v_pk_fma_f32 v[10:11], v[10:11], v[18:19], v[28:29]
	v_pk_fma_f32 v[26:27], v[26:27], v[16:17], v[8:9]

; DI void sb_unit(const bf16_t* QKV, bf16_t* ATT, LAS unsigned char* lds3, int b, int head, int qb, int wid, int lane) {
;     ...
;         if (__all(carry < -104.f)) break;
;     }
;     ...
;     bf16_t* op = ATT + (rowbase + q0 + r32) * DM + head * 64;
.LBB0_306:
	s_waitcnt vmcnt(0)
	s_and_b64 vcc, exec, s[6:7]

; #define LAS __attribute__((address_space(3)))
; #define SB_LOAD(K0) do { _Pragma("unroll") for (int c = 0; c < 4; ++c) kf[c] = *(const bf16x8*)(QKV + (rowbase + (K0) + r32) * QKVW + kcol + 16 * c + 8 * hi); \
;         _Pragma("unroll") for (int i = 0; i < 4; ++i) { const int id = lane + 64 * i, key = id >> 3, ch = id & 7; vv[i] = *(const u32x4*)(QKV + (rowbase + (K0) + key) * QKVW + vcol + ch * 8); } } while (0)
; DI void sb_unit(const bf16_t* QKV, bf16_t* ATT, LAS unsigned char* lds3, int b, int head, int qb, int wid, int lane) {
;     const int r32 = lane & 31, hi = lane >> 5;
;     const size_t rowbase = (size_t)b * SEQ;
;     const int q0 = qb * 256 + wid * 32;
;     const int qcol = head * 64, kcol = 512 + head * 64, vcol = 1024 + head * 64;
;     bf16x8 qf[4];
; #pragma unroll
;     for (int c = 0; c < 4; ++c) qf[c] = *(const bf16x8*)(QKV + (rowbase + q0 + r32) * QKVW + qcol + 16 * c + 8 * hi);
;     f32x16 o[2];
; #pragma unroll
;     for (int i = 0; i < 16; ++i) { o[0][i] = 0.f; o[1][i] = 0.f; }
;     float carry = 0.f;
;     LAS unsigned char* vimg = lds3 + wid * 4096;
;     LAS unsigned char* vrd = vimg + (4 * hi + ((lane & 15) >> 2)) * 64 + ((lane >> 4) & 1) * 32 + (lane & 3) * 8;
;     bf16x8 kf[4]; u32x4 vv[4];
;     ...
;     SB_LOAD(q0);
;     for (int k0 = q0; k0 >= 0; k0 -= 32) {
;         const bf16x8 kc0 = kf[0], kc1 = kf[1], kc2 = kf[2], kc3 = kf[3];
.LBB0_308:
	s_ashr_i32 s6, s35, 9
	s_ashr_i32 s7, s6, 31
	s_lshl_b64 s[22:23], s[6:7], 14
	s_lshl_b32 s6, s35, 8
	s_and_b32 s6, s6, 0x3f00
	s_add_i32 s6, s6, s24
	s_and_b32 s36, s35, 0x1c0
	s_ashr_i32 s7, s6, 31
	s_add_u32 s8, s22, s6
	s_addc_u32 s7, s23, s7
	v_mov_b32_e32 v129, s7
	v_or_b32_e32 v128, s8, v108
	s_cmp_lt_i32 s6, 0
	v_mov_b32_e32 v15, 0
	v_mov_b32_e32 v14, 0
	v_mov_b32_e32 v13, 0
	v_mov_b32_e32 v12, 0
	v_mov_b32_e32 v11, 0
	v_mov_b32_e32 v10, 0
	v_mov_b32_e32 v9, 0
	v_mov_b32_e32 v8, 0
	v_mov_b32_e32 v7, 0
	v_mov_b32_e32 v6, 0
	v_mov_b32_e32 v5, 0
	v_mov_b32_e32 v4, 0
	v_mov_b32_e32 v3, 0
	v_mov_b32_e32 v2, 0
	v_mov_b32_e32 v1, 0
	v_mov_b32_e32 v0, 0
	v_mov_b32_e32 v31, 0
	v_mov_b32_e32 v30, 0
	v_mov_b32_e32 v29, 0
	v_mov_b32_e32 v28, 0
	v_mov_b32_e32 v27, 0
	v_mov_b32_e32 v26, 0
	v_mov_b32_e32 v25, 0
	v_mov_b32_e32 v24, 0
	v_mov_b32_e32 v23, 0
	v_mov_b32_e32 v22, 0
	v_mov_b32_e32 v21, 0
	v_mov_b32_e32 v20, 0
	v_mov_b32_e32 v19, 0
	v_mov_b32_e32 v18, 0
	v_mov_b32_e32 v17, 0
	v_mov_b32_e32 v16, 0
	s_cbranch_scc1 .LBB0_307
	s_lshl_b32 s20, s36, 1
	v_lshl_add_u64 v[130:131], v[124:125], 0, s[20:21]
	v_or_b32_e32 v0, s8, v120
	v_mad_u64_u32 v[0:1], s[10:11], v0, s28, v[130:131]
	v_or_b32_e32 v2, s8, v118
	v_mad_i32_i24 v1, s7, v117, v1
	v_mad_u64_u32 v[2:3], s[10:11], v2, s28, v[130:131]
	v_mad_i32_i24 v3, s7, v117, v3
	global_load_dwordx4 v[76:79], v[0:1], off offset:2048
	global_load_dwordx4 v[72:75], v[2:3], off offset:2048
	v_or_b32_e32 v0, s8, v116
	v_mad_u64_u32 v[0:1], s[10:11], v0, s28, v[130:131]
	v_or_b32_e32 v2, s8, v114
	v_mad_i32_i24 v1, s7, v117, v1
	v_mad_u64_u32 v[2:3], s[8:9], v2, s28, v[130:131]
	v_mad_i32_i24 v3, s7, v117, v3
	global_load_dwordx4 v[68:71], v[0:1], off offset:2048
	global_load_dwordx4 v[64:67], v[2:3], off offset:2048
	v_mov_b64_e32 v[0:1], s[16:17]
	v_mad_u64_u32 v[0:1], s[8:9], v128, s28, v[0:1]
	v_mad_i32_i24 v1, v129, s28, v1
	v_lshl_add_u64 v[0:1], v[0:1], 0, s[20:21]
	v_mov_b32_e32 v127, v111
	v_lshl_add_u64 v[0:1], v[0:1], 0, v[126:127]
	global_load_dwordx4 v[96:99], v[0:1], off offset:1120
	global_load_dwordx4 v[100:103], v[0:1], off offset:1088
	global_load_dwordx4 v[104:107], v[0:1], off offset:1056
	global_load_dwordx4 v[32:35], v[0:1], off offset:1024
	global_load_dwordx4 v[48:51], v[0:1], off offset:96
	global_load_dwordx4 v[52:55], v[0:1], off offset:64
	global_load_dwordx4 v[56:59], v[0:1], off offset:32
	global_load_dwordx4 v[60:63], v[0:1], off
	s_and_b32 s7, s26, 0x3f00
	v_cmp_lt_i32_e32 vcc, v121, v135
	v_or_b32_e32 v134, s6, v108
	v_mov_b32_e32 v127, 0
	v_cndmask_b32_e32 v1, v119, v121, vcc
	s_add_i32 s6, s25, s7
	v_mov_b32_e32 v133, s23
	v_or_b32_e32 v132, s22, v108
	v_mov_b32_e32 v16, 0
	v_mov_b32_e32 v0, 0
	v_lshl_add_u64 v[136:137], v[122:123], 0, s[20:21]
	v_lshlrev_b32_e32 v140, 2, v1
	v_mov_b32_e32 v109, v134
	v_mov_b32_e32 v17, v127
	v_mov_b32_e32 v18, v127
	v_mov_b32_e32 v19, v127
	v_mov_b32_e32 v20, v127
	v_mov_b32_e32 v21, v127
	v_mov_b32_e32 v22, v127
	v_mov_b32_e32 v23, v127
	v_mov_b32_e32 v24, v127
	v_mov_b32_e32 v25, v127
	v_mov_b32_e32 v26, v127
	v_mov_b32_e32 v27, v127
	v_mov_b32_e32 v28, v127
	v_mov_b32_e32 v29, v127
	v_mov_b32_e32 v30, v127
	v_mov_b32_e32 v31, v127
	v_mov_b32_e32 v1, v127
	v_mov_b32_e32 v2, v127
	v_mov_b32_e32 v3, v127
	v_mov_b32_e32 v4, v127
	v_mov_b32_e32 v5, v127
	v_mov_b32_e32 v6, v127
	v_mov_b32_e32 v7, v127
	v_mov_b32_e32 v8, v127
	v_mov_b32_e32 v9, v127
	v_mov_b32_e32 v10, v127
	v_mov_b32_e32 v11, v127
	v_mov_b32_e32 v12, v127
	v_mov_b32_e32 v13, v127
	v_mov_b32_e32 v14, v127
	v_mov_b32_e32 v15, v127
	s_mov_b32 s20, s6
	s_waitcnt vmcnt(7)
	v_mov_b64_e32 v[92:93], v[96:97]
	s_waitcnt vmcnt(6)
	v_mov_b64_e32 v[88:89], v[100:101]
	s_waitcnt vmcnt(5)
	v_mov_b64_e32 v[84:85], v[104:105]
	s_waitcnt vmcnt(4)
	v_mov_b64_e32 v[82:83], v[34:35]
	v_mov_b64_e32 v[80:81], v[32:33]
	v_mov_b64_e32 v[86:87], v[106:107]
	v_mov_b64_e32 v[90:91], v[102:103]
	v_mov_b64_e32 v[94:95], v[98:99]
	s_waitcnt vmcnt(0)

; DI int crow(int i, int hi) { return (i & 3) + 8 * (i >> 2) + 4 * hi; }
; DI f32x16 mfma32(bf16x8 a, bf16x8 b, f32x16 c) { return __builtin_amdgcn_mfma_f32_32x32x16_bf16(a, b, c, 0, 0, 0); }
; DI void sb_unit(const bf16_t* QKV, bf16_t* ATT, LAS unsigned char* lds3, int b, int head, int qb, int wid, int lane) {
;     ...
;         f32x16 s;
; #pragma unroll
;         for (int i = 0; i < 16; ++i) s[i] = 0.f;
;         s = mfma32(kc0, qf[0], s); s = mfma32(kc1, qf[1], s); s = mfma32(kc2, qf[2], s); s = mfma32(kc3, qf[3], s);
;         const int qpos = q0 + r32;
;         float lk[16];
; #pragma unroll
;         for (int i = 0; i < 16; ++i) {
;             const float z = s[i] * 0.125f;
;             const bool past = (k0 + crow(i, hi)) < qpos;
;             const float sp = fmaxf(z, 0.f) + __logf(1.f + __expf(-fabsf(z)));
;             lk[i] = past ? -sp : 0.f;
;             s[i] = past ? z : -INFINITY;
;         }
.LBB0_312:
	v_mfma_f32_32x32x16_bf16 v[32:47], v[32:35], v[60:63], 0
	s_waitcnt lgkmcnt(0)
	v_mfma_f32_32x32x16_bf16 v[32:47], v[104:107], v[56:59], v[32:47]
	v_mfma_f32_32x32x16_bf16 v[32:47], v[100:103], v[52:55], v[32:47]
	v_add_u32_e32 v100, s20, v112
	v_add_u32_e32 v101, 32, v100
	v_add_u32_e32 v102, 33, v100
	v_or_b32_e32 v160, 17, v101
	v_or_b32_e32 v158, 24, v101
	v_or_b32_e32 v159, 16, v101
	v_cmp_lt_i32_e64 s[12:13], v158, v109
	v_mfma_f32_32x32x16_bf16 v[32:47], v[96:99], v[48:51], v[32:47]
	v_or_b32_e32 v161, 26, v101
	v_or_b32_e32 v162, 27, v101
	s_nop 9
	v_mul_f32_e32 v32, 0x3e000000, v32
	v_mul_f32_e32 v33, 0x3e000000, v33
	v_mul_f32_e64 v97, |v32|, s29
	v_mul_f32_e64 v98, |v33|, s29
	v_exp_f32_e32 v97, v97
	v_exp_f32_e32 v98, v98
	v_mul_f32_e32 v34, 0x3e000000, v34
	v_mul_f32_e64 v99, |v34|, s29
	v_add_f32_e32 v97, 1.0, v97
	v_add_f32_e32 v98, 1.0, v98
	v_cmp_gt_f32_e32 vcc, s30, v97
	v_cmp_gt_f32_e64 s[6:7], s30, v98
	v_exp_f32_e32 v99, v99
	v_cndmask_b32_e64 v104, 0, 32, vcc
	v_cndmask_b32_e64 v105, 0, 32, s[6:7]
	v_ldexp_f32 v97, v97, v104
	v_ldexp_f32 v98, v98, v105
	v_log_f32_e32 v97, v97
	v_log_f32_e32 v98, v98
	v_cndmask_b32_e32 v104, 0, v138, vcc
	v_add_f32_e32 v99, 1.0, v99
	v_mul_f32_e32 v106, 0x3f317217, v97
	v_mul_f32_e32 v107, 0x3f317217, v98
	v_fma_f32 v106, v97, s31, -v106
	v_fma_f32 v107, v98, s31, -v107
	v_fmac_f32_e32 v106, 0x3377d1cf, v97
	v_fmac_f32_e32 v107, 0x3377d1cf, v98
	v_fmac_f32_e32 v106, 0x3f317217, v97
	v_cmp_lt_f32_e64 vcc, |v97|, s33
	v_fmac_f32_e32 v107, 0x3f317217, v98
	v_cndmask_b32_e64 v105, 0, v138, s[6:7]
	v_cndmask_b32_e32 v97, v97, v106, vcc
	v_cmp_lt_f32_e64 vcc, |v98|, s33
	v_cmp_gt_f32_e64 s[6:7], s30, v99
	v_max_f32_e32 v96, 0, v32
	v_cndmask_b32_e32 v98, v98, v107, vcc
	v_cmp_lt_i32_e32 vcc, v101, v134
	v_sub_f32_e32 v97, v97, v104
	v_max_f32_e32 v103, 0, v33
	v_cndmask_b32_e32 v104, v139, v32, vcc
	v_cndmask_b32_e64 v32, 0, 32, s[6:7]
	v_ldexp_f32 v32, v99, v32
	v_log_f32_e32 v32, v32
	v_sub_f32_e32 v98, v98, v105
	v_add_f32_e32 v96, v96, v97
	v_add_f32_e32 v97, v103, v98
	v_cndmask_b32_e64 v103, 0, -v96, vcc
	v_cmp_lt_i32_e32 vcc, v102, v134
	v_mul_f32_e32 v35, 0x3e000000, v35
	v_max_f32_e32 v96, 0, v34
	v_cndmask_b32_e64 v102, 0, -v97, vcc
	v_mul_f32_e32 v97, 0x3f317217, v32
	v_fma_f32 v97, v32, s31, -v97
	v_fmac_f32_e32 v97, 0x3377d1cf, v32
	v_cndmask_b32_e32 v105, v139, v33, vcc
	v_fmac_f32_e32 v97, 0x3f317217, v32
	v_cmp_lt_f32_e64 vcc, |v32|, s33
	v_add_u32_e32 v33, 34, v100
	v_mul_f32_e32 v36, 0x3e000000, v36
	v_cndmask_b32_e32 v32, v32, v97, vcc
	v_cndmask_b32_e64 v97, 0, v138, s[6:7]
	v_sub_f32_e32 v32, v32, v97
	v_mul_f32_e64 v97, |v35|, s29
	v_exp_f32_e32 v97, v97
	v_add_f32_e32 v32, v96, v32
	v_cmp_lt_i32_e32 vcc, v33, v134
	v_mul_f32_e32 v99, 0x3e000000, v40
	v_mul_f32_e32 v151, 0x3e000000, v42
	v_cndmask_b32_e64 v106, 0, -v32, vcc
	v_add_f32_e32 v32, 1.0, v97
	v_cmp_gt_f32_e64 s[6:7], s30, v32
	v_cndmask_b32_e32 v107, v139, v34, vcc
	v_max_f32_e32 v34, 0, v35
	v_cndmask_b32_e64 v33, 0, 32, s[6:7]
	v_ldexp_f32 v32, v32, v33
	v_log_f32_e32 v32, v32
	v_add_u32_e32 v33, 35, v100
	v_mul_f32_e32 v152, 0x3e000000, v43
	v_mul_f32_e32 v153, 0x3e000000, v44
	v_mul_f32_e32 v96, 0x3f317217, v32
	v_fma_f32 v96, v32, s31, -v96
	v_fmac_f32_e32 v96, 0x3377d1cf, v32
	v_fmac_f32_e32 v96, 0x3f317217, v32
	v_cmp_lt_f32_e64 vcc, |v32|, s33
	v_mul_f32_e32 v154, 0x3e000000, v45
	v_mul_f32_e32 v155, 0x3e000000, v46
	v_cndmask_b32_e32 v32, v32, v96, vcc
	v_cndmask_b32_e64 v96, 0, v138, s[6:7]
	v_sub_f32_e32 v32, v32, v96
	v_mul_f32_e64 v96, |v36|, s29
	v_exp_f32_e32 v96, v96
	v_add_f32_e32 v32, v34, v32
	v_cmp_lt_i32_e32 vcc, v33, v134
	v_max_f32_e32 v34, 0, v36
	v_mul_f32_e64 v43, |v155|, s29
	v_cndmask_b32_e64 v141, 0, -v32, vcc
	v_add_f32_e32 v32, 1.0, v96
	v_cmp_gt_f32_e64 s[6:7], s30, v32
	v_cndmask_b32_e32 v142, v139, v35, vcc
	v_exp_f32_e32 v43, v43
	v_cndmask_b32_e64 v33, 0, 32, s[6:7]
	v_ldexp_f32 v32, v32, v33
	v_log_f32_e32 v32, v32
	v_add_u32_e32 v33, 40, v100
	v_mul_f32_e32 v47, 0x3e000000, v47
	v_mul_f32_e64 v46, |v47|, s29
	v_mul_f32_e32 v35, 0x3f317217, v32
	v_fma_f32 v35, v32, s31, -v35
	v_fmac_f32_e32 v35, 0x3377d1cf, v32
	v_fmac_f32_e32 v35, 0x3f317217, v32
	v_cmp_lt_f32_e64 vcc, |v32|, s33
	v_exp_f32_e32 v46, v46
	v_max_f32_e32 v40, 0, v151
	v_cndmask_b32_e32 v32, v32, v35, vcc
	v_cndmask_b32_e64 v35, 0, v138, s[6:7]
	v_sub_f32_e32 v32, v32, v35
	v_mul_f32_e32 v35, 0x3e000000, v37
	v_mul_f32_e64 v37, |v35|, s29
	v_exp_f32_e32 v37, v37
	v_add_f32_e32 v32, v34, v32
	v_cmp_lt_i32_e32 vcc, v33, v134
	v_max_f32_e32 v34, 0, v35
	v_max_f32_e32 v96, 0, v152
	v_cndmask_b32_e64 v143, 0, -v32, vcc
	v_add_f32_e32 v32, 1.0, v37
	v_cmp_gt_f32_e64 s[6:7], s30, v32
	v_cndmask_b32_e32 v144, v139, v36, vcc
	v_max_f32_e32 v97, 0, v47
	v_cndmask_b32_e64 v33, 0, 32, s[6:7]
	v_ldexp_f32 v32, v32, v33
	v_log_f32_e32 v32, v32
	v_add_u32_e32 v33, 41, v100
	v_add_f32_e32 v98, v106, v141
	v_mul_f32_e32 v36, 0x3f317217, v32
	v_fma_f32 v36, v32, s31, -v36
	v_fmac_f32_e32 v36, 0x3377d1cf, v32
	v_fmac_f32_e32 v36, 0x3f317217, v32
	v_cmp_lt_f32_e64 vcc, |v32|, s33
	s_nop 1
	v_cndmask_b32_e32 v32, v32, v36, vcc
	v_cndmask_b32_e64 v36, 0, v138, s[6:7]
	v_sub_f32_e32 v32, v32, v36
	v_mul_f32_e32 v36, 0x3e000000, v38
	v_mul_f32_e64 v37, |v36|, s29
	v_exp_f32_e32 v37, v37
	v_add_f32_e32 v32, v34, v32
	v_cmp_lt_i32_e32 vcc, v33, v134
	v_max_f32_e32 v34, 0, v36
	s_nop 0
	v_cndmask_b32_e64 v145, 0, -v32, vcc
	v_add_f32_e32 v32, 1.0, v37
	v_cmp_gt_f32_e64 s[6:7], s30, v32
	v_cndmask_b32_e32 v146, v139, v35, vcc
	s_nop 0
	v_cndmask_b32_e64 v33, 0, 32, s[6:7]
	v_ldexp_f32 v32, v32, v33
	v_log_f32_e32 v32, v32
; DI float xhalf(float v) { return __shfl_xor(v, 32); }
; DI int crow(int i, int hi) { return (i & 3) + 8 * (i >> 2) + 4 * hi; }
; DI void sb_unit(const bf16_t* QKV, bf16_t* ATT, LAS unsigned char* lds3, int b, int head, int qb, int wid, int lane) {
;     ...
;         for (int i = 0; i < 16; ++i) {
;             const float z = s[i] * 0.125f;
;             const bool past = (k0 + crow(i, hi)) < qpos;
;             const float sp = fmaxf(z, 0.f) + __logf(1.f + __expf(-fabsf(z)));
;             lk[i] = past ? -sp : 0.f;
;             s[i] = past ? z : -INFINITY;
;         }
;         float gs[4], go[4];
; #pragma unroll
;         for (int g = 0; g < 4; ++g) { gs[g] = (lk[4 * g] + lk[4 * g + 1]) + (lk[4 * g + 2] + lk[4 * g + 3]); go[g] = xhalf(gs[g]); }
;         const float ps0 = gs[0] + go[0], ps1 = gs[1] + go[1], ps2 = gs[2] + go[2], ps3 = gs[3] + go[3];
	v_add_u32_e32 v33, 42, v100
	v_mul_f32_e32 v35, 0x3f317217, v32
	v_fma_f32 v35, v32, s31, -v35
	v_fmac_f32_e32 v35, 0x3377d1cf, v32
	v_fmac_f32_e32 v35, 0x3f317217, v32
	v_cmp_lt_f32_e64 vcc, |v32|, s33
	s_nop 1
	v_cndmask_b32_e32 v32, v32, v35, vcc
	v_cndmask_b32_e64 v35, 0, v138, s[6:7]
	v_sub_f32_e32 v32, v32, v35
	v_mul_f32_e32 v35, 0x3e000000, v39
	v_mul_f32_e64 v37, |v35|, s29
	v_exp_f32_e32 v37, v37
	v_add_f32_e32 v32, v34, v32
	v_cmp_lt_i32_e32 vcc, v33, v134
	v_max_f32_e32 v34, 0, v35
	v_mul_f32_e64 v39, |v154|, s29
	v_cndmask_b32_e64 v147, 0, -v32, vcc
	v_add_f32_e32 v32, 1.0, v37
	v_cmp_gt_f32_e64 s[6:7], s30, v32
	v_cndmask_b32_e32 v148, v139, v36, vcc
	v_exp_f32_e32 v39, v39
	v_cndmask_b32_e64 v33, 0, 32, s[6:7]
	v_ldexp_f32 v32, v32, v33
	v_log_f32_e32 v32, v32
	v_cndmask_b32_e64 v37, 0, v138, s[6:7]
	v_add_u32_e32 v33, 43, v100
	v_cmp_lt_i32_e64 s[6:7], v33, v134
	v_mul_f32_e32 v36, 0x3f317217, v32
	v_fma_f32 v36, v32, s31, -v36
	v_fmac_f32_e32 v36, 0x3377d1cf, v32
	v_fmac_f32_e32 v36, 0x3f317217, v32
	v_cmp_lt_f32_e64 vcc, |v32|, s33
	v_mul_f32_e32 v100, 0x3e000000, v41
	v_cndmask_b32_e64 v150, v139, v35, s[6:7]
	v_cndmask_b32_e32 v32, v32, v36, vcc
	v_mul_f32_e64 v36, |v99|, s29
	v_exp_f32_e32 v36, v36
	v_sub_f32_e32 v32, v32, v37
	v_add_f32_e32 v32, v34, v32
	v_mul_f32_e64 v35, |v100|, s29
	v_add_f32_e32 v34, 1.0, v36
	v_cmp_gt_f32_e32 vcc, s30, v34
	v_exp_f32_e32 v35, v35
	v_cndmask_b32_e64 v149, 0, -v32, s[6:7]
	v_cndmask_b32_e64 v36, 0, 32, vcc
	v_ldexp_f32 v34, v34, v36
	v_log_f32_e32 v34, v34
	v_mul_f32_e64 v37, |v151|, s29
	v_exp_f32_e32 v37, v37
	v_max_f32_e32 v32, 0, v99
	v_mul_f32_e32 v33, 0x3f317217, v34
	v_fma_f32 v33, v34, s31, -v33
	v_fmac_f32_e32 v33, 0x3377d1cf, v34
	v_fmac_f32_e32 v33, 0x3f317217, v34
	v_cmp_lt_f32_e64 s[6:7], |v34|, s33
	v_max_f32_e32 v36, 0, v100
	s_nop 0
	v_cndmask_b32_e64 v33, v34, v33, s[6:7]
	v_add_f32_e32 v34, 1.0, v35
	v_cmp_gt_f32_e64 s[6:7], s30, v34
	s_nop 1
	v_cndmask_b32_e64 v35, 0, 32, s[6:7]
	v_ldexp_f32 v34, v34, v35
	v_log_f32_e32 v35, v34
	v_cndmask_b32_e32 v34, 0, v138, vcc
	v_sub_f32_e32 v34, v33, v34
	v_mul_f32_e32 v33, 0x3f317217, v35
	v_fma_f32 v33, v35, s31, -v33
	v_fmac_f32_e32 v33, 0x3377d1cf, v35
	v_fmac_f32_e32 v33, 0x3f317217, v35
	v_cmp_lt_f32_e64 vcc, |v35|, s33
	s_nop 1
	v_cndmask_b32_e32 v33, v35, v33, vcc
	v_add_f32_e32 v35, 1.0, v37
	v_cmp_gt_f32_e32 vcc, s30, v35
	s_nop 1
	v_cndmask_b32_e64 v37, 0, 32, vcc
	v_ldexp_f32 v35, v35, v37
	v_log_f32_e32 v35, v35
	v_cndmask_b32_e64 v37, 0, v138, s[6:7]
	v_sub_f32_e32 v38, v33, v37
	v_mul_f32_e64 v37, |v152|, s29
	v_mul_f32_e32 v33, 0x3f317217, v35
	v_exp_f32_e32 v37, v37
	v_fma_f32 v33, v35, s31, -v33
	v_fmac_f32_e32 v33, 0x3377d1cf, v35
	v_fmac_f32_e32 v33, 0x3f317217, v35
	v_cmp_lt_f32_e64 s[6:7], |v35|, s33
	s_nop 1
	v_cndmask_b32_e64 v33, v35, v33, s[6:7]
	v_add_f32_e32 v35, 1.0, v37
	v_cmp_gt_f32_e64 s[6:7], s30, v35
	s_nop 1
	v_cndmask_b32_e64 v37, 0, 32, s[6:7]
	v_ldexp_f32 v35, v35, v37
	v_log_f32_e32 v35, v35
	v_cndmask_b32_e32 v37, 0, v138, vcc
	v_sub_f32_e32 v42, v33, v37
	v_mul_f32_e64 v37, |v153|, s29
	v_mul_f32_e32 v33, 0x3f317217, v35
	v_exp_f32_e32 v37, v37
	v_fma_f32 v33, v35, s31, -v33
	v_fmac_f32_e32 v33, 0x3377d1cf, v35
	v_fmac_f32_e32 v33, 0x3f317217, v35
	v_cmp_lt_f32_e64 vcc, |v35|, s33
	s_nop 1
	v_cndmask_b32_e32 v33, v35, v33, vcc
	v_add_f32_e32 v35, 1.0, v37
	v_cmp_gt_f32_e32 vcc, s30, v35
	s_nop 1
	v_cndmask_b32_e64 v37, 0, 32, vcc
	v_ldexp_f32 v35, v35, v37
	v_log_f32_e32 v35, v35
	v_cndmask_b32_e64 v37, 0, v138, s[6:7]
	v_sub_f32_e32 v44, v33, v37
	v_max_f32_e32 v33, 0, v153
	v_mul_f32_e32 v37, 0x3f317217, v35
	v_fma_f32 v37, v35, s31, -v37
	v_fmac_f32_e32 v37, 0x3377d1cf, v35
	v_fmac_f32_e32 v37, 0x3f317217, v35
	v_cmp_lt_f32_e64 s[6:7], |v35|, s33
	s_nop 1
	v_cndmask_b32_e64 v35, v35, v37, s[6:7]
	v_add_f32_e32 v37, 1.0, v39
	v_cmp_gt_f32_e64 s[6:7], s30, v37
	s_nop 1
	v_cndmask_b32_e64 v39, 0, 32, s[6:7]
	v_ldexp_f32 v37, v37, v39
	v_log_f32_e32 v39, v37
	v_cndmask_b32_e32 v37, 0, v138, vcc
	v_sub_f32_e32 v35, v35, v37
	v_max_f32_e32 v37, 0, v154
	v_mul_f32_e32 v41, 0x3f317217, v39
	v_fma_f32 v41, v39, s31, -v41
	v_fmac_f32_e32 v41, 0x3377d1cf, v39
	v_fmac_f32_e32 v41, 0x3f317217, v39
	v_cmp_lt_f32_e64 vcc, |v39|, s33
	v_pk_add_f32 v[32:33], v[32:33], v[34:35]
	s_nop 0
	v_cndmask_b32_e32 v39, v39, v41, vcc
	v_add_f32_e32 v41, 1.0, v43
	v_cmp_gt_f32_e32 vcc, s30, v41
	s_nop 1
	v_cndmask_b32_e64 v43, 0, 32, vcc
	v_ldexp_f32 v41, v41, v43
	v_log_f32_e32 v43, v41
	v_cndmask_b32_e64 v41, 0, v138, s[6:7]
	v_sub_f32_e32 v39, v39, v41
	v_max_f32_e32 v41, 0, v155
	v_mul_f32_e32 v45, 0x3f317217, v43
	v_fma_f32 v45, v43, s31, -v45
	v_fmac_f32_e32 v45, 0x3377d1cf, v43
	v_fmac_f32_e32 v45, 0x3f317217, v43
	v_cmp_lt_f32_e64 s[6:7], |v43|, s33
	s_nop 1
	v_cndmask_b32_e64 v43, v43, v45, s[6:7]
	v_add_f32_e32 v45, 1.0, v46
	v_cmp_gt_f32_e64 s[6:7], s30, v45
	s_nop 1
	v_cndmask_b32_e64 v46, 0, 32, s[6:7]
	v_ldexp_f32 v45, v45, v46
	v_log_f32_e32 v45, v45
	v_cndmask_b32_e32 v46, 0, v138, vcc
	v_sub_f32_e32 v43, v43, v46
	v_pk_add_f32 v[34:35], v[40:41], v[42:43]
	v_mul_f32_e32 v46, 0x3f317217, v45
	v_fma_f32 v46, v45, s31, -v46
	v_fmac_f32_e32 v46, 0x3377d1cf, v45
	v_fmac_f32_e32 v46, 0x3f317217, v45
	v_cmp_lt_f32_e64 vcc, |v45|, s33
	v_cndmask_b32_e64 v42, v139, v153, s[12:13]
	s_nop 0
	v_cndmask_b32_e32 v45, v45, v46, vcc
	v_cndmask_b32_e64 v46, 0, v138, s[6:7]
	v_cmp_lt_i32_e64 s[6:7], v160, v134
	v_cmp_lt_i32_e32 vcc, v159, v134
	v_sub_f32_e32 v45, v45, v46
	v_cndmask_b32_e64 v160, v139, v100, s[6:7]
	v_or_b32_e32 v100, 18, v101
	v_cmp_lt_i32_e64 s[8:9], v100, v134
	v_or_b32_e32 v100, 19, v101
	v_cndmask_b32_e32 v159, v139, v99, vcc
	v_or_b32_e32 v99, 25, v101
	v_cmp_lt_i32_e64 s[10:11], v100, v134
	v_cndmask_b32_e64 v101, 0, -v33, s[12:13]
	v_cndmask_b32_e64 v100, 0, -v32, vcc
	v_pk_add_f32 v[32:33], v[36:37], v[38:39]
	v_cndmask_b32_e64 v151, v139, v151, s[8:9]
	v_cmp_lt_i32_e32 vcc, v99, v109
	v_cndmask_b32_e64 v32, 0, -v32, s[6:7]
	v_cmp_lt_i32_e64 s[6:7], v161, v109
	v_cndmask_b32_e64 v34, 0, -v34, s[8:9]
	v_pk_add_f32 v[36:37], v[96:97], v[44:45]
	v_cmp_lt_i32_e64 s[8:9], v162, v109
	v_cndmask_b32_e64 v33, 0, -v33, vcc
	v_cndmask_b32_e64 v35, 0, -v35, s[6:7]
	v_cndmask_b32_e64 v37, 0, -v37, s[8:9]
	v_cndmask_b32_e64 v36, 0, -v36, s[10:11]
	v_pk_add_f32 v[38:39], v[100:101], v[32:33]
	v_pk_add_f32 v[40:41], v[34:35], v[36:37]
	v_add_f32_e32 v46, v103, v102
	v_pk_add_f32 v[38:39], v[38:39], v[40:41]
	v_add_f32_e32 v156, v46, v98
	v_add_f32_e32 v46, v143, v145
	v_add_f32_e32 v98, v147, v149
	ds_bpermute_b32 v40, v140, v38
	ds_bpermute_b32 v41, v140, v39
	v_add_f32_e32 v46, v46, v98
	ds_bpermute_b32 v98, v140, v46
	ds_bpermute_b32 v157, v140, v156
	v_cndmask_b32_e64 v45, v139, v47, s[8:9]
	s_waitcnt lgkmcnt(2)
; DI float xhalf(float v) { return __shfl_xor(v, 32); }
; DI f32x16 mfma32(bf16x8 a, bf16x8 b, f32x16 c) { return __builtin_amdgcn_mfma_f32_32x32x16_bf16(a, b, c, 0, 0, 0); }
; DI bf16x8 vfrag(LAS unsigned char* p) { const s16x4 lo = tr_read(p), hi = tr_read(p + 512); return __builtin_shufflevector(lo, hi, 0, 1, 2, 3, 4, 5, 6, 7); }
; DI void sb_unit(const bf16_t* QKV, bf16_t* ATT, LAS unsigned char* lds3, int b, int head, int qb, int wid, int lane) {
;     ...
;         float gs[4], go[4];
; #pragma unroll
;         for (int g = 0; g < 4; ++g) { gs[g] = (lk[4 * g] + lk[4 * g + 1]) + (lk[4 * g + 2] + lk[4 * g + 3]); go[g] = xhalf(gs[g]); }
;         const float ps0 = gs[0] + go[0], ps1 = gs[1] + go[1], ps2 = gs[2] + go[2], ps3 = gs[3] + go[3];
;         float ap[4]; ap[3] = 0.f; ap[2] = ps3; ap[1] = ps3 + ps2; ap[0] = ps3 + ps2 + ps1;
; #pragma unroll
;         for (int g = 0; g < 4; ++g) {
;             const float aft = carry + ap[g] + (hi == 0 ? go[g] : 0.f);
;             const float w3 = aft, w2 = aft + lk[4 * g + 3], w1 = w2 + lk[4 * g + 2], w0 = w1 + lk[4 * g + 1];
;             s[4 * g + 3] = __expf(s[4 * g + 3] + lk[4 * g + 3] + w3);
;             s[4 * g + 2] = __expf(s[4 * g + 2] + lk[4 * g + 2] + w2);
;             s[4 * g + 1] = __expf(s[4 * g + 1] + lk[4 * g + 1] + w1);
;             s[4 * g + 0] = __expf(s[4 * g + 0] + lk[4 * g + 0] + w0);
;         }
;         carry += (ps0 + ps1) + (ps2 + ps3);
;         const bf16x8 p0 = packP<0>(s), p1 = packP<1>(s);
;         asm volatile("s_waitcnt lgkmcnt(0)" ::: "memory");
; #pragma unroll
;         for (int dt = 0; dt < 2; ++dt) {
;             const bf16x8 v0 = vfrag(vrd + dt * 2048), v1 = vfrag(vrd + dt * 2048 + 1024);
;             o[dt] = mfma32(v0, p0, o[dt]); o[dt] = mfma32(v1, p1, o[dt]);
;         }
;         asm volatile("s_waitcnt lgkmcnt(0)" ::: "memory");
;         if (__all(carry < -104.f)) break;
;     }
	v_pk_add_f32 v[38:39], v[38:39], v[40:41]
	v_cndmask_b32_e64 v40, 0, v40, s[4:5]
	v_mov_b32_e32 v47, v38
	v_mov_b32_e32 v99, v39
	s_waitcnt lgkmcnt(1)
	v_pk_add_f32 v[96:97], v[46:47], v[98:99]
	s_waitcnt lgkmcnt(0)
	v_cndmask_b32_e64 v46, 0, v157, s[4:5]
	v_add_f32_e32 v38, v96, v97
	v_add_f32_e32 v38, v127, v38
	v_add_f32_e32 v38, v46, v38
	v_add_f32_e32 v46, v141, v38
	v_add_f32_e32 v47, v106, v46
	v_add_f32_e32 v99, v102, v47
	v_add_f32_e32 v102, v105, v102
	v_add_f32_e32 v47, v102, v47
	v_add_f32_e32 v102, v104, v103
	v_add_f32_e32 v99, v102, v99
	v_add_f32_e32 v102, v127, v97
	v_cndmask_b32_e64 v98, 0, v98, s[4:5]
	v_add_f32_e32 v98, v98, v102
	v_add_f32_e32 v105, v150, v149
	v_add_f32_e32 v102, v149, v98
	v_add_f32_e32 v98, v105, v98
	v_add_f32_e32 v105, v148, v147
	v_add_f32_e32 v39, v127, v39
	v_add_f32_e32 v103, v147, v102
	v_add_f32_e32 v102, v105, v102
	v_add_f32_e32 v105, v146, v145
	v_add_f32_e32 v39, v40, v39
	v_add_f32_e32 v104, v145, v103
	v_add_f32_e32 v103, v105, v103
	v_add_f32_e32 v105, v144, v143
	v_add_f32_e32 v40, v36, v39
	v_add_f32_e32 v106, v107, v106
	v_add_f32_e32 v104, v105, v104
	v_add_f32_e32 v105, v34, v40
	v_add_f32_e32 v46, v106, v46
	v_add_f32_e32 v106, v32, v105
	v_add_f32_e32 v32, v160, v32
	v_add_f32_e32 v32, v32, v105
	v_mul_f32_e32 v32, 0x3fb8aa3b, v32
	v_add_f32_e32 v34, v151, v34
	v_exp_f32_e32 v105, v32
	v_add_f32_e32 v32, v159, v100
	v_add_f32_e32 v34, v34, v40
	v_add_f32_e32 v32, v32, v106
	v_add_f32_e32 v141, v142, v141
	v_mul_f32_e32 v34, 0x3fb8aa3b, v34
	v_mul_f32_e32 v32, 0x3fb8aa3b, v32
	v_add_f32_e32 v38, v141, v38
	v_exp_f32_e32 v141, v34
	v_exp_f32_e32 v100, v32
	v_add_f32_e32 v32, 0, v127
	v_cndmask_b32_e64 v34, 0, v41, s[4:5]
	v_add_f32_e32 v32, v32, v34
	v_add_f32_e32 v34, v32, v37
	v_add_f32_e32 v37, v45, v37
	v_cndmask_b32_e64 v152, v139, v152, s[10:11]
	v_add_f32_e32 v32, v32, v37
	v_cndmask_b32_e64 v44, v139, v155, s[6:7]
	v_add_f32_e32 v36, v152, v36
	v_mul_f32_e32 v32, 0x3fb8aa3b, v32
	v_add_f32_e32 v36, v36, v39
	v_exp_f32_e32 v45, v32
	v_add_f32_e32 v32, v44, v35
	v_cndmask_b32_e32 v43, v139, v154, vcc
	v_mul_f32_e32 v36, 0x3fb8aa3b, v36
	v_add_f32_e32 v32, v34, v32
	v_exp_f32_e32 v107, v36
	v_add_f32_e32 v36, v35, v34
	v_mul_f32_e32 v44, 0x3fb8aa3b, v32
	v_add_f32_e32 v32, v43, v33
	v_add_f32_e32 v32, v32, v36
	v_mul_f32_e32 v38, 0x3fb8aa3b, v38
	v_mul_f32_e32 v46, 0x3fb8aa3b, v46
	v_mul_f32_e32 v47, 0x3fb8aa3b, v47
	v_mul_f32_e32 v99, 0x3fb8aa3b, v99
	v_mul_f32_e32 v98, 0x3fb8aa3b, v98
	v_mul_f32_e32 v102, 0x3fb8aa3b, v102
	v_mul_f32_e32 v103, 0x3fb8aa3b, v103
	v_mul_f32_e32 v104, 0x3fb8aa3b, v104
	v_mul_f32_e32 v32, 0x3fb8aa3b, v32
	v_exp_f32_e32 v38, v38
	v_exp_f32_e32 v46, v46
	v_exp_f32_e32 v47, v47
	v_exp_f32_e32 v99, v99
	v_exp_f32_e32 v98, v98
	v_exp_f32_e32 v102, v102
	v_exp_f32_e32 v103, v103
	v_exp_f32_e32 v104, v104
	v_add_f32_e32 v39, v33, v36
	v_exp_f32_e32 v106, v32
	ds_read_b64_tr_b16 v[32:33], v115
	ds_read_b64_tr_b16 v[34:35], v115 offset:512
	v_add_f32_e32 v36, v42, v101
	v_add_f32_e32 v101, v36, v39
	v_cvt_pk_bf16_f32 v36, v99, v47
	v_cvt_pk_bf16_f32 v37, v46, v38
	v_cvt_pk_bf16_f32 v38, v104, v103
	v_cvt_pk_bf16_f32 v39, v102, v98
	ds_read_b64_tr_b16 v[40:41], v115 offset:1024
	ds_read_b64_tr_b16 v[42:43], v115 offset:1536
	s_waitcnt lgkmcnt(2)
	v_mfma_f32_32x32x16_bf16 v[16:31], v[32:35], v[36:39], v[16:31]
	v_mul_f32_e32 v32, 0x3fb8aa3b, v101
	v_exp_f32_e32 v34, v32
	v_exp_f32_e32 v35, v44
	v_cvt_pk_bf16_f32 v32, v100, v105
	v_cvt_pk_bf16_f32 v33, v141, v107
	v_cvt_pk_bf16_f32 v34, v34, v106
	v_cvt_pk_bf16_f32 v35, v35, v45
	s_mov_b64 s[6:7], -1
	s_mov_b64 s[8:9], -1
	s_waitcnt lgkmcnt(0)
	v_mfma_f32_32x32x16_bf16 v[16:31], v[40:43], v[32:35], v[16:31]
	ds_read_b64_tr_b16 v[40:41], v115 offset:2048
	ds_read_b64_tr_b16 v[42:43], v115 offset:2560
	ds_read_b64_tr_b16 v[44:45], v115 offset:3072
	ds_read_b64_tr_b16 v[46:47], v115 offset:3584
	s_waitcnt lgkmcnt(0)
	s_waitcnt lgkmcnt(2)
	v_mfma_f32_32x32x16_bf16 v[0:15], v[40:43], v[36:39], v[0:15]
	v_add_f32_e32 v36, v156, v157
	v_add_f32_e32 v36, v36, v96
	v_add_f32_e32 v36, v36, v97
	v_add_f32_e32 v127, v127, v36
	v_cmp_gt_f32_e32 vcc, s34, v127
	s_cmp_lg_u64 vcc, exec
	s_waitcnt lgkmcnt(0)
	v_mfma_f32_32x32x16_bf16 v[0:15], v[44:47], v[32:35], v[0:15]
	s_cbranch_scc0 .LBB0_314
	s_sub_i32 s20, s20, 32
	s_cmpk_eq_i32 s20, 0xffc0
	s_mov_b64 s[6:7], 0
	s_cselect_b64 s[8:9], -1, 0
.LBB0_314:
	s_andn2_b64 vcc, exec, s[8:9]
	s_cbranch_vccz .LBB0_306
	s_waitcnt vmcnt(0)
	v_mov_b64_e32 v[32:33], v[80:81]
	v_mov_b64_e32 v[106:107], v[86:87]
	v_mov_b64_e32 v[102:103], v[90:91]
	v_mov_b64_e32 v[98:99], v[94:95]
	v_mov_b64_e32 v[34:35], v[82:83]
	v_mov_b64_e32 v[104:105], v[84:85]
	v_mov_b64_e32 v[100:101], v[88:89]
	v_mov_b64_e32 v[96:97], v[92:93]
	s_branch .LBB0_310

; DI unsigned pk_bf16(float lo, float hi) { typedef float f2 __attribute__((ext_vector_type(2))); typedef __bf16 b2 __attribute__((ext_vector_type(2))); f2 v = {lo, hi}; b2 b = __builtin_convertvector(v, b2); return __builtin_bit_cast(unsigned, b); }
;     DI void operator()(const f32x4 (&acc)[2][2][4][2], const pg8::Unit& u, int wr, int wc, int fr, int fq) const {
;     ...
;                 const int row = row0 + ai * 128 + m * 16;
;                 bf16_t* rowp = O + (size_t)row * ldc + col0;
;                 float rs = 1.f;
;                 if (part) { const f32x4* pq = (const f32x4*)(part + (size_t)row * 16); const f32x4 t4 = (pq[0] + pq[1]) + (pq[2] + pq[3]); rs = 1.0f / sqrtf(((t4.x + t4.y) + (t4.z + t4.w)) * (1.f / DM) + NORM_EPS); }
;                 f32x4 c0 = {1.f, 1.f, 1.f, 1.f}, c1 = c0, s0 = {0.f, 0.f, 0.f, 0.f}, s1 = s0;
;                 if (do_rope && mine) { const float* cs = rope + (size_t)row * 16; c0 = *(const f32x4*)cs; c1 = *(const f32x4*)(cs + 4); s0 = *(const f32x4*)(cs + 8) * sgn; s1 = *(const f32x4*)(cs + 12) * sgn; }
; #pragma unroll
;                 for (int bj = 0; bj < 2; ++bj) {
;                     f32x4 v0 = acc[ai][bj][m][0] * rs, v1 = acc[ai][bj][m][1] * rs;
;                     if (act == 2) {
; #pragma unroll
;                         for (int k = 0; k < 4; ++k) { const float a = fmaxf(v0[k], 0.f), b = fmaxf(v1[k], 0.f); v0[k] = a * a; v1[k] = b * b; }
;                     }
;                     if (do_rope) {
;                         f32x4 p0, p1;
; #pragma unroll
;                         for (int k = 0; k < 4; ++k) { p0[k] = __shfl_xor(v0[k], 16); p1[k] = __shfl_xor(v1[k], 16); }
;                         v0 = v0 * c0 + p0 * s0; v1 = v1 * c1 + p1 * s1;
;                     }
;                     u32x4 w; w.x = pk_bf16(v0[0], v0[1]); w.y = pk_bf16(v0[2], v0[3]); w.z = pk_bf16(v1[0], v1[1]); w.w = pk_bf16(v1[2], v1[3]);
;                     *(u32x4*)(rowp + bj * 128) = w;
.LBB0_480:
	v_lshl_add_u32 v146, s6, 8, v148
	v_ashrrev_i32_e32 v147, 31, v146
	v_lshlrev_b64 v[144:145], 6, v[146:147]
	v_lshl_add_u64 v[144:145], s[14:15], 0, v[144:145]
	global_load_dwordx4 v[170:173], v[144:145], off
	global_load_dwordx4 v[174:177], v[144:145], off offset:16
	global_load_dwordx4 v[178:181], v[144:145], off offset:32
	global_load_dwordx4 v[186:189], v[144:145], off offset:48
	v_lshlrev_b64 v[190:191], 13, v[146:147]
	v_lshl_or_b32 v144, s7, 8, v150
	v_ashrrev_i32_e32 v145, 31, v144
	v_or_b32_e32 v182, 16, v146
	v_lshlrev_b64 v[144:145], 1, v[144:145]
	v_ashrrev_i32_e32 v183, 31, v182
	s_waitcnt vmcnt(0)
	v_pk_add_f32 v[172:173], v[172:173], v[176:177]
	v_pk_add_f32 v[170:171], v[170:171], v[174:175]
	v_pk_add_f32 v[174:175], v[180:181], v[188:189]
	v_pk_add_f32 v[176:177], v[178:179], v[186:187]
	v_pk_add_f32 v[172:173], v[172:173], v[174:175]
	v_pk_add_f32 v[170:171], v[170:171], v[176:177]
	s_nop 0
	v_pk_mov_b32 v[174:175], v[170:171], v[172:173] op_sel:[1,0]
	v_mov_b32_e32 v171, v173
	v_pk_add_f32 v[170:171], v[174:175], v[170:171]
	v_lshlrev_b64 v[172:173], 6, v[182:183]
	v_add_f32_e32 v147, v170, v171
	v_fmamk_f32 v147, v147, 0x3a800000, v167
	v_mul_f32_e32 v169, 0x4f800000, v147
	v_cmp_gt_f32_e32 vcc, s62, v147
	v_lshl_add_u64 v[170:171], s[12:13], 0, v[190:191]
	v_lshl_add_u64 v[170:171], v[170:171], 0, v[144:145]
	v_cndmask_b32_e32 v147, v147, v169, vcc
	v_sqrt_f32_e32 v169, v147
	v_lshl_add_u64 v[172:173], s[14:15], 0, v[172:173]
	s_nop 1
	v_mul_f32_e32 v174, 0x37800000, v169
	v_cndmask_b32_e32 v169, v169, v174, vcc
	v_cmp_class_f32_e32 vcc, v147, v168
	s_nop 1
	v_cndmask_b32_e32 v147, v169, v147, vcc
	v_div_scale_f32 v175, vcc, 1.0, v147, 1.0
	v_rcp_f32_e32 v169, v147
	s_nop 0
	v_mul_f32_e32 v174, 1.0, v169
	v_pk_mul_f32 v[126:127], v[126:127], v[174:175] op_sel_hi:[1,0]
	v_pk_mul_f32 v[124:125], v[124:125], v[174:175] op_sel_hi:[1,0]
	v_pk_mul_f32 v[122:123], v[122:123], v[174:175] op_sel_hi:[1,0]
	v_pk_mul_f32 v[120:121], v[120:121], v[174:175] op_sel_hi:[1,0]
	v_pk_mul_f32 v[118:119], v[118:119], v[174:175] op_sel_hi:[1,0]
	v_pk_mul_f32 v[116:117], v[116:117], v[174:175] op_sel_hi:[1,0]
	v_pk_mul_f32 v[114:115], v[114:115], v[174:175] op_sel_hi:[1,0]
	v_pk_mul_f32 v[112:113], v[112:113], v[174:175] op_sel_hi:[1,0]
	v_max_f32_e32 v124, 0, v124
	v_max_f32_e32 v120, 0, v120
	v_max_f32_e32 v125, 0, v125
	v_max_f32_e32 v121, 0, v121
	v_max_f32_e32 v126, 0, v126
	v_max_f32_e32 v122, 0, v122
	v_max_f32_e32 v127, 0, v127
	v_max_f32_e32 v123, 0, v123
	v_max_f32_e32 v116, 0, v116
	v_max_f32_e32 v112, 0, v112
	v_max_f32_e32 v117, 0, v117
	v_max_f32_e32 v113, 0, v113
	v_max_f32_e32 v118, 0, v118
	v_max_f32_e32 v114, 0, v114
	v_max_f32_e32 v119, 0, v119
	v_max_f32_e32 v115, 0, v115
	v_pk_mul_f32 v[124:125], v[124:125], v[124:125]
	v_pk_mul_f32 v[120:121], v[120:121], v[120:121]
	v_pk_mul_f32 v[126:127], v[126:127], v[126:127]
	v_pk_mul_f32 v[122:123], v[122:123], v[122:123]
	v_pk_mul_f32 v[116:117], v[116:117], v[116:117]
	v_pk_mul_f32 v[174:175], v[112:113], v[112:113]
	v_pk_mul_f32 v[118:119], v[118:119], v[118:119]
	v_pk_mul_f32 v[176:177], v[114:115], v[114:115]
	v_cvt_pk_bf16_f32 v112, v124, v125
	v_cvt_pk_bf16_f32 v113, v126, v127
	v_cvt_pk_bf16_f32 v114, v120, v121
	v_cvt_pk_bf16_f32 v115, v122, v123
	v_cvt_pk_bf16_f32 v116, v116, v117
	v_cvt_pk_bf16_f32 v117, v118, v119
	v_cvt_pk_bf16_f32 v118, v174, v175
	v_cvt_pk_bf16_f32 v119, v176, v177
	global_store_dwordx4 v[170:171], v[112:115], off
	global_store_dwordx4 v[170:171], v[116:119], off offset:256
	global_load_dwordx4 v[112:115], v[172:173], off
	s_nop 0
	global_load_dwordx4 v[116:119], v[172:173], off offset:16
	global_load_dwordx4 v[120:123], v[172:173], off offset:32
	global_load_dwordx4 v[124:127], v[172:173], off offset:48
	v_or_b32_e32 v170, 32, v146
	v_lshlrev_b64 v[172:173], 13, v[182:183]
	v_ashrrev_i32_e32 v171, 31, v170
	s_waitcnt vmcnt(2)
	v_pk_add_f32 v[114:115], v[114:115], v[118:119]
	v_pk_add_f32 v[112:113], v[112:113], v[116:117]
	s_waitcnt vmcnt(0)
	v_pk_add_f32 v[116:117], v[122:123], v[126:127]
	v_pk_add_f32 v[118:119], v[120:121], v[124:125]
	v_pk_add_f32 v[114:115], v[114:115], v[116:117]
	v_pk_add_f32 v[112:113], v[112:113], v[118:119]
	s_nop 0
	v_pk_mov_b32 v[116:117], v[112:113], v[114:115] op_sel:[1,0]
	v_mov_b32_e32 v113, v115
	v_pk_add_f32 v[112:113], v[116:117], v[112:113]
	v_lshl_add_u64 v[114:115], s[12:13], 0, v[172:173]
	v_add_f32_e32 v112, v112, v113
	v_fmamk_f32 v112, v112, 0x3a800000, v167
	v_mul_f32_e32 v113, 0x4f800000, v112
	v_cmp_gt_f32_e32 vcc, s62, v112
	v_lshl_add_u64 v[114:115], v[114:115], 0, v[144:145]
	s_nop 0
	v_cndmask_b32_e32 v116, v112, v113, vcc
	v_sqrt_f32_e32 v117, v116
	v_lshlrev_b64 v[112:113], 6, v[170:171]
	v_lshl_add_u64 v[112:113], s[14:15], 0, v[112:113]
	s_nop 1
	v_mul_f32_e32 v118, 0x37800000, v117
	v_cndmask_b32_e32 v117, v117, v118, vcc
	v_cmp_class_f32_e32 vcc, v116, v168
	s_nop 1
	v_cndmask_b32_e32 v116, v117, v116, vcc
	v_div_scale_f32 v117, s[6:7], v116, v116, 1.0
	v_rcp_f32_e32 v118, v117
	v_div_scale_f32 v119, vcc, 1.0, v116, 1.0
	v_fma_f32 v120, -v117, v118, 1.0
	v_fmac_f32_e32 v118, v120, v118
	v_mul_f32_e32 v120, v119, v118
	v_fma_f32 v121, -v117, v120, v119
	v_fmac_f32_e32 v120, v121, v118
	v_rcp_f32_e32 v117, v116
	s_nop 0
	v_mul_f32_e32 v116, 1.0, v117
	v_pk_mul_f32 v[110:111], v[110:111], v[116:117] op_sel_hi:[1,0]
	v_pk_mul_f32 v[108:109], v[108:109], v[116:117] op_sel_hi:[1,0]
	v_pk_mul_f32 v[106:107], v[106:107], v[116:117] op_sel_hi:[1,0]
	v_pk_mul_f32 v[104:105], v[104:105], v[116:117] op_sel_hi:[1,0]
	v_pk_mul_f32 v[102:103], v[102:103], v[116:117] op_sel_hi:[1,0]
; DI unsigned pk_bf16(float lo, float hi) { typedef float f2 __attribute__((ext_vector_type(2))); typedef __bf16 b2 __attribute__((ext_vector_type(2))); f2 v = {lo, hi}; b2 b = __builtin_convertvector(v, b2); return __builtin_bit_cast(unsigned, b); }
;     DI void operator()(const f32x4 (&acc)[2][2][4][2], const pg8::Unit& u, int wr, int wc, int fr, int fq) const {
;     ...
;                 const int row = row0 + ai * 128 + m * 16;
;                 bf16_t* rowp = O + (size_t)row * ldc + col0;
;                 float rs = 1.f;
;                 if (part) { const f32x4* pq = (const f32x4*)(part + (size_t)row * 16); const f32x4 t4 = (pq[0] + pq[1]) + (pq[2] + pq[3]); rs = 1.0f / sqrtf(((t4.x + t4.y) + (t4.z + t4.w)) * (1.f / DM) + NORM_EPS); }
;                 f32x4 c0 = {1.f, 1.f, 1.f, 1.f}, c1 = c0, s0 = {0.f, 0.f, 0.f, 0.f}, s1 = s0;
;                 if (do_rope && mine) { const float* cs = rope + (size_t)row * 16; c0 = *(const f32x4*)cs; c1 = *(const f32x4*)(cs + 4); s0 = *(const f32x4*)(cs + 8) * sgn; s1 = *(const f32x4*)(cs + 12) * sgn; }
; #pragma unroll
;                 for (int bj = 0; bj < 2; ++bj) {
;                     f32x4 v0 = acc[ai][bj][m][0] * rs, v1 = acc[ai][bj][m][1] * rs;
;                     if (act == 2) {
; #pragma unroll
;                         for (int k = 0; k < 4; ++k) { const float a = fmaxf(v0[k], 0.f), b = fmaxf(v1[k], 0.f); v0[k] = a * a; v1[k] = b * b; }
;                     }
;                     if (do_rope) {
;                         f32x4 p0, p1;
; #pragma unroll
;                         for (int k = 0; k < 4; ++k) { p0[k] = __shfl_xor(v0[k], 16); p1[k] = __shfl_xor(v1[k], 16); }
;                         v0 = v0 * c0 + p0 * s0; v1 = v1 * c1 + p1 * s1;
;                     }
;                     u32x4 w; w.x = pk_bf16(v0[0], v0[1]); w.y = pk_bf16(v0[2], v0[3]); w.z = pk_bf16(v1[0], v1[1]); w.w = pk_bf16(v1[2], v1[3]);
;                     *(u32x4*)(rowp + bj * 128) = w;
	v_pk_mul_f32 v[100:101], v[100:101], v[116:117] op_sel_hi:[1,0]
	v_pk_mul_f32 v[98:99], v[98:99], v[116:117] op_sel_hi:[1,0]
	v_pk_mul_f32 v[96:97], v[96:97], v[116:117] op_sel_hi:[1,0]
	v_max_f32_e32 v108, 0, v108
	v_max_f32_e32 v104, 0, v104
	v_max_f32_e32 v109, 0, v109
	v_max_f32_e32 v105, 0, v105
	v_max_f32_e32 v110, 0, v110
	v_max_f32_e32 v106, 0, v106
	v_max_f32_e32 v111, 0, v111
	v_max_f32_e32 v107, 0, v107
	v_max_f32_e32 v100, 0, v100
	v_max_f32_e32 v96, 0, v96
	v_max_f32_e32 v101, 0, v101
	v_max_f32_e32 v97, 0, v97
	v_max_f32_e32 v102, 0, v102
	v_max_f32_e32 v98, 0, v98
	v_max_f32_e32 v103, 0, v103
	v_max_f32_e32 v99, 0, v99
	v_pk_mul_f32 v[108:109], v[108:109], v[108:109]
	v_pk_mul_f32 v[104:105], v[104:105], v[104:105]
	v_pk_mul_f32 v[110:111], v[110:111], v[110:111]
	v_pk_mul_f32 v[106:107], v[106:107], v[106:107]
	v_pk_mul_f32 v[100:101], v[100:101], v[100:101]
	v_pk_mul_f32 v[116:117], v[96:97], v[96:97]
	v_pk_mul_f32 v[102:103], v[102:103], v[102:103]
	v_pk_mul_f32 v[118:119], v[98:99], v[98:99]
	v_cvt_pk_bf16_f32 v96, v108, v109
	v_cvt_pk_bf16_f32 v97, v110, v111
	v_cvt_pk_bf16_f32 v98, v104, v105
	v_cvt_pk_bf16_f32 v99, v106, v107
	v_cvt_pk_bf16_f32 v100, v100, v101
	v_cvt_pk_bf16_f32 v101, v102, v103
	v_cvt_pk_bf16_f32 v102, v116, v117
	v_cvt_pk_bf16_f32 v103, v118, v119
	global_store_dwordx4 v[114:115], v[96:99], off
	global_store_dwordx4 v[114:115], v[100:103], off offset:256
	global_load_dwordx4 v[96:99], v[112:113], off
	s_nop 0
	global_load_dwordx4 v[100:103], v[112:113], off offset:16
	global_load_dwordx4 v[104:107], v[112:113], off offset:32
	global_load_dwordx4 v[108:111], v[112:113], off offset:48
	v_or_b32_e32 v112, 48, v146
	v_lshlrev_b64 v[114:115], 13, v[170:171]
	v_ashrrev_i32_e32 v113, 31, v112
	s_waitcnt vmcnt(2)
	v_pk_add_f32 v[98:99], v[98:99], v[102:103]
	v_pk_add_f32 v[96:97], v[96:97], v[100:101]
	s_waitcnt vmcnt(0)
	v_pk_add_f32 v[100:101], v[106:107], v[110:111]
	v_pk_add_f32 v[102:103], v[104:105], v[108:109]
	v_pk_add_f32 v[98:99], v[98:99], v[100:101]
	v_pk_add_f32 v[96:97], v[96:97], v[102:103]
	s_nop 0
	v_pk_mov_b32 v[100:101], v[96:97], v[98:99] op_sel:[1,0]
	v_mov_b32_e32 v97, v99
	v_pk_add_f32 v[96:97], v[100:101], v[96:97]
	v_lshl_add_u64 v[98:99], s[12:13], 0, v[114:115]
	v_add_f32_e32 v96, v96, v97
	v_fmamk_f32 v96, v96, 0x3a800000, v167
	v_mul_f32_e32 v97, 0x4f800000, v96
	v_cmp_gt_f32_e32 vcc, s62, v96
	v_lshl_add_u64 v[98:99], v[98:99], 0, v[144:145]
	s_nop 0
	v_cndmask_b32_e32 v100, v96, v97, vcc
	v_sqrt_f32_e32 v101, v100
	v_lshlrev_b64 v[96:97], 6, v[112:113]
	v_lshl_add_u64 v[96:97], s[14:15], 0, v[96:97]
	s_nop 1
	v_mul_f32_e32 v102, 0x37800000, v101
	v_cndmask_b32_e32 v101, v101, v102, vcc
	v_cmp_class_f32_e32 vcc, v100, v168
	s_nop 1
	v_cndmask_b32_e32 v100, v101, v100, vcc
	v_div_scale_f32 v101, s[6:7], v100, v100, 1.0
	v_rcp_f32_e32 v102, v101
	v_div_scale_f32 v103, vcc, 1.0, v100, 1.0
	v_fma_f32 v104, -v101, v102, 1.0
	v_fmac_f32_e32 v102, v104, v102
	v_mul_f32_e32 v104, v103, v102
	v_fma_f32 v105, -v101, v104, v103
	v_fmac_f32_e32 v104, v105, v102
	v_rcp_f32_e32 v101, v100
	s_nop 0
	v_mul_f32_e32 v100, 1.0, v101
	v_pk_mul_f32 v[94:95], v[94:95], v[100:101] op_sel_hi:[1,0]
	v_pk_mul_f32 v[92:93], v[92:93], v[100:101] op_sel_hi:[1,0]
	v_pk_mul_f32 v[90:91], v[90:91], v[100:101] op_sel_hi:[1,0]
	v_pk_mul_f32 v[88:89], v[88:89], v[100:101] op_sel_hi:[1,0]
	v_pk_mul_f32 v[86:87], v[86:87], v[100:101] op_sel_hi:[1,0]
	v_pk_mul_f32 v[84:85], v[84:85], v[100:101] op_sel_hi:[1,0]
	v_pk_mul_f32 v[82:83], v[82:83], v[100:101] op_sel_hi:[1,0]
	v_pk_mul_f32 v[80:81], v[80:81], v[100:101] op_sel_hi:[1,0]
	v_max_f32_e32 v92, 0, v92
	v_max_f32_e32 v88, 0, v88
	v_max_f32_e32 v93, 0, v93
	v_max_f32_e32 v89, 0, v89
	v_max_f32_e32 v94, 0, v94
	v_max_f32_e32 v90, 0, v90
	v_max_f32_e32 v95, 0, v95
	v_max_f32_e32 v91, 0, v91
	v_max_f32_e32 v84, 0, v84
	v_max_f32_e32 v80, 0, v80
	v_max_f32_e32 v85, 0, v85
	v_max_f32_e32 v81, 0, v81
	v_max_f32_e32 v86, 0, v86
	v_max_f32_e32 v82, 0, v82
	v_max_f32_e32 v87, 0, v87
	v_max_f32_e32 v83, 0, v83
	v_pk_mul_f32 v[92:93], v[92:93], v[92:93]
	v_pk_mul_f32 v[88:89], v[88:89], v[88:89]
	v_pk_mul_f32 v[94:95], v[94:95], v[94:95]
	v_pk_mul_f32 v[90:91], v[90:91], v[90:91]
	v_pk_mul_f32 v[84:85], v[84:85], v[84:85]
	v_pk_mul_f32 v[100:101], v[80:81], v[80:81]
	v_pk_mul_f32 v[86:87], v[86:87], v[86:87]
	v_pk_mul_f32 v[102:103], v[82:83], v[82:83]
	v_cvt_pk_bf16_f32 v80, v92, v93
	v_cvt_pk_bf16_f32 v81, v94, v95
	v_cvt_pk_bf16_f32 v82, v88, v89
	v_cvt_pk_bf16_f32 v83, v90, v91
	v_cvt_pk_bf16_f32 v84, v84, v85
	v_cvt_pk_bf16_f32 v85, v86, v87
	v_cvt_pk_bf16_f32 v86, v100, v101
	v_cvt_pk_bf16_f32 v87, v102, v103
	global_store_dwordx4 v[98:99], v[80:83], off
	global_store_dwordx4 v[98:99], v[84:87], off offset:256
	global_load_dwordx4 v[80:83], v[96:97], off
	s_nop 0
	global_load_dwordx4 v[84:87], v[96:97], off offset:16
	global_load_dwordx4 v[88:91], v[96:97], off offset:32
	global_load_dwordx4 v[92:95], v[96:97], off offset:48
	v_add_u32_e32 v96, 0x80, v146
	v_lshlrev_b64 v[98:99], 13, v[112:113]
	v_ashrrev_i32_e32 v97, 31, v96
	s_waitcnt vmcnt(2)
	v_pk_add_f32 v[82:83], v[82:83], v[86:87]
	v_pk_add_f32 v[80:81], v[80:81], v[84:85]
	s_waitcnt vmcnt(0)
; DI unsigned pk_bf16(float lo, float hi) { typedef float f2 __attribute__((ext_vector_type(2))); typedef __bf16 b2 __attribute__((ext_vector_type(2))); f2 v = {lo, hi}; b2 b = __builtin_convertvector(v, b2); return __builtin_bit_cast(unsigned, b); }
;     DI void operator()(const f32x4 (&acc)[2][2][4][2], const pg8::Unit& u, int wr, int wc, int fr, int fq) const {
;     ...
;                 const int row = row0 + ai * 128 + m * 16;
;                 bf16_t* rowp = O + (size_t)row * ldc + col0;
;                 float rs = 1.f;
;                 if (part) { const f32x4* pq = (const f32x4*)(part + (size_t)row * 16); const f32x4 t4 = (pq[0] + pq[1]) + (pq[2] + pq[3]); rs = 1.0f / sqrtf(((t4.x + t4.y) + (t4.z + t4.w)) * (1.f / DM) + NORM_EPS); }
;                 f32x4 c0 = {1.f, 1.f, 1.f, 1.f}, c1 = c0, s0 = {0.f, 0.f, 0.f, 0.f}, s1 = s0;
;                 if (do_rope && mine) { const float* cs = rope + (size_t)row * 16; c0 = *(const f32x4*)cs; c1 = *(const f32x4*)(cs + 4); s0 = *(const f32x4*)(cs + 8) * sgn; s1 = *(const f32x4*)(cs + 12) * sgn; }
; #pragma unroll
;                 for (int bj = 0; bj < 2; ++bj) {
;                     f32x4 v0 = acc[ai][bj][m][0] * rs, v1 = acc[ai][bj][m][1] * rs;
;                     if (act == 2) {
; #pragma unroll
;                         for (int k = 0; k < 4; ++k) { const float a = fmaxf(v0[k], 0.f), b = fmaxf(v1[k], 0.f); v0[k] = a * a; v1[k] = b * b; }
;                     }
;                     if (do_rope) {
;                         f32x4 p0, p1;
; #pragma unroll
;                         for (int k = 0; k < 4; ++k) { p0[k] = __shfl_xor(v0[k], 16); p1[k] = __shfl_xor(v1[k], 16); }
;                         v0 = v0 * c0 + p0 * s0; v1 = v1 * c1 + p1 * s1;
;                     }
;                     u32x4 w; w.x = pk_bf16(v0[0], v0[1]); w.y = pk_bf16(v0[2], v0[3]); w.z = pk_bf16(v1[0], v1[1]); w.w = pk_bf16(v1[2], v1[3]);
;                     *(u32x4*)(rowp + bj * 128) = w;
	v_pk_add_f32 v[84:85], v[90:91], v[94:95]
	v_pk_add_f32 v[86:87], v[88:89], v[92:93]
	v_pk_add_f32 v[82:83], v[82:83], v[84:85]
	v_pk_add_f32 v[80:81], v[80:81], v[86:87]
	s_nop 0
	v_pk_mov_b32 v[84:85], v[80:81], v[82:83] op_sel:[1,0]
	v_mov_b32_e32 v81, v83
	v_pk_add_f32 v[80:81], v[84:85], v[80:81]
	v_lshl_add_u64 v[82:83], s[12:13], 0, v[98:99]
	v_add_f32_e32 v80, v80, v81
	v_fmamk_f32 v80, v80, 0x3a800000, v167
	v_mul_f32_e32 v81, 0x4f800000, v80
	v_cmp_gt_f32_e32 vcc, s62, v80
	v_lshl_add_u64 v[82:83], v[82:83], 0, v[144:145]
	s_nop 0
	v_cndmask_b32_e32 v84, v80, v81, vcc
	v_sqrt_f32_e32 v85, v84
	v_lshlrev_b64 v[80:81], 6, v[96:97]
	v_lshl_add_u64 v[80:81], s[14:15], 0, v[80:81]
	s_nop 1
	v_mul_f32_e32 v86, 0x37800000, v85
	v_cndmask_b32_e32 v85, v85, v86, vcc
	v_cmp_class_f32_e32 vcc, v84, v168
	s_nop 1
	v_cndmask_b32_e32 v84, v85, v84, vcc
	v_div_scale_f32 v85, s[6:7], v84, v84, 1.0
	v_rcp_f32_e32 v86, v85
	v_div_scale_f32 v87, vcc, 1.0, v84, 1.0
	v_fma_f32 v88, -v85, v86, 1.0
	v_fmac_f32_e32 v86, v88, v86
	v_mul_f32_e32 v88, v87, v86
	v_fma_f32 v89, -v85, v88, v87
	v_fmac_f32_e32 v88, v89, v86
	v_rcp_f32_e32 v85, v84
	s_nop 0
	v_mul_f32_e32 v84, 1.0, v85
	v_pk_mul_f32 v[78:79], v[78:79], v[84:85] op_sel_hi:[1,0]
	v_pk_mul_f32 v[76:77], v[76:77], v[84:85] op_sel_hi:[1,0]
	v_pk_mul_f32 v[74:75], v[74:75], v[84:85] op_sel_hi:[1,0]
	v_pk_mul_f32 v[72:73], v[72:73], v[84:85] op_sel_hi:[1,0]
	v_pk_mul_f32 v[70:71], v[70:71], v[84:85] op_sel_hi:[1,0]
	v_pk_mul_f32 v[68:69], v[68:69], v[84:85] op_sel_hi:[1,0]
	v_pk_mul_f32 v[66:67], v[66:67], v[84:85] op_sel_hi:[1,0]
	v_pk_mul_f32 v[64:65], v[64:65], v[84:85] op_sel_hi:[1,0]
	v_max_f32_e32 v76, 0, v76
	v_max_f32_e32 v72, 0, v72
	v_max_f32_e32 v77, 0, v77
	v_max_f32_e32 v73, 0, v73
	v_max_f32_e32 v78, 0, v78
	v_max_f32_e32 v74, 0, v74
	v_max_f32_e32 v79, 0, v79
	v_max_f32_e32 v75, 0, v75
	v_max_f32_e32 v68, 0, v68
	v_max_f32_e32 v64, 0, v64
	v_max_f32_e32 v69, 0, v69
	v_max_f32_e32 v65, 0, v65
	v_max_f32_e32 v70, 0, v70
	v_max_f32_e32 v66, 0, v66
	v_max_f32_e32 v71, 0, v71
	v_max_f32_e32 v67, 0, v67
	v_pk_mul_f32 v[76:77], v[76:77], v[76:77]
	v_pk_mul_f32 v[72:73], v[72:73], v[72:73]
	v_pk_mul_f32 v[78:79], v[78:79], v[78:79]
	v_pk_mul_f32 v[74:75], v[74:75], v[74:75]
	v_pk_mul_f32 v[68:69], v[68:69], v[68:69]
	v_pk_mul_f32 v[84:85], v[64:65], v[64:65]
	v_pk_mul_f32 v[70:71], v[70:71], v[70:71]
	v_pk_mul_f32 v[86:87], v[66:67], v[66:67]
	v_cvt_pk_bf16_f32 v64, v76, v77
	v_cvt_pk_bf16_f32 v65, v78, v79
	v_cvt_pk_bf16_f32 v66, v72, v73
	v_cvt_pk_bf16_f32 v67, v74, v75
	v_cvt_pk_bf16_f32 v68, v68, v69
	v_cvt_pk_bf16_f32 v69, v70, v71
	v_cvt_pk_bf16_f32 v70, v84, v85
	v_cvt_pk_bf16_f32 v71, v86, v87
	global_store_dwordx4 v[82:83], v[64:67], off
	global_store_dwordx4 v[82:83], v[68:71], off offset:256
	global_load_dwordx4 v[64:67], v[80:81], off
	s_nop 0
	global_load_dwordx4 v[68:71], v[80:81], off offset:16
	global_load_dwordx4 v[72:75], v[80:81], off offset:32
	global_load_dwordx4 v[76:79], v[80:81], off offset:48
	v_add_u32_e32 v80, 0x90, v146
	v_lshlrev_b64 v[82:83], 13, v[96:97]
	v_ashrrev_i32_e32 v81, 31, v80
	s_waitcnt vmcnt(2)
	v_pk_add_f32 v[66:67], v[66:67], v[70:71]
	v_pk_add_f32 v[64:65], v[64:65], v[68:69]
	s_waitcnt vmcnt(0)
	v_pk_add_f32 v[68:69], v[74:75], v[78:79]
	v_pk_add_f32 v[70:71], v[72:73], v[76:77]
	v_pk_add_f32 v[66:67], v[66:67], v[68:69]
	v_pk_add_f32 v[64:65], v[64:65], v[70:71]
	s_nop 0
	v_pk_mov_b32 v[68:69], v[64:65], v[66:67] op_sel:[1,0]
	v_mov_b32_e32 v65, v67
	v_pk_add_f32 v[64:65], v[68:69], v[64:65]
	v_lshl_add_u64 v[66:67], s[12:13], 0, v[82:83]
	v_add_f32_e32 v64, v64, v65
	v_fmamk_f32 v64, v64, 0x3a800000, v167
	v_mul_f32_e32 v65, 0x4f800000, v64
	v_cmp_gt_f32_e32 vcc, s62, v64
	v_lshl_add_u64 v[66:67], v[66:67], 0, v[144:145]
	s_nop 0
	v_cndmask_b32_e32 v68, v64, v65, vcc
	v_sqrt_f32_e32 v69, v68
	v_lshlrev_b64 v[64:65], 6, v[80:81]
	v_lshl_add_u64 v[64:65], s[14:15], 0, v[64:65]
	s_nop 1
	v_mul_f32_e32 v70, 0x37800000, v69
	v_cndmask_b32_e32 v69, v69, v70, vcc
	v_cmp_class_f32_e32 vcc, v68, v168
	s_nop 1
	v_cndmask_b32_e32 v68, v69, v68, vcc
	v_div_scale_f32 v69, s[6:7], v68, v68, 1.0
	v_rcp_f32_e32 v70, v69
	v_div_scale_f32 v71, vcc, 1.0, v68, 1.0
	v_fma_f32 v72, -v69, v70, 1.0
	v_fmac_f32_e32 v70, v72, v70
	v_mul_f32_e32 v72, v71, v70
	v_fma_f32 v73, -v69, v72, v71
	v_fmac_f32_e32 v72, v73, v70
	v_rcp_f32_e32 v69, v68
	s_nop 0
	v_mul_f32_e32 v68, 1.0, v69
	v_pk_mul_f32 v[62:63], v[62:63], v[68:69] op_sel_hi:[1,0]
	v_pk_mul_f32 v[60:61], v[60:61], v[68:69] op_sel_hi:[1,0]
	v_pk_mul_f32 v[58:59], v[58:59], v[68:69] op_sel_hi:[1,0]
	v_pk_mul_f32 v[56:57], v[56:57], v[68:69] op_sel_hi:[1,0]
	v_pk_mul_f32 v[54:55], v[54:55], v[68:69] op_sel_hi:[1,0]
	v_pk_mul_f32 v[52:53], v[52:53], v[68:69] op_sel_hi:[1,0]
	v_pk_mul_f32 v[50:51], v[50:51], v[68:69] op_sel_hi:[1,0]
	v_pk_mul_f32 v[48:49], v[48:49], v[68:69] op_sel_hi:[1,0]
	v_max_f32_e32 v60, 0, v60
	v_max_f32_e32 v56, 0, v56
	v_max_f32_e32 v61, 0, v61
	v_max_f32_e32 v57, 0, v57
	v_max_f32_e32 v62, 0, v62
	v_max_f32_e32 v58, 0, v58
	v_max_f32_e32 v63, 0, v63
	v_max_f32_e32 v59, 0, v59
	v_max_f32_e32 v52, 0, v52
	v_max_f32_e32 v48, 0, v48
	v_max_f32_e32 v53, 0, v53
	v_max_f32_e32 v49, 0, v49
	v_max_f32_e32 v54, 0, v54
	v_max_f32_e32 v50, 0, v50
	v_max_f32_e32 v55, 0, v55
	v_max_f32_e32 v51, 0, v51
	v_pk_mul_f32 v[60:61], v[60:61], v[60:61]
	v_pk_mul_f32 v[56:57], v[56:57], v[56:57]
	v_pk_mul_f32 v[62:63], v[62:63], v[62:63]
	v_pk_mul_f32 v[58:59], v[58:59], v[58:59]
	v_pk_mul_f32 v[52:53], v[52:53], v[52:53]
	v_pk_mul_f32 v[68:69], v[48:49], v[48:49]
	v_pk_mul_f32 v[54:55], v[54:55], v[54:55]
	v_pk_mul_f32 v[70:71], v[50:51], v[50:51]
	v_cvt_pk_bf16_f32 v48, v60, v61
	v_cvt_pk_bf16_f32 v49, v62, v63
	v_cvt_pk_bf16_f32 v50, v56, v57
	v_cvt_pk_bf16_f32 v51, v58, v59
	v_cvt_pk_bf16_f32 v52, v52, v53
	v_cvt_pk_bf16_f32 v53, v54, v55
	v_cvt_pk_bf16_f32 v54, v68, v69
	v_cvt_pk_bf16_f32 v55, v70, v71
	global_store_dwordx4 v[66:67], v[48:51], off
	global_store_dwordx4 v[66:67], v[52:55], off offset:256
	global_load_dwordx4 v[48:51], v[64:65], off
	s_nop 0
	global_load_dwordx4 v[52:55], v[64:65], off offset:16
	global_load_dwordx4 v[56:59], v[64:65], off offset:32
	global_load_dwordx4 v[60:63], v[64:65], off offset:48
	v_add_u32_e32 v64, 0xa0, v146
	v_lshlrev_b64 v[66:67], 13, v[80:81]
	v_ashrrev_i32_e32 v65, 31, v64
	s_waitcnt vmcnt(2)
; DI unsigned pk_bf16(float lo, float hi) { typedef float f2 __attribute__((ext_vector_type(2))); typedef __bf16 b2 __attribute__((ext_vector_type(2))); f2 v = {lo, hi}; b2 b = __builtin_convertvector(v, b2); return __builtin_bit_cast(unsigned, b); }
;     DI void operator()(const f32x4 (&acc)[2][2][4][2], const pg8::Unit& u, int wr, int wc, int fr, int fq) const {
;     ...
;                 const int row = row0 + ai * 128 + m * 16;
;                 bf16_t* rowp = O + (size_t)row * ldc + col0;
;                 float rs = 1.f;
;                 if (part) { const f32x4* pq = (const f32x4*)(part + (size_t)row * 16); const f32x4 t4 = (pq[0] + pq[1]) + (pq[2] + pq[3]); rs = 1.0f / sqrtf(((t4.x + t4.y) + (t4.z + t4.w)) * (1.f / DM) + NORM_EPS); }
;                 f32x4 c0 = {1.f, 1.f, 1.f, 1.f}, c1 = c0, s0 = {0.f, 0.f, 0.f, 0.f}, s1 = s0;
;                 if (do_rope && mine) { const float* cs = rope + (size_t)row * 16; c0 = *(const f32x4*)cs; c1 = *(const f32x4*)(cs + 4); s0 = *(const f32x4*)(cs + 8) * sgn; s1 = *(const f32x4*)(cs + 12) * sgn; }
; #pragma unroll
;                 for (int bj = 0; bj < 2; ++bj) {
;                     f32x4 v0 = acc[ai][bj][m][0] * rs, v1 = acc[ai][bj][m][1] * rs;
;                     if (act == 2) {
; #pragma unroll
;                         for (int k = 0; k < 4; ++k) { const float a = fmaxf(v0[k], 0.f), b = fmaxf(v1[k], 0.f); v0[k] = a * a; v1[k] = b * b; }
;                     }
;                     if (do_rope) {
;                         f32x4 p0, p1;
; #pragma unroll
;                         for (int k = 0; k < 4; ++k) { p0[k] = __shfl_xor(v0[k], 16); p1[k] = __shfl_xor(v1[k], 16); }
;                         v0 = v0 * c0 + p0 * s0; v1 = v1 * c1 + p1 * s1;
;                     }
;                     u32x4 w; w.x = pk_bf16(v0[0], v0[1]); w.y = pk_bf16(v0[2], v0[3]); w.z = pk_bf16(v1[0], v1[1]); w.w = pk_bf16(v1[2], v1[3]);
;                     *(u32x4*)(rowp + bj * 128) = w;
	v_pk_add_f32 v[50:51], v[50:51], v[54:55]
	v_pk_add_f32 v[48:49], v[48:49], v[52:53]
	s_waitcnt vmcnt(0)
	v_pk_add_f32 v[52:53], v[58:59], v[62:63]
	v_pk_add_f32 v[54:55], v[56:57], v[60:61]
	v_pk_add_f32 v[50:51], v[50:51], v[52:53]
	v_pk_add_f32 v[48:49], v[48:49], v[54:55]
	s_nop 0
	v_pk_mov_b32 v[52:53], v[48:49], v[50:51] op_sel:[1,0]
	v_mov_b32_e32 v49, v51
	v_pk_add_f32 v[48:49], v[52:53], v[48:49]
	v_lshl_add_u64 v[50:51], s[12:13], 0, v[66:67]
	v_add_f32_e32 v48, v48, v49
	v_fmamk_f32 v48, v48, 0x3a800000, v167
	v_mul_f32_e32 v49, 0x4f800000, v48
	v_cmp_gt_f32_e32 vcc, s62, v48
	v_lshl_add_u64 v[50:51], v[50:51], 0, v[144:145]
	s_nop 0
	v_cndmask_b32_e32 v52, v48, v49, vcc
	v_sqrt_f32_e32 v53, v52
	v_lshlrev_b64 v[48:49], 6, v[64:65]
	v_lshl_add_u64 v[48:49], s[14:15], 0, v[48:49]
	s_nop 1
	v_mul_f32_e32 v54, 0x37800000, v53
	v_cndmask_b32_e32 v53, v53, v54, vcc
	v_cmp_class_f32_e32 vcc, v52, v168
	s_nop 1
	v_cndmask_b32_e32 v52, v53, v52, vcc
	v_div_scale_f32 v53, s[6:7], v52, v52, 1.0
	v_rcp_f32_e32 v54, v53
	v_div_scale_f32 v55, vcc, 1.0, v52, 1.0
	v_fma_f32 v56, -v53, v54, 1.0
	v_fmac_f32_e32 v54, v56, v54
	v_mul_f32_e32 v56, v55, v54
	v_fma_f32 v57, -v53, v56, v55
	v_fmac_f32_e32 v56, v57, v54
	v_rcp_f32_e32 v53, v52
	s_nop 0
	v_mul_f32_e32 v52, 1.0, v53
	v_pk_mul_f32 v[46:47], v[46:47], v[52:53] op_sel_hi:[1,0]
	v_pk_mul_f32 v[44:45], v[44:45], v[52:53] op_sel_hi:[1,0]
	v_pk_mul_f32 v[42:43], v[42:43], v[52:53] op_sel_hi:[1,0]
	v_pk_mul_f32 v[40:41], v[40:41], v[52:53] op_sel_hi:[1,0]
	v_pk_mul_f32 v[38:39], v[38:39], v[52:53] op_sel_hi:[1,0]
	v_pk_mul_f32 v[36:37], v[36:37], v[52:53] op_sel_hi:[1,0]
	v_pk_mul_f32 v[34:35], v[34:35], v[52:53] op_sel_hi:[1,0]
	v_pk_mul_f32 v[32:33], v[32:33], v[52:53] op_sel_hi:[1,0]
	v_max_f32_e32 v44, 0, v44
	v_max_f32_e32 v40, 0, v40
	v_max_f32_e32 v45, 0, v45
	v_max_f32_e32 v41, 0, v41
	v_max_f32_e32 v46, 0, v46
	v_max_f32_e32 v42, 0, v42
	v_max_f32_e32 v47, 0, v47
	v_max_f32_e32 v43, 0, v43
	v_max_f32_e32 v36, 0, v36
	v_max_f32_e32 v32, 0, v32
	v_max_f32_e32 v37, 0, v37
	v_max_f32_e32 v33, 0, v33
	v_max_f32_e32 v38, 0, v38
	v_max_f32_e32 v34, 0, v34
	v_max_f32_e32 v39, 0, v39
	v_max_f32_e32 v35, 0, v35
	v_pk_mul_f32 v[44:45], v[44:45], v[44:45]
	v_pk_mul_f32 v[40:41], v[40:41], v[40:41]
	v_pk_mul_f32 v[46:47], v[46:47], v[46:47]
	v_pk_mul_f32 v[42:43], v[42:43], v[42:43]
	v_pk_mul_f32 v[36:37], v[36:37], v[36:37]
	v_pk_mul_f32 v[52:53], v[32:33], v[32:33]
	v_pk_mul_f32 v[38:39], v[38:39], v[38:39]
	v_pk_mul_f32 v[54:55], v[34:35], v[34:35]
	v_cvt_pk_bf16_f32 v32, v44, v45
	v_cvt_pk_bf16_f32 v33, v46, v47
	v_cvt_pk_bf16_f32 v34, v40, v41
	v_cvt_pk_bf16_f32 v35, v42, v43
	v_cvt_pk_bf16_f32 v36, v36, v37
	v_cvt_pk_bf16_f32 v37, v38, v39
	v_cvt_pk_bf16_f32 v38, v52, v53
	v_cvt_pk_bf16_f32 v39, v54, v55
	global_store_dwordx4 v[50:51], v[32:35], off
	global_store_dwordx4 v[50:51], v[36:39], off offset:256
	global_load_dwordx4 v[32:35], v[48:49], off
	s_nop 0
	global_load_dwordx4 v[36:39], v[48:49], off offset:16
	global_load_dwordx4 v[40:43], v[48:49], off offset:32
	global_load_dwordx4 v[44:47], v[48:49], off offset:48
	v_add_u32_e32 v48, 0xb0, v146
	v_lshlrev_b64 v[50:51], 13, v[64:65]
	v_ashrrev_i32_e32 v49, 31, v48
	s_waitcnt vmcnt(2)
	v_pk_add_f32 v[34:35], v[34:35], v[38:39]
	v_pk_add_f32 v[32:33], v[32:33], v[36:37]
	s_waitcnt vmcnt(0)
; DI unsigned pk_bf16(float lo, float hi) { typedef float f2 __attribute__((ext_vector_type(2))); typedef __bf16 b2 __attribute__((ext_vector_type(2))); f2 v = {lo, hi}; b2 b = __builtin_convertvector(v, b2); return __builtin_bit_cast(unsigned, b); }
;     DI void operator()(const f32x4 (&acc)[2][2][4][2], const pg8::Unit& u, int wr, int wc, int fr, int fq) const {
;     ...
;                 const int row = row0 + ai * 128 + m * 16;
;                 bf16_t* rowp = O + (size_t)row * ldc + col0;
;                 float rs = 1.f;
;                 if (part) { const f32x4* pq = (const f32x4*)(part + (size_t)row * 16); const f32x4 t4 = (pq[0] + pq[1]) + (pq[2] + pq[3]); rs = 1.0f / sqrtf(((t4.x + t4.y) + (t4.z + t4.w)) * (1.f / DM) + NORM_EPS); }
;                 f32x4 c0 = {1.f, 1.f, 1.f, 1.f}, c1 = c0, s0 = {0.f, 0.f, 0.f, 0.f}, s1 = s0;
;                 if (do_rope && mine) { const float* cs = rope + (size_t)row * 16; c0 = *(const f32x4*)cs; c1 = *(const f32x4*)(cs + 4); s0 = *(const f32x4*)(cs + 8) * sgn; s1 = *(const f32x4*)(cs + 12) * sgn; }
; #pragma unroll
;                 for (int bj = 0; bj < 2; ++bj) {
;                     f32x4 v0 = acc[ai][bj][m][0] * rs, v1 = acc[ai][bj][m][1] * rs;
;                     if (act == 2) {
; #pragma unroll
;                         for (int k = 0; k < 4; ++k) { const float a = fmaxf(v0[k], 0.f), b = fmaxf(v1[k], 0.f); v0[k] = a * a; v1[k] = b * b; }
;                     }
;                     if (do_rope) {
;                         f32x4 p0, p1;
; #pragma unroll
;                         for (int k = 0; k < 4; ++k) { p0[k] = __shfl_xor(v0[k], 16); p1[k] = __shfl_xor(v1[k], 16); }
;                         v0 = v0 * c0 + p0 * s0; v1 = v1 * c1 + p1 * s1;
;                     }
;                     u32x4 w; w.x = pk_bf16(v0[0], v0[1]); w.y = pk_bf16(v0[2], v0[3]); w.z = pk_bf16(v1[0], v1[1]); w.w = pk_bf16(v1[2], v1[3]);
;                     *(u32x4*)(rowp + bj * 128) = w;
	v_pk_add_f32 v[36:37], v[42:43], v[46:47]
	v_pk_add_f32 v[38:39], v[40:41], v[44:45]
	v_pk_add_f32 v[34:35], v[34:35], v[36:37]
	v_pk_add_f32 v[32:33], v[32:33], v[38:39]
	s_nop 0
	v_pk_mov_b32 v[36:37], v[32:33], v[34:35] op_sel:[1,0]
	v_mov_b32_e32 v33, v35
	v_pk_add_f32 v[32:33], v[36:37], v[32:33]
	v_lshl_add_u64 v[34:35], s[12:13], 0, v[50:51]
	v_add_f32_e32 v32, v32, v33
	v_fmamk_f32 v32, v32, 0x3a800000, v167
	v_mul_f32_e32 v33, 0x4f800000, v32
	v_cmp_gt_f32_e32 vcc, s62, v32
	v_lshl_add_u64 v[34:35], v[34:35], 0, v[144:145]
	s_nop 0
	v_cndmask_b32_e32 v36, v32, v33, vcc
	v_sqrt_f32_e32 v37, v36
	v_lshlrev_b64 v[32:33], 6, v[48:49]
	v_lshl_add_u64 v[32:33], s[14:15], 0, v[32:33]
	s_nop 1
	v_mul_f32_e32 v38, 0x37800000, v37
	v_cndmask_b32_e32 v37, v37, v38, vcc
	v_cmp_class_f32_e32 vcc, v36, v168
	s_nop 1
	v_cndmask_b32_e32 v36, v37, v36, vcc
	v_div_scale_f32 v37, s[6:7], v36, v36, 1.0
	v_rcp_f32_e32 v38, v37
	v_div_scale_f32 v39, vcc, 1.0, v36, 1.0
	v_fma_f32 v40, -v37, v38, 1.0
	v_fmac_f32_e32 v38, v40, v38
	v_mul_f32_e32 v40, v39, v38
	v_fma_f32 v41, -v37, v40, v39
	v_fmac_f32_e32 v40, v41, v38
	v_rcp_f32_e32 v37, v36
	s_nop 0
	v_mul_f32_e32 v36, 1.0, v37
	v_pk_mul_f32 v[30:31], v[30:31], v[36:37] op_sel_hi:[1,0]
	v_pk_mul_f32 v[28:29], v[28:29], v[36:37] op_sel_hi:[1,0]
	v_pk_mul_f32 v[26:27], v[26:27], v[36:37] op_sel_hi:[1,0]
	v_pk_mul_f32 v[24:25], v[24:25], v[36:37] op_sel_hi:[1,0]
	v_pk_mul_f32 v[22:23], v[22:23], v[36:37] op_sel_hi:[1,0]
	v_pk_mul_f32 v[20:21], v[20:21], v[36:37] op_sel_hi:[1,0]
	v_pk_mul_f32 v[18:19], v[18:19], v[36:37] op_sel_hi:[1,0]
	v_pk_mul_f32 v[16:17], v[16:17], v[36:37] op_sel_hi:[1,0]
	v_max_f32_e32 v28, 0, v28
	v_max_f32_e32 v24, 0, v24
	v_max_f32_e32 v29, 0, v29
	v_max_f32_e32 v25, 0, v25
	v_max_f32_e32 v30, 0, v30
	v_max_f32_e32 v26, 0, v26
	v_max_f32_e32 v31, 0, v31
	v_max_f32_e32 v27, 0, v27
	v_max_f32_e32 v20, 0, v20
	v_max_f32_e32 v16, 0, v16
	v_max_f32_e32 v21, 0, v21
	v_max_f32_e32 v17, 0, v17
	v_max_f32_e32 v22, 0, v22
	v_max_f32_e32 v18, 0, v18
	v_max_f32_e32 v23, 0, v23
	v_max_f32_e32 v19, 0, v19
	v_pk_mul_f32 v[28:29], v[28:29], v[28:29]
	v_pk_mul_f32 v[24:25], v[24:25], v[24:25]
	v_pk_mul_f32 v[30:31], v[30:31], v[30:31]
	v_pk_mul_f32 v[26:27], v[26:27], v[26:27]
	v_pk_mul_f32 v[20:21], v[20:21], v[20:21]
	v_pk_mul_f32 v[36:37], v[16:17], v[16:17]
	v_pk_mul_f32 v[22:23], v[22:23], v[22:23]
	v_pk_mul_f32 v[38:39], v[18:19], v[18:19]
	v_cvt_pk_bf16_f32 v16, v28, v29
	v_cvt_pk_bf16_f32 v17, v30, v31
	v_cvt_pk_bf16_f32 v18, v24, v25
	v_cvt_pk_bf16_f32 v19, v26, v27
	v_cvt_pk_bf16_f32 v20, v20, v21
	v_cvt_pk_bf16_f32 v21, v22, v23
	v_cvt_pk_bf16_f32 v22, v36, v37
	v_cvt_pk_bf16_f32 v23, v38, v39
	global_store_dwordx4 v[34:35], v[16:19], off
	global_store_dwordx4 v[34:35], v[20:23], off offset:256
	global_load_dwordx4 v[16:19], v[32:33], off
	s_nop 0
	global_load_dwordx4 v[20:23], v[32:33], off offset:16
	global_load_dwordx4 v[24:27], v[32:33], off offset:32
	global_load_dwordx4 v[28:31], v[32:33], off offset:48
	s_waitcnt vmcnt(2)
	v_pk_add_f32 v[18:19], v[18:19], v[22:23]
	v_pk_add_f32 v[16:17], v[16:17], v[20:21]
	s_waitcnt vmcnt(0)
	v_pk_add_f32 v[20:21], v[26:27], v[30:31]
	v_pk_add_f32 v[22:23], v[24:25], v[28:29]
	v_pk_add_f32 v[18:19], v[18:19], v[20:21]
	v_pk_add_f32 v[16:17], v[16:17], v[22:23]
	s_nop 0
	v_pk_mov_b32 v[20:21], v[16:17], v[18:19] op_sel:[1,0]
	v_mov_b32_e32 v17, v19
	v_pk_add_f32 v[16:17], v[20:21], v[16:17]
	s_nop 0
	v_add_f32_e32 v16, v16, v17
	v_fmamk_f32 v16, v16, 0x3a800000, v167
	v_mul_f32_e32 v17, 0x4f800000, v16
	v_cmp_gt_f32_e32 vcc, s62, v16
	s_nop 1
	v_cndmask_b32_e32 v18, v16, v17, vcc
	v_sqrt_f32_e32 v19, v18
	v_lshlrev_b64 v[16:17], 13, v[48:49]
	v_lshl_add_u64 v[16:17], s[12:13], 0, v[16:17]
	v_lshl_add_u64 v[16:17], v[16:17], 0, v[144:145]
	s_nop 1
	v_mul_f32_e32 v20, 0x37800000, v19
	v_cndmask_b32_e32 v19, v19, v20, vcc
	v_cmp_class_f32_e32 vcc, v18, v168
	s_nop 1
	v_cndmask_b32_e32 v18, v19, v18, vcc
	v_div_scale_f32 v19, s[6:7], v18, v18, 1.0
	v_rcp_f32_e32 v20, v19
	v_div_scale_f32 v21, vcc, 1.0, v18, 1.0
	v_fma_f32 v22, -v19, v20, 1.0
	v_fmac_f32_e32 v20, v22, v20
	v_mul_f32_e32 v22, v21, v20
	v_fma_f32 v23, -v19, v22, v21
	v_fmac_f32_e32 v22, v23, v20
	v_rcp_f32_e32 v19, v18
	s_nop 0
	v_mul_f32_e32 v18, 1.0, v19
	v_pk_mul_f32 v[14:15], v[14:15], v[18:19] op_sel_hi:[1,0]
	v_pk_mul_f32 v[12:13], v[12:13], v[18:19] op_sel_hi:[1,0]
	v_pk_mul_f32 v[10:11], v[10:11], v[18:19] op_sel_hi:[1,0]
	v_pk_mul_f32 v[8:9], v[8:9], v[18:19] op_sel_hi:[1,0]
	v_pk_mul_f32 v[6:7], v[6:7], v[18:19] op_sel_hi:[1,0]
	v_pk_mul_f32 v[4:5], v[4:5], v[18:19] op_sel_hi:[1,0]
	v_pk_mul_f32 v[2:3], v[2:3], v[18:19] op_sel_hi:[1,0]
	v_pk_mul_f32 v[0:1], v[0:1], v[18:19] op_sel_hi:[1,0]
	v_max_f32_e32 v12, 0, v12
	v_max_f32_e32 v8, 0, v8
	v_max_f32_e32 v13, 0, v13
	v_max_f32_e32 v9, 0, v9
	v_max_f32_e32 v14, 0, v14
	v_max_f32_e32 v10, 0, v10
	v_max_f32_e32 v15, 0, v15
	v_max_f32_e32 v11, 0, v11
	v_max_f32_e32 v4, 0, v4
	v_max_f32_e32 v0, 0, v0
	v_max_f32_e32 v5, 0, v5
	v_max_f32_e32 v1, 0, v1
	v_max_f32_e32 v6, 0, v6
	v_max_f32_e32 v2, 0, v2
	v_max_f32_e32 v7, 0, v7
	v_max_f32_e32 v3, 0, v3
	v_pk_mul_f32 v[12:13], v[12:13], v[12:13]
	v_pk_mul_f32 v[8:9], v[8:9], v[8:9]
	v_pk_mul_f32 v[14:15], v[14:15], v[14:15]
	v_pk_mul_f32 v[10:11], v[10:11], v[10:11]
	s_andn2_b64 vcc, exec, s[4:5]
	v_pk_mul_f32 v[4:5], v[4:5], v[4:5]
	v_pk_mul_f32 v[18:19], v[0:1], v[0:1]
	v_pk_mul_f32 v[6:7], v[6:7], v[6:7]
	v_pk_mul_f32 v[20:21], v[2:3], v[2:3]
	v_cvt_pk_bf16_f32 v0, v12, v13
	v_cvt_pk_bf16_f32 v1, v14, v15
	v_cvt_pk_bf16_f32 v2, v8, v9
	v_cvt_pk_bf16_f32 v3, v10, v11
	s_mov_b64 s[4:5], -1
	v_cvt_pk_bf16_f32 v4, v4, v5
	v_cvt_pk_bf16_f32 v5, v6, v7
	v_cvt_pk_bf16_f32 v6, v18, v19
	v_cvt_pk_bf16_f32 v7, v20, v21
	global_store_dwordx4 v[16:17], v[0:3], off
	global_store_dwordx4 v[16:17], v[4:7], off offset:256
	s_cbranch_vccnz .LBB0_473
	s_andn2_b64 vcc, exec, s[10:11]
	s_cbranch_vccnz .LBB0_472
	s_barrier
	s_branch .LBB0_472

; DI unsigned pk_bf16(float lo, float hi) { typedef float f2 __attribute__((ext_vector_type(2))); typedef __bf16 b2 __attribute__((ext_vector_type(2))); f2 v = {lo, hi}; b2 b = __builtin_convertvector(v, b2); return __builtin_bit_cast(unsigned, b); }
; DI float bf_lo(unsigned w) { return __uint_as_float(w << 16); }
; DI float bf_hi(unsigned w) { return __uint_as_float(w & 0xffff0000u); }
;     DI void operator()(const f32x4 (&acc)[2][2][4][2], const pg8::Unit& u, int wr, int wc, int fr, int fq) const {
;     ...
;                 const int row = row0 + ai * 128 + m * 16;
;                 const size_t off = (size_t)row * ldc + col0;
;                 const f32x4* pq = (const f32x4*)(partin + (size_t)row * 16); const f32x4 t4 = (pq[0] + pq[1]) + (pq[2] + pq[3]);
;                 const float rs = -1.0f / sqrtf(((t4.x + t4.y) + (t4.z + t4.w)) * (1.f / DM) + NORM_EPS);
;                 float ss = 0.f;
; #pragma unroll
;                 for (int bj = 0; bj < 2; ++bj) {
;                     const size_t o2 = off + bj * 128;
;                     const u32x4 pw = *(const u32x4*)(pp + o2), bw = *(const u32x4*)(base + o2);
;                     const f32x4 a0 = acc[ai][bj][m][0] * rs, a1 = acc[ai][bj][m][1] * rs;
;                     f32x4 r0, r1;
;                     r0[0] = bf_lo(bw.x) + bf_lo(pw.x) / (1.f + __expf(a0[0])); r0[1] = bf_hi(bw.x) + bf_hi(pw.x) / (1.f + __expf(a0[1]));
;                     r0[2] = bf_lo(bw.y) + bf_lo(pw.y) / (1.f + __expf(a0[2])); r0[3] = bf_hi(bw.y) + bf_hi(pw.y) / (1.f + __expf(a0[3]));
;                     r1[0] = bf_lo(bw.z) + bf_lo(pw.z) / (1.f + __expf(a1[0])); r1[1] = bf_hi(bw.z) + bf_hi(pw.z) / (1.f + __expf(a1[1]));
;                     r1[2] = bf_lo(bw.w) + bf_lo(pw.w) / (1.f + __expf(a1[2])); r1[3] = bf_hi(bw.w) + bf_hi(pw.w) / (1.f + __expf(a1[3]));
;                     u32x4 w; w.x = pk_bf16(r0[0], r0[1]); w.y = pk_bf16(r0[2], r0[3]); w.z = pk_bf16(r1[0], r1[1]); w.w = pk_bf16(r1[2], r1[3]);
;                     *(u32x4*)(hb + o2) = w;
;                     ss += ((r0[0] * r0[0] + r0[1] * r0[1]) + (r0[2] * r0[2] + r0[3] * r0[3])) + ((r1[0] * r1[0] + r1[1] * r1[1]) + (r1[2] * r1[2] + r1[3] * r1[3]));
;                 }
;                 ss += __shfl_xor(ss, 16); ss += __shfl_xor(ss, 32);
;                 if (fq == 0) part[(size_t)row * 16 + u.pn * 4 + wc] = ss;
.LBB0_674:
	v_lshl_add_u32 v154, s8, 8, v158
	v_ashrrev_i32_e32 v155, 31, v154
	v_lshlrev_b64 v[128:129], 6, v[154:155]
	v_lshl_or_b32 v152, s34, 8, v160
	v_lshl_add_u64 v[128:129], s[26:27], 0, v[128:129]
	global_load_dwordx4 v[180:183], v[128:129], off
	global_load_dwordx4 v[186:189], v[128:129], off offset:16
	global_load_dwordx4 v[190:193], v[128:129], off offset:32
	global_load_dwordx4 v[194:197], v[128:129], off offset:48
	v_ashrrev_i32_e32 v153, 31, v152
	v_lshlrev_b64 v[128:129], 10, v[154:155]
	v_lshl_add_u64 v[128:129], v[128:129], 0, v[152:153]
	v_lshlrev_b64 v[156:157], 1, v[128:129]
	v_lshl_add_u64 v[128:129], s[20:21], 0, v[156:157]
	global_load_dwordx4 v[128:131], v[128:129], off
	v_lshl_add_u64 v[132:133], s[24:25], 0, v[156:157]
	global_load_dwordx4 v[132:135], v[132:133], off
	s_lshl_b32 s48, s34, 2
	s_ashr_i32 s49, s48, 31
	s_waitcnt vmcnt(0)
	v_pk_add_f32 v[182:183], v[182:183], v[188:189]
	v_pk_add_f32 v[180:181], v[180:181], v[186:187]
	v_pk_add_f32 v[186:187], v[192:193], v[196:197]
	v_pk_add_f32 v[188:189], v[190:191], v[194:195]
	v_pk_add_f32 v[182:183], v[182:183], v[186:187]
	v_pk_add_f32 v[180:181], v[180:181], v[188:189]
	v_lshlrev_b32_e32 v185, 16, v132
	v_pk_mov_b32 v[186:187], v[180:181], v[182:183] op_sel:[1,0]
	v_mov_b32_e32 v181, v183
	v_pk_add_f32 v[180:181], v[186:187], v[180:181]
	v_lshlrev_b32_e32 v182, 16, v128
	v_and_b32_e32 v183, 0xffff0000, v128
	v_add_f32_e32 v128, v180, v181
	v_fmamk_f32 v128, v128, 0x3a800000, v178
	v_mul_f32_e32 v180, 0x4f800000, v128
	v_cmp_gt_f32_e32 vcc, s70, v128
	v_and_b32_e32 v132, 0xffff0000, v132
	v_lshlrev_b32_e32 v186, 16, v133
	v_cndmask_b32_e32 v180, v128, v180, vcc
	v_sqrt_f32_e32 v181, v180
	v_and_b32_e32 v133, 0xffff0000, v133
	v_lshlrev_b32_e32 v128, 16, v129
	v_and_b32_e32 v129, 0xffff0000, v129
	s_nop 1
	v_mul_f32_e32 v187, 0x37800000, v181
	v_cndmask_b32_e32 v181, v181, v187, vcc
	v_cmp_class_f32_e32 vcc, v180, v179
	s_nop 1
	v_cndmask_b32_e32 v180, v181, v180, vcc
	v_rcp_f32_e32 v181, v180
	s_nop 0
	v_mul_f32_e32 v180, -1.0, v181
	v_pk_mul_f32 v[124:125], v[124:125], v[180:181] op_sel_hi:[1,0]
	v_pk_mul_f32 v[126:127], v[126:127], v[180:181] op_sel_hi:[1,0]
	v_mul_f32_e32 v124, 0x3fb8aa3b, v124
	v_mul_f32_e32 v125, 0x3fb8aa3b, v125
	v_exp_f32_e32 v124, v124
	v_exp_f32_e32 v125, v125
	v_mul_f32_e32 v126, 0x3fb8aa3b, v126
	v_mul_f32_e32 v127, 0x3fb8aa3b, v127
	v_exp_f32_e32 v126, v126
	v_exp_f32_e32 v127, v127
	v_pk_add_f32 v[124:125], v[124:125], 1.0 op_sel_hi:[1,0]
	v_pk_mul_f32 v[122:123], v[122:123], v[180:181] op_sel_hi:[1,0]
	v_pk_mul_f32 v[120:121], v[120:121], v[180:181] op_sel_hi:[1,0]
	v_div_scale_f32 v181, s[8:9], v125, v125, v132
	v_pk_add_f32 v[126:127], v[126:127], 1.0 op_sel_hi:[1,0]
	v_div_scale_f32 v188, s[8:9], v124, v124, v185
	v_rcp_f32_e32 v194, v181
	v_div_scale_f32 v190, s[10:11], v127, v127, v133
	v_rcp_f32_e32 v195, v188
	v_div_scale_f32 v192, s[12:13], v126, v126, v186
	v_rcp_f32_e32 v196, v190
	v_rcp_f32_e32 v197, v192
	v_fma_f32 v198, -v181, v194, 1.0
	v_div_scale_f32 v187, vcc, v132, v125, v132
	v_fma_f32 v199, -v188, v195, 1.0
	v_fmac_f32_e32 v194, v198, v194
	v_div_scale_f32 v189, s[8:9], v185, v124, v185
	v_fma_f32 v200, -v190, v196, 1.0
	v_fmac_f32_e32 v195, v199, v195
	v_mul_f32_e32 v198, v187, v194
	v_div_scale_f32 v191, s[10:11], v133, v127, v133
	v_fma_f32 v201, -v192, v197, 1.0
	v_fmac_f32_e32 v196, v200, v196
	v_mul_f32_e32 v199, v189, v195
	v_fma_f32 v202, -v181, v198, v187
	v_div_scale_f32 v193, s[12:13], v186, v126, v186
	v_fmac_f32_e32 v197, v201, v197
	v_mul_f32_e32 v200, v191, v196
	v_fma_f32 v203, -v188, v199, v189
	v_fmac_f32_e32 v198, v202, v194
	v_mul_f32_e32 v120, 0x3fb8aa3b, v120
	v_mul_f32_e32 v201, v193, v197
	v_fma_f32 v204, -v190, v200, v191
	v_fmac_f32_e32 v199, v203, v195
	v_mul_f32_e32 v121, 0x3fb8aa3b, v121
	v_exp_f32_e32 v120, v120
	v_fma_f32 v205, -v192, v201, v193
	v_fmac_f32_e32 v200, v204, v196
	v_exp_f32_e32 v121, v121
	v_fmac_f32_e32 v201, v205, v197
	v_rcp_f32_e32 v181, v125
	s_nop 0
	v_mul_f32_e32 v125, v132, v181
	v_rcp_f32_e32 v132, v124
	s_nop 0
	v_mul_f32_e32 v124, v185, v132
	v_pk_add_f32 v[182:183], v[124:125], v[182:183]
	v_rcp_f32_e32 v124, v126
	s_nop 0
	v_mul_f32_e32 v124, v186, v124
	v_and_b32_e32 v126, 0xffff0000, v134
	v_pk_add_f32 v[120:121], v[120:121], 1.0 op_sel_hi:[1,0]
	v_rcp_f32_e32 v132, v127
	s_nop 0
	v_mul_f32_e32 v125, v133, v132
	v_div_scale_f32 v127, s[8:9], v121, v121, v126
	v_pk_add_f32 v[186:187], v[124:125], v[128:129]
	v_rcp_f32_e32 v128, v127
	v_lshlrev_b32_e32 v124, 16, v130
	v_and_b32_e32 v125, 0xffff0000, v130
	v_lshlrev_b32_e32 v129, 16, v134
	v_fma_f32 v130, -v127, v128, 1.0
	v_fmac_f32_e32 v128, v130, v128
	v_div_scale_f32 v130, vcc, v126, v121, v126
	v_mul_f32_e32 v132, v130, v128
	v_fma_f32 v133, -v127, v132, v130
	v_fmac_f32_e32 v132, v133, v128
	v_div_scale_f32 v130, s[8:9], v120, v120, v129
	v_rcp_f32_e32 v133, v130
	v_rcp_f32_e32 v127, v121
	s_nop 0
	v_mul_f32_e32 v121, v126, v127
	v_mul_f32_e32 v122, 0x3fb8aa3b, v122
	v_fma_f32 v126, -v130, v133, 1.0
	v_fmac_f32_e32 v133, v126, v133
	v_mul_f32_e32 v123, 0x3fb8aa3b, v123
	v_exp_f32_e32 v122, v122
	v_exp_f32_e32 v123, v123
	v_rcp_f32_e32 v126, v120
	s_nop 0
	v_mul_f32_e32 v120, v129, v126
	v_pk_add_f32 v[188:189], v[120:121], v[124:125]
	v_and_b32_e32 v124, 0xffff0000, v135
	v_pk_add_f32 v[120:121], v[122:123], 1.0 op_sel_hi:[1,0]
	v_lshlrev_b32_e32 v127, 16, v135
	v_div_scale_f32 v125, s[8:9], v121, v121, v124
	v_rcp_f32_e32 v126, v125
	v_lshlrev_b32_e32 v122, 16, v131
	v_and_b32_e32 v123, 0xffff0000, v131
	v_pk_mul_f32 v[116:117], v[116:117], v[180:181] op_sel_hi:[1,0]
	v_fma_f32 v128, -v125, v126, 1.0
; DI unsigned pk_bf16(float lo, float hi) { typedef float f2 __attribute__((ext_vector_type(2))); typedef __bf16 b2 __attribute__((ext_vector_type(2))); f2 v = {lo, hi}; b2 b = __builtin_convertvector(v, b2); return __builtin_bit_cast(unsigned, b); }
; DI float bf_lo(unsigned w) { return __uint_as_float(w << 16); }
; DI float bf_hi(unsigned w) { return __uint_as_float(w & 0xffff0000u); }
;     DI void operator()(const f32x4 (&acc)[2][2][4][2], const pg8::Unit& u, int wr, int wc, int fr, int fq) const {
;     ...
;                 const int row = row0 + ai * 128 + m * 16;
;                 const size_t off = (size_t)row * ldc + col0;
;                 const f32x4* pq = (const f32x4*)(partin + (size_t)row * 16); const f32x4 t4 = (pq[0] + pq[1]) + (pq[2] + pq[3]);
;                 const float rs = -1.0f / sqrtf(((t4.x + t4.y) + (t4.z + t4.w)) * (1.f / DM) + NORM_EPS);
;                 float ss = 0.f;
; #pragma unroll
;                 for (int bj = 0; bj < 2; ++bj) {
;                     const size_t o2 = off + bj * 128;
;                     const u32x4 pw = *(const u32x4*)(pp + o2), bw = *(const u32x4*)(base + o2);
;                     const f32x4 a0 = acc[ai][bj][m][0] * rs, a1 = acc[ai][bj][m][1] * rs;
;                     f32x4 r0, r1;
;                     r0[0] = bf_lo(bw.x) + bf_lo(pw.x) / (1.f + __expf(a0[0])); r0[1] = bf_hi(bw.x) + bf_hi(pw.x) / (1.f + __expf(a0[1]));
;                     r0[2] = bf_lo(bw.y) + bf_lo(pw.y) / (1.f + __expf(a0[2])); r0[3] = bf_hi(bw.y) + bf_hi(pw.y) / (1.f + __expf(a0[3]));
;                     r1[0] = bf_lo(bw.z) + bf_lo(pw.z) / (1.f + __expf(a1[0])); r1[1] = bf_hi(bw.z) + bf_hi(pw.z) / (1.f + __expf(a1[1]));
;                     r1[2] = bf_lo(bw.w) + bf_lo(pw.w) / (1.f + __expf(a1[2])); r1[3] = bf_hi(bw.w) + bf_hi(pw.w) / (1.f + __expf(a1[3]));
;                     u32x4 w; w.x = pk_bf16(r0[0], r0[1]); w.y = pk_bf16(r0[2], r0[3]); w.z = pk_bf16(r1[0], r1[1]); w.w = pk_bf16(r1[2], r1[3]);
;                     *(u32x4*)(hb + o2) = w;
;                     ss += ((r0[0] * r0[0] + r0[1] * r0[1]) + (r0[2] * r0[2] + r0[3] * r0[3])) + ((r1[0] * r1[0] + r1[1] * r1[1]) + (r1[2] * r1[2] + r1[3] * r1[3]));
;                 }
;                 ss += __shfl_xor(ss, 16); ss += __shfl_xor(ss, 32);
;                 if (fq == 0) part[(size_t)row * 16 + u.pn * 4 + wc] = ss;
	v_fmac_f32_e32 v126, v128, v126
	v_div_scale_f32 v128, vcc, v124, v121, v124
	v_mul_f32_e32 v129, v128, v126
	v_fma_f32 v130, -v125, v129, v128
	v_fmac_f32_e32 v129, v130, v126
	v_div_scale_f32 v128, s[8:9], v120, v120, v127
	v_rcp_f32_e32 v130, v128
	v_rcp_f32_e32 v125, v121
	s_nop 0
	v_mul_f32_e32 v121, v124, v125
	v_mul_f32_e32 v116, 0x3fb8aa3b, v116
	v_fma_f32 v124, -v128, v130, 1.0
	v_fmac_f32_e32 v130, v124, v130
	v_div_scale_f32 v124, vcc, v127, v120, v127
	v_mul_f32_e32 v125, v124, v130
	v_fma_f32 v126, -v128, v125, v124
	v_rcp_f32_e32 v124, v120
	s_nop 0
	v_mul_f32_e32 v120, v127, v124
	v_pk_add_f32 v[134:135], v[120:121], v[122:123]
	v_cvt_pk_bf16_f32 v122, v182, v183
	v_cvt_pk_bf16_f32 v123, v186, v187
	v_cvt_pk_bf16_f32 v124, v188, v189
	v_cvt_pk_bf16_f32 v125, v134, v135
	v_lshl_add_u64 v[120:121], s[16:17], 0, v[156:157]
	v_or_b32_e32 v156, 0x100, v156
	global_store_dwordx4 v[120:121], v[122:125], off
	v_mul_f32_e32 v117, 0x3fb8aa3b, v117
	v_exp_f32_e32 v116, v116
	v_lshl_add_u64 v[122:123], s[24:25], 0, v[156:157]
	global_load_dwordx4 v[126:129], v[122:123], off
	v_lshl_add_u64 v[122:123], s[20:21], 0, v[156:157]
	global_load_dwordx4 v[130:133], v[122:123], off
	v_exp_f32_e32 v117, v117
	v_and_b32_e32 v123, 64, v177
	v_pk_mul_f32 v[156:157], v[186:187], v[186:187]
	v_xor_b32_e32 v122, 16, v177
	v_pk_add_f32 v[116:117], v[116:117], 1.0 op_sel_hi:[1,0]
	v_add_u32_e32 v123, 64, v123
	v_cmp_lt_i32_e32 vcc, v122, v123
	v_pk_mul_f32 v[118:119], v[118:119], v[180:181] op_sel_hi:[1,0]
	v_pk_mul_f32 v[114:115], v[114:115], v[180:181] op_sel_hi:[1,0]
	v_cndmask_b32_e32 v122, v177, v122, vcc
	v_lshlrev_b32_e32 v124, 2, v122
	v_xor_b32_e32 v122, 32, v177
	v_cmp_lt_i32_e32 vcc, v122, v123
	v_pk_mul_f32 v[112:113], v[112:113], v[180:181] op_sel_hi:[1,0]
	v_mul_f32_e32 v118, 0x3fb8aa3b, v118
	v_cndmask_b32_e32 v125, v177, v122, vcc
	v_pk_mul_f32 v[122:123], v[182:183], v[182:183]
	v_pk_mul_f32 v[182:183], v[188:189], v[188:189]
	v_mul_f32_e32 v119, 0x3fb8aa3b, v119
	v_exp_f32_e32 v118, v118
	v_exp_f32_e32 v119, v119
	v_mul_f32_e32 v112, 0x3fb8aa3b, v112
	v_mul_f32_e32 v113, 0x3fb8aa3b, v113
	v_exp_f32_e32 v112, v112
	v_pk_add_f32 v[118:119], v[118:119], 1.0 op_sel_hi:[1,0]
	v_exp_f32_e32 v113, v113
	v_mul_f32_e32 v114, 0x3fb8aa3b, v114
	v_mul_f32_e32 v115, 0x3fb8aa3b, v115
	v_exp_f32_e32 v114, v114
	v_pk_add_f32 v[112:113], v[112:113], 1.0 op_sel_hi:[1,0]
	v_exp_f32_e32 v115, v115
	v_pk_mul_f32 v[134:135], v[134:135], v[134:135]
	v_add_f32_e32 v122, v122, v123
	v_add_f32_e32 v134, v134, v135
	v_add_f32_e32 v135, v182, v183
	v_add_f32_e32 v134, v135, v134
	v_add_f32_e32 v135, v156, v157
	v_add_f32_e32 v122, v122, v135
	v_add_f32_e32 v122, v122, v134
	v_lshlrev_b32_e32 v125, 2, v125
	s_waitcnt vmcnt(1)
	v_and_b32_e32 v185, 0xffff0000, v126
	v_div_scale_f32 v186, s[8:9], v117, v117, v185
	v_rcp_f32_e32 v187, v186
	s_waitcnt vmcnt(0)
	v_lshlrev_b32_e32 v180, 16, v130
	v_and_b32_e32 v181, 0xffff0000, v130
	v_lshlrev_b32_e32 v126, 16, v126
	v_fma_f32 v130, -v186, v187, 1.0
	v_fmac_f32_e32 v187, v130, v187
	v_div_scale_f32 v130, vcc, v185, v117, v185
	v_mul_f32_e32 v188, v130, v187
	v_fma_f32 v189, -v186, v188, v130
	v_fmac_f32_e32 v188, v189, v187
	v_div_scale_f32 v186, s[8:9], v116, v116, v126
	v_rcp_f32_e32 v189, v186
	v_rcp_f32_e32 v130, v117
	s_nop 0
	v_mul_f32_e32 v117, v185, v130
	v_fma_f32 v130, -v186, v189, 1.0
	v_fmac_f32_e32 v189, v130, v189
	v_rcp_f32_e32 v130, v116
	s_nop 0
	v_mul_f32_e32 v116, v126, v130
	v_and_b32_e32 v126, 0xffff0000, v127
	v_pk_add_f32 v[116:117], v[116:117], v[180:181]
	v_div_scale_f32 v180, s[8:9], v119, v119, v126
	v_rcp_f32_e32 v181, v180
	v_lshlrev_b32_e32 v127, 16, v127
	v_lshlrev_b32_e32 v130, 16, v131
	v_and_b32_e32 v131, 0xffff0000, v131
	v_fma_f32 v185, -v180, v181, 1.0
	v_fmac_f32_e32 v181, v185, v181
	v_div_scale_f32 v185, vcc, v126, v119, v126
	v_mul_f32_e32 v186, v185, v181
	v_fma_f32 v187, -v180, v186, v185
	v_fmac_f32_e32 v186, v187, v181
	v_div_scale_f32 v185, s[8:9], v118, v118, v127
	v_rcp_f32_e32 v187, v185
	v_rcp_f32_e32 v180, v119
	s_nop 0
	v_mul_f32_e32 v119, v126, v180
	v_fma_f32 v126, -v185, v187, 1.0
	v_fmac_f32_e32 v187, v126, v187
	v_rcp_f32_e32 v126, v118
	s_nop 0
	v_mul_f32_e32 v118, v127, v126
	v_pk_add_f32 v[118:119], v[118:119], v[130:131]
	v_and_b32_e32 v130, 0xffff0000, v128
	v_div_scale_f32 v131, s[8:9], v113, v113, v130
	v_rcp_f32_e32 v180, v131
	v_lshlrev_b32_e32 v126, 16, v132
	v_and_b32_e32 v127, 0xffff0000, v132
	v_lshlrev_b32_e32 v128, 16, v128
	v_fma_f32 v132, -v131, v180, 1.0
	v_fmac_f32_e32 v180, v132, v180
	v_div_scale_f32 v132, vcc, v130, v113, v130
	v_mul_f32_e32 v181, v132, v180
	v_fma_f32 v185, -v131, v181, v132
	v_fmac_f32_e32 v181, v185, v180
	v_div_scale_f32 v132, s[8:9], v112, v112, v128
	v_rcp_f32_e32 v185, v132
	v_rcp_f32_e32 v131, v113
	s_nop 0
	v_mul_f32_e32 v113, v130, v131
	v_fma_f32 v130, -v132, v185, 1.0
	v_fmac_f32_e32 v185, v130, v185
	v_rcp_f32_e32 v130, v112
	s_nop 0
	v_mul_f32_e32 v112, v128, v130
	v_pk_add_f32 v[126:127], v[112:113], v[126:127]
	v_and_b32_e32 v128, 0xffff0000, v129
	v_pk_add_f32 v[112:113], v[114:115], 1.0 op_sel_hi:[1,0]
	v_lshlrev_b32_e32 v114, 16, v133
	v_and_b32_e32 v115, 0xffff0000, v133
	v_lshlrev_b32_e32 v129, 16, v129
	v_div_scale_f32 v132, s[8:9], v112, v112, v129
	v_rcp_f32_e32 v180, v132
	v_rcp_f32_e32 v130, v113
	s_nop 0
	v_mul_f32_e32 v113, v128, v130
	v_fma_f32 v128, -v132, v180, 1.0
	v_fmac_f32_e32 v180, v128, v180
	v_div_scale_f32 v128, vcc, v129, v112, v129
	v_rcp_f32_e32 v128, v112
	s_nop 0
	v_mul_f32_e32 v112, v129, v128
	v_pk_add_f32 v[128:129], v[112:113], v[114:115]
	v_pk_mul_f32 v[112:113], v[116:117], v[116:117]
	v_pk_mul_f32 v[114:115], v[118:119], v[118:119]
	v_pk_mul_f32 v[130:131], v[126:127], v[126:127]
	v_pk_mul_f32 v[132:133], v[128:129], v[128:129]
	v_add_f32_e32 v130, v130, v131
	v_add_f32_e32 v123, v132, v133
	v_add_f32_e32 v114, v114, v115
	v_add_f32_e32 v112, v112, v113
	v_add_f32_e32 v123, v130, v123
	v_add_f32_e32 v112, v112, v114
	v_add_f32_e32 v112, v112, v123
	v_add_f32_e32 v112, v122, v112
	ds_bpermute_b32 v113, v124, v112
	v_cvt_pk_bf16_f32 v114, v116, v117
	v_cvt_pk_bf16_f32 v115, v118, v119
	v_cvt_pk_bf16_f32 v116, v126, v127
	v_cvt_pk_bf16_f32 v117, v128, v129
	s_waitcnt lgkmcnt(0)
	v_add_f32_e32 v112, v112, v113
	ds_bpermute_b32 v113, v125, v112
	global_store_dwordx4 v[120:121], v[114:117], off offset:256
	s_and_saveexec_b64 s[8:9], s[4:5]
	s_cbranch_execz .LBB0_676
	v_lshlrev_b64 v[114:115], 4, v[154:155]
	s_waitcnt lgkmcnt(0)
	v_add_f32_e32 v116, v112, v113
	v_lshl_add_u64 v[112:113], v[114:115], 2, s[18:19]
	v_lshl_add_u64 v[112:113], s[48:49], 2, v[112:113]
	s_lshl_b32 s34, s59, 2
	v_lshl_add_u64 v[112:113], v[112:113], 0, s[34:35]
	global_store_dword v[112:113], v116, off
; DI unsigned pk_bf16(float lo, float hi) { typedef float f2 __attribute__((ext_vector_type(2))); typedef __bf16 b2 __attribute__((ext_vector_type(2))); f2 v = {lo, hi}; b2 b = __builtin_convertvector(v, b2); return __builtin_bit_cast(unsigned, b); }
; DI float bf_lo(unsigned w) { return __uint_as_float(w << 16); }
; DI float bf_hi(unsigned w) { return __uint_as_float(w & 0xffff0000u); }
;     DI void operator()(const f32x4 (&acc)[2][2][4][2], const pg8::Unit& u, int wr, int wc, int fr, int fq) const {
;     ...
;                 const int row = row0 + ai * 128 + m * 16;
;                 const size_t off = (size_t)row * ldc + col0;
;                 const f32x4* pq = (const f32x4*)(partin + (size_t)row * 16); const f32x4 t4 = (pq[0] + pq[1]) + (pq[2] + pq[3]);
;                 const float rs = -1.0f / sqrtf(((t4.x + t4.y) + (t4.z + t4.w)) * (1.f / DM) + NORM_EPS);
;                 float ss = 0.f;
; #pragma unroll
;                 for (int bj = 0; bj < 2; ++bj) {
;                     const size_t o2 = off + bj * 128;
;                     const u32x4 pw = *(const u32x4*)(pp + o2), bw = *(const u32x4*)(base + o2);
;                     const f32x4 a0 = acc[ai][bj][m][0] * rs, a1 = acc[ai][bj][m][1] * rs;
;                     f32x4 r0, r1;
;                     r0[0] = bf_lo(bw.x) + bf_lo(pw.x) / (1.f + __expf(a0[0])); r0[1] = bf_hi(bw.x) + bf_hi(pw.x) / (1.f + __expf(a0[1]));
;                     r0[2] = bf_lo(bw.y) + bf_lo(pw.y) / (1.f + __expf(a0[2])); r0[3] = bf_hi(bw.y) + bf_hi(pw.y) / (1.f + __expf(a0[3]));
;                     r1[0] = bf_lo(bw.z) + bf_lo(pw.z) / (1.f + __expf(a1[0])); r1[1] = bf_hi(bw.z) + bf_hi(pw.z) / (1.f + __expf(a1[1]));
;                     r1[2] = bf_lo(bw.w) + bf_lo(pw.w) / (1.f + __expf(a1[2])); r1[3] = bf_hi(bw.w) + bf_hi(pw.w) / (1.f + __expf(a1[3]));
;                     u32x4 w; w.x = pk_bf16(r0[0], r0[1]); w.y = pk_bf16(r0[2], r0[3]); w.z = pk_bf16(r1[0], r1[1]); w.w = pk_bf16(r1[2], r1[3]);
;                     *(u32x4*)(hb + o2) = w;
;                     ss += ((r0[0] * r0[0] + r0[1] * r0[1]) + (r0[2] * r0[2] + r0[3] * r0[3])) + ((r1[0] * r1[0] + r1[1] * r1[1]) + (r1[2] * r1[2] + r1[3] * r1[3]));
;                 }
;                 ss += __shfl_xor(ss, 16); ss += __shfl_xor(ss, 32);
;                 if (fq == 0) part[(size_t)row * 16 + u.pn * 4 + wc] = ss;
.LBB0_676:
	s_or_b64 exec, exec, s[8:9]
	v_or_b32_e32 v120, 16, v154
	v_ashrrev_i32_e32 v121, 31, v120
	s_waitcnt lgkmcnt(0)
	v_lshlrev_b64 v[112:113], 6, v[120:121]
	v_lshl_add_u64 v[112:113], s[26:27], 0, v[112:113]
	global_load_dwordx4 v[126:129], v[112:113], off
	global_load_dwordx4 v[130:133], v[112:113], off offset:16
	global_load_dwordx4 v[180:183], v[112:113], off offset:32
	global_load_dwordx4 v[186:189], v[112:113], off offset:48
	v_lshlrev_b64 v[112:113], 10, v[120:121]
	v_lshl_add_u64 v[112:113], v[112:113], 0, v[152:153]
	v_lshlrev_b64 v[122:123], 1, v[112:113]
	v_lshl_add_u64 v[112:113], s[20:21], 0, v[122:123]
	global_load_dwordx4 v[112:115], v[112:113], off
	v_lshl_add_u64 v[116:117], s[24:25], 0, v[122:123]
	global_load_dwordx4 v[116:119], v[116:117], off
	s_waitcnt vmcnt(4)
	v_pk_add_f32 v[128:129], v[128:129], v[132:133]
	v_pk_add_f32 v[126:127], v[126:127], v[130:131]
	s_waitcnt vmcnt(2)
	v_pk_add_f32 v[130:131], v[182:183], v[188:189]
	v_pk_add_f32 v[132:133], v[180:181], v[186:187]
	v_pk_add_f32 v[128:129], v[128:129], v[130:131]
	v_pk_add_f32 v[126:127], v[126:127], v[132:133]
	s_waitcnt vmcnt(0)
	v_lshlrev_b32_e32 v132, 16, v116
	v_pk_mov_b32 v[130:131], v[126:127], v[128:129] op_sel:[1,0]
	v_mov_b32_e32 v127, v129
	v_pk_add_f32 v[126:127], v[130:131], v[126:127]
	v_lshlrev_b32_e32 v128, 16, v112
	v_and_b32_e32 v129, 0xffff0000, v112
	v_add_f32_e32 v112, v126, v127
	v_fmamk_f32 v112, v112, 0x3a800000, v178
	v_and_b32_e32 v133, 0xffff0000, v116
	v_mul_f32_e32 v116, 0x4f800000, v112
	v_cmp_gt_f32_e32 vcc, s70, v112
	v_lshlrev_b32_e32 v130, 16, v117
	v_and_b32_e32 v117, 0xffff0000, v117
	v_cndmask_b32_e32 v116, v112, v116, vcc
	v_sqrt_f32_e32 v126, v116
	v_lshlrev_b32_e32 v112, 16, v113
	v_and_b32_e32 v113, 0xffff0000, v113
	s_nop 1
	v_mul_f32_e32 v127, 0x37800000, v126
	v_cndmask_b32_e32 v126, v126, v127, vcc
	v_cmp_class_f32_e32 vcc, v116, v179
	s_nop 1
	v_cndmask_b32_e32 v116, v126, v116, vcc
	v_rcp_f32_e32 v126, v116
	s_nop 0
	v_mul_f32_e32 v116, -1.0, v126
	v_pk_mul_f32 v[108:109], v[108:109], v[116:117] op_sel_hi:[1,0]
	v_pk_mul_f32 v[104:105], v[104:105], v[116:117] op_sel_hi:[1,0]
	v_mul_f32_e32 v108, 0x3fb8aa3b, v108
	v_mul_f32_e32 v109, 0x3fb8aa3b, v109
	v_pk_mul_f32 v[110:111], v[110:111], v[116:117] op_sel_hi:[1,0]
	v_mul_f32_e32 v126, 0x3fb8aa3b, v104
	v_mul_f32_e32 v127, 0x3fb8aa3b, v105
	v_exp_f32_e32 v104, v108
	v_exp_f32_e32 v105, v109
	v_mul_f32_e32 v110, 0x3fb8aa3b, v110
	v_mul_f32_e32 v111, 0x3fb8aa3b, v111
	v_exp_f32_e32 v108, v110
	v_exp_f32_e32 v109, v111
	v_pk_add_f32 v[104:105], v[104:105], 1.0 op_sel_hi:[1,0]
	v_exp_f32_e32 v110, v126
	v_div_scale_f32 v126, s[8:9], v105, v105, v133
	v_pk_add_f32 v[108:109], v[108:109], 1.0 op_sel_hi:[1,0]
	v_div_scale_f32 v131, s[8:9], v104, v104, v132
	v_rcp_f32_e32 v180, v126
	v_div_scale_f32 v135, s[10:11], v109, v109, v117
	v_rcp_f32_e32 v181, v131
	v_div_scale_f32 v156, s[12:13], v108, v108, v130
	v_rcp_f32_e32 v182, v135
	v_rcp_f32_e32 v183, v156
	v_fma_f32 v185, -v126, v180, 1.0
	v_exp_f32_e32 v111, v127
	v_div_scale_f32 v127, vcc, v133, v105, v133
	v_fma_f32 v186, -v131, v181, 1.0
	v_fmac_f32_e32 v180, v185, v180
	v_div_scale_f32 v134, s[8:9], v132, v104, v132
	v_fma_f32 v187, -v135, v182, 1.0
	v_fmac_f32_e32 v181, v186, v181
	v_mul_f32_e32 v185, v127, v180
	v_div_scale_f32 v155, s[10:11], v117, v109, v117
	v_fma_f32 v188, -v156, v183, 1.0
	v_fmac_f32_e32 v182, v187, v182
	v_mul_f32_e32 v186, v134, v181
	v_fma_f32 v189, -v126, v185, v127
	v_div_scale_f32 v157, s[12:13], v130, v108, v130
	v_fmac_f32_e32 v183, v188, v183
	v_mul_f32_e32 v187, v155, v182
	v_fma_f32 v190, -v131, v186, v134
	v_fmac_f32_e32 v185, v189, v180
	v_mul_f32_e32 v188, v157, v183
	v_fma_f32 v191, -v135, v187, v155
	v_fmac_f32_e32 v186, v190, v181
	v_fma_f32 v192, -v156, v188, v157
	v_fmac_f32_e32 v187, v191, v182
	v_fmac_f32_e32 v188, v192, v183
	v_rcp_f32_e32 v126, v105
	s_nop 0
	v_mul_f32_e32 v105, v133, v126
	v_fma_f32 v134, -v156, v188, v157
	v_rcp_f32_e32 v126, v104
	s_nop 0
	v_mul_f32_e32 v104, v132, v126
	v_pk_add_f32 v[126:127], v[104:105], v[128:129]
	v_rcp_f32_e32 v131, v109
	s_nop 0
	v_mul_f32_e32 v105, v117, v131
	v_rcp_f32_e32 v104, v108
	s_nop 0
	v_mul_f32_e32 v104, v130, v104
	v_pk_add_f32 v[128:129], v[104:105], v[112:113]
	v_and_b32_e32 v112, 0xffff0000, v118
	v_pk_add_f32 v[104:105], v[110:111], 1.0 op_sel_hi:[1,0]
	v_lshlrev_b32_e32 v108, 16, v114
	v_div_scale_f32 v110, s[8:9], v105, v105, v112
	v_rcp_f32_e32 v111, v110
	v_and_b32_e32 v109, 0xffff0000, v114
	v_pk_mul_f32 v[106:107], v[106:107], v[116:117] op_sel_hi:[1,0]
	v_lshlrev_b32_e32 v113, 16, v118
	v_fma_f32 v114, -v110, v111, 1.0
	v_fmac_f32_e32 v111, v114, v111
	v_div_scale_f32 v114, vcc, v112, v105, v112
	v_mul_f32_e32 v117, v114, v111
	v_fma_f32 v118, -v110, v117, v114
	v_fmac_f32_e32 v117, v118, v111
	v_rcp_f32_e32 v110, v105
	s_nop 0
	v_mul_f32_e32 v105, v112, v110
	v_mul_f32_e32 v106, 0x3fb8aa3b, v106
	v_mul_f32_e32 v107, 0x3fb8aa3b, v107
	v_exp_f32_e32 v106, v106
	v_exp_f32_e32 v107, v107
	v_rcp_f32_e32 v110, v104
	s_nop 0
	v_mul_f32_e32 v104, v113, v110
	v_pk_add_f32 v[130:131], v[104:105], v[108:109]
	v_and_b32_e32 v108, 0xffff0000, v119
	v_pk_add_f32 v[104:105], v[106:107], 1.0 op_sel_hi:[1,0]
	v_lshlrev_b32_e32 v111, 16, v119
	v_div_scale_f32 v109, s[8:9], v105, v105, v108
	v_rcp_f32_e32 v110, v109
	v_lshlrev_b32_e32 v106, 16, v115
	v_and_b32_e32 v107, 0xffff0000, v115
	v_pk_mul_f32 v[100:101], v[100:101], v[116:117] op_sel_hi:[1,0]
	v_fma_f32 v112, -v109, v110, 1.0
	v_fmac_f32_e32 v110, v112, v110
	v_div_scale_f32 v112, vcc, v108, v105, v108
	v_mul_f32_e32 v113, v112, v110
; DI unsigned pk_bf16(float lo, float hi) { typedef float f2 __attribute__((ext_vector_type(2))); typedef __bf16 b2 __attribute__((ext_vector_type(2))); f2 v = {lo, hi}; b2 b = __builtin_convertvector(v, b2); return __builtin_bit_cast(unsigned, b); }
; DI float bf_lo(unsigned w) { return __uint_as_float(w << 16); }
; DI float bf_hi(unsigned w) { return __uint_as_float(w & 0xffff0000u); }
;     DI void operator()(const f32x4 (&acc)[2][2][4][2], const pg8::Unit& u, int wr, int wc, int fr, int fq) const {
;     ...
;                 const int row = row0 + ai * 128 + m * 16;
;                 const size_t off = (size_t)row * ldc + col0;
;                 const f32x4* pq = (const f32x4*)(partin + (size_t)row * 16); const f32x4 t4 = (pq[0] + pq[1]) + (pq[2] + pq[3]);
;                 const float rs = -1.0f / sqrtf(((t4.x + t4.y) + (t4.z + t4.w)) * (1.f / DM) + NORM_EPS);
;                 float ss = 0.f;
; #pragma unroll
;                 for (int bj = 0; bj < 2; ++bj) {
;                     const size_t o2 = off + bj * 128;
;                     const u32x4 pw = *(const u32x4*)(pp + o2), bw = *(const u32x4*)(base + o2);
;                     const f32x4 a0 = acc[ai][bj][m][0] * rs, a1 = acc[ai][bj][m][1] * rs;
;                     f32x4 r0, r1;
;                     r0[0] = bf_lo(bw.x) + bf_lo(pw.x) / (1.f + __expf(a0[0])); r0[1] = bf_hi(bw.x) + bf_hi(pw.x) / (1.f + __expf(a0[1]));
;                     r0[2] = bf_lo(bw.y) + bf_lo(pw.y) / (1.f + __expf(a0[2])); r0[3] = bf_hi(bw.y) + bf_hi(pw.y) / (1.f + __expf(a0[3]));
;                     r1[0] = bf_lo(bw.z) + bf_lo(pw.z) / (1.f + __expf(a1[0])); r1[1] = bf_hi(bw.z) + bf_hi(pw.z) / (1.f + __expf(a1[1]));
;                     r1[2] = bf_lo(bw.w) + bf_lo(pw.w) / (1.f + __expf(a1[2])); r1[3] = bf_hi(bw.w) + bf_hi(pw.w) / (1.f + __expf(a1[3]));
;                     u32x4 w; w.x = pk_bf16(r0[0], r0[1]); w.y = pk_bf16(r0[2], r0[3]); w.z = pk_bf16(r1[0], r1[1]); w.w = pk_bf16(r1[2], r1[3]);
;                     *(u32x4*)(hb + o2) = w;
;                     ss += ((r0[0] * r0[0] + r0[1] * r0[1]) + (r0[2] * r0[2] + r0[3] * r0[3])) + ((r1[0] * r1[0] + r1[1] * r1[1]) + (r1[2] * r1[2] + r1[3] * r1[3]));
;                 }
;                 ss += __shfl_xor(ss, 16); ss += __shfl_xor(ss, 32);
;                 if (fq == 0) part[(size_t)row * 16 + u.pn * 4 + wc] = ss;
	v_fma_f32 v114, -v109, v113, v112
	v_fmac_f32_e32 v113, v114, v110
	v_div_scale_f32 v112, s[8:9], v104, v104, v111
	v_rcp_f32_e32 v109, v105
	s_nop 0
	v_mul_f32_e32 v105, v108, v109
	v_mul_f32_e32 v100, 0x3fb8aa3b, v100
	v_div_scale_f32 v108, vcc, v111, v104, v111
	v_rcp_f32_e32 v108, v104
	s_nop 0
	v_mul_f32_e32 v104, v111, v108
	v_pk_add_f32 v[114:115], v[104:105], v[106:107]
	v_cvt_pk_bf16_f32 v106, v126, v127
	v_cvt_pk_bf16_f32 v107, v128, v129
	v_cvt_pk_bf16_f32 v108, v130, v131
	v_cvt_pk_bf16_f32 v109, v114, v115
	v_lshl_add_u64 v[104:105], s[16:17], 0, v[122:123]
	v_or_b32_e32 v122, 0x100, v122
	global_store_dwordx4 v[104:105], v[106:109], off
	v_lshl_add_u64 v[110:111], s[20:21], 0, v[122:123]
	global_load_dwordx4 v[110:113], v[110:111], off
	v_lshl_add_u64 v[106:107], s[24:25], 0, v[122:123]
	global_load_dwordx4 v[106:109], v[106:107], off
	v_mul_f32_e32 v101, 0x3fb8aa3b, v101
	v_exp_f32_e32 v100, v100
	v_exp_f32_e32 v101, v101
	v_pk_mul_f32 v[122:123], v[128:129], v[128:129]
	v_pk_mul_f32 v[118:119], v[126:127], v[126:127]
	v_pk_mul_f32 v[126:127], v[130:131], v[130:131]
	v_pk_add_f32 v[100:101], v[100:101], 1.0 op_sel_hi:[1,0]
	v_pk_mul_f32 v[102:103], v[102:103], v[116:117] op_sel_hi:[1,0]
	v_pk_mul_f32 v[98:99], v[98:99], v[116:117] op_sel_hi:[1,0]
	v_pk_mul_f32 v[96:97], v[96:97], v[116:117] op_sel_hi:[1,0]
	v_mul_f32_e32 v102, 0x3fb8aa3b, v102
	v_mul_f32_e32 v103, 0x3fb8aa3b, v103
	v_exp_f32_e32 v102, v102
	v_exp_f32_e32 v103, v103
	v_mul_f32_e32 v96, 0x3fb8aa3b, v96
	v_mul_f32_e32 v97, 0x3fb8aa3b, v97
	v_exp_f32_e32 v96, v96
	v_pk_add_f32 v[102:103], v[102:103], 1.0 op_sel_hi:[1,0]
	v_exp_f32_e32 v97, v97
	v_mul_f32_e32 v98, 0x3fb8aa3b, v98
	v_mul_f32_e32 v99, 0x3fb8aa3b, v99
	v_exp_f32_e32 v98, v98
	v_pk_add_f32 v[96:97], v[96:97], 1.0 op_sel_hi:[1,0]
	v_exp_f32_e32 v99, v99
	v_pk_mul_f32 v[114:115], v[114:115], v[114:115]
	s_waitcnt vmcnt(1)
	v_lshlrev_b32_e32 v116, 16, v110
	v_and_b32_e32 v117, 0xffff0000, v110
	s_waitcnt vmcnt(0)
	v_and_b32_e32 v128, 0xffff0000, v106
	v_div_scale_f32 v129, s[8:9], v101, v101, v128
	v_rcp_f32_e32 v130, v129
	v_lshlrev_b32_e32 v106, 16, v106
	v_add_f32_e32 v114, v114, v115
	v_add_f32_e32 v115, v126, v127
	v_fma_f32 v110, -v129, v130, 1.0
	v_fmac_f32_e32 v130, v110, v130
	v_div_scale_f32 v110, vcc, v128, v101, v128
	v_mul_f32_e32 v131, v110, v130
	v_fma_f32 v132, -v129, v131, v110
	v_fmac_f32_e32 v131, v132, v130
	v_div_scale_f32 v129, s[8:9], v100, v100, v106
	v_rcp_f32_e32 v132, v129
	v_rcp_f32_e32 v110, v101
	s_nop 0
	v_mul_f32_e32 v101, v128, v110
	v_add_f32_e32 v114, v115, v114
	v_fma_f32 v110, -v129, v132, 1.0
	v_fmac_f32_e32 v132, v110, v132
	v_rcp_f32_e32 v110, v100
	s_nop 0
	v_mul_f32_e32 v100, v106, v110
	v_and_b32_e32 v106, 0xffff0000, v107
	v_pk_add_f32 v[100:101], v[100:101], v[116:117]
	v_div_scale_f32 v116, s[8:9], v103, v103, v106
	v_rcp_f32_e32 v117, v116
	v_lshlrev_b32_e32 v107, 16, v107
	v_lshlrev_b32_e32 v110, 16, v111
	v_and_b32_e32 v111, 0xffff0000, v111
	v_fma_f32 v128, -v116, v117, 1.0
	v_fmac_f32_e32 v117, v128, v117
	v_div_scale_f32 v128, vcc, v106, v103, v106
	v_mul_f32_e32 v129, v128, v117
	v_fma_f32 v130, -v116, v129, v128
	v_fmac_f32_e32 v129, v130, v117
	v_div_scale_f32 v128, s[8:9], v102, v102, v107
	v_rcp_f32_e32 v130, v128
	v_rcp_f32_e32 v116, v103
	s_nop 0
	v_mul_f32_e32 v103, v106, v116
	v_add_f32_e32 v115, v122, v123
	v_fma_f32 v106, -v128, v130, 1.0
	v_fmac_f32_e32 v130, v106, v130
	v_rcp_f32_e32 v106, v102
	s_nop 0
	v_mul_f32_e32 v102, v107, v106
	v_pk_add_f32 v[102:103], v[102:103], v[110:111]
	v_and_b32_e32 v110, 0xffff0000, v108
	v_div_scale_f32 v111, s[8:9], v97, v97, v110
	v_rcp_f32_e32 v116, v111
	v_lshlrev_b32_e32 v106, 16, v112
	v_and_b32_e32 v107, 0xffff0000, v112
	v_lshlrev_b32_e32 v108, 16, v108
	v_fma_f32 v112, -v111, v116, 1.0
	v_fmac_f32_e32 v116, v112, v116
	v_div_scale_f32 v112, vcc, v110, v97, v110
	v_mul_f32_e32 v117, v112, v116
	v_fma_f32 v128, -v111, v117, v112
	v_fmac_f32_e32 v117, v128, v116
	v_div_scale_f32 v112, s[8:9], v96, v96, v108
	v_rcp_f32_e32 v128, v112
	v_rcp_f32_e32 v111, v97
	s_nop 0
	v_mul_f32_e32 v97, v110, v111
	v_fma_f32 v110, -v112, v128, 1.0
	v_fmac_f32_e32 v128, v110, v128
	v_rcp_f32_e32 v110, v96
	s_nop 0
	v_mul_f32_e32 v96, v108, v110
	v_pk_add_f32 v[106:107], v[96:97], v[106:107]
	v_and_b32_e32 v108, 0xffff0000, v109
	v_pk_add_f32 v[96:97], v[98:99], 1.0 op_sel_hi:[1,0]
	v_lshlrev_b32_e32 v98, 16, v113
	v_and_b32_e32 v99, 0xffff0000, v113
	v_lshlrev_b32_e32 v109, 16, v109
	v_div_scale_f32 v112, s[8:9], v96, v96, v109
	v_rcp_f32_e32 v110, v97
	s_nop 0
	v_mul_f32_e32 v97, v108, v110
	v_div_scale_f32 v108, vcc, v109, v96, v109
	v_rcp_f32_e32 v108, v96
	s_nop 0
	v_mul_f32_e32 v96, v109, v108
	v_pk_add_f32 v[108:109], v[96:97], v[98:99]
	v_pk_mul_f32 v[96:97], v[100:101], v[100:101]
	v_pk_mul_f32 v[98:99], v[102:103], v[102:103]
	v_pk_mul_f32 v[110:111], v[106:107], v[106:107]
	v_pk_mul_f32 v[112:113], v[108:109], v[108:109]
	v_add_f32_e32 v116, v118, v119
	v_add_f32_e32 v112, v112, v113
	v_add_f32_e32 v110, v110, v111
	v_add_f32_e32 v98, v98, v99
	v_add_f32_e32 v96, v96, v97
	v_add_f32_e32 v115, v116, v115
	v_add_f32_e32 v110, v110, v112
	v_add_f32_e32 v96, v96, v98
	v_add_f32_e32 v114, v115, v114
	v_add_f32_e32 v96, v96, v110
	v_add_f32_e32 v96, v114, v96
	ds_bpermute_b32 v97, v124, v96
	v_cvt_pk_bf16_f32 v98, v100, v101
	v_cvt_pk_bf16_f32 v99, v102, v103
	v_cvt_pk_bf16_f32 v100, v106, v107
	v_cvt_pk_bf16_f32 v101, v108, v109
	s_waitcnt lgkmcnt(0)
	v_add_f32_e32 v96, v96, v97
	ds_bpermute_b32 v97, v125, v96
	global_store_dwordx4 v[104:105], v[98:101], off offset:256
	s_and_saveexec_b64 s[8:9], s[4:5]
	s_cbranch_execz .LBB0_678
	v_lshlrev_b64 v[98:99], 4, v[120:121]
	s_waitcnt lgkmcnt(0)
	v_add_f32_e32 v100, v96, v97
	v_lshl_add_u64 v[96:97], v[98:99], 2, s[18:19]
	v_lshl_add_u64 v[96:97], s[48:49], 2, v[96:97]
	s_lshl_b32 s34, s59, 2
	v_lshl_add_u64 v[96:97], v[96:97], 0, s[34:35]
	global_store_dword v[96:97], v100, off
; DI unsigned pk_bf16(float lo, float hi) { typedef float f2 __attribute__((ext_vector_type(2))); typedef __bf16 b2 __attribute__((ext_vector_type(2))); f2 v = {lo, hi}; b2 b = __builtin_convertvector(v, b2); return __builtin_bit_cast(unsigned, b); }
; DI float bf_lo(unsigned w) { return __uint_as_float(w << 16); }
; DI float bf_hi(unsigned w) { return __uint_as_float(w & 0xffff0000u); }
;     DI void operator()(const f32x4 (&acc)[2][2][4][2], const pg8::Unit& u, int wr, int wc, int fr, int fq) const {
;     ...
;                 const int row = row0 + ai * 128 + m * 16;
;                 const size_t off = (size_t)row * ldc + col0;
;                 const f32x4* pq = (const f32x4*)(partin + (size_t)row * 16); const f32x4 t4 = (pq[0] + pq[1]) + (pq[2] + pq[3]);
;                 const float rs = -1.0f / sqrtf(((t4.x + t4.y) + (t4.z + t4.w)) * (1.f / DM) + NORM_EPS);
;                 float ss = 0.f;
; #pragma unroll
;                 for (int bj = 0; bj < 2; ++bj) {
;                     const size_t o2 = off + bj * 128;
;                     const u32x4 pw = *(const u32x4*)(pp + o2), bw = *(const u32x4*)(base + o2);
;                     const f32x4 a0 = acc[ai][bj][m][0] * rs, a1 = acc[ai][bj][m][1] * rs;
;                     f32x4 r0, r1;
;                     r0[0] = bf_lo(bw.x) + bf_lo(pw.x) / (1.f + __expf(a0[0])); r0[1] = bf_hi(bw.x) + bf_hi(pw.x) / (1.f + __expf(a0[1]));
;                     r0[2] = bf_lo(bw.y) + bf_lo(pw.y) / (1.f + __expf(a0[2])); r0[3] = bf_hi(bw.y) + bf_hi(pw.y) / (1.f + __expf(a0[3]));
;                     r1[0] = bf_lo(bw.z) + bf_lo(pw.z) / (1.f + __expf(a1[0])); r1[1] = bf_hi(bw.z) + bf_hi(pw.z) / (1.f + __expf(a1[1]));
;                     r1[2] = bf_lo(bw.w) + bf_lo(pw.w) / (1.f + __expf(a1[2])); r1[3] = bf_hi(bw.w) + bf_hi(pw.w) / (1.f + __expf(a1[3]));
;                     u32x4 w; w.x = pk_bf16(r0[0], r0[1]); w.y = pk_bf16(r0[2], r0[3]); w.z = pk_bf16(r1[0], r1[1]); w.w = pk_bf16(r1[2], r1[3]);
;                     *(u32x4*)(hb + o2) = w;
;                     ss += ((r0[0] * r0[0] + r0[1] * r0[1]) + (r0[2] * r0[2] + r0[3] * r0[3])) + ((r1[0] * r1[0] + r1[1] * r1[1]) + (r1[2] * r1[2] + r1[3] * r1[3]));
;                 }
;                 ss += __shfl_xor(ss, 16); ss += __shfl_xor(ss, 32);
;                 if (fq == 0) part[(size_t)row * 16 + u.pn * 4 + wc] = ss;
.LBB0_678:
	s_or_b64 exec, exec, s[8:9]
	v_or_b32_e32 v104, 32, v154
	v_ashrrev_i32_e32 v105, 31, v104
	s_waitcnt lgkmcnt(0)
	v_lshlrev_b64 v[96:97], 6, v[104:105]
	v_lshl_add_u64 v[96:97], s[26:27], 0, v[96:97]
	global_load_dwordx4 v[108:111], v[96:97], off
	global_load_dwordx4 v[112:115], v[96:97], off offset:16
	global_load_dwordx4 v[116:119], v[96:97], off offset:32
	global_load_dwordx4 v[120:123], v[96:97], off offset:48
	v_lshlrev_b64 v[96:97], 10, v[104:105]
	v_lshl_add_u64 v[96:97], v[96:97], 0, v[152:153]
	v_lshlrev_b64 v[106:107], 1, v[96:97]
	v_lshl_add_u64 v[96:97], s[20:21], 0, v[106:107]
	global_load_dwordx4 v[96:99], v[96:97], off
	v_lshl_add_u64 v[100:101], s[24:25], 0, v[106:107]
	global_load_dwordx4 v[100:103], v[100:101], off
	s_waitcnt vmcnt(4)
	v_pk_add_f32 v[110:111], v[110:111], v[114:115]
	v_pk_add_f32 v[108:109], v[108:109], v[112:113]
	s_waitcnt vmcnt(2)
	v_pk_add_f32 v[112:113], v[118:119], v[122:123]
	v_pk_add_f32 v[114:115], v[116:117], v[120:121]
	v_pk_add_f32 v[110:111], v[110:111], v[112:113]
	v_pk_add_f32 v[108:109], v[108:109], v[114:115]
	s_waitcnt vmcnt(0)
	v_lshlrev_b32_e32 v114, 16, v100
	v_pk_mov_b32 v[112:113], v[108:109], v[110:111] op_sel:[1,0]
	v_mov_b32_e32 v109, v111
	v_pk_add_f32 v[108:109], v[112:113], v[108:109]
	v_lshlrev_b32_e32 v110, 16, v96
	v_and_b32_e32 v111, 0xffff0000, v96
	v_add_f32_e32 v96, v108, v109
	v_fmamk_f32 v96, v96, 0x3a800000, v178
	v_and_b32_e32 v115, 0xffff0000, v100
	v_mul_f32_e32 v100, 0x4f800000, v96
	v_cmp_gt_f32_e32 vcc, s70, v96
	v_lshlrev_b32_e32 v112, 16, v101
	v_and_b32_e32 v101, 0xffff0000, v101
	v_cndmask_b32_e32 v100, v96, v100, vcc
	v_sqrt_f32_e32 v108, v100
	v_lshlrev_b32_e32 v96, 16, v97
	v_and_b32_e32 v97, 0xffff0000, v97
	s_nop 1
	v_mul_f32_e32 v109, 0x37800000, v108
	v_cndmask_b32_e32 v108, v108, v109, vcc
	v_cmp_class_f32_e32 vcc, v100, v179
	s_nop 1
	v_cndmask_b32_e32 v100, v108, v100, vcc
	v_rcp_f32_e32 v108, v100
	s_nop 0
	v_mul_f32_e32 v100, -1.0, v108
	v_pk_mul_f32 v[92:93], v[92:93], v[100:101] op_sel_hi:[1,0]
	v_pk_mul_f32 v[88:89], v[88:89], v[100:101] op_sel_hi:[1,0]
	v_mul_f32_e32 v92, 0x3fb8aa3b, v92
	v_mul_f32_e32 v93, 0x3fb8aa3b, v93
	v_pk_mul_f32 v[94:95], v[94:95], v[100:101] op_sel_hi:[1,0]
	v_mul_f32_e32 v108, 0x3fb8aa3b, v88
	v_mul_f32_e32 v109, 0x3fb8aa3b, v89
	v_exp_f32_e32 v88, v92
	v_exp_f32_e32 v89, v93
	v_mul_f32_e32 v94, 0x3fb8aa3b, v94
	v_mul_f32_e32 v95, 0x3fb8aa3b, v95
	v_exp_f32_e32 v92, v94
	v_exp_f32_e32 v93, v95
	v_pk_add_f32 v[88:89], v[88:89], 1.0 op_sel_hi:[1,0]
	v_exp_f32_e32 v94, v108
	v_div_scale_f32 v108, s[8:9], v89, v89, v115
	v_pk_add_f32 v[92:93], v[92:93], 1.0 op_sel_hi:[1,0]
	v_div_scale_f32 v113, s[8:9], v88, v88, v114
	v_rcp_f32_e32 v121, v108
	v_div_scale_f32 v117, s[10:11], v93, v93, v101
	v_rcp_f32_e32 v122, v113
	v_div_scale_f32 v119, s[12:13], v92, v92, v112
	v_rcp_f32_e32 v123, v117
	v_rcp_f32_e32 v126, v119
	v_fma_f32 v127, -v108, v121, 1.0
	v_exp_f32_e32 v95, v109
	v_div_scale_f32 v109, vcc, v115, v89, v115
	v_fma_f32 v128, -v113, v122, 1.0
	v_fmac_f32_e32 v121, v127, v121
	v_div_scale_f32 v116, s[8:9], v114, v88, v114
	v_fma_f32 v129, -v117, v123, 1.0
	v_fmac_f32_e32 v122, v128, v122
	v_mul_f32_e32 v127, v109, v121
	v_div_scale_f32 v118, s[10:11], v101, v93, v101
	v_fma_f32 v130, -v119, v126, 1.0
	v_fmac_f32_e32 v123, v129, v123
	v_mul_f32_e32 v128, v116, v122
	v_fma_f32 v131, -v108, v127, v109
	v_div_scale_f32 v120, s[12:13], v112, v92, v112
	v_fmac_f32_e32 v126, v130, v126
	v_mul_f32_e32 v129, v118, v123
	v_fma_f32 v132, -v113, v128, v116
	v_fmac_f32_e32 v127, v131, v121
	v_mul_f32_e32 v130, v120, v126
	v_fma_f32 v133, -v117, v129, v118
	v_fmac_f32_e32 v128, v132, v122
	v_fma_f32 v134, -v119, v130, v120
	v_fmac_f32_e32 v129, v133, v123
	v_fmac_f32_e32 v130, v134, v126
	v_rcp_f32_e32 v108, v89
	s_nop 0
	v_mul_f32_e32 v89, v115, v108
	v_fma_f32 v116, -v119, v130, v120
	v_rcp_f32_e32 v108, v88
	s_nop 0
	v_mul_f32_e32 v88, v114, v108
	v_pk_add_f32 v[108:109], v[88:89], v[110:111]
	v_rcp_f32_e32 v113, v93
	s_nop 0
	v_mul_f32_e32 v89, v101, v113
	v_rcp_f32_e32 v88, v92
	s_nop 0
	v_mul_f32_e32 v88, v112, v88
	v_pk_add_f32 v[110:111], v[88:89], v[96:97]
	v_and_b32_e32 v96, 0xffff0000, v102
	v_pk_add_f32 v[88:89], v[94:95], 1.0 op_sel_hi:[1,0]
	v_lshlrev_b32_e32 v92, 16, v98
	v_div_scale_f32 v94, s[8:9], v89, v89, v96
	v_rcp_f32_e32 v95, v94
	v_and_b32_e32 v93, 0xffff0000, v98
	v_pk_mul_f32 v[90:91], v[90:91], v[100:101] op_sel_hi:[1,0]
	v_lshlrev_b32_e32 v97, 16, v102
	v_fma_f32 v98, -v94, v95, 1.0
	v_fmac_f32_e32 v95, v98, v95
	v_div_scale_f32 v98, vcc, v96, v89, v96
	v_mul_f32_e32 v101, v98, v95
	v_fma_f32 v102, -v94, v101, v98
	v_fmac_f32_e32 v101, v102, v95
	v_rcp_f32_e32 v94, v89
	s_nop 0
	v_mul_f32_e32 v89, v96, v94
	v_mul_f32_e32 v90, 0x3fb8aa3b, v90
	v_mul_f32_e32 v91, 0x3fb8aa3b, v91
	v_exp_f32_e32 v90, v90
	v_exp_f32_e32 v91, v91
	v_rcp_f32_e32 v94, v88
	s_nop 0
	v_mul_f32_e32 v88, v97, v94
	v_pk_add_f32 v[112:113], v[88:89], v[92:93]
	v_and_b32_e32 v92, 0xffff0000, v103
	v_pk_add_f32 v[88:89], v[90:91], 1.0 op_sel_hi:[1,0]
	v_lshlrev_b32_e32 v95, 16, v103
	v_div_scale_f32 v93, s[8:9], v89, v89, v92
	v_rcp_f32_e32 v94, v93
	v_lshlrev_b32_e32 v90, 16, v99
	v_and_b32_e32 v91, 0xffff0000, v99
	v_pk_mul_f32 v[84:85], v[84:85], v[100:101] op_sel_hi:[1,0]
	v_fma_f32 v96, -v93, v94, 1.0
	v_fmac_f32_e32 v94, v96, v94
	v_div_scale_f32 v96, vcc, v92, v89, v92
	v_mul_f32_e32 v97, v96, v94
	v_fma_f32 v98, -v93, v97, v96
	v_fmac_f32_e32 v97, v98, v94
	v_div_scale_f32 v96, s[8:9], v88, v88, v95
	v_rcp_f32_e32 v93, v89
	s_nop 0
	v_mul_f32_e32 v89, v92, v93
	v_mul_f32_e32 v84, 0x3fb8aa3b, v84
; DI unsigned pk_bf16(float lo, float hi) { typedef float f2 __attribute__((ext_vector_type(2))); typedef __bf16 b2 __attribute__((ext_vector_type(2))); f2 v = {lo, hi}; b2 b = __builtin_convertvector(v, b2); return __builtin_bit_cast(unsigned, b); }
; DI float bf_lo(unsigned w) { return __uint_as_float(w << 16); }
; DI float bf_hi(unsigned w) { return __uint_as_float(w & 0xffff0000u); }
;     DI void operator()(const f32x4 (&acc)[2][2][4][2], const pg8::Unit& u, int wr, int wc, int fr, int fq) const {
;     ...
;                 const int row = row0 + ai * 128 + m * 16;
;                 const size_t off = (size_t)row * ldc + col0;
;                 const f32x4* pq = (const f32x4*)(partin + (size_t)row * 16); const f32x4 t4 = (pq[0] + pq[1]) + (pq[2] + pq[3]);
;                 const float rs = -1.0f / sqrtf(((t4.x + t4.y) + (t4.z + t4.w)) * (1.f / DM) + NORM_EPS);
;                 float ss = 0.f;
; #pragma unroll
;                 for (int bj = 0; bj < 2; ++bj) {
;                     const size_t o2 = off + bj * 128;
;                     const u32x4 pw = *(const u32x4*)(pp + o2), bw = *(const u32x4*)(base + o2);
;                     const f32x4 a0 = acc[ai][bj][m][0] * rs, a1 = acc[ai][bj][m][1] * rs;
;                     f32x4 r0, r1;
;                     r0[0] = bf_lo(bw.x) + bf_lo(pw.x) / (1.f + __expf(a0[0])); r0[1] = bf_hi(bw.x) + bf_hi(pw.x) / (1.f + __expf(a0[1]));
;                     r0[2] = bf_lo(bw.y) + bf_lo(pw.y) / (1.f + __expf(a0[2])); r0[3] = bf_hi(bw.y) + bf_hi(pw.y) / (1.f + __expf(a0[3]));
;                     r1[0] = bf_lo(bw.z) + bf_lo(pw.z) / (1.f + __expf(a1[0])); r1[1] = bf_hi(bw.z) + bf_hi(pw.z) / (1.f + __expf(a1[1]));
;                     r1[2] = bf_lo(bw.w) + bf_lo(pw.w) / (1.f + __expf(a1[2])); r1[3] = bf_hi(bw.w) + bf_hi(pw.w) / (1.f + __expf(a1[3]));
;                     u32x4 w; w.x = pk_bf16(r0[0], r0[1]); w.y = pk_bf16(r0[2], r0[3]); w.z = pk_bf16(r1[0], r1[1]); w.w = pk_bf16(r1[2], r1[3]);
;                     *(u32x4*)(hb + o2) = w;
;                     ss += ((r0[0] * r0[0] + r0[1] * r0[1]) + (r0[2] * r0[2] + r0[3] * r0[3])) + ((r1[0] * r1[0] + r1[1] * r1[1]) + (r1[2] * r1[2] + r1[3] * r1[3]));
;                 }
;                 ss += __shfl_xor(ss, 16); ss += __shfl_xor(ss, 32);
;                 if (fq == 0) part[(size_t)row * 16 + u.pn * 4 + wc] = ss;
	v_div_scale_f32 v92, vcc, v95, v88, v95
	v_rcp_f32_e32 v92, v88
	s_nop 0
	v_mul_f32_e32 v88, v95, v92
	v_pk_add_f32 v[98:99], v[88:89], v[90:91]
	v_cvt_pk_bf16_f32 v90, v108, v109
	v_cvt_pk_bf16_f32 v91, v110, v111
	v_cvt_pk_bf16_f32 v92, v112, v113
	v_cvt_pk_bf16_f32 v93, v98, v99
	v_lshl_add_u64 v[88:89], s[16:17], 0, v[106:107]
	v_or_b32_e32 v106, 0x100, v106
	global_store_dwordx4 v[88:89], v[90:93], off
	v_lshl_add_u64 v[94:95], s[20:21], 0, v[106:107]
	global_load_dwordx4 v[94:97], v[94:95], off
	v_lshl_add_u64 v[90:91], s[24:25], 0, v[106:107]
	global_load_dwordx4 v[90:93], v[90:91], off
	v_mul_f32_e32 v85, 0x3fb8aa3b, v85
	v_exp_f32_e32 v84, v84
	v_exp_f32_e32 v85, v85
	v_pk_mul_f32 v[106:107], v[110:111], v[110:111]
	v_pk_mul_f32 v[102:103], v[108:109], v[108:109]
	v_pk_mul_f32 v[108:109], v[112:113], v[112:113]
	v_pk_add_f32 v[84:85], v[84:85], 1.0 op_sel_hi:[1,0]
	v_pk_mul_f32 v[86:87], v[86:87], v[100:101] op_sel_hi:[1,0]
	v_pk_mul_f32 v[82:83], v[82:83], v[100:101] op_sel_hi:[1,0]
	v_pk_mul_f32 v[80:81], v[80:81], v[100:101] op_sel_hi:[1,0]
	v_mul_f32_e32 v86, 0x3fb8aa3b, v86
	v_mul_f32_e32 v87, 0x3fb8aa3b, v87
	v_exp_f32_e32 v86, v86
	v_exp_f32_e32 v87, v87
	v_mul_f32_e32 v80, 0x3fb8aa3b, v80
	v_mul_f32_e32 v81, 0x3fb8aa3b, v81
	v_exp_f32_e32 v80, v80
	v_pk_add_f32 v[86:87], v[86:87], 1.0 op_sel_hi:[1,0]
	v_exp_f32_e32 v81, v81
	v_mul_f32_e32 v82, 0x3fb8aa3b, v82
	v_mul_f32_e32 v83, 0x3fb8aa3b, v83
	v_exp_f32_e32 v82, v82
	v_pk_add_f32 v[80:81], v[80:81], 1.0 op_sel_hi:[1,0]
	v_exp_f32_e32 v83, v83
	v_pk_mul_f32 v[98:99], v[98:99], v[98:99]
	s_waitcnt vmcnt(1)
	v_lshlrev_b32_e32 v100, 16, v94
	v_and_b32_e32 v101, 0xffff0000, v94
	s_waitcnt vmcnt(0)
	v_and_b32_e32 v110, 0xffff0000, v90
	v_div_scale_f32 v111, s[8:9], v85, v85, v110
	v_rcp_f32_e32 v112, v111
	v_lshlrev_b32_e32 v90, 16, v90
	v_add_f32_e32 v98, v98, v99
	v_add_f32_e32 v99, v108, v109
	v_fma_f32 v94, -v111, v112, 1.0
	v_fmac_f32_e32 v112, v94, v112
	v_div_scale_f32 v94, vcc, v110, v85, v110
	v_mul_f32_e32 v113, v94, v112
	v_fma_f32 v114, -v111, v113, v94
	v_fmac_f32_e32 v113, v114, v112
	v_div_scale_f32 v111, s[8:9], v84, v84, v90
	v_rcp_f32_e32 v114, v111
	v_rcp_f32_e32 v94, v85
	s_nop 0
	v_mul_f32_e32 v85, v110, v94
	v_add_f32_e32 v98, v99, v98
	v_fma_f32 v94, -v111, v114, 1.0
	v_fmac_f32_e32 v114, v94, v114
	v_rcp_f32_e32 v94, v84
	s_nop 0
	v_mul_f32_e32 v84, v90, v94
	v_and_b32_e32 v90, 0xffff0000, v91
	v_pk_add_f32 v[84:85], v[84:85], v[100:101]
	v_div_scale_f32 v100, s[8:9], v87, v87, v90
	v_rcp_f32_e32 v101, v100
	v_lshlrev_b32_e32 v91, 16, v91
	v_lshlrev_b32_e32 v94, 16, v95
	v_and_b32_e32 v95, 0xffff0000, v95
	v_fma_f32 v110, -v100, v101, 1.0
	v_fmac_f32_e32 v101, v110, v101
	v_div_scale_f32 v110, vcc, v90, v87, v90
	v_mul_f32_e32 v111, v110, v101
	v_fma_f32 v112, -v100, v111, v110
	v_fmac_f32_e32 v111, v112, v101
	v_div_scale_f32 v110, s[8:9], v86, v86, v91
	v_rcp_f32_e32 v112, v110
	v_rcp_f32_e32 v100, v87
	s_nop 0
	v_mul_f32_e32 v87, v90, v100
	v_add_f32_e32 v99, v106, v107
	v_fma_f32 v90, -v110, v112, 1.0
	v_fmac_f32_e32 v112, v90, v112
	v_rcp_f32_e32 v90, v86
	s_nop 0
	v_mul_f32_e32 v86, v91, v90
	v_pk_add_f32 v[86:87], v[86:87], v[94:95]
	v_and_b32_e32 v94, 0xffff0000, v92
	v_div_scale_f32 v95, s[8:9], v81, v81, v94
	v_rcp_f32_e32 v100, v95
	v_lshlrev_b32_e32 v90, 16, v96
	v_and_b32_e32 v91, 0xffff0000, v96
	v_lshlrev_b32_e32 v92, 16, v92
	v_fma_f32 v96, -v95, v100, 1.0
	v_fmac_f32_e32 v100, v96, v100
	v_div_scale_f32 v96, vcc, v94, v81, v94
	v_mul_f32_e32 v101, v96, v100
	v_fma_f32 v110, -v95, v101, v96
	v_fmac_f32_e32 v101, v110, v100
	v_div_scale_f32 v96, s[8:9], v80, v80, v92
	v_rcp_f32_e32 v110, v96
	v_rcp_f32_e32 v95, v81
	s_nop 0
	v_mul_f32_e32 v81, v94, v95
	v_fma_f32 v94, -v96, v110, 1.0
	v_fmac_f32_e32 v110, v94, v110
	v_rcp_f32_e32 v94, v80
	s_nop 0
	v_mul_f32_e32 v80, v92, v94
	v_pk_add_f32 v[90:91], v[80:81], v[90:91]
	v_and_b32_e32 v92, 0xffff0000, v93
	v_pk_add_f32 v[80:81], v[82:83], 1.0 op_sel_hi:[1,0]
	v_lshlrev_b32_e32 v82, 16, v97
	v_and_b32_e32 v83, 0xffff0000, v97
	v_lshlrev_b32_e32 v93, 16, v93
	v_div_scale_f32 v96, s[8:9], v80, v80, v93
	v_rcp_f32_e32 v94, v81
	s_nop 0
	v_mul_f32_e32 v81, v92, v94
	v_div_scale_f32 v92, vcc, v93, v80, v93
	v_rcp_f32_e32 v92, v80
	s_nop 0
	v_mul_f32_e32 v80, v93, v92
	v_pk_add_f32 v[92:93], v[80:81], v[82:83]
	v_pk_mul_f32 v[80:81], v[84:85], v[84:85]
	v_pk_mul_f32 v[82:83], v[86:87], v[86:87]
	v_pk_mul_f32 v[94:95], v[90:91], v[90:91]
	v_pk_mul_f32 v[96:97], v[92:93], v[92:93]
	v_add_f32_e32 v100, v102, v103
	v_add_f32_e32 v96, v96, v97
	v_add_f32_e32 v94, v94, v95
	v_add_f32_e32 v82, v82, v83
	v_add_f32_e32 v80, v80, v81
	v_add_f32_e32 v99, v100, v99
	v_add_f32_e32 v94, v94, v96
	v_add_f32_e32 v80, v80, v82
	v_add_f32_e32 v98, v99, v98
	v_add_f32_e32 v80, v80, v94
	v_add_f32_e32 v80, v98, v80
	ds_bpermute_b32 v81, v124, v80
	v_cvt_pk_bf16_f32 v82, v84, v85
	v_cvt_pk_bf16_f32 v83, v86, v87
	v_cvt_pk_bf16_f32 v84, v90, v91
	v_cvt_pk_bf16_f32 v85, v92, v93
	s_waitcnt lgkmcnt(0)
	v_add_f32_e32 v80, v80, v81
	ds_bpermute_b32 v81, v125, v80
	global_store_dwordx4 v[88:89], v[82:85], off offset:256
	s_and_saveexec_b64 s[8:9], s[4:5]
	s_cbranch_execz .LBB0_680
	v_lshlrev_b64 v[82:83], 4, v[104:105]
	s_waitcnt lgkmcnt(0)
	v_add_f32_e32 v84, v80, v81
	v_lshl_add_u64 v[80:81], v[82:83], 2, s[18:19]
	v_lshl_add_u64 v[80:81], s[48:49], 2, v[80:81]
	s_lshl_b32 s34, s59, 2
	v_lshl_add_u64 v[80:81], v[80:81], 0, s[34:35]
	global_store_dword v[80:81], v84, off
; DI unsigned pk_bf16(float lo, float hi) { typedef float f2 __attribute__((ext_vector_type(2))); typedef __bf16 b2 __attribute__((ext_vector_type(2))); f2 v = {lo, hi}; b2 b = __builtin_convertvector(v, b2); return __builtin_bit_cast(unsigned, b); }
; DI float bf_lo(unsigned w) { return __uint_as_float(w << 16); }
; DI float bf_hi(unsigned w) { return __uint_as_float(w & 0xffff0000u); }
;     DI void operator()(const f32x4 (&acc)[2][2][4][2], const pg8::Unit& u, int wr, int wc, int fr, int fq) const {
;     ...
;                 const int row = row0 + ai * 128 + m * 16;
;                 const size_t off = (size_t)row * ldc + col0;
;                 const f32x4* pq = (const f32x4*)(partin + (size_t)row * 16); const f32x4 t4 = (pq[0] + pq[1]) + (pq[2] + pq[3]);
;                 const float rs = -1.0f / sqrtf(((t4.x + t4.y) + (t4.z + t4.w)) * (1.f / DM) + NORM_EPS);
;                 float ss = 0.f;
; #pragma unroll
;                 for (int bj = 0; bj < 2; ++bj) {
;                     const size_t o2 = off + bj * 128;
;                     const u32x4 pw = *(const u32x4*)(pp + o2), bw = *(const u32x4*)(base + o2);
;                     const f32x4 a0 = acc[ai][bj][m][0] * rs, a1 = acc[ai][bj][m][1] * rs;
;                     f32x4 r0, r1;
;                     r0[0] = bf_lo(bw.x) + bf_lo(pw.x) / (1.f + __expf(a0[0])); r0[1] = bf_hi(bw.x) + bf_hi(pw.x) / (1.f + __expf(a0[1]));
;                     r0[2] = bf_lo(bw.y) + bf_lo(pw.y) / (1.f + __expf(a0[2])); r0[3] = bf_hi(bw.y) + bf_hi(pw.y) / (1.f + __expf(a0[3]));
;                     r1[0] = bf_lo(bw.z) + bf_lo(pw.z) / (1.f + __expf(a1[0])); r1[1] = bf_hi(bw.z) + bf_hi(pw.z) / (1.f + __expf(a1[1]));
;                     r1[2] = bf_lo(bw.w) + bf_lo(pw.w) / (1.f + __expf(a1[2])); r1[3] = bf_hi(bw.w) + bf_hi(pw.w) / (1.f + __expf(a1[3]));
;                     u32x4 w; w.x = pk_bf16(r0[0], r0[1]); w.y = pk_bf16(r0[2], r0[3]); w.z = pk_bf16(r1[0], r1[1]); w.w = pk_bf16(r1[2], r1[3]);
;                     *(u32x4*)(hb + o2) = w;
.LBB0_680:
	s_or_b64 exec, exec, s[8:9]
	v_or_b32_e32 v88, 48, v154
	v_ashrrev_i32_e32 v89, 31, v88
	s_waitcnt lgkmcnt(0)
	v_lshlrev_b64 v[80:81], 6, v[88:89]
	v_lshl_add_u64 v[80:81], s[26:27], 0, v[80:81]
	global_load_dwordx4 v[92:95], v[80:81], off
	global_load_dwordx4 v[96:99], v[80:81], off offset:16
	global_load_dwordx4 v[100:103], v[80:81], off offset:32
	global_load_dwordx4 v[104:107], v[80:81], off offset:48
	v_lshlrev_b64 v[80:81], 10, v[88:89]
	v_lshl_add_u64 v[80:81], v[80:81], 0, v[152:153]
	v_lshlrev_b64 v[90:91], 1, v[80:81]
	v_lshl_add_u64 v[80:81], s[20:21], 0, v[90:91]
	global_load_dwordx4 v[80:83], v[80:81], off
	v_lshl_add_u64 v[84:85], s[24:25], 0, v[90:91]
	global_load_dwordx4 v[84:87], v[84:85], off
	s_waitcnt vmcnt(4)
	v_pk_add_f32 v[94:95], v[94:95], v[98:99]
	v_pk_add_f32 v[92:93], v[92:93], v[96:97]
	s_waitcnt vmcnt(2)
	v_pk_add_f32 v[96:97], v[102:103], v[106:107]
	v_pk_add_f32 v[98:99], v[100:101], v[104:105]
	v_pk_add_f32 v[94:95], v[94:95], v[96:97]
	v_pk_add_f32 v[92:93], v[92:93], v[98:99]
	s_waitcnt vmcnt(0)
	v_lshlrev_b32_e32 v98, 16, v84
	v_pk_mov_b32 v[96:97], v[92:93], v[94:95] op_sel:[1,0]
	v_mov_b32_e32 v93, v95
	v_pk_add_f32 v[92:93], v[96:97], v[92:93]
	v_lshlrev_b32_e32 v94, 16, v80
	v_and_b32_e32 v95, 0xffff0000, v80
	v_add_f32_e32 v80, v92, v93
	v_fmamk_f32 v80, v80, 0x3a800000, v178
	v_and_b32_e32 v99, 0xffff0000, v84
	v_mul_f32_e32 v84, 0x4f800000, v80
	v_cmp_gt_f32_e32 vcc, s70, v80
	v_lshlrev_b32_e32 v96, 16, v85
	v_and_b32_e32 v85, 0xffff0000, v85
	v_cndmask_b32_e32 v84, v80, v84, vcc
	v_sqrt_f32_e32 v92, v84
	v_lshlrev_b32_e32 v80, 16, v81
	v_and_b32_e32 v81, 0xffff0000, v81
	s_nop 1
	v_mul_f32_e32 v93, 0x37800000, v92
	v_cndmask_b32_e32 v92, v92, v93, vcc
	v_cmp_class_f32_e32 vcc, v84, v179
	s_nop 1
	v_cndmask_b32_e32 v84, v92, v84, vcc
	v_rcp_f32_e32 v92, v84
	s_nop 0
	v_mul_f32_e32 v84, -1.0, v92
	v_pk_mul_f32 v[76:77], v[76:77], v[84:85] op_sel_hi:[1,0]
	v_pk_mul_f32 v[72:73], v[72:73], v[84:85] op_sel_hi:[1,0]
	v_mul_f32_e32 v76, 0x3fb8aa3b, v76
	v_mul_f32_e32 v77, 0x3fb8aa3b, v77
	v_pk_mul_f32 v[78:79], v[78:79], v[84:85] op_sel_hi:[1,0]
	v_mul_f32_e32 v92, 0x3fb8aa3b, v72
	v_mul_f32_e32 v93, 0x3fb8aa3b, v73
	v_exp_f32_e32 v72, v76
	v_exp_f32_e32 v73, v77
	v_mul_f32_e32 v78, 0x3fb8aa3b, v78
	v_mul_f32_e32 v79, 0x3fb8aa3b, v79
	v_exp_f32_e32 v76, v78
	v_exp_f32_e32 v77, v79
	v_pk_add_f32 v[72:73], v[72:73], 1.0 op_sel_hi:[1,0]
	v_exp_f32_e32 v78, v92
	v_div_scale_f32 v92, s[8:9], v73, v73, v99
	v_pk_add_f32 v[76:77], v[76:77], 1.0 op_sel_hi:[1,0]
	v_div_scale_f32 v97, s[8:9], v72, v72, v98
	v_rcp_f32_e32 v105, v92
	v_div_scale_f32 v101, s[10:11], v77, v77, v85
	v_rcp_f32_e32 v106, v97
	v_div_scale_f32 v103, s[12:13], v76, v76, v96
	v_rcp_f32_e32 v107, v101
	v_rcp_f32_e32 v108, v103
	v_fma_f32 v109, -v92, v105, 1.0
	v_exp_f32_e32 v79, v93
	v_div_scale_f32 v93, vcc, v99, v73, v99
	v_fma_f32 v110, -v97, v106, 1.0
	v_fmac_f32_e32 v105, v109, v105
	v_div_scale_f32 v100, s[8:9], v98, v72, v98
	v_fma_f32 v111, -v101, v107, 1.0
	v_fmac_f32_e32 v106, v110, v106
	v_mul_f32_e32 v109, v93, v105
	v_div_scale_f32 v102, s[10:11], v85, v77, v85
	v_fma_f32 v112, -v103, v108, 1.0
	v_fmac_f32_e32 v107, v111, v107
	v_mul_f32_e32 v110, v100, v106
	v_fma_f32 v113, -v92, v109, v93
	v_div_scale_f32 v104, s[12:13], v96, v76, v96
	v_fmac_f32_e32 v108, v112, v108
	v_mul_f32_e32 v111, v102, v107
	v_fma_f32 v114, -v97, v110, v100
	v_fmac_f32_e32 v109, v113, v105
	v_mul_f32_e32 v112, v104, v108
	v_fma_f32 v115, -v101, v111, v102
	v_fmac_f32_e32 v110, v114, v106
	v_fma_f32 v116, -v103, v112, v104
	v_fmac_f32_e32 v111, v115, v107
	v_fmac_f32_e32 v112, v116, v108
	v_rcp_f32_e32 v92, v73
	s_nop 0
	v_mul_f32_e32 v73, v99, v92
	v_fma_f32 v100, -v103, v112, v104
	v_rcp_f32_e32 v92, v72
	s_nop 0
	v_mul_f32_e32 v72, v98, v92
	v_pk_add_f32 v[92:93], v[72:73], v[94:95]
	v_rcp_f32_e32 v97, v77
	s_nop 0
	v_mul_f32_e32 v73, v85, v97
	v_rcp_f32_e32 v72, v76
	s_nop 0
	v_mul_f32_e32 v72, v96, v72
	v_pk_add_f32 v[94:95], v[72:73], v[80:81]
	v_and_b32_e32 v80, 0xffff0000, v86
	v_pk_add_f32 v[72:73], v[78:79], 1.0 op_sel_hi:[1,0]
	v_lshlrev_b32_e32 v76, 16, v82
	v_div_scale_f32 v78, s[8:9], v73, v73, v80
	v_rcp_f32_e32 v79, v78
	v_and_b32_e32 v77, 0xffff0000, v82
	v_pk_mul_f32 v[74:75], v[74:75], v[84:85] op_sel_hi:[1,0]
	v_lshlrev_b32_e32 v81, 16, v86
	v_fma_f32 v82, -v78, v79, 1.0
	v_fmac_f32_e32 v79, v82, v79
	v_div_scale_f32 v82, vcc, v80, v73, v80
	v_mul_f32_e32 v85, v82, v79
	v_fma_f32 v86, -v78, v85, v82
	v_fmac_f32_e32 v85, v86, v79
	v_rcp_f32_e32 v78, v73
	s_nop 0
	v_mul_f32_e32 v73, v80, v78
	v_mul_f32_e32 v74, 0x3fb8aa3b, v74
	v_mul_f32_e32 v75, 0x3fb8aa3b, v75
	v_exp_f32_e32 v74, v74
	v_exp_f32_e32 v75, v75
	v_rcp_f32_e32 v78, v72
	s_nop 0
	v_mul_f32_e32 v72, v81, v78
	v_pk_add_f32 v[96:97], v[72:73], v[76:77]
	v_and_b32_e32 v76, 0xffff0000, v87
	v_pk_add_f32 v[72:73], v[74:75], 1.0 op_sel_hi:[1,0]
	v_lshlrev_b32_e32 v79, 16, v87
	v_div_scale_f32 v77, s[8:9], v73, v73, v76
	v_rcp_f32_e32 v78, v77
	v_lshlrev_b32_e32 v74, 16, v83
	v_and_b32_e32 v75, 0xffff0000, v83
	v_pk_mul_f32 v[68:69], v[68:69], v[84:85] op_sel_hi:[1,0]
	v_fma_f32 v80, -v77, v78, 1.0
	v_fmac_f32_e32 v78, v80, v78
	v_div_scale_f32 v80, vcc, v76, v73, v76
	v_mul_f32_e32 v81, v80, v78
	v_fma_f32 v82, -v77, v81, v80
	v_fmac_f32_e32 v81, v82, v78
	v_div_scale_f32 v80, s[8:9], v72, v72, v79
	v_rcp_f32_e32 v77, v73
	s_nop 0
	v_mul_f32_e32 v73, v76, v77
	v_mul_f32_e32 v68, 0x3fb8aa3b, v68
	v_div_scale_f32 v76, vcc, v79, v72, v79
	v_rcp_f32_e32 v76, v72
	s_nop 0
	v_mul_f32_e32 v72, v79, v76
	v_pk_add_f32 v[82:83], v[72:73], v[74:75]
	v_cvt_pk_bf16_f32 v74, v92, v93
	v_cvt_pk_bf16_f32 v75, v94, v95
	v_cvt_pk_bf16_f32 v76, v96, v97
	v_cvt_pk_bf16_f32 v77, v82, v83
	v_lshl_add_u64 v[72:73], s[16:17], 0, v[90:91]
	v_or_b32_e32 v90, 0x100, v90
	global_store_dwordx4 v[72:73], v[74:77], off
	v_lshl_add_u64 v[78:79], s[20:21], 0, v[90:91]
	global_load_dwordx4 v[78:81], v[78:79], off
	v_lshl_add_u64 v[74:75], s[24:25], 0, v[90:91]
	global_load_dwordx4 v[74:77], v[74:75], off
	v_mul_f32_e32 v69, 0x3fb8aa3b, v69
	v_exp_f32_e32 v68, v68
	v_exp_f32_e32 v69, v69
	v_pk_mul_f32 v[90:91], v[94:95], v[94:95]
	v_pk_mul_f32 v[86:87], v[92:93], v[92:93]
	v_pk_mul_f32 v[92:93], v[96:97], v[96:97]
	v_pk_add_f32 v[68:69], v[68:69], 1.0 op_sel_hi:[1,0]
	v_pk_mul_f32 v[70:71], v[70:71], v[84:85] op_sel_hi:[1,0]
	v_pk_mul_f32 v[66:67], v[66:67], v[84:85] op_sel_hi:[1,0]
	v_pk_mul_f32 v[64:65], v[64:65], v[84:85] op_sel_hi:[1,0]
	v_mul_f32_e32 v70, 0x3fb8aa3b, v70
	v_mul_f32_e32 v71, 0x3fb8aa3b, v71
	v_exp_f32_e32 v70, v70
	v_exp_f32_e32 v71, v71
	v_mul_f32_e32 v64, 0x3fb8aa3b, v64
	v_mul_f32_e32 v65, 0x3fb8aa3b, v65
	v_exp_f32_e32 v64, v64
	v_pk_add_f32 v[70:71], v[70:71], 1.0 op_sel_hi:[1,0]
	v_exp_f32_e32 v65, v65
	v_mul_f32_e32 v66, 0x3fb8aa3b, v66
	v_mul_f32_e32 v67, 0x3fb8aa3b, v67
	v_exp_f32_e32 v66, v66
	v_pk_add_f32 v[64:65], v[64:65], 1.0 op_sel_hi:[1,0]
	v_exp_f32_e32 v67, v67
	v_pk_mul_f32 v[82:83], v[82:83], v[82:83]
	s_waitcnt vmcnt(1)
; DI unsigned pk_bf16(float lo, float hi) { typedef float f2 __attribute__((ext_vector_type(2))); typedef __bf16 b2 __attribute__((ext_vector_type(2))); f2 v = {lo, hi}; b2 b = __builtin_convertvector(v, b2); return __builtin_bit_cast(unsigned, b); }
; DI float bf_lo(unsigned w) { return __uint_as_float(w << 16); }
; DI float bf_hi(unsigned w) { return __uint_as_float(w & 0xffff0000u); }
;     DI void operator()(const f32x4 (&acc)[2][2][4][2], const pg8::Unit& u, int wr, int wc, int fr, int fq) const {
;     ...
;                 const int row = row0 + ai * 128 + m * 16;
;                 const size_t off = (size_t)row * ldc + col0;
;                 const f32x4* pq = (const f32x4*)(partin + (size_t)row * 16); const f32x4 t4 = (pq[0] + pq[1]) + (pq[2] + pq[3]);
;     ...
;                     const u32x4 pw = *(const u32x4*)(pp + o2), bw = *(const u32x4*)(base + o2);
;                     const f32x4 a0 = acc[ai][bj][m][0] * rs, a1 = acc[ai][bj][m][1] * rs;
;                     f32x4 r0, r1;
;                     r0[0] = bf_lo(bw.x) + bf_lo(pw.x) / (1.f + __expf(a0[0])); r0[1] = bf_hi(bw.x) + bf_hi(pw.x) / (1.f + __expf(a0[1]));
;                     r0[2] = bf_lo(bw.y) + bf_lo(pw.y) / (1.f + __expf(a0[2])); r0[3] = bf_hi(bw.y) + bf_hi(pw.y) / (1.f + __expf(a0[3]));
;                     r1[0] = bf_lo(bw.z) + bf_lo(pw.z) / (1.f + __expf(a1[0])); r1[1] = bf_hi(bw.z) + bf_hi(pw.z) / (1.f + __expf(a1[1]));
;                     r1[2] = bf_lo(bw.w) + bf_lo(pw.w) / (1.f + __expf(a1[2])); r1[3] = bf_hi(bw.w) + bf_hi(pw.w) / (1.f + __expf(a1[3]));
;                     u32x4 w; w.x = pk_bf16(r0[0], r0[1]); w.y = pk_bf16(r0[2], r0[3]); w.z = pk_bf16(r1[0], r1[1]); w.w = pk_bf16(r1[2], r1[3]);
;                     *(u32x4*)(hb + o2) = w;
;                     ss += ((r0[0] * r0[0] + r0[1] * r0[1]) + (r0[2] * r0[2] + r0[3] * r0[3])) + ((r1[0] * r1[0] + r1[1] * r1[1]) + (r1[2] * r1[2] + r1[3] * r1[3]));
;                 }
;                 ss += __shfl_xor(ss, 16); ss += __shfl_xor(ss, 32);
;                 if (fq == 0) part[(size_t)row * 16 + u.pn * 4 + wc] = ss;
	v_lshlrev_b32_e32 v84, 16, v78
	v_and_b32_e32 v85, 0xffff0000, v78
	s_waitcnt vmcnt(0)
	v_and_b32_e32 v94, 0xffff0000, v74
	v_div_scale_f32 v95, s[8:9], v69, v69, v94
	v_rcp_f32_e32 v96, v95
	v_lshlrev_b32_e32 v74, 16, v74
	v_add_f32_e32 v82, v82, v83
	v_add_f32_e32 v83, v92, v93
	v_fma_f32 v78, -v95, v96, 1.0
	v_fmac_f32_e32 v96, v78, v96
	v_div_scale_f32 v78, vcc, v94, v69, v94
	v_mul_f32_e32 v97, v78, v96
	v_fma_f32 v98, -v95, v97, v78
	v_fmac_f32_e32 v97, v98, v96
	v_div_scale_f32 v95, s[8:9], v68, v68, v74
	v_rcp_f32_e32 v98, v95
	v_rcp_f32_e32 v78, v69
	s_nop 0
	v_mul_f32_e32 v69, v94, v78
	v_add_f32_e32 v82, v83, v82
	v_fma_f32 v78, -v95, v98, 1.0
	v_fmac_f32_e32 v98, v78, v98
	v_rcp_f32_e32 v78, v68
	s_nop 0
	v_mul_f32_e32 v68, v74, v78
	v_and_b32_e32 v74, 0xffff0000, v75
	v_pk_add_f32 v[68:69], v[68:69], v[84:85]
	v_div_scale_f32 v84, s[8:9], v71, v71, v74
	v_rcp_f32_e32 v85, v84
	v_lshlrev_b32_e32 v75, 16, v75
	v_lshlrev_b32_e32 v78, 16, v79
	v_and_b32_e32 v79, 0xffff0000, v79
	v_fma_f32 v94, -v84, v85, 1.0
	v_fmac_f32_e32 v85, v94, v85
	v_div_scale_f32 v94, vcc, v74, v71, v74
	v_mul_f32_e32 v95, v94, v85
	v_fma_f32 v96, -v84, v95, v94
	v_fmac_f32_e32 v95, v96, v85
	v_div_scale_f32 v94, s[8:9], v70, v70, v75
	v_rcp_f32_e32 v96, v94
	v_rcp_f32_e32 v84, v71
	s_nop 0
	v_mul_f32_e32 v71, v74, v84
	v_add_f32_e32 v83, v90, v91
	v_fma_f32 v74, -v94, v96, 1.0
	v_fmac_f32_e32 v96, v74, v96
	v_rcp_f32_e32 v74, v70
	s_nop 0
	v_mul_f32_e32 v70, v75, v74
	v_pk_add_f32 v[70:71], v[70:71], v[78:79]
	v_and_b32_e32 v78, 0xffff0000, v76
	v_div_scale_f32 v79, s[8:9], v65, v65, v78
	v_rcp_f32_e32 v84, v79
	v_lshlrev_b32_e32 v74, 16, v80
	v_and_b32_e32 v75, 0xffff0000, v80
	v_lshlrev_b32_e32 v76, 16, v76
	v_fma_f32 v80, -v79, v84, 1.0
	v_fmac_f32_e32 v84, v80, v84
	v_div_scale_f32 v80, vcc, v78, v65, v78
	v_mul_f32_e32 v85, v80, v84
	v_fma_f32 v94, -v79, v85, v80
	v_fmac_f32_e32 v85, v94, v84
	v_div_scale_f32 v80, s[8:9], v64, v64, v76
	v_rcp_f32_e32 v94, v80
	v_rcp_f32_e32 v79, v65
	s_nop 0
	v_mul_f32_e32 v65, v78, v79
	v_fma_f32 v78, -v80, v94, 1.0
	v_fmac_f32_e32 v94, v78, v94
	v_rcp_f32_e32 v78, v64
	s_nop 0
	v_mul_f32_e32 v64, v76, v78
	v_pk_add_f32 v[74:75], v[64:65], v[74:75]
	v_and_b32_e32 v76, 0xffff0000, v77
	v_pk_add_f32 v[64:65], v[66:67], 1.0 op_sel_hi:[1,0]
	v_lshlrev_b32_e32 v66, 16, v81
	v_and_b32_e32 v67, 0xffff0000, v81
	v_lshlrev_b32_e32 v77, 16, v77
	v_div_scale_f32 v80, s[8:9], v64, v64, v77
	v_rcp_f32_e32 v78, v65
	s_nop 0
	v_mul_f32_e32 v65, v76, v78
	v_div_scale_f32 v76, vcc, v77, v64, v77
	v_rcp_f32_e32 v76, v64
	s_nop 0
	v_mul_f32_e32 v64, v77, v76
	v_pk_add_f32 v[76:77], v[64:65], v[66:67]
	v_pk_mul_f32 v[64:65], v[68:69], v[68:69]
	v_pk_mul_f32 v[66:67], v[70:71], v[70:71]
	v_pk_mul_f32 v[78:79], v[74:75], v[74:75]
	v_pk_mul_f32 v[80:81], v[76:77], v[76:77]
	v_add_f32_e32 v84, v86, v87
	v_add_f32_e32 v80, v80, v81
	v_add_f32_e32 v78, v78, v79
	v_add_f32_e32 v66, v66, v67
	v_add_f32_e32 v64, v64, v65
	v_add_f32_e32 v83, v84, v83
	v_add_f32_e32 v78, v78, v80
	v_add_f32_e32 v64, v64, v66
	v_add_f32_e32 v82, v83, v82
	v_add_f32_e32 v64, v64, v78
	v_add_f32_e32 v64, v82, v64
	ds_bpermute_b32 v65, v124, v64
	v_cvt_pk_bf16_f32 v66, v68, v69
	v_cvt_pk_bf16_f32 v67, v70, v71
	v_cvt_pk_bf16_f32 v68, v74, v75
	v_cvt_pk_bf16_f32 v69, v76, v77
	s_waitcnt lgkmcnt(0)
	v_add_f32_e32 v64, v64, v65
	ds_bpermute_b32 v65, v125, v64
	global_store_dwordx4 v[72:73], v[66:69], off offset:256
	s_and_saveexec_b64 s[8:9], s[4:5]
	s_cbranch_execz .LBB0_682
	v_lshlrev_b64 v[66:67], 4, v[88:89]
	s_waitcnt lgkmcnt(0)
	v_add_f32_e32 v68, v64, v65
	v_lshl_add_u64 v[64:65], v[66:67], 2, s[18:19]
	v_lshl_add_u64 v[64:65], s[48:49], 2, v[64:65]
	s_lshl_b32 s34, s59, 2
	v_lshl_add_u64 v[64:65], v[64:65], 0, s[34:35]
	global_store_dword v[64:65], v68, off
.LBB0_682:
	s_or_b64 exec, exec, s[8:9]
	v_add_u32_e32 v72, 0x80, v154
	v_ashrrev_i32_e32 v73, 31, v72
	s_waitcnt lgkmcnt(0)
	v_lshlrev_b64 v[64:65], 6, v[72:73]
	v_lshl_add_u64 v[64:65], s[26:27], 0, v[64:65]
	global_load_dwordx4 v[76:79], v[64:65], off
	global_load_dwordx4 v[80:83], v[64:65], off offset:16
	global_load_dwordx4 v[84:87], v[64:65], off offset:32
	global_load_dwordx4 v[88:91], v[64:65], off offset:48
	v_lshlrev_b64 v[64:65], 10, v[72:73]
	v_lshl_add_u64 v[64:65], v[64:65], 0, v[152:153]
	v_lshlrev_b64 v[74:75], 1, v[64:65]
	v_lshl_add_u64 v[64:65], s[20:21], 0, v[74:75]
	global_load_dwordx4 v[64:67], v[64:65], off
	v_lshl_add_u64 v[68:69], s[24:25], 0, v[74:75]
	global_load_dwordx4 v[68:71], v[68:69], off
	s_waitcnt vmcnt(4)
	v_pk_add_f32 v[78:79], v[78:79], v[82:83]
	v_pk_add_f32 v[76:77], v[76:77], v[80:81]
	s_waitcnt vmcnt(2)
	v_pk_add_f32 v[80:81], v[86:87], v[90:91]
	v_pk_add_f32 v[82:83], v[84:85], v[88:89]
	v_pk_add_f32 v[78:79], v[78:79], v[80:81]
	v_pk_add_f32 v[76:77], v[76:77], v[82:83]
	s_waitcnt vmcnt(0)
; DI unsigned pk_bf16(float lo, float hi) { typedef float f2 __attribute__((ext_vector_type(2))); typedef __bf16 b2 __attribute__((ext_vector_type(2))); f2 v = {lo, hi}; b2 b = __builtin_convertvector(v, b2); return __builtin_bit_cast(unsigned, b); }
; DI float bf_lo(unsigned w) { return __uint_as_float(w << 16); }
; DI float bf_hi(unsigned w) { return __uint_as_float(w & 0xffff0000u); }
;     DI void operator()(const f32x4 (&acc)[2][2][4][2], const pg8::Unit& u, int wr, int wc, int fr, int fq) const {
;     ...
;                 const int row = row0 + ai * 128 + m * 16;
;                 const size_t off = (size_t)row * ldc + col0;
;                 const f32x4* pq = (const f32x4*)(partin + (size_t)row * 16); const f32x4 t4 = (pq[0] + pq[1]) + (pq[2] + pq[3]);
;                 const float rs = -1.0f / sqrtf(((t4.x + t4.y) + (t4.z + t4.w)) * (1.f / DM) + NORM_EPS);
;                 float ss = 0.f;
; #pragma unroll
;                 for (int bj = 0; bj < 2; ++bj) {
;                     const size_t o2 = off + bj * 128;
;                     const u32x4 pw = *(const u32x4*)(pp + o2), bw = *(const u32x4*)(base + o2);
;                     const f32x4 a0 = acc[ai][bj][m][0] * rs, a1 = acc[ai][bj][m][1] * rs;
;                     f32x4 r0, r1;
;                     r0[0] = bf_lo(bw.x) + bf_lo(pw.x) / (1.f + __expf(a0[0])); r0[1] = bf_hi(bw.x) + bf_hi(pw.x) / (1.f + __expf(a0[1]));
;                     r0[2] = bf_lo(bw.y) + bf_lo(pw.y) / (1.f + __expf(a0[2])); r0[3] = bf_hi(bw.y) + bf_hi(pw.y) / (1.f + __expf(a0[3]));
;                     r1[0] = bf_lo(bw.z) + bf_lo(pw.z) / (1.f + __expf(a1[0])); r1[1] = bf_hi(bw.z) + bf_hi(pw.z) / (1.f + __expf(a1[1]));
;                     r1[2] = bf_lo(bw.w) + bf_lo(pw.w) / (1.f + __expf(a1[2])); r1[3] = bf_hi(bw.w) + bf_hi(pw.w) / (1.f + __expf(a1[3]));
;                     u32x4 w; w.x = pk_bf16(r0[0], r0[1]); w.y = pk_bf16(r0[2], r0[3]); w.z = pk_bf16(r1[0], r1[1]); w.w = pk_bf16(r1[2], r1[3]);
;                     *(u32x4*)(hb + o2) = w;
	v_lshlrev_b32_e32 v82, 16, v68
	v_pk_mov_b32 v[80:81], v[76:77], v[78:79] op_sel:[1,0]
	v_mov_b32_e32 v77, v79
	v_pk_add_f32 v[76:77], v[80:81], v[76:77]
	v_lshlrev_b32_e32 v78, 16, v64
	v_and_b32_e32 v79, 0xffff0000, v64
	v_add_f32_e32 v64, v76, v77
	v_fmamk_f32 v64, v64, 0x3a800000, v178
	v_and_b32_e32 v83, 0xffff0000, v68
	v_mul_f32_e32 v68, 0x4f800000, v64
	v_cmp_gt_f32_e32 vcc, s70, v64
	v_lshlrev_b32_e32 v80, 16, v69
	v_and_b32_e32 v69, 0xffff0000, v69
	v_cndmask_b32_e32 v68, v64, v68, vcc
	v_sqrt_f32_e32 v76, v68
	v_lshlrev_b32_e32 v64, 16, v65
	v_and_b32_e32 v65, 0xffff0000, v65
	s_nop 1
	v_mul_f32_e32 v77, 0x37800000, v76
	v_cndmask_b32_e32 v76, v76, v77, vcc
	v_cmp_class_f32_e32 vcc, v68, v179
	s_nop 1
	v_cndmask_b32_e32 v68, v76, v68, vcc
	v_rcp_f32_e32 v76, v68
	s_nop 0
	v_mul_f32_e32 v68, -1.0, v76
	v_pk_mul_f32 v[60:61], v[60:61], v[68:69] op_sel_hi:[1,0]
	v_pk_mul_f32 v[56:57], v[56:57], v[68:69] op_sel_hi:[1,0]
	v_mul_f32_e32 v60, 0x3fb8aa3b, v60
	v_mul_f32_e32 v61, 0x3fb8aa3b, v61
	v_pk_mul_f32 v[62:63], v[62:63], v[68:69] op_sel_hi:[1,0]
	v_mul_f32_e32 v76, 0x3fb8aa3b, v56
	v_mul_f32_e32 v77, 0x3fb8aa3b, v57
	v_exp_f32_e32 v56, v60
	v_exp_f32_e32 v57, v61
	v_mul_f32_e32 v62, 0x3fb8aa3b, v62
	v_mul_f32_e32 v63, 0x3fb8aa3b, v63
	v_exp_f32_e32 v60, v62
	v_exp_f32_e32 v61, v63
	v_pk_add_f32 v[56:57], v[56:57], 1.0 op_sel_hi:[1,0]
	v_exp_f32_e32 v62, v76
	v_div_scale_f32 v76, s[8:9], v57, v57, v83
	v_pk_add_f32 v[60:61], v[60:61], 1.0 op_sel_hi:[1,0]
	v_div_scale_f32 v81, s[8:9], v56, v56, v82
	v_rcp_f32_e32 v89, v76
	v_div_scale_f32 v85, s[10:11], v61, v61, v69
	v_rcp_f32_e32 v90, v81
	v_div_scale_f32 v87, s[12:13], v60, v60, v80
	v_rcp_f32_e32 v91, v85
	v_rcp_f32_e32 v92, v87
	v_fma_f32 v93, -v76, v89, 1.0
	v_exp_f32_e32 v63, v77
	v_div_scale_f32 v77, vcc, v83, v57, v83
	v_fma_f32 v94, -v81, v90, 1.0
	v_fmac_f32_e32 v89, v93, v89
	v_div_scale_f32 v84, s[8:9], v82, v56, v82
	v_fma_f32 v95, -v85, v91, 1.0
	v_fmac_f32_e32 v90, v94, v90
	v_mul_f32_e32 v93, v77, v89
	v_div_scale_f32 v86, s[10:11], v69, v61, v69
	v_fma_f32 v96, -v87, v92, 1.0
	v_fmac_f32_e32 v91, v95, v91
	v_mul_f32_e32 v94, v84, v90
	v_fma_f32 v97, -v76, v93, v77
	v_div_scale_f32 v88, s[12:13], v80, v60, v80
	v_fmac_f32_e32 v92, v96, v92
	v_mul_f32_e32 v95, v86, v91
	v_fma_f32 v98, -v81, v94, v84
	v_fmac_f32_e32 v93, v97, v89
	v_mul_f32_e32 v96, v88, v92
	v_fma_f32 v99, -v85, v95, v86
	v_fmac_f32_e32 v94, v98, v90
	v_fma_f32 v100, -v87, v96, v88
	v_fmac_f32_e32 v95, v99, v91
	v_fmac_f32_e32 v96, v100, v92
	v_rcp_f32_e32 v76, v57
	s_nop 0
	v_mul_f32_e32 v57, v83, v76
	v_fma_f32 v84, -v87, v96, v88
	v_rcp_f32_e32 v76, v56
	s_nop 0
	v_mul_f32_e32 v56, v82, v76
	v_pk_add_f32 v[76:77], v[56:57], v[78:79]
	v_rcp_f32_e32 v81, v61
	s_nop 0
	v_mul_f32_e32 v57, v69, v81
	v_rcp_f32_e32 v56, v60
	s_nop 0
	v_mul_f32_e32 v56, v80, v56
	v_pk_add_f32 v[78:79], v[56:57], v[64:65]
	v_and_b32_e32 v64, 0xffff0000, v70
	v_pk_add_f32 v[56:57], v[62:63], 1.0 op_sel_hi:[1,0]
	v_lshlrev_b32_e32 v60, 16, v66
	v_div_scale_f32 v62, s[8:9], v57, v57, v64
	v_rcp_f32_e32 v63, v62
	v_and_b32_e32 v61, 0xffff0000, v66
	v_pk_mul_f32 v[58:59], v[58:59], v[68:69] op_sel_hi:[1,0]
	v_lshlrev_b32_e32 v65, 16, v70
	v_fma_f32 v66, -v62, v63, 1.0
	v_fmac_f32_e32 v63, v66, v63
	v_div_scale_f32 v66, vcc, v64, v57, v64
	v_mul_f32_e32 v69, v66, v63
	v_fma_f32 v70, -v62, v69, v66
	v_fmac_f32_e32 v69, v70, v63
	v_rcp_f32_e32 v62, v57
	s_nop 0
	v_mul_f32_e32 v57, v64, v62
	v_mul_f32_e32 v58, 0x3fb8aa3b, v58
	v_mul_f32_e32 v59, 0x3fb8aa3b, v59
	v_exp_f32_e32 v58, v58
	v_exp_f32_e32 v59, v59
	v_rcp_f32_e32 v62, v56
	s_nop 0
	v_mul_f32_e32 v56, v65, v62
	v_pk_add_f32 v[80:81], v[56:57], v[60:61]
	v_and_b32_e32 v60, 0xffff0000, v71
	v_pk_add_f32 v[56:57], v[58:59], 1.0 op_sel_hi:[1,0]
	v_lshlrev_b32_e32 v63, 16, v71
	v_div_scale_f32 v61, s[8:9], v57, v57, v60
	v_rcp_f32_e32 v62, v61
	v_lshlrev_b32_e32 v58, 16, v67
	v_and_b32_e32 v59, 0xffff0000, v67
	v_pk_mul_f32 v[52:53], v[52:53], v[68:69] op_sel_hi:[1,0]
	v_fma_f32 v64, -v61, v62, 1.0
	v_fmac_f32_e32 v62, v64, v62
	v_div_scale_f32 v64, vcc, v60, v57, v60
	v_mul_f32_e32 v65, v64, v62
	v_fma_f32 v66, -v61, v65, v64
	v_fmac_f32_e32 v65, v66, v62
	v_div_scale_f32 v64, s[8:9], v56, v56, v63
	v_rcp_f32_e32 v61, v57
	s_nop 0
	v_mul_f32_e32 v57, v60, v61
	v_mul_f32_e32 v52, 0x3fb8aa3b, v52
	v_div_scale_f32 v60, vcc, v63, v56, v63
	v_rcp_f32_e32 v60, v56
	s_nop 0
	v_mul_f32_e32 v56, v63, v60
	v_pk_add_f32 v[66:67], v[56:57], v[58:59]
	v_cvt_pk_bf16_f32 v58, v76, v77
	v_cvt_pk_bf16_f32 v59, v78, v79
	v_cvt_pk_bf16_f32 v60, v80, v81
	v_cvt_pk_bf16_f32 v61, v66, v67
	v_lshl_add_u64 v[56:57], s[16:17], 0, v[74:75]
	v_or_b32_e32 v74, 0x100, v74
	global_store_dwordx4 v[56:57], v[58:61], off
	v_lshl_add_u64 v[62:63], s[20:21], 0, v[74:75]
	global_load_dwordx4 v[62:65], v[62:63], off
	v_lshl_add_u64 v[58:59], s[24:25], 0, v[74:75]
	global_load_dwordx4 v[58:61], v[58:59], off
	v_mul_f32_e32 v53, 0x3fb8aa3b, v53
	v_exp_f32_e32 v52, v52
	v_exp_f32_e32 v53, v53
	v_pk_mul_f32 v[74:75], v[78:79], v[78:79]
	v_pk_mul_f32 v[70:71], v[76:77], v[76:77]
	v_pk_mul_f32 v[76:77], v[80:81], v[80:81]
	v_pk_add_f32 v[52:53], v[52:53], 1.0 op_sel_hi:[1,0]
	v_pk_mul_f32 v[54:55], v[54:55], v[68:69] op_sel_hi:[1,0]
	v_pk_mul_f32 v[50:51], v[50:51], v[68:69] op_sel_hi:[1,0]
	v_pk_mul_f32 v[48:49], v[48:49], v[68:69] op_sel_hi:[1,0]
	v_mul_f32_e32 v54, 0x3fb8aa3b, v54
	v_mul_f32_e32 v55, 0x3fb8aa3b, v55
	v_exp_f32_e32 v54, v54
	v_exp_f32_e32 v55, v55
	v_mul_f32_e32 v48, 0x3fb8aa3b, v48
	v_mul_f32_e32 v49, 0x3fb8aa3b, v49
	v_exp_f32_e32 v48, v48
	v_pk_add_f32 v[54:55], v[54:55], 1.0 op_sel_hi:[1,0]
	v_exp_f32_e32 v49, v49
	v_mul_f32_e32 v50, 0x3fb8aa3b, v50
	v_mul_f32_e32 v51, 0x3fb8aa3b, v51
	v_exp_f32_e32 v50, v50
	v_pk_add_f32 v[48:49], v[48:49], 1.0 op_sel_hi:[1,0]
	v_exp_f32_e32 v51, v51
	v_pk_mul_f32 v[66:67], v[66:67], v[66:67]
	s_waitcnt vmcnt(1)
; DI unsigned pk_bf16(float lo, float hi) { typedef float f2 __attribute__((ext_vector_type(2))); typedef __bf16 b2 __attribute__((ext_vector_type(2))); f2 v = {lo, hi}; b2 b = __builtin_convertvector(v, b2); return __builtin_bit_cast(unsigned, b); }
; DI float bf_lo(unsigned w) { return __uint_as_float(w << 16); }
; DI float bf_hi(unsigned w) { return __uint_as_float(w & 0xffff0000u); }
;     DI void operator()(const f32x4 (&acc)[2][2][4][2], const pg8::Unit& u, int wr, int wc, int fr, int fq) const {
;     ...
;                 const int row = row0 + ai * 128 + m * 16;
;                 const size_t off = (size_t)row * ldc + col0;
;                 const f32x4* pq = (const f32x4*)(partin + (size_t)row * 16); const f32x4 t4 = (pq[0] + pq[1]) + (pq[2] + pq[3]);
;     ...
;                     const u32x4 pw = *(const u32x4*)(pp + o2), bw = *(const u32x4*)(base + o2);
;                     const f32x4 a0 = acc[ai][bj][m][0] * rs, a1 = acc[ai][bj][m][1] * rs;
;                     f32x4 r0, r1;
;                     r0[0] = bf_lo(bw.x) + bf_lo(pw.x) / (1.f + __expf(a0[0])); r0[1] = bf_hi(bw.x) + bf_hi(pw.x) / (1.f + __expf(a0[1]));
;                     r0[2] = bf_lo(bw.y) + bf_lo(pw.y) / (1.f + __expf(a0[2])); r0[3] = bf_hi(bw.y) + bf_hi(pw.y) / (1.f + __expf(a0[3]));
;                     r1[0] = bf_lo(bw.z) + bf_lo(pw.z) / (1.f + __expf(a1[0])); r1[1] = bf_hi(bw.z) + bf_hi(pw.z) / (1.f + __expf(a1[1]));
;                     r1[2] = bf_lo(bw.w) + bf_lo(pw.w) / (1.f + __expf(a1[2])); r1[3] = bf_hi(bw.w) + bf_hi(pw.w) / (1.f + __expf(a1[3]));
;                     u32x4 w; w.x = pk_bf16(r0[0], r0[1]); w.y = pk_bf16(r0[2], r0[3]); w.z = pk_bf16(r1[0], r1[1]); w.w = pk_bf16(r1[2], r1[3]);
;                     *(u32x4*)(hb + o2) = w;
;                     ss += ((r0[0] * r0[0] + r0[1] * r0[1]) + (r0[2] * r0[2] + r0[3] * r0[3])) + ((r1[0] * r1[0] + r1[1] * r1[1]) + (r1[2] * r1[2] + r1[3] * r1[3]));
;                 }
;                 ss += __shfl_xor(ss, 16); ss += __shfl_xor(ss, 32);
;                 if (fq == 0) part[(size_t)row * 16 + u.pn * 4 + wc] = ss;
	v_lshlrev_b32_e32 v68, 16, v62
	v_and_b32_e32 v69, 0xffff0000, v62
	s_waitcnt vmcnt(0)
	v_and_b32_e32 v78, 0xffff0000, v58
	v_div_scale_f32 v79, s[8:9], v53, v53, v78
	v_rcp_f32_e32 v80, v79
	v_lshlrev_b32_e32 v58, 16, v58
	v_add_f32_e32 v66, v66, v67
	v_add_f32_e32 v67, v76, v77
	v_fma_f32 v62, -v79, v80, 1.0
	v_fmac_f32_e32 v80, v62, v80
	v_div_scale_f32 v62, vcc, v78, v53, v78
	v_mul_f32_e32 v81, v62, v80
	v_fma_f32 v82, -v79, v81, v62
	v_fmac_f32_e32 v81, v82, v80
	v_div_scale_f32 v79, s[8:9], v52, v52, v58
	v_rcp_f32_e32 v82, v79
	v_rcp_f32_e32 v62, v53
	s_nop 0
	v_mul_f32_e32 v53, v78, v62
	v_add_f32_e32 v66, v67, v66
	v_fma_f32 v62, -v79, v82, 1.0
	v_fmac_f32_e32 v82, v62, v82
	v_rcp_f32_e32 v62, v52
	s_nop 0
	v_mul_f32_e32 v52, v58, v62
	v_and_b32_e32 v58, 0xffff0000, v59
	v_pk_add_f32 v[52:53], v[52:53], v[68:69]
	v_div_scale_f32 v68, s[8:9], v55, v55, v58
	v_rcp_f32_e32 v69, v68
	v_lshlrev_b32_e32 v59, 16, v59
	v_lshlrev_b32_e32 v62, 16, v63
	v_and_b32_e32 v63, 0xffff0000, v63
	v_fma_f32 v78, -v68, v69, 1.0
	v_fmac_f32_e32 v69, v78, v69
	v_div_scale_f32 v78, vcc, v58, v55, v58
	v_mul_f32_e32 v79, v78, v69
	v_fma_f32 v80, -v68, v79, v78
	v_fmac_f32_e32 v79, v80, v69
	v_div_scale_f32 v78, s[8:9], v54, v54, v59
	v_rcp_f32_e32 v80, v78
	v_rcp_f32_e32 v68, v55
	s_nop 0
	v_mul_f32_e32 v55, v58, v68
	v_add_f32_e32 v67, v74, v75
	v_fma_f32 v58, -v78, v80, 1.0
	v_fmac_f32_e32 v80, v58, v80
	v_rcp_f32_e32 v58, v54
	s_nop 0
	v_mul_f32_e32 v54, v59, v58
	v_pk_add_f32 v[54:55], v[54:55], v[62:63]
	v_and_b32_e32 v62, 0xffff0000, v60
	v_div_scale_f32 v63, s[8:9], v49, v49, v62
	v_rcp_f32_e32 v68, v63
	v_lshlrev_b32_e32 v58, 16, v64
	v_and_b32_e32 v59, 0xffff0000, v64
	v_lshlrev_b32_e32 v60, 16, v60
	v_fma_f32 v64, -v63, v68, 1.0
	v_fmac_f32_e32 v68, v64, v68
	v_div_scale_f32 v64, vcc, v62, v49, v62
	v_mul_f32_e32 v69, v64, v68
	v_fma_f32 v78, -v63, v69, v64
	v_fmac_f32_e32 v69, v78, v68
	v_div_scale_f32 v64, s[8:9], v48, v48, v60
	v_rcp_f32_e32 v78, v64
	v_rcp_f32_e32 v63, v49
	s_nop 0
	v_mul_f32_e32 v49, v62, v63
	v_fma_f32 v62, -v64, v78, 1.0
	v_fmac_f32_e32 v78, v62, v78
	v_rcp_f32_e32 v62, v48
	s_nop 0
	v_mul_f32_e32 v48, v60, v62
	v_pk_add_f32 v[58:59], v[48:49], v[58:59]
	v_and_b32_e32 v60, 0xffff0000, v61
	v_pk_add_f32 v[48:49], v[50:51], 1.0 op_sel_hi:[1,0]
	v_lshlrev_b32_e32 v50, 16, v65
	v_and_b32_e32 v51, 0xffff0000, v65
	v_lshlrev_b32_e32 v61, 16, v61
	v_div_scale_f32 v64, s[8:9], v48, v48, v61
	v_rcp_f32_e32 v62, v49
	s_nop 0
	v_mul_f32_e32 v49, v60, v62
	v_div_scale_f32 v60, vcc, v61, v48, v61
	v_rcp_f32_e32 v60, v48
	s_nop 0
	v_mul_f32_e32 v48, v61, v60
	v_pk_add_f32 v[60:61], v[48:49], v[50:51]
	v_pk_mul_f32 v[48:49], v[52:53], v[52:53]
	v_pk_mul_f32 v[50:51], v[54:55], v[54:55]
	v_pk_mul_f32 v[62:63], v[58:59], v[58:59]
	v_pk_mul_f32 v[64:65], v[60:61], v[60:61]
	v_add_f32_e32 v68, v70, v71
	v_add_f32_e32 v64, v64, v65
	v_add_f32_e32 v62, v62, v63
	v_add_f32_e32 v50, v50, v51
	v_add_f32_e32 v48, v48, v49
	v_add_f32_e32 v67, v68, v67
	v_add_f32_e32 v62, v62, v64
	v_add_f32_e32 v48, v48, v50
	v_add_f32_e32 v66, v67, v66
	v_add_f32_e32 v48, v48, v62
	v_add_f32_e32 v48, v66, v48
	ds_bpermute_b32 v49, v124, v48
	v_cvt_pk_bf16_f32 v50, v52, v53
	v_cvt_pk_bf16_f32 v51, v54, v55
	v_cvt_pk_bf16_f32 v52, v58, v59
	v_cvt_pk_bf16_f32 v53, v60, v61
	s_waitcnt lgkmcnt(0)
	v_add_f32_e32 v48, v48, v49
	ds_bpermute_b32 v49, v125, v48
	global_store_dwordx4 v[56:57], v[50:53], off offset:256
	s_and_saveexec_b64 s[8:9], s[4:5]
	s_cbranch_execz .LBB0_684
	v_lshlrev_b64 v[50:51], 4, v[72:73]
	s_waitcnt lgkmcnt(0)
	v_add_f32_e32 v52, v48, v49
	v_lshl_add_u64 v[48:49], v[50:51], 2, s[18:19]
	v_lshl_add_u64 v[48:49], s[48:49], 2, v[48:49]
	s_lshl_b32 s34, s59, 2
	v_lshl_add_u64 v[48:49], v[48:49], 0, s[34:35]
	global_store_dword v[48:49], v52, off
.LBB0_684:
	s_or_b64 exec, exec, s[8:9]
	v_add_u32_e32 v56, 0x90, v154
	v_ashrrev_i32_e32 v57, 31, v56
	s_waitcnt lgkmcnt(0)
	v_lshlrev_b64 v[48:49], 6, v[56:57]
	v_lshl_add_u64 v[48:49], s[26:27], 0, v[48:49]
	global_load_dwordx4 v[60:63], v[48:49], off
	global_load_dwordx4 v[64:67], v[48:49], off offset:16
	global_load_dwordx4 v[68:71], v[48:49], off offset:32
	global_load_dwordx4 v[72:75], v[48:49], off offset:48
	v_lshlrev_b64 v[48:49], 10, v[56:57]
	v_lshl_add_u64 v[48:49], v[48:49], 0, v[152:153]
	v_lshlrev_b64 v[58:59], 1, v[48:49]
	v_lshl_add_u64 v[48:49], s[20:21], 0, v[58:59]
	global_load_dwordx4 v[48:51], v[48:49], off
	v_lshl_add_u64 v[52:53], s[24:25], 0, v[58:59]
	global_load_dwordx4 v[52:55], v[52:53], off
	s_waitcnt vmcnt(4)
	v_pk_add_f32 v[62:63], v[62:63], v[66:67]
	v_pk_add_f32 v[60:61], v[60:61], v[64:65]
	s_waitcnt vmcnt(2)
	v_pk_add_f32 v[64:65], v[70:71], v[74:75]
	v_pk_add_f32 v[66:67], v[68:69], v[72:73]
	v_pk_add_f32 v[62:63], v[62:63], v[64:65]
	v_pk_add_f32 v[60:61], v[60:61], v[66:67]
	s_waitcnt vmcnt(0)
; DI unsigned pk_bf16(float lo, float hi) { typedef float f2 __attribute__((ext_vector_type(2))); typedef __bf16 b2 __attribute__((ext_vector_type(2))); f2 v = {lo, hi}; b2 b = __builtin_convertvector(v, b2); return __builtin_bit_cast(unsigned, b); }
; DI float bf_lo(unsigned w) { return __uint_as_float(w << 16); }
; DI float bf_hi(unsigned w) { return __uint_as_float(w & 0xffff0000u); }
;     DI void operator()(const f32x4 (&acc)[2][2][4][2], const pg8::Unit& u, int wr, int wc, int fr, int fq) const {
;     ...
;                 const int row = row0 + ai * 128 + m * 16;
;                 const size_t off = (size_t)row * ldc + col0;
;                 const f32x4* pq = (const f32x4*)(partin + (size_t)row * 16); const f32x4 t4 = (pq[0] + pq[1]) + (pq[2] + pq[3]);
;                 const float rs = -1.0f / sqrtf(((t4.x + t4.y) + (t4.z + t4.w)) * (1.f / DM) + NORM_EPS);
;                 float ss = 0.f;
; #pragma unroll
;                 for (int bj = 0; bj < 2; ++bj) {
;                     const size_t o2 = off + bj * 128;
;                     const u32x4 pw = *(const u32x4*)(pp + o2), bw = *(const u32x4*)(base + o2);
;                     const f32x4 a0 = acc[ai][bj][m][0] * rs, a1 = acc[ai][bj][m][1] * rs;
;                     f32x4 r0, r1;
;                     r0[0] = bf_lo(bw.x) + bf_lo(pw.x) / (1.f + __expf(a0[0])); r0[1] = bf_hi(bw.x) + bf_hi(pw.x) / (1.f + __expf(a0[1]));
;                     r0[2] = bf_lo(bw.y) + bf_lo(pw.y) / (1.f + __expf(a0[2])); r0[3] = bf_hi(bw.y) + bf_hi(pw.y) / (1.f + __expf(a0[3]));
;                     r1[0] = bf_lo(bw.z) + bf_lo(pw.z) / (1.f + __expf(a1[0])); r1[1] = bf_hi(bw.z) + bf_hi(pw.z) / (1.f + __expf(a1[1]));
;                     r1[2] = bf_lo(bw.w) + bf_lo(pw.w) / (1.f + __expf(a1[2])); r1[3] = bf_hi(bw.w) + bf_hi(pw.w) / (1.f + __expf(a1[3]));
;                     u32x4 w; w.x = pk_bf16(r0[0], r0[1]); w.y = pk_bf16(r0[2], r0[3]); w.z = pk_bf16(r1[0], r1[1]); w.w = pk_bf16(r1[2], r1[3]);
;                     *(u32x4*)(hb + o2) = w;
	v_lshlrev_b32_e32 v66, 16, v52
	v_pk_mov_b32 v[64:65], v[60:61], v[62:63] op_sel:[1,0]
	v_mov_b32_e32 v61, v63
	v_pk_add_f32 v[60:61], v[64:65], v[60:61]
	v_lshlrev_b32_e32 v62, 16, v48
	v_and_b32_e32 v63, 0xffff0000, v48
	v_add_f32_e32 v48, v60, v61
	v_fmamk_f32 v48, v48, 0x3a800000, v178
	v_and_b32_e32 v67, 0xffff0000, v52
	v_mul_f32_e32 v52, 0x4f800000, v48
	v_cmp_gt_f32_e32 vcc, s70, v48
	v_lshlrev_b32_e32 v64, 16, v53
	v_and_b32_e32 v53, 0xffff0000, v53
	v_cndmask_b32_e32 v52, v48, v52, vcc
	v_sqrt_f32_e32 v60, v52
	v_lshlrev_b32_e32 v48, 16, v49
	v_and_b32_e32 v49, 0xffff0000, v49
	s_nop 1
	v_mul_f32_e32 v61, 0x37800000, v60
	v_cndmask_b32_e32 v60, v60, v61, vcc
	v_cmp_class_f32_e32 vcc, v52, v179
	s_nop 1
	v_cndmask_b32_e32 v52, v60, v52, vcc
	v_rcp_f32_e32 v60, v52
	s_nop 0
	v_mul_f32_e32 v52, -1.0, v60
	v_pk_mul_f32 v[44:45], v[44:45], v[52:53] op_sel_hi:[1,0]
	v_pk_mul_f32 v[40:41], v[40:41], v[52:53] op_sel_hi:[1,0]
	v_mul_f32_e32 v44, 0x3fb8aa3b, v44
	v_mul_f32_e32 v45, 0x3fb8aa3b, v45
	v_pk_mul_f32 v[46:47], v[46:47], v[52:53] op_sel_hi:[1,0]
	v_mul_f32_e32 v60, 0x3fb8aa3b, v40
	v_mul_f32_e32 v61, 0x3fb8aa3b, v41
	v_exp_f32_e32 v40, v44
	v_exp_f32_e32 v41, v45
	v_mul_f32_e32 v46, 0x3fb8aa3b, v46
	v_mul_f32_e32 v47, 0x3fb8aa3b, v47
	v_exp_f32_e32 v44, v46
	v_exp_f32_e32 v45, v47
	v_pk_add_f32 v[40:41], v[40:41], 1.0 op_sel_hi:[1,0]
	v_exp_f32_e32 v46, v60
	v_div_scale_f32 v60, s[8:9], v41, v41, v67
	v_pk_add_f32 v[44:45], v[44:45], 1.0 op_sel_hi:[1,0]
	v_div_scale_f32 v65, s[8:9], v40, v40, v66
	v_rcp_f32_e32 v73, v60
	v_div_scale_f32 v69, s[10:11], v45, v45, v53
	v_rcp_f32_e32 v74, v65
	v_div_scale_f32 v71, s[12:13], v44, v44, v64
	v_rcp_f32_e32 v75, v69
	v_rcp_f32_e32 v76, v71
	v_fma_f32 v77, -v60, v73, 1.0
	v_exp_f32_e32 v47, v61
	v_div_scale_f32 v61, vcc, v67, v41, v67
	v_fma_f32 v78, -v65, v74, 1.0
	v_fmac_f32_e32 v73, v77, v73
	v_div_scale_f32 v68, s[8:9], v66, v40, v66
	v_fma_f32 v79, -v69, v75, 1.0
	v_fmac_f32_e32 v74, v78, v74
	v_mul_f32_e32 v77, v61, v73
	v_div_scale_f32 v70, s[10:11], v53, v45, v53
	v_fma_f32 v80, -v71, v76, 1.0
	v_fmac_f32_e32 v75, v79, v75
	v_mul_f32_e32 v78, v68, v74
	v_fma_f32 v81, -v60, v77, v61
	v_div_scale_f32 v72, s[12:13], v64, v44, v64
	v_fmac_f32_e32 v76, v80, v76
	v_mul_f32_e32 v79, v70, v75
	v_fma_f32 v82, -v65, v78, v68
	v_fmac_f32_e32 v77, v81, v73
	v_mul_f32_e32 v80, v72, v76
	v_fma_f32 v83, -v69, v79, v70
	v_fmac_f32_e32 v78, v82, v74
	v_fma_f32 v84, -v71, v80, v72
	v_fmac_f32_e32 v79, v83, v75
	v_fmac_f32_e32 v80, v84, v76
	v_rcp_f32_e32 v60, v41
	s_nop 0
	v_mul_f32_e32 v41, v67, v60
	v_fma_f32 v68, -v71, v80, v72
	v_rcp_f32_e32 v60, v40
	s_nop 0
	v_mul_f32_e32 v40, v66, v60
	v_pk_add_f32 v[60:61], v[40:41], v[62:63]
	v_rcp_f32_e32 v65, v45
	s_nop 0
	v_mul_f32_e32 v41, v53, v65
	v_rcp_f32_e32 v40, v44
	s_nop 0
	v_mul_f32_e32 v40, v64, v40
	v_pk_add_f32 v[62:63], v[40:41], v[48:49]
	v_and_b32_e32 v48, 0xffff0000, v54
	v_pk_add_f32 v[40:41], v[46:47], 1.0 op_sel_hi:[1,0]
	v_lshlrev_b32_e32 v44, 16, v50
	v_div_scale_f32 v46, s[8:9], v41, v41, v48
	v_rcp_f32_e32 v47, v46
	v_and_b32_e32 v45, 0xffff0000, v50
	v_pk_mul_f32 v[42:43], v[42:43], v[52:53] op_sel_hi:[1,0]
	v_lshlrev_b32_e32 v49, 16, v54
	v_fma_f32 v50, -v46, v47, 1.0
	v_fmac_f32_e32 v47, v50, v47
	v_div_scale_f32 v50, vcc, v48, v41, v48
	v_mul_f32_e32 v53, v50, v47
	v_fma_f32 v54, -v46, v53, v50
	v_fmac_f32_e32 v53, v54, v47
	v_rcp_f32_e32 v46, v41
	s_nop 0
	v_mul_f32_e32 v41, v48, v46
	v_mul_f32_e32 v42, 0x3fb8aa3b, v42
	v_mul_f32_e32 v43, 0x3fb8aa3b, v43
	v_exp_f32_e32 v42, v42
	v_exp_f32_e32 v43, v43
	v_rcp_f32_e32 v46, v40
	s_nop 0
	v_mul_f32_e32 v40, v49, v46
	v_pk_add_f32 v[64:65], v[40:41], v[44:45]
	v_and_b32_e32 v44, 0xffff0000, v55
	v_pk_add_f32 v[40:41], v[42:43], 1.0 op_sel_hi:[1,0]
	v_lshlrev_b32_e32 v47, 16, v55
	v_div_scale_f32 v45, s[8:9], v41, v41, v44
	v_rcp_f32_e32 v46, v45
	v_lshlrev_b32_e32 v42, 16, v51
	v_and_b32_e32 v43, 0xffff0000, v51
	v_pk_mul_f32 v[36:37], v[36:37], v[52:53] op_sel_hi:[1,0]
	v_fma_f32 v48, -v45, v46, 1.0
	v_fmac_f32_e32 v46, v48, v46
	v_div_scale_f32 v48, vcc, v44, v41, v44
	v_mul_f32_e32 v49, v48, v46
	v_fma_f32 v50, -v45, v49, v48
	v_fmac_f32_e32 v49, v50, v46
	v_div_scale_f32 v48, s[8:9], v40, v40, v47
	v_rcp_f32_e32 v45, v41
	s_nop 0
	v_mul_f32_e32 v41, v44, v45
	v_mul_f32_e32 v36, 0x3fb8aa3b, v36
	v_div_scale_f32 v44, vcc, v47, v40, v47
	v_rcp_f32_e32 v44, v40
	s_nop 0
	v_mul_f32_e32 v40, v47, v44
	v_pk_add_f32 v[50:51], v[40:41], v[42:43]
	v_cvt_pk_bf16_f32 v42, v60, v61
	v_cvt_pk_bf16_f32 v43, v62, v63
	v_cvt_pk_bf16_f32 v44, v64, v65
	v_cvt_pk_bf16_f32 v45, v50, v51
	v_lshl_add_u64 v[40:41], s[16:17], 0, v[58:59]
	v_or_b32_e32 v58, 0x100, v58
	global_store_dwordx4 v[40:41], v[42:45], off
	v_lshl_add_u64 v[46:47], s[20:21], 0, v[58:59]
	global_load_dwordx4 v[46:49], v[46:47], off
	v_lshl_add_u64 v[42:43], s[24:25], 0, v[58:59]
	global_load_dwordx4 v[42:45], v[42:43], off
	v_mul_f32_e32 v37, 0x3fb8aa3b, v37
	v_exp_f32_e32 v36, v36
	v_exp_f32_e32 v37, v37
	v_pk_mul_f32 v[58:59], v[62:63], v[62:63]
	v_pk_mul_f32 v[54:55], v[60:61], v[60:61]
	v_pk_mul_f32 v[60:61], v[64:65], v[64:65]
	v_pk_add_f32 v[36:37], v[36:37], 1.0 op_sel_hi:[1,0]
	v_pk_mul_f32 v[38:39], v[38:39], v[52:53] op_sel_hi:[1,0]
	v_pk_mul_f32 v[34:35], v[34:35], v[52:53] op_sel_hi:[1,0]
	v_pk_mul_f32 v[32:33], v[32:33], v[52:53] op_sel_hi:[1,0]
	v_mul_f32_e32 v38, 0x3fb8aa3b, v38
	v_mul_f32_e32 v39, 0x3fb8aa3b, v39
	v_exp_f32_e32 v38, v38
	v_exp_f32_e32 v39, v39
	v_mul_f32_e32 v32, 0x3fb8aa3b, v32
	v_mul_f32_e32 v33, 0x3fb8aa3b, v33
	v_exp_f32_e32 v32, v32
	v_pk_add_f32 v[38:39], v[38:39], 1.0 op_sel_hi:[1,0]
	v_exp_f32_e32 v33, v33
	v_mul_f32_e32 v34, 0x3fb8aa3b, v34
	v_mul_f32_e32 v35, 0x3fb8aa3b, v35
	v_exp_f32_e32 v34, v34
	v_pk_add_f32 v[32:33], v[32:33], 1.0 op_sel_hi:[1,0]
	v_exp_f32_e32 v35, v35
	v_pk_mul_f32 v[50:51], v[50:51], v[50:51]
	s_waitcnt vmcnt(1)
; DI unsigned pk_bf16(float lo, float hi) { typedef float f2 __attribute__((ext_vector_type(2))); typedef __bf16 b2 __attribute__((ext_vector_type(2))); f2 v = {lo, hi}; b2 b = __builtin_convertvector(v, b2); return __builtin_bit_cast(unsigned, b); }
; DI float bf_lo(unsigned w) { return __uint_as_float(w << 16); }
; DI float bf_hi(unsigned w) { return __uint_as_float(w & 0xffff0000u); }
;     DI void operator()(const f32x4 (&acc)[2][2][4][2], const pg8::Unit& u, int wr, int wc, int fr, int fq) const {
;     ...
;                 const int row = row0 + ai * 128 + m * 16;
;                 const size_t off = (size_t)row * ldc + col0;
;                 const f32x4* pq = (const f32x4*)(partin + (size_t)row * 16); const f32x4 t4 = (pq[0] + pq[1]) + (pq[2] + pq[3]);
;     ...
;                     const u32x4 pw = *(const u32x4*)(pp + o2), bw = *(const u32x4*)(base + o2);
;                     const f32x4 a0 = acc[ai][bj][m][0] * rs, a1 = acc[ai][bj][m][1] * rs;
;                     f32x4 r0, r1;
;                     r0[0] = bf_lo(bw.x) + bf_lo(pw.x) / (1.f + __expf(a0[0])); r0[1] = bf_hi(bw.x) + bf_hi(pw.x) / (1.f + __expf(a0[1]));
;                     r0[2] = bf_lo(bw.y) + bf_lo(pw.y) / (1.f + __expf(a0[2])); r0[3] = bf_hi(bw.y) + bf_hi(pw.y) / (1.f + __expf(a0[3]));
;                     r1[0] = bf_lo(bw.z) + bf_lo(pw.z) / (1.f + __expf(a1[0])); r1[1] = bf_hi(bw.z) + bf_hi(pw.z) / (1.f + __expf(a1[1]));
;                     r1[2] = bf_lo(bw.w) + bf_lo(pw.w) / (1.f + __expf(a1[2])); r1[3] = bf_hi(bw.w) + bf_hi(pw.w) / (1.f + __expf(a1[3]));
;                     u32x4 w; w.x = pk_bf16(r0[0], r0[1]); w.y = pk_bf16(r0[2], r0[3]); w.z = pk_bf16(r1[0], r1[1]); w.w = pk_bf16(r1[2], r1[3]);
;                     *(u32x4*)(hb + o2) = w;
;                     ss += ((r0[0] * r0[0] + r0[1] * r0[1]) + (r0[2] * r0[2] + r0[3] * r0[3])) + ((r1[0] * r1[0] + r1[1] * r1[1]) + (r1[2] * r1[2] + r1[3] * r1[3]));
;                 }
;                 ss += __shfl_xor(ss, 16); ss += __shfl_xor(ss, 32);
;                 if (fq == 0) part[(size_t)row * 16 + u.pn * 4 + wc] = ss;
	v_lshlrev_b32_e32 v52, 16, v46
	v_and_b32_e32 v53, 0xffff0000, v46
	s_waitcnt vmcnt(0)
	v_and_b32_e32 v62, 0xffff0000, v42
	v_div_scale_f32 v63, s[8:9], v37, v37, v62
	v_rcp_f32_e32 v64, v63
	v_lshlrev_b32_e32 v42, 16, v42
	v_add_f32_e32 v50, v50, v51
	v_add_f32_e32 v51, v60, v61
	v_fma_f32 v46, -v63, v64, 1.0
	v_fmac_f32_e32 v64, v46, v64
	v_div_scale_f32 v46, vcc, v62, v37, v62
	v_mul_f32_e32 v65, v46, v64
	v_fma_f32 v66, -v63, v65, v46
	v_fmac_f32_e32 v65, v66, v64
	v_div_scale_f32 v63, s[8:9], v36, v36, v42
	v_rcp_f32_e32 v66, v63
	v_rcp_f32_e32 v46, v37
	s_nop 0
	v_mul_f32_e32 v37, v62, v46
	v_add_f32_e32 v50, v51, v50
	v_fma_f32 v46, -v63, v66, 1.0
	v_fmac_f32_e32 v66, v46, v66
	v_rcp_f32_e32 v46, v36
	s_nop 0
	v_mul_f32_e32 v36, v42, v46
	v_and_b32_e32 v42, 0xffff0000, v43
	v_pk_add_f32 v[36:37], v[36:37], v[52:53]
	v_div_scale_f32 v52, s[8:9], v39, v39, v42
	v_rcp_f32_e32 v53, v52
	v_lshlrev_b32_e32 v43, 16, v43
	v_lshlrev_b32_e32 v46, 16, v47
	v_and_b32_e32 v47, 0xffff0000, v47
	v_fma_f32 v62, -v52, v53, 1.0
	v_fmac_f32_e32 v53, v62, v53
	v_div_scale_f32 v62, vcc, v42, v39, v42
	v_mul_f32_e32 v63, v62, v53
	v_fma_f32 v64, -v52, v63, v62
	v_fmac_f32_e32 v63, v64, v53
	v_div_scale_f32 v62, s[8:9], v38, v38, v43
	v_rcp_f32_e32 v64, v62
	v_rcp_f32_e32 v52, v39
	s_nop 0
	v_mul_f32_e32 v39, v42, v52
	v_add_f32_e32 v51, v58, v59
	v_fma_f32 v42, -v62, v64, 1.0
	v_fmac_f32_e32 v64, v42, v64
	v_rcp_f32_e32 v42, v38
	s_nop 0
	v_mul_f32_e32 v38, v43, v42
	v_pk_add_f32 v[38:39], v[38:39], v[46:47]
	v_and_b32_e32 v46, 0xffff0000, v44
	v_div_scale_f32 v47, s[8:9], v33, v33, v46
	v_rcp_f32_e32 v52, v47
	v_lshlrev_b32_e32 v42, 16, v48
	v_and_b32_e32 v43, 0xffff0000, v48
	v_lshlrev_b32_e32 v44, 16, v44
	v_fma_f32 v48, -v47, v52, 1.0
	v_fmac_f32_e32 v52, v48, v52
	v_div_scale_f32 v48, vcc, v46, v33, v46
	v_mul_f32_e32 v53, v48, v52
	v_fma_f32 v62, -v47, v53, v48
	v_fmac_f32_e32 v53, v62, v52
	v_div_scale_f32 v48, s[8:9], v32, v32, v44
	v_rcp_f32_e32 v62, v48
	v_rcp_f32_e32 v47, v33
	s_nop 0
	v_mul_f32_e32 v33, v46, v47
	v_fma_f32 v46, -v48, v62, 1.0
	v_fmac_f32_e32 v62, v46, v62
	v_rcp_f32_e32 v46, v32
	s_nop 0
	v_mul_f32_e32 v32, v44, v46
	v_pk_add_f32 v[42:43], v[32:33], v[42:43]
	v_and_b32_e32 v44, 0xffff0000, v45
	v_pk_add_f32 v[32:33], v[34:35], 1.0 op_sel_hi:[1,0]
	v_lshlrev_b32_e32 v34, 16, v49
	v_and_b32_e32 v35, 0xffff0000, v49
	v_lshlrev_b32_e32 v45, 16, v45
	v_div_scale_f32 v48, s[8:9], v32, v32, v45
	v_rcp_f32_e32 v46, v33
	s_nop 0
	v_mul_f32_e32 v33, v44, v46
	v_div_scale_f32 v44, vcc, v45, v32, v45
	v_rcp_f32_e32 v44, v32
	s_nop 0
	v_mul_f32_e32 v32, v45, v44
	v_pk_add_f32 v[44:45], v[32:33], v[34:35]
	v_pk_mul_f32 v[32:33], v[36:37], v[36:37]
	v_pk_mul_f32 v[34:35], v[38:39], v[38:39]
	v_pk_mul_f32 v[46:47], v[42:43], v[42:43]
	v_pk_mul_f32 v[48:49], v[44:45], v[44:45]
	v_add_f32_e32 v52, v54, v55
	v_add_f32_e32 v48, v48, v49
	v_add_f32_e32 v46, v46, v47
	v_add_f32_e32 v34, v34, v35
	v_add_f32_e32 v32, v32, v33
	v_add_f32_e32 v51, v52, v51
	v_add_f32_e32 v46, v46, v48
	v_add_f32_e32 v32, v32, v34
	v_add_f32_e32 v50, v51, v50
	v_add_f32_e32 v32, v32, v46
	v_add_f32_e32 v32, v50, v32
	ds_bpermute_b32 v33, v124, v32
	v_cvt_pk_bf16_f32 v34, v36, v37
	v_cvt_pk_bf16_f32 v35, v38, v39
	v_cvt_pk_bf16_f32 v36, v42, v43
	v_cvt_pk_bf16_f32 v37, v44, v45
	s_waitcnt lgkmcnt(0)
	v_add_f32_e32 v32, v32, v33
	ds_bpermute_b32 v33, v125, v32
	global_store_dwordx4 v[40:41], v[34:37], off offset:256
	s_and_saveexec_b64 s[8:9], s[4:5]
	s_cbranch_execz .LBB0_686
	v_lshlrev_b64 v[34:35], 4, v[56:57]
	s_waitcnt lgkmcnt(0)
	v_add_f32_e32 v36, v32, v33
	v_lshl_add_u64 v[32:33], v[34:35], 2, s[18:19]
	v_lshl_add_u64 v[32:33], s[48:49], 2, v[32:33]
	s_lshl_b32 s34, s59, 2
	v_lshl_add_u64 v[32:33], v[32:33], 0, s[34:35]
	global_store_dword v[32:33], v36, off
.LBB0_686:
	s_or_b64 exec, exec, s[8:9]
	v_add_u32_e32 v40, 0xa0, v154
	v_ashrrev_i32_e32 v41, 31, v40
	s_waitcnt lgkmcnt(0)
	v_lshlrev_b64 v[32:33], 6, v[40:41]
	v_lshl_add_u64 v[32:33], s[26:27], 0, v[32:33]
	global_load_dwordx4 v[44:47], v[32:33], off
	global_load_dwordx4 v[48:51], v[32:33], off offset:16
	global_load_dwordx4 v[52:55], v[32:33], off offset:32
	global_load_dwordx4 v[56:59], v[32:33], off offset:48
	v_lshlrev_b64 v[32:33], 10, v[40:41]
	v_lshl_add_u64 v[32:33], v[32:33], 0, v[152:153]
	v_lshlrev_b64 v[42:43], 1, v[32:33]
	v_lshl_add_u64 v[32:33], s[20:21], 0, v[42:43]
	global_load_dwordx4 v[32:35], v[32:33], off
	v_lshl_add_u64 v[36:37], s[24:25], 0, v[42:43]
	global_load_dwordx4 v[36:39], v[36:37], off
	s_waitcnt vmcnt(4)
	v_pk_add_f32 v[46:47], v[46:47], v[50:51]
	v_pk_add_f32 v[44:45], v[44:45], v[48:49]
	s_waitcnt vmcnt(2)
	v_pk_add_f32 v[48:49], v[54:55], v[58:59]
	v_pk_add_f32 v[50:51], v[52:53], v[56:57]
	v_pk_add_f32 v[46:47], v[46:47], v[48:49]
	v_pk_add_f32 v[44:45], v[44:45], v[50:51]
	s_waitcnt vmcnt(0)
; DI unsigned pk_bf16(float lo, float hi) { typedef float f2 __attribute__((ext_vector_type(2))); typedef __bf16 b2 __attribute__((ext_vector_type(2))); f2 v = {lo, hi}; b2 b = __builtin_convertvector(v, b2); return __builtin_bit_cast(unsigned, b); }
; DI float bf_lo(unsigned w) { return __uint_as_float(w << 16); }
; DI float bf_hi(unsigned w) { return __uint_as_float(w & 0xffff0000u); }
;     DI void operator()(const f32x4 (&acc)[2][2][4][2], const pg8::Unit& u, int wr, int wc, int fr, int fq) const {
;     ...
;                 const int row = row0 + ai * 128 + m * 16;
;                 const size_t off = (size_t)row * ldc + col0;
;                 const f32x4* pq = (const f32x4*)(partin + (size_t)row * 16); const f32x4 t4 = (pq[0] + pq[1]) + (pq[2] + pq[3]);
;                 const float rs = -1.0f / sqrtf(((t4.x + t4.y) + (t4.z + t4.w)) * (1.f / DM) + NORM_EPS);
;                 float ss = 0.f;
; #pragma unroll
;                 for (int bj = 0; bj < 2; ++bj) {
;                     const size_t o2 = off + bj * 128;
;                     const u32x4 pw = *(const u32x4*)(pp + o2), bw = *(const u32x4*)(base + o2);
;                     const f32x4 a0 = acc[ai][bj][m][0] * rs, a1 = acc[ai][bj][m][1] * rs;
;                     f32x4 r0, r1;
;                     r0[0] = bf_lo(bw.x) + bf_lo(pw.x) / (1.f + __expf(a0[0])); r0[1] = bf_hi(bw.x) + bf_hi(pw.x) / (1.f + __expf(a0[1]));
;                     r0[2] = bf_lo(bw.y) + bf_lo(pw.y) / (1.f + __expf(a0[2])); r0[3] = bf_hi(bw.y) + bf_hi(pw.y) / (1.f + __expf(a0[3]));
;                     r1[0] = bf_lo(bw.z) + bf_lo(pw.z) / (1.f + __expf(a1[0])); r1[1] = bf_hi(bw.z) + bf_hi(pw.z) / (1.f + __expf(a1[1]));
;                     r1[2] = bf_lo(bw.w) + bf_lo(pw.w) / (1.f + __expf(a1[2])); r1[3] = bf_hi(bw.w) + bf_hi(pw.w) / (1.f + __expf(a1[3]));
;                     u32x4 w; w.x = pk_bf16(r0[0], r0[1]); w.y = pk_bf16(r0[2], r0[3]); w.z = pk_bf16(r1[0], r1[1]); w.w = pk_bf16(r1[2], r1[3]);
;                     *(u32x4*)(hb + o2) = w;
	v_lshlrev_b32_e32 v50, 16, v36
	v_pk_mov_b32 v[48:49], v[44:45], v[46:47] op_sel:[1,0]
	v_mov_b32_e32 v45, v47
	v_pk_add_f32 v[44:45], v[48:49], v[44:45]
	v_lshlrev_b32_e32 v46, 16, v32
	v_and_b32_e32 v47, 0xffff0000, v32
	v_add_f32_e32 v32, v44, v45
	v_fmamk_f32 v32, v32, 0x3a800000, v178
	v_and_b32_e32 v51, 0xffff0000, v36
	v_mul_f32_e32 v36, 0x4f800000, v32
	v_cmp_gt_f32_e32 vcc, s70, v32
	v_lshlrev_b32_e32 v48, 16, v37
	v_and_b32_e32 v37, 0xffff0000, v37
	v_cndmask_b32_e32 v36, v32, v36, vcc
	v_sqrt_f32_e32 v44, v36
	v_lshlrev_b32_e32 v32, 16, v33
	v_and_b32_e32 v33, 0xffff0000, v33
	s_nop 1
	v_mul_f32_e32 v45, 0x37800000, v44
	v_cndmask_b32_e32 v44, v44, v45, vcc
	v_cmp_class_f32_e32 vcc, v36, v179
	s_nop 1
	v_cndmask_b32_e32 v36, v44, v36, vcc
	v_rcp_f32_e32 v44, v36
	s_nop 0
	v_mul_f32_e32 v36, -1.0, v44
	v_pk_mul_f32 v[28:29], v[28:29], v[36:37] op_sel_hi:[1,0]
	v_pk_mul_f32 v[24:25], v[24:25], v[36:37] op_sel_hi:[1,0]
	v_mul_f32_e32 v28, 0x3fb8aa3b, v28
	v_mul_f32_e32 v29, 0x3fb8aa3b, v29
	v_pk_mul_f32 v[30:31], v[30:31], v[36:37] op_sel_hi:[1,0]
	v_mul_f32_e32 v44, 0x3fb8aa3b, v24
	v_mul_f32_e32 v45, 0x3fb8aa3b, v25
	v_exp_f32_e32 v24, v28
	v_exp_f32_e32 v25, v29
	v_mul_f32_e32 v30, 0x3fb8aa3b, v30
	v_mul_f32_e32 v31, 0x3fb8aa3b, v31
	v_exp_f32_e32 v28, v30
	v_exp_f32_e32 v29, v31
	v_pk_add_f32 v[24:25], v[24:25], 1.0 op_sel_hi:[1,0]
	v_exp_f32_e32 v30, v44
	v_div_scale_f32 v44, s[8:9], v25, v25, v51
	v_pk_add_f32 v[28:29], v[28:29], 1.0 op_sel_hi:[1,0]
	v_div_scale_f32 v49, s[8:9], v24, v24, v50
	v_rcp_f32_e32 v57, v44
	v_div_scale_f32 v53, s[10:11], v29, v29, v37
	v_rcp_f32_e32 v58, v49
	v_div_scale_f32 v55, s[12:13], v28, v28, v48
	v_rcp_f32_e32 v59, v53
	v_rcp_f32_e32 v60, v55
	v_fma_f32 v61, -v44, v57, 1.0
	v_exp_f32_e32 v31, v45
	v_div_scale_f32 v45, vcc, v51, v25, v51
	v_fma_f32 v62, -v49, v58, 1.0
	v_fmac_f32_e32 v57, v61, v57
	v_div_scale_f32 v52, s[8:9], v50, v24, v50
	v_fma_f32 v63, -v53, v59, 1.0
	v_fmac_f32_e32 v58, v62, v58
	v_mul_f32_e32 v61, v45, v57
	v_div_scale_f32 v54, s[10:11], v37, v29, v37
	v_fma_f32 v64, -v55, v60, 1.0
	v_fmac_f32_e32 v59, v63, v59
	v_mul_f32_e32 v62, v52, v58
	v_fma_f32 v65, -v44, v61, v45
	v_div_scale_f32 v56, s[12:13], v48, v28, v48
	v_fmac_f32_e32 v60, v64, v60
	v_mul_f32_e32 v63, v54, v59
	v_fma_f32 v66, -v49, v62, v52
	v_fmac_f32_e32 v61, v65, v57
	v_mul_f32_e32 v64, v56, v60
	v_fma_f32 v67, -v53, v63, v54
	v_fmac_f32_e32 v62, v66, v58
	v_fma_f32 v68, -v55, v64, v56
	v_fmac_f32_e32 v63, v67, v59
	v_fmac_f32_e32 v64, v68, v60
	v_rcp_f32_e32 v44, v25
	s_nop 0
	v_mul_f32_e32 v25, v51, v44
	v_fma_f32 v52, -v55, v64, v56
	v_rcp_f32_e32 v44, v24
	s_nop 0
	v_mul_f32_e32 v24, v50, v44
	v_pk_add_f32 v[44:45], v[24:25], v[46:47]
	v_rcp_f32_e32 v49, v29
	s_nop 0
	v_mul_f32_e32 v25, v37, v49
	v_rcp_f32_e32 v24, v28
	s_nop 0
	v_mul_f32_e32 v24, v48, v24
	v_pk_add_f32 v[46:47], v[24:25], v[32:33]
	v_and_b32_e32 v32, 0xffff0000, v38
	v_pk_add_f32 v[24:25], v[30:31], 1.0 op_sel_hi:[1,0]
	v_lshlrev_b32_e32 v28, 16, v34
	v_div_scale_f32 v30, s[8:9], v25, v25, v32
	v_rcp_f32_e32 v31, v30
	v_and_b32_e32 v29, 0xffff0000, v34
	v_pk_mul_f32 v[26:27], v[26:27], v[36:37] op_sel_hi:[1,0]
	v_lshlrev_b32_e32 v33, 16, v38
	v_fma_f32 v34, -v30, v31, 1.0
	v_fmac_f32_e32 v31, v34, v31
	v_div_scale_f32 v34, vcc, v32, v25, v32
	v_mul_f32_e32 v37, v34, v31
	v_fma_f32 v38, -v30, v37, v34
	v_fmac_f32_e32 v37, v38, v31
	v_rcp_f32_e32 v30, v25
	s_nop 0
	v_mul_f32_e32 v25, v32, v30
	v_mul_f32_e32 v26, 0x3fb8aa3b, v26
	v_mul_f32_e32 v27, 0x3fb8aa3b, v27
	v_exp_f32_e32 v26, v26
	v_exp_f32_e32 v27, v27
	v_rcp_f32_e32 v30, v24
	s_nop 0
	v_mul_f32_e32 v24, v33, v30
	v_pk_add_f32 v[48:49], v[24:25], v[28:29]
	v_and_b32_e32 v28, 0xffff0000, v39
	v_pk_add_f32 v[24:25], v[26:27], 1.0 op_sel_hi:[1,0]
	v_lshlrev_b32_e32 v31, 16, v39
	v_div_scale_f32 v29, s[8:9], v25, v25, v28
	v_rcp_f32_e32 v30, v29
	v_lshlrev_b32_e32 v26, 16, v35
	v_and_b32_e32 v27, 0xffff0000, v35
	v_pk_mul_f32 v[20:21], v[20:21], v[36:37] op_sel_hi:[1,0]
	v_fma_f32 v32, -v29, v30, 1.0
	v_fmac_f32_e32 v30, v32, v30
	v_div_scale_f32 v32, vcc, v28, v25, v28
	v_mul_f32_e32 v33, v32, v30
	v_fma_f32 v34, -v29, v33, v32
	v_fmac_f32_e32 v33, v34, v30
	v_div_scale_f32 v32, s[8:9], v24, v24, v31
	v_rcp_f32_e32 v29, v25
	s_nop 0
	v_mul_f32_e32 v25, v28, v29
	v_mul_f32_e32 v20, 0x3fb8aa3b, v20
	v_div_scale_f32 v28, vcc, v31, v24, v31
	v_rcp_f32_e32 v28, v24
	s_nop 0
	v_mul_f32_e32 v24, v31, v28
	v_pk_add_f32 v[34:35], v[24:25], v[26:27]
	v_cvt_pk_bf16_f32 v26, v44, v45
	v_cvt_pk_bf16_f32 v27, v46, v47
	v_cvt_pk_bf16_f32 v28, v48, v49
	v_cvt_pk_bf16_f32 v29, v34, v35
	v_lshl_add_u64 v[24:25], s[16:17], 0, v[42:43]
	v_or_b32_e32 v42, 0x100, v42
	global_store_dwordx4 v[24:25], v[26:29], off
	v_lshl_add_u64 v[30:31], s[20:21], 0, v[42:43]
	global_load_dwordx4 v[30:33], v[30:31], off
	v_lshl_add_u64 v[26:27], s[24:25], 0, v[42:43]
	global_load_dwordx4 v[26:29], v[26:27], off
	v_mul_f32_e32 v21, 0x3fb8aa3b, v21
	v_exp_f32_e32 v20, v20
	v_exp_f32_e32 v21, v21
	v_pk_mul_f32 v[42:43], v[46:47], v[46:47]
	v_pk_mul_f32 v[38:39], v[44:45], v[44:45]
	v_pk_mul_f32 v[44:45], v[48:49], v[48:49]
	v_pk_add_f32 v[20:21], v[20:21], 1.0 op_sel_hi:[1,0]
	v_pk_mul_f32 v[22:23], v[22:23], v[36:37] op_sel_hi:[1,0]
	v_pk_mul_f32 v[18:19], v[18:19], v[36:37] op_sel_hi:[1,0]
	v_pk_mul_f32 v[16:17], v[16:17], v[36:37] op_sel_hi:[1,0]
	v_mul_f32_e32 v22, 0x3fb8aa3b, v22
	v_mul_f32_e32 v23, 0x3fb8aa3b, v23
	v_exp_f32_e32 v22, v22
	v_exp_f32_e32 v23, v23
	v_mul_f32_e32 v16, 0x3fb8aa3b, v16
	v_mul_f32_e32 v17, 0x3fb8aa3b, v17
	v_exp_f32_e32 v16, v16
	v_pk_add_f32 v[22:23], v[22:23], 1.0 op_sel_hi:[1,0]
	v_exp_f32_e32 v17, v17
	v_mul_f32_e32 v18, 0x3fb8aa3b, v18
	v_mul_f32_e32 v19, 0x3fb8aa3b, v19
	v_exp_f32_e32 v18, v18
	v_pk_add_f32 v[16:17], v[16:17], 1.0 op_sel_hi:[1,0]
	v_exp_f32_e32 v19, v19
	v_pk_mul_f32 v[34:35], v[34:35], v[34:35]
	s_waitcnt vmcnt(1)
; DI unsigned pk_bf16(float lo, float hi) { typedef float f2 __attribute__((ext_vector_type(2))); typedef __bf16 b2 __attribute__((ext_vector_type(2))); f2 v = {lo, hi}; b2 b = __builtin_convertvector(v, b2); return __builtin_bit_cast(unsigned, b); }
; DI float bf_lo(unsigned w) { return __uint_as_float(w << 16); }
; DI float bf_hi(unsigned w) { return __uint_as_float(w & 0xffff0000u); }
;     DI void operator()(const f32x4 (&acc)[2][2][4][2], const pg8::Unit& u, int wr, int wc, int fr, int fq) const {
;     ...
;                 const int row = row0 + ai * 128 + m * 16;
;                 const size_t off = (size_t)row * ldc + col0;
;                 const f32x4* pq = (const f32x4*)(partin + (size_t)row * 16); const f32x4 t4 = (pq[0] + pq[1]) + (pq[2] + pq[3]);
;     ...
;                     const u32x4 pw = *(const u32x4*)(pp + o2), bw = *(const u32x4*)(base + o2);
;                     const f32x4 a0 = acc[ai][bj][m][0] * rs, a1 = acc[ai][bj][m][1] * rs;
;                     f32x4 r0, r1;
;                     r0[0] = bf_lo(bw.x) + bf_lo(pw.x) / (1.f + __expf(a0[0])); r0[1] = bf_hi(bw.x) + bf_hi(pw.x) / (1.f + __expf(a0[1]));
;                     r0[2] = bf_lo(bw.y) + bf_lo(pw.y) / (1.f + __expf(a0[2])); r0[3] = bf_hi(bw.y) + bf_hi(pw.y) / (1.f + __expf(a0[3]));
;                     r1[0] = bf_lo(bw.z) + bf_lo(pw.z) / (1.f + __expf(a1[0])); r1[1] = bf_hi(bw.z) + bf_hi(pw.z) / (1.f + __expf(a1[1]));
;                     r1[2] = bf_lo(bw.w) + bf_lo(pw.w) / (1.f + __expf(a1[2])); r1[3] = bf_hi(bw.w) + bf_hi(pw.w) / (1.f + __expf(a1[3]));
;                     u32x4 w; w.x = pk_bf16(r0[0], r0[1]); w.y = pk_bf16(r0[2], r0[3]); w.z = pk_bf16(r1[0], r1[1]); w.w = pk_bf16(r1[2], r1[3]);
;                     *(u32x4*)(hb + o2) = w;
;                     ss += ((r0[0] * r0[0] + r0[1] * r0[1]) + (r0[2] * r0[2] + r0[3] * r0[3])) + ((r1[0] * r1[0] + r1[1] * r1[1]) + (r1[2] * r1[2] + r1[3] * r1[3]));
;                 }
;                 ss += __shfl_xor(ss, 16); ss += __shfl_xor(ss, 32);
;                 if (fq == 0) part[(size_t)row * 16 + u.pn * 4 + wc] = ss;
	v_lshlrev_b32_e32 v36, 16, v30
	v_and_b32_e32 v37, 0xffff0000, v30
	s_waitcnt vmcnt(0)
	v_and_b32_e32 v46, 0xffff0000, v26
	v_div_scale_f32 v47, s[8:9], v21, v21, v46
	v_rcp_f32_e32 v48, v47
	v_lshlrev_b32_e32 v26, 16, v26
	v_add_f32_e32 v34, v34, v35
	v_add_f32_e32 v35, v44, v45
	v_fma_f32 v30, -v47, v48, 1.0
	v_fmac_f32_e32 v48, v30, v48
	v_div_scale_f32 v30, vcc, v46, v21, v46
	v_mul_f32_e32 v49, v30, v48
	v_fma_f32 v50, -v47, v49, v30
	v_fmac_f32_e32 v49, v50, v48
	v_div_scale_f32 v47, s[8:9], v20, v20, v26
	v_rcp_f32_e32 v50, v47
	v_rcp_f32_e32 v30, v21
	s_nop 0
	v_mul_f32_e32 v21, v46, v30
	v_add_f32_e32 v34, v35, v34
	v_fma_f32 v30, -v47, v50, 1.0
	v_fmac_f32_e32 v50, v30, v50
	v_rcp_f32_e32 v30, v20
	s_nop 0
	v_mul_f32_e32 v20, v26, v30
	v_and_b32_e32 v26, 0xffff0000, v27
	v_pk_add_f32 v[20:21], v[20:21], v[36:37]
	v_div_scale_f32 v36, s[8:9], v23, v23, v26
	v_rcp_f32_e32 v37, v36
	v_lshlrev_b32_e32 v27, 16, v27
	v_lshlrev_b32_e32 v30, 16, v31
	v_and_b32_e32 v31, 0xffff0000, v31
	v_fma_f32 v46, -v36, v37, 1.0
	v_fmac_f32_e32 v37, v46, v37
	v_div_scale_f32 v46, vcc, v26, v23, v26
	v_mul_f32_e32 v47, v46, v37
	v_fma_f32 v48, -v36, v47, v46
	v_fmac_f32_e32 v47, v48, v37
	v_div_scale_f32 v46, s[8:9], v22, v22, v27
	v_rcp_f32_e32 v48, v46
	v_rcp_f32_e32 v36, v23
	s_nop 0
	v_mul_f32_e32 v23, v26, v36
	v_add_f32_e32 v35, v42, v43
	v_fma_f32 v26, -v46, v48, 1.0
	v_fmac_f32_e32 v48, v26, v48
	v_rcp_f32_e32 v26, v22
	s_nop 0
	v_mul_f32_e32 v22, v27, v26
	v_pk_add_f32 v[22:23], v[22:23], v[30:31]
	v_and_b32_e32 v30, 0xffff0000, v28
	v_div_scale_f32 v31, s[8:9], v17, v17, v30
	v_rcp_f32_e32 v36, v31
	v_lshlrev_b32_e32 v26, 16, v32
	v_and_b32_e32 v27, 0xffff0000, v32
	v_lshlrev_b32_e32 v28, 16, v28
	v_fma_f32 v32, -v31, v36, 1.0
	v_fmac_f32_e32 v36, v32, v36
	v_div_scale_f32 v32, vcc, v30, v17, v30
	v_mul_f32_e32 v37, v32, v36
	v_fma_f32 v46, -v31, v37, v32
	v_fmac_f32_e32 v37, v46, v36
	v_div_scale_f32 v32, s[8:9], v16, v16, v28
	v_rcp_f32_e32 v46, v32
	v_rcp_f32_e32 v31, v17
	s_nop 0
	v_mul_f32_e32 v17, v30, v31
	v_fma_f32 v30, -v32, v46, 1.0
	v_fmac_f32_e32 v46, v30, v46
	v_rcp_f32_e32 v30, v16
	s_nop 0
	v_mul_f32_e32 v16, v28, v30
	v_pk_add_f32 v[26:27], v[16:17], v[26:27]
	v_and_b32_e32 v28, 0xffff0000, v29
	v_pk_add_f32 v[16:17], v[18:19], 1.0 op_sel_hi:[1,0]
	v_lshlrev_b32_e32 v18, 16, v33
	v_and_b32_e32 v19, 0xffff0000, v33
	v_lshlrev_b32_e32 v29, 16, v29
	v_div_scale_f32 v32, s[8:9], v16, v16, v29
	v_rcp_f32_e32 v30, v17
	s_nop 0
	v_mul_f32_e32 v17, v28, v30
	v_div_scale_f32 v28, vcc, v29, v16, v29
	v_rcp_f32_e32 v28, v16
	s_nop 0
	v_mul_f32_e32 v16, v29, v28
	v_pk_add_f32 v[28:29], v[16:17], v[18:19]
	v_pk_mul_f32 v[16:17], v[20:21], v[20:21]
	v_pk_mul_f32 v[18:19], v[22:23], v[22:23]
	v_pk_mul_f32 v[30:31], v[26:27], v[26:27]
	v_pk_mul_f32 v[32:33], v[28:29], v[28:29]
	v_add_f32_e32 v36, v38, v39
	v_add_f32_e32 v32, v32, v33
	v_add_f32_e32 v30, v30, v31
	v_add_f32_e32 v18, v18, v19
	v_add_f32_e32 v16, v16, v17
	v_add_f32_e32 v35, v36, v35
	v_add_f32_e32 v30, v30, v32
	v_add_f32_e32 v16, v16, v18
	v_add_f32_e32 v34, v35, v34
	v_add_f32_e32 v16, v16, v30
	v_add_f32_e32 v16, v34, v16
	ds_bpermute_b32 v17, v124, v16
	v_cvt_pk_bf16_f32 v18, v20, v21
	v_cvt_pk_bf16_f32 v19, v22, v23
	v_cvt_pk_bf16_f32 v20, v26, v27
	v_cvt_pk_bf16_f32 v21, v28, v29
	s_waitcnt lgkmcnt(0)
	v_add_f32_e32 v16, v16, v17
	ds_bpermute_b32 v17, v125, v16
	global_store_dwordx4 v[24:25], v[18:21], off offset:256
	s_and_saveexec_b64 s[8:9], s[4:5]
	s_cbranch_execz .LBB0_688
	v_lshlrev_b64 v[18:19], 4, v[40:41]
	s_waitcnt lgkmcnt(0)
	v_add_f32_e32 v20, v16, v17
	v_lshl_add_u64 v[16:17], v[18:19], 2, s[18:19]
	v_lshl_add_u64 v[16:17], s[48:49], 2, v[16:17]
	s_lshl_b32 s34, s59, 2
	v_lshl_add_u64 v[16:17], v[16:17], 0, s[34:35]
	global_store_dword v[16:17], v20, off
.LBB0_688:
	s_or_b64 exec, exec, s[8:9]
	v_add_u32_e32 v24, 0xb0, v154
	v_ashrrev_i32_e32 v25, 31, v24
	s_waitcnt lgkmcnt(0)
	v_lshlrev_b64 v[16:17], 6, v[24:25]
	v_lshl_add_u64 v[16:17], s[26:27], 0, v[16:17]
	global_load_dwordx4 v[28:31], v[16:17], off
	global_load_dwordx4 v[32:35], v[16:17], off offset:16
	global_load_dwordx4 v[36:39], v[16:17], off offset:32
	global_load_dwordx4 v[40:43], v[16:17], off offset:48
	v_lshlrev_b64 v[16:17], 10, v[24:25]
	v_lshl_add_u64 v[16:17], v[16:17], 0, v[152:153]
	v_lshlrev_b64 v[26:27], 1, v[16:17]
	v_lshl_add_u64 v[16:17], s[20:21], 0, v[26:27]
	global_load_dwordx4 v[16:19], v[16:17], off
	v_lshl_add_u64 v[20:21], s[24:25], 0, v[26:27]
	global_load_dwordx4 v[20:23], v[20:21], off
	s_waitcnt vmcnt(4)
	v_pk_add_f32 v[30:31], v[30:31], v[34:35]
	v_pk_add_f32 v[28:29], v[28:29], v[32:33]
	s_waitcnt vmcnt(2)
	v_pk_add_f32 v[32:33], v[38:39], v[42:43]
	v_pk_add_f32 v[34:35], v[36:37], v[40:41]
	v_pk_add_f32 v[30:31], v[30:31], v[32:33]
	v_pk_add_f32 v[28:29], v[28:29], v[34:35]
	s_waitcnt vmcnt(0)
; DI unsigned pk_bf16(float lo, float hi) { typedef float f2 __attribute__((ext_vector_type(2))); typedef __bf16 b2 __attribute__((ext_vector_type(2))); f2 v = {lo, hi}; b2 b = __builtin_convertvector(v, b2); return __builtin_bit_cast(unsigned, b); }
; DI float bf_lo(unsigned w) { return __uint_as_float(w << 16); }
; DI float bf_hi(unsigned w) { return __uint_as_float(w & 0xffff0000u); }
;     DI void operator()(const f32x4 (&acc)[2][2][4][2], const pg8::Unit& u, int wr, int wc, int fr, int fq) const {
;     ...
;                 const int row = row0 + ai * 128 + m * 16;
;                 const size_t off = (size_t)row * ldc + col0;
;                 const f32x4* pq = (const f32x4*)(partin + (size_t)row * 16); const f32x4 t4 = (pq[0] + pq[1]) + (pq[2] + pq[3]);
;                 const float rs = -1.0f / sqrtf(((t4.x + t4.y) + (t4.z + t4.w)) * (1.f / DM) + NORM_EPS);
;                 float ss = 0.f;
; #pragma unroll
;                 for (int bj = 0; bj < 2; ++bj) {
;                     const size_t o2 = off + bj * 128;
;                     const u32x4 pw = *(const u32x4*)(pp + o2), bw = *(const u32x4*)(base + o2);
;                     const f32x4 a0 = acc[ai][bj][m][0] * rs, a1 = acc[ai][bj][m][1] * rs;
;                     f32x4 r0, r1;
;                     r0[0] = bf_lo(bw.x) + bf_lo(pw.x) / (1.f + __expf(a0[0])); r0[1] = bf_hi(bw.x) + bf_hi(pw.x) / (1.f + __expf(a0[1]));
;                     r0[2] = bf_lo(bw.y) + bf_lo(pw.y) / (1.f + __expf(a0[2])); r0[3] = bf_hi(bw.y) + bf_hi(pw.y) / (1.f + __expf(a0[3]));
;                     r1[0] = bf_lo(bw.z) + bf_lo(pw.z) / (1.f + __expf(a1[0])); r1[1] = bf_hi(bw.z) + bf_hi(pw.z) / (1.f + __expf(a1[1]));
;                     r1[2] = bf_lo(bw.w) + bf_lo(pw.w) / (1.f + __expf(a1[2])); r1[3] = bf_hi(bw.w) + bf_hi(pw.w) / (1.f + __expf(a1[3]));
;                     u32x4 w; w.x = pk_bf16(r0[0], r0[1]); w.y = pk_bf16(r0[2], r0[3]); w.z = pk_bf16(r1[0], r1[1]); w.w = pk_bf16(r1[2], r1[3]);
;                     *(u32x4*)(hb + o2) = w;
	v_lshlrev_b32_e32 v34, 16, v20
	v_pk_mov_b32 v[32:33], v[28:29], v[30:31] op_sel:[1,0]
	v_mov_b32_e32 v29, v31
	v_pk_add_f32 v[28:29], v[32:33], v[28:29]
	v_lshlrev_b32_e32 v30, 16, v16
	v_and_b32_e32 v31, 0xffff0000, v16
	v_add_f32_e32 v16, v28, v29
	v_fmamk_f32 v16, v16, 0x3a800000, v178
	v_and_b32_e32 v35, 0xffff0000, v20
	v_mul_f32_e32 v20, 0x4f800000, v16
	v_cmp_gt_f32_e32 vcc, s70, v16
	v_lshlrev_b32_e32 v32, 16, v21
	v_and_b32_e32 v21, 0xffff0000, v21
	v_cndmask_b32_e32 v20, v16, v20, vcc
	v_sqrt_f32_e32 v28, v20
	v_lshlrev_b32_e32 v16, 16, v17
	v_and_b32_e32 v17, 0xffff0000, v17
	s_nop 1
	v_mul_f32_e32 v29, 0x37800000, v28
	v_cndmask_b32_e32 v28, v28, v29, vcc
	v_cmp_class_f32_e32 vcc, v20, v179
	s_nop 1
	v_cndmask_b32_e32 v20, v28, v20, vcc
	v_rcp_f32_e32 v28, v20
	s_nop 0
	v_mul_f32_e32 v20, -1.0, v28
	v_pk_mul_f32 v[12:13], v[12:13], v[20:21] op_sel_hi:[1,0]
	v_pk_mul_f32 v[8:9], v[8:9], v[20:21] op_sel_hi:[1,0]
	v_mul_f32_e32 v12, 0x3fb8aa3b, v12
	v_mul_f32_e32 v13, 0x3fb8aa3b, v13
	v_pk_mul_f32 v[14:15], v[14:15], v[20:21] op_sel_hi:[1,0]
	v_mul_f32_e32 v28, 0x3fb8aa3b, v8
	v_mul_f32_e32 v29, 0x3fb8aa3b, v9
	v_exp_f32_e32 v8, v12
	v_exp_f32_e32 v9, v13
	v_mul_f32_e32 v14, 0x3fb8aa3b, v14
	v_mul_f32_e32 v15, 0x3fb8aa3b, v15
	v_exp_f32_e32 v12, v14
	v_exp_f32_e32 v13, v15
	v_pk_add_f32 v[8:9], v[8:9], 1.0 op_sel_hi:[1,0]
	v_exp_f32_e32 v14, v28
	v_div_scale_f32 v28, s[8:9], v9, v9, v35
	v_pk_add_f32 v[12:13], v[12:13], 1.0 op_sel_hi:[1,0]
	v_div_scale_f32 v33, s[8:9], v8, v8, v34
	v_rcp_f32_e32 v41, v28
	v_div_scale_f32 v37, s[10:11], v13, v13, v21
	v_rcp_f32_e32 v42, v33
	v_div_scale_f32 v39, s[12:13], v12, v12, v32
	v_rcp_f32_e32 v43, v37
	v_rcp_f32_e32 v44, v39
	v_fma_f32 v45, -v28, v41, 1.0
	v_exp_f32_e32 v15, v29
	v_div_scale_f32 v29, vcc, v35, v9, v35
	v_fma_f32 v46, -v33, v42, 1.0
	v_fmac_f32_e32 v41, v45, v41
	v_div_scale_f32 v36, s[8:9], v34, v8, v34
	v_fma_f32 v47, -v37, v43, 1.0
	v_fmac_f32_e32 v42, v46, v42
	v_mul_f32_e32 v45, v29, v41
	v_div_scale_f32 v38, s[10:11], v21, v13, v21
	v_fma_f32 v48, -v39, v44, 1.0
	v_fmac_f32_e32 v43, v47, v43
	v_mul_f32_e32 v46, v36, v42
	v_fma_f32 v49, -v28, v45, v29
	v_div_scale_f32 v40, s[12:13], v32, v12, v32
	v_fmac_f32_e32 v44, v48, v44
	v_mul_f32_e32 v47, v38, v43
	v_fma_f32 v50, -v33, v46, v36
	v_fmac_f32_e32 v45, v49, v41
	v_mul_f32_e32 v48, v40, v44
	v_fma_f32 v51, -v37, v47, v38
	v_fmac_f32_e32 v46, v50, v42
	v_fma_f32 v52, -v39, v48, v40
	v_fmac_f32_e32 v47, v51, v43
	v_fmac_f32_e32 v48, v52, v44
	v_rcp_f32_e32 v28, v9
	s_nop 0
	v_mul_f32_e32 v9, v35, v28
	v_fma_f32 v36, -v39, v48, v40
	v_rcp_f32_e32 v28, v8
	s_nop 0
	v_mul_f32_e32 v8, v34, v28
	v_pk_add_f32 v[28:29], v[8:9], v[30:31]
	v_rcp_f32_e32 v33, v13
	s_nop 0
	v_mul_f32_e32 v9, v21, v33
	v_rcp_f32_e32 v8, v12
	s_nop 0
	v_mul_f32_e32 v8, v32, v8
	v_pk_add_f32 v[30:31], v[8:9], v[16:17]
	v_and_b32_e32 v16, 0xffff0000, v22
	v_pk_add_f32 v[8:9], v[14:15], 1.0 op_sel_hi:[1,0]
	v_lshlrev_b32_e32 v12, 16, v18
	v_div_scale_f32 v14, s[8:9], v9, v9, v16
	v_rcp_f32_e32 v15, v14
	v_and_b32_e32 v13, 0xffff0000, v18
	v_pk_mul_f32 v[10:11], v[10:11], v[20:21] op_sel_hi:[1,0]
	v_lshlrev_b32_e32 v17, 16, v22
	v_fma_f32 v18, -v14, v15, 1.0
	v_fmac_f32_e32 v15, v18, v15
	v_div_scale_f32 v18, vcc, v16, v9, v16
	v_mul_f32_e32 v21, v18, v15
	v_fma_f32 v22, -v14, v21, v18
	v_fmac_f32_e32 v21, v22, v15
	v_rcp_f32_e32 v14, v9
	s_nop 0
	v_mul_f32_e32 v9, v16, v14
	v_mul_f32_e32 v10, 0x3fb8aa3b, v10
	v_mul_f32_e32 v11, 0x3fb8aa3b, v11
	v_exp_f32_e32 v10, v10
	v_exp_f32_e32 v11, v11
	v_rcp_f32_e32 v14, v8
	s_nop 0
	v_mul_f32_e32 v8, v17, v14
	v_pk_add_f32 v[32:33], v[8:9], v[12:13]
	v_and_b32_e32 v12, 0xffff0000, v23
	v_pk_add_f32 v[8:9], v[10:11], 1.0 op_sel_hi:[1,0]
	v_lshlrev_b32_e32 v15, 16, v23
	v_div_scale_f32 v13, s[8:9], v9, v9, v12
	v_rcp_f32_e32 v14, v13
	v_lshlrev_b32_e32 v10, 16, v19
	v_and_b32_e32 v11, 0xffff0000, v19
	v_pk_mul_f32 v[4:5], v[4:5], v[20:21] op_sel_hi:[1,0]
	v_fma_f32 v16, -v13, v14, 1.0
	v_fmac_f32_e32 v14, v16, v14
	v_div_scale_f32 v16, vcc, v12, v9, v12
	v_mul_f32_e32 v17, v16, v14
	v_fma_f32 v18, -v13, v17, v16
	v_fmac_f32_e32 v17, v18, v14
	v_div_scale_f32 v16, s[8:9], v8, v8, v15
	v_rcp_f32_e32 v13, v9
	s_nop 0
	v_mul_f32_e32 v9, v12, v13
	v_mul_f32_e32 v4, 0x3fb8aa3b, v4
	v_div_scale_f32 v12, vcc, v15, v8, v15
	v_rcp_f32_e32 v12, v8
	s_nop 0
	v_mul_f32_e32 v8, v15, v12
	v_pk_add_f32 v[18:19], v[8:9], v[10:11]
	v_cvt_pk_bf16_f32 v10, v28, v29
	v_cvt_pk_bf16_f32 v11, v30, v31
	v_cvt_pk_bf16_f32 v12, v32, v33
	v_cvt_pk_bf16_f32 v13, v18, v19
	v_lshl_add_u64 v[8:9], s[16:17], 0, v[26:27]
	v_or_b32_e32 v26, 0x100, v26
	global_store_dwordx4 v[8:9], v[10:13], off
	v_lshl_add_u64 v[14:15], s[20:21], 0, v[26:27]
	global_load_dwordx4 v[14:17], v[14:15], off
	v_lshl_add_u64 v[10:11], s[24:25], 0, v[26:27]
	global_load_dwordx4 v[10:13], v[10:11], off
	v_mul_f32_e32 v5, 0x3fb8aa3b, v5
	v_exp_f32_e32 v4, v4
	v_exp_f32_e32 v5, v5
	v_pk_mul_f32 v[26:27], v[30:31], v[30:31]
	v_pk_mul_f32 v[22:23], v[28:29], v[28:29]
	v_pk_mul_f32 v[28:29], v[32:33], v[32:33]
	v_pk_add_f32 v[4:5], v[4:5], 1.0 op_sel_hi:[1,0]
	v_pk_mul_f32 v[6:7], v[6:7], v[20:21] op_sel_hi:[1,0]
	v_pk_mul_f32 v[2:3], v[2:3], v[20:21] op_sel_hi:[1,0]
	v_pk_mul_f32 v[0:1], v[0:1], v[20:21] op_sel_hi:[1,0]
	v_mul_f32_e32 v6, 0x3fb8aa3b, v6
	v_mul_f32_e32 v7, 0x3fb8aa3b, v7
	v_exp_f32_e32 v6, v6
	v_exp_f32_e32 v7, v7
	v_mul_f32_e32 v0, 0x3fb8aa3b, v0
	v_mul_f32_e32 v1, 0x3fb8aa3b, v1
	v_exp_f32_e32 v0, v0
	v_pk_add_f32 v[6:7], v[6:7], 1.0 op_sel_hi:[1,0]
	v_exp_f32_e32 v1, v1
	v_mul_f32_e32 v2, 0x3fb8aa3b, v2
	v_mul_f32_e32 v3, 0x3fb8aa3b, v3
	v_exp_f32_e32 v2, v2
	v_pk_add_f32 v[0:1], v[0:1], 1.0 op_sel_hi:[1,0]
	v_exp_f32_e32 v3, v3
	v_pk_mul_f32 v[18:19], v[18:19], v[18:19]
	s_waitcnt vmcnt(1)
; DI unsigned pk_bf16(float lo, float hi) { typedef float f2 __attribute__((ext_vector_type(2))); typedef __bf16 b2 __attribute__((ext_vector_type(2))); f2 v = {lo, hi}; b2 b = __builtin_convertvector(v, b2); return __builtin_bit_cast(unsigned, b); }
; DI float bf_lo(unsigned w) { return __uint_as_float(w << 16); }
; DI float bf_hi(unsigned w) { return __uint_as_float(w & 0xffff0000u); }
;     DI void operator()(const f32x4 (&acc)[2][2][4][2], const pg8::Unit& u, int wr, int wc, int fr, int fq) const {
;     ...
;                     const u32x4 pw = *(const u32x4*)(pp + o2), bw = *(const u32x4*)(base + o2);
;                     const f32x4 a0 = acc[ai][bj][m][0] * rs, a1 = acc[ai][bj][m][1] * rs;
;                     f32x4 r0, r1;
;                     r0[0] = bf_lo(bw.x) + bf_lo(pw.x) / (1.f + __expf(a0[0])); r0[1] = bf_hi(bw.x) + bf_hi(pw.x) / (1.f + __expf(a0[1]));
;                     r0[2] = bf_lo(bw.y) + bf_lo(pw.y) / (1.f + __expf(a0[2])); r0[3] = bf_hi(bw.y) + bf_hi(pw.y) / (1.f + __expf(a0[3]));
;                     r1[0] = bf_lo(bw.z) + bf_lo(pw.z) / (1.f + __expf(a1[0])); r1[1] = bf_hi(bw.z) + bf_hi(pw.z) / (1.f + __expf(a1[1]));
;                     r1[2] = bf_lo(bw.w) + bf_lo(pw.w) / (1.f + __expf(a1[2])); r1[3] = bf_hi(bw.w) + bf_hi(pw.w) / (1.f + __expf(a1[3]));
;                     u32x4 w; w.x = pk_bf16(r0[0], r0[1]); w.y = pk_bf16(r0[2], r0[3]); w.z = pk_bf16(r1[0], r1[1]); w.w = pk_bf16(r1[2], r1[3]);
;                     *(u32x4*)(hb + o2) = w;
;                     ss += ((r0[0] * r0[0] + r0[1] * r0[1]) + (r0[2] * r0[2] + r0[3] * r0[3])) + ((r1[0] * r1[0] + r1[1] * r1[1]) + (r1[2] * r1[2] + r1[3] * r1[3]));
;                 }
;                 ss += __shfl_xor(ss, 16); ss += __shfl_xor(ss, 32);
;                 if (fq == 0) part[(size_t)row * 16 + u.pn * 4 + wc] = ss;
	v_lshlrev_b32_e32 v20, 16, v14
	v_and_b32_e32 v21, 0xffff0000, v14
	s_waitcnt vmcnt(0)
	v_and_b32_e32 v30, 0xffff0000, v10
	v_div_scale_f32 v31, s[8:9], v5, v5, v30
	v_rcp_f32_e32 v32, v31
	v_lshlrev_b32_e32 v10, 16, v10
	v_add_f32_e32 v18, v18, v19
	v_add_f32_e32 v19, v28, v29
	v_fma_f32 v14, -v31, v32, 1.0
	v_fmac_f32_e32 v32, v14, v32
	v_div_scale_f32 v14, vcc, v30, v5, v30
	v_mul_f32_e32 v33, v14, v32
	v_fma_f32 v34, -v31, v33, v14
	v_fmac_f32_e32 v33, v34, v32
	v_div_scale_f32 v31, s[8:9], v4, v4, v10
	v_rcp_f32_e32 v34, v31
	v_rcp_f32_e32 v14, v5
	s_nop 0
	v_mul_f32_e32 v5, v30, v14
	v_add_f32_e32 v18, v19, v18
	v_fma_f32 v14, -v31, v34, 1.0
	v_fmac_f32_e32 v34, v14, v34
	v_rcp_f32_e32 v14, v4
	s_nop 0
	v_mul_f32_e32 v4, v10, v14
	v_and_b32_e32 v10, 0xffff0000, v11
	v_pk_add_f32 v[4:5], v[4:5], v[20:21]
	v_div_scale_f32 v20, s[8:9], v7, v7, v10
	v_rcp_f32_e32 v21, v20
	v_lshlrev_b32_e32 v11, 16, v11
	v_lshlrev_b32_e32 v14, 16, v15
	v_and_b32_e32 v15, 0xffff0000, v15
	v_fma_f32 v30, -v20, v21, 1.0
	v_fmac_f32_e32 v21, v30, v21
	v_div_scale_f32 v30, vcc, v10, v7, v10
	v_mul_f32_e32 v31, v30, v21
	v_fma_f32 v32, -v20, v31, v30
	v_fmac_f32_e32 v31, v32, v21
	v_div_scale_f32 v30, s[8:9], v6, v6, v11
	v_rcp_f32_e32 v32, v30
	v_rcp_f32_e32 v20, v7
	s_nop 0
	v_mul_f32_e32 v7, v10, v20
	v_add_f32_e32 v19, v26, v27
	v_fma_f32 v10, -v30, v32, 1.0
	v_fmac_f32_e32 v32, v10, v32
	v_rcp_f32_e32 v10, v6
	s_nop 0
	v_mul_f32_e32 v6, v11, v10
	v_pk_add_f32 v[6:7], v[6:7], v[14:15]
	v_and_b32_e32 v14, 0xffff0000, v12
	v_div_scale_f32 v15, s[8:9], v1, v1, v14
	v_rcp_f32_e32 v20, v15
	v_lshlrev_b32_e32 v10, 16, v16
	v_and_b32_e32 v11, 0xffff0000, v16
	v_lshlrev_b32_e32 v12, 16, v12
	v_fma_f32 v16, -v15, v20, 1.0
	v_fmac_f32_e32 v20, v16, v20
	v_div_scale_f32 v16, vcc, v14, v1, v14
	v_mul_f32_e32 v21, v16, v20
	v_fma_f32 v30, -v15, v21, v16
	v_fmac_f32_e32 v21, v30, v20
	v_div_scale_f32 v16, s[8:9], v0, v0, v12
	v_rcp_f32_e32 v30, v16
	v_rcp_f32_e32 v15, v1
	s_nop 0
	v_mul_f32_e32 v1, v14, v15
	v_fma_f32 v14, -v16, v30, 1.0
	v_fmac_f32_e32 v30, v14, v30
	v_rcp_f32_e32 v14, v0
	s_nop 0
	v_mul_f32_e32 v0, v12, v14
	v_pk_add_f32 v[10:11], v[0:1], v[10:11]
	v_and_b32_e32 v12, 0xffff0000, v13
	v_pk_add_f32 v[0:1], v[2:3], 1.0 op_sel_hi:[1,0]
	v_lshlrev_b32_e32 v2, 16, v17
	v_and_b32_e32 v3, 0xffff0000, v17
	v_lshlrev_b32_e32 v13, 16, v13
	v_div_scale_f32 v16, s[8:9], v0, v0, v13
	v_rcp_f32_e32 v14, v1
	s_nop 0
	v_mul_f32_e32 v1, v12, v14
	v_div_scale_f32 v12, vcc, v13, v0, v13
	v_rcp_f32_e32 v12, v0
	s_nop 0
	v_mul_f32_e32 v0, v13, v12
	v_pk_add_f32 v[12:13], v[0:1], v[2:3]
	v_pk_mul_f32 v[0:1], v[4:5], v[4:5]
	v_pk_mul_f32 v[2:3], v[6:7], v[6:7]
	v_pk_mul_f32 v[14:15], v[10:11], v[10:11]
	v_pk_mul_f32 v[16:17], v[12:13], v[12:13]
	v_add_f32_e32 v20, v22, v23
	v_add_f32_e32 v16, v16, v17
	v_add_f32_e32 v14, v14, v15
	v_add_f32_e32 v2, v2, v3
	v_add_f32_e32 v0, v0, v1
	v_add_f32_e32 v19, v20, v19
	v_add_f32_e32 v14, v14, v16
	v_add_f32_e32 v0, v0, v2
	v_add_f32_e32 v18, v19, v18
	v_add_f32_e32 v0, v0, v14
	v_add_f32_e32 v0, v18, v0
	ds_bpermute_b32 v1, v124, v0
	v_cvt_pk_bf16_f32 v2, v4, v5
	v_cvt_pk_bf16_f32 v3, v6, v7
	v_cvt_pk_bf16_f32 v4, v10, v11
	v_cvt_pk_bf16_f32 v5, v12, v13
	s_waitcnt lgkmcnt(0)
	v_add_f32_e32 v0, v0, v1
	ds_bpermute_b32 v1, v125, v0
	global_store_dwordx4 v[8:9], v[2:5], off offset:256
	s_and_saveexec_b64 s[8:9], s[4:5]
	s_cbranch_execz .LBB0_690
	v_lshlrev_b64 v[2:3], 4, v[24:25]
	s_waitcnt lgkmcnt(0)
	v_add_f32_e32 v4, v0, v1
	v_lshl_add_u64 v[0:1], v[2:3], 2, s[18:19]
	v_lshl_add_u64 v[0:1], s[48:49], 2, v[0:1]
	s_lshl_b32 s34, s59, 2
	v_lshl_add_u64 v[0:1], v[0:1], 0, s[34:35]
	global_store_dword v[0:1], v4, off

;     DI void operator()(const f32x4 (&acc)[2][2][4][2], const pg8::Unit& u, int wr, int wc, int fr, int fq) const {
;     ...
;                 if (part) { const f32x4* pq = (const f32x4*)(part + (size_t)row * 16); const f32x4 t4 = (pq[0] + pq[1]) + (pq[2] + pq[3]); rs = 1.0f / sqrtf(((t4.x + t4.y) + (t4.z + t4.w)) * (1.f / DM) + NORM_EPS); }
;                 f32x4 c0 = {1.f, 1.f, 1.f, 1.f}, c1 = c0, s0 = {0.f, 0.f, 0.f, 0.f}, s1 = s0;
;                 if (do_rope && mine) { const float* cs = rope + (size_t)row * 16; c0 = *(const f32x4*)cs; c1 = *(const f32x4*)(cs + 4); s0 = *(const f32x4*)(cs + 8) * sgn; s1 = *(const f32x4*)(cs + 12) * sgn; }
; #pragma unroll
;                 for (int bj = 0; bj < 2; ++bj) {
;                     f32x4 v0 = acc[ai][bj][m][0] * rs, v1 = acc[ai][bj][m][1] * rs;
;                     if (act == 2) {
; #pragma unroll
;                         for (int k = 0; k < 4; ++k) { const float a = fmaxf(v0[k], 0.f), b = fmaxf(v1[k], 0.f); v0[k] = a * a; v1[k] = b * b; }
;                     }
;                     if (do_rope) {
;                         f32x4 p0, p1;
; #pragma unroll
;                         for (int k = 0; k < 4; ++k) { p0[k] = __shfl_xor(v0[k], 16); p1[k] = __shfl_xor(v1[k], 16); }
;                         v0 = v0 * c0 + p0 * s0; v1 = v1 * c1 + p1 * s1;
.LBB0_765:
	s_or_b64 exec, exec, s[8:9]
	s_waitcnt vmcnt(0)
	v_pk_add_f32 v[146:147], v[150:151], v[146:147]
	v_pk_add_f32 v[144:145], v[148:149], v[144:145]
	v_pk_add_f32 v[136:137], v[140:141], v[136:137]
	v_pk_add_f32 v[138:139], v[142:143], v[138:139]
	v_pk_add_f32 v[136:137], v[144:145], v[136:137]
	v_pk_add_f32 v[138:139], v[146:147], v[138:139]
	v_add_f32_e32 v136, v136, v137
	v_add_f32_e32 v137, v138, v139
	v_add_f32_e32 v136, v136, v137
	v_fmamk_f32 v136, v136, 0x3a800000, v204
	v_mul_f32_e32 v137, 0x4f800000, v136
	v_cmp_gt_f32_e32 vcc, s70, v136
	s_nop 1
	v_cndmask_b32_e32 v136, v136, v137, vcc
	v_sqrt_f32_e32 v137, v136
	s_nop 0
	s_nop 0
	v_mov_b32_e32 v138, v137
	s_nop 1
	v_mov_b32_e32 v137, v138
	v_mul_f32_e32 v138, 0x37800000, v137
	v_cndmask_b32_e32 v137, v137, v138, vcc
	v_cmp_class_f32_e32 vcc, v136, v205
	s_nop 1
	v_cndmask_b32_e32 v136, v137, v136, vcc
	v_div_scale_f32 v139, vcc, 1.0, v136, 1.0
	v_rcp_f32_e32 v137, v136
	s_nop 0
	v_mul_f32_e32 v138, 1.0, v137
	v_cndmask_b32_e64 v136, 0, 1, s[46:47]
	v_pk_mul_f32 v[126:127], v[126:127], v[138:139] op_sel_hi:[1,0]
	v_pk_mul_f32 v[124:125], v[124:125], v[138:139] op_sel_hi:[1,0]
	v_pk_mul_f32 v[122:123], v[122:123], v[138:139] op_sel_hi:[1,0]
	v_cmp_ne_u32_e64 s[8:9], 1, v136
	s_andn2_b64 vcc, exec, s[46:47]
	v_pk_mul_f32 v[140:141], v[120:121], v[138:139] op_sel_hi:[1,0]
	s_cbranch_vccnz .LBB0_767
	v_and_b32_e32 v121, 64, v206
	v_xor_b32_e32 v120, 16, v206
	v_add_u32_e32 v121, 64, v121
	v_cmp_lt_i32_e32 vcc, v120, v121
	s_nop 1
	v_cndmask_b32_e32 v120, v206, v120, vcc
	v_lshlrev_b32_e32 v139, 2, v120
	ds_bpermute_b32 v120, v139, v124
	ds_bpermute_b32 v121, v139, v125
	ds_bpermute_b32 v136, v139, v140
	ds_bpermute_b32 v142, v139, v126
	ds_bpermute_b32 v143, v139, v127
	ds_bpermute_b32 v137, v139, v141
	ds_bpermute_b32 v144, v139, v122
	ds_bpermute_b32 v145, v139, v123
	s_waitcnt lgkmcnt(6)
	v_pk_mul_f32 v[120:121], v[178:179], v[120:121]
	s_waitcnt lgkmcnt(3)
	v_pk_mul_f32 v[142:143], v[180:181], v[142:143]
	v_pk_fma_f32 v[124:125], v[124:125], v[132:133], v[120:121]
	s_waitcnt lgkmcnt(2)
	v_pk_mul_f32 v[120:121], v[176:177], v[136:137]
	s_waitcnt lgkmcnt(0)
	v_pk_mul_f32 v[136:137], v[174:175], v[144:145]
	v_pk_fma_f32 v[126:127], v[126:127], v[134:135], v[142:143]
	v_pk_fma_f32 v[122:123], v[122:123], v[130:131], v[136:137]
	v_pk_fma_f32 v[140:141], v[140:141], v[128:129], v[120:121]

; DI unsigned pk_bf16(float lo, float hi) { typedef float f2 __attribute__((ext_vector_type(2))); typedef __bf16 b2 __attribute__((ext_vector_type(2))); f2 v = {lo, hi}; b2 b = __builtin_convertvector(v, b2); return __builtin_bit_cast(unsigned, b); }
; DI float bf_lo(unsigned w) { return __uint_as_float(w << 16); }
; DI float bf_hi(unsigned w) { return __uint_as_float(w & 0xffff0000u); }
;     DI void operator()(const f32x4 (&acc)[2][2][4][2], const pg8::Unit& u, int wr, int wc, int fr, int fq) const {
;     ...
;                 const int row = row0 + ai * 128 + m * 16;
;                 const size_t off = (size_t)row * ldc + col0;
;                 const f32x4* pq = (const f32x4*)(partin + (size_t)row * 16); const f32x4 t4 = (pq[0] + pq[1]) + (pq[2] + pq[3]);
;                 const float rs = -1.0f / sqrtf(((t4.x + t4.y) + (t4.z + t4.w)) * (1.f / DM) + NORM_EPS);
;                 float ss = 0.f;
; #pragma unroll
;                 for (int bj = 0; bj < 2; ++bj) {
;                     const size_t o2 = off + bj * 128;
;                     const u32x4 pw = *(const u32x4*)(pp + o2), bw = *(const u32x4*)(base + o2);
;                     const f32x4 a0 = acc[ai][bj][m][0] * rs, a1 = acc[ai][bj][m][1] * rs;
;                     f32x4 r0, r1;
;                     r0[0] = bf_lo(bw.x) + bf_lo(pw.x) / (1.f + __expf(a0[0])); r0[1] = bf_hi(bw.x) + bf_hi(pw.x) / (1.f + __expf(a0[1]));
;                     r0[2] = bf_lo(bw.y) + bf_lo(pw.y) / (1.f + __expf(a0[2])); r0[3] = bf_hi(bw.y) + bf_hi(pw.y) / (1.f + __expf(a0[3]));
;                     r1[0] = bf_lo(bw.z) + bf_lo(pw.z) / (1.f + __expf(a1[0])); r1[1] = bf_hi(bw.z) + bf_hi(pw.z) / (1.f + __expf(a1[1]));
;                     r1[2] = bf_lo(bw.w) + bf_lo(pw.w) / (1.f + __expf(a1[2])); r1[3] = bf_hi(bw.w) + bf_hi(pw.w) / (1.f + __expf(a1[3]));
;                     u32x4 w; w.x = pk_bf16(r0[0], r0[1]); w.y = pk_bf16(r0[2], r0[3]); w.z = pk_bf16(r1[0], r1[1]); w.w = pk_bf16(r1[2], r1[3]);
;                     *(u32x4*)(hb + o2) = w;
.LBB0_1747:
	v_lshl_add_u32 v154, s10, 8, v158
	v_ashrrev_i32_e32 v155, 31, v154
	v_lshlrev_b64 v[128:129], 6, v[154:155]
	v_lshl_or_b32 v152, s8, 8, v160
	v_lshl_add_u64 v[128:129], s[22:23], 0, v[128:129]
	global_load_dwordx4 v[186:189], v[128:129], off
	global_load_dwordx4 v[190:193], v[128:129], off offset:16
	global_load_dwordx4 v[194:197], v[128:129], off offset:32
	global_load_dwordx4 v[198:201], v[128:129], off offset:48
	v_ashrrev_i32_e32 v153, 31, v152
	v_lshlrev_b64 v[128:129], 10, v[154:155]
	v_lshl_add_u64 v[128:129], v[128:129], 0, v[152:153]
	v_lshlrev_b64 v[156:157], 1, v[128:129]
	v_lshl_add_u64 v[128:129], s[16:17], 0, v[156:157]
	global_load_dwordx4 v[128:131], v[128:129], off
	v_lshl_add_u64 v[132:133], s[20:21], 0, v[156:157]
	global_load_dwordx4 v[132:135], v[132:133], off
	v_and_b32_e32 v181, 64, v177
	v_xor_b32_e32 v180, 16, v177
	v_add_u32_e32 v181, 64, v181
	v_xor_b32_e32 v182, 32, v177
	v_cmp_lt_i32_e32 vcc, v180, v181
	s_lshl_b32 s48, s8, 2
	s_ashr_i32 s49, s48, 31
	v_cndmask_b32_e32 v180, v177, v180, vcc
	v_cmp_lt_i32_e32 vcc, v182, v181
	v_lshlrev_b32_e32 v181, 2, v180
	s_waitcnt vmcnt(0)
	v_pk_add_f32 v[186:187], v[186:187], v[190:191]
	v_cndmask_b32_e32 v182, v177, v182, vcc
	v_lshlrev_b32_e32 v180, 2, v182
	v_pk_add_f32 v[182:183], v[188:189], v[192:193]
	v_pk_add_f32 v[188:189], v[196:197], v[200:201]
	v_pk_add_f32 v[190:191], v[194:195], v[198:199]
	v_pk_add_f32 v[182:183], v[182:183], v[188:189]
	v_pk_add_f32 v[186:187], v[186:187], v[190:191]
	v_lshlrev_b32_e32 v185, 16, v132
	v_pk_mov_b32 v[188:189], v[186:187], v[182:183] op_sel:[1,0]
	v_mov_b32_e32 v187, v183
	v_pk_add_f32 v[186:187], v[188:189], v[186:187]
	v_lshlrev_b32_e32 v182, 16, v128
	v_and_b32_e32 v183, 0xffff0000, v128
	v_add_f32_e32 v128, v186, v187
	v_fmamk_f32 v128, v128, 0x3a800000, v178
	v_and_b32_e32 v190, 0xffff0000, v132
	v_mul_f32_e32 v132, 0x4f800000, v128
	v_cmp_gt_f32_e32 vcc, s72, v128
	v_lshlrev_b32_e32 v186, 16, v129
	v_and_b32_e32 v187, 0xffff0000, v129
	v_cndmask_b32_e32 v128, v128, v132, vcc
	v_sqrt_f32_e32 v132, v128
	v_lshlrev_b32_e32 v129, 16, v133
	s_nop 1
	v_mul_f32_e32 v188, 0x37800000, v132
	v_cndmask_b32_e32 v132, v132, v188, vcc
	v_cmp_class_f32_e32 vcc, v128, v179
	v_and_b32_e32 v189, 0xffff0000, v133
	s_nop 0
	v_cndmask_b32_e32 v128, v132, v128, vcc
	v_rcp_f32_e32 v132, v128
	s_nop 0
	v_mul_f32_e32 v128, -1.0, v132
	v_pk_mul_f32 v[124:125], v[124:125], v[128:129] op_sel_hi:[1,0]
	v_pk_mul_f32 v[126:127], v[126:127], v[128:129] op_sel_hi:[1,0]
	v_mul_f32_e32 v124, 0x3fb8aa3b, v124
	v_mul_f32_e32 v125, 0x3fb8aa3b, v125
	v_mul_f32_e32 v126, 0x3fb8aa3b, v126
	v_mul_f32_e32 v127, 0x3fb8aa3b, v127
	v_exp_f32_e32 v124, v124
	v_exp_f32_e32 v125, v125
	v_exp_f32_e32 v126, v126
	v_exp_f32_e32 v127, v127
	v_pk_mul_f32 v[132:133], v[122:123], v[128:129] op_sel_hi:[1,0]
	v_pk_add_f32 v[122:123], v[124:125], 1.0 op_sel_hi:[1,0]
	v_pk_mul_f32 v[120:121], v[120:121], v[128:129] op_sel_hi:[1,0]
	v_pk_add_f32 v[124:125], v[126:127], 1.0 op_sel_hi:[1,0]
	v_div_scale_f32 v126, s[8:9], v123, v123, v190
	v_div_scale_f32 v188, s[8:9], v122, v122, v185
	v_rcp_f32_e32 v195, v126
	v_rcp_f32_e32 v196, v188
	v_div_scale_f32 v192, s[10:11], v125, v125, v189
	v_rcp_f32_e32 v197, v192
	v_fma_f32 v199, -v126, v195, 1.0
	v_div_scale_f32 v127, vcc, v190, v123, v190
	v_fma_f32 v200, -v188, v196, 1.0
	v_fmac_f32_e32 v195, v199, v195
	v_div_scale_f32 v191, s[8:9], v185, v122, v185
	v_fmac_f32_e32 v196, v200, v196
	v_mul_f32_e32 v199, v127, v195
	v_mul_f32_e32 v200, v191, v196
	v_fma_f32 v202, -v126, v199, v127
	v_div_scale_f32 v194, s[12:13], v124, v124, v129
	v_fma_f32 v201, -v192, v197, 1.0
	v_fma_f32 v203, -v188, v200, v191
	v_fmac_f32_e32 v199, v202, v195
	v_div_scale_f32 v193, s[10:11], v189, v125, v189
	v_rcp_f32_e32 v198, v194
	v_fmac_f32_e32 v197, v201, v197
	v_fmac_f32_e32 v200, v203, v196
	v_mul_f32_e32 v201, v193, v197
	v_fma_f32 v204, -v192, v201, v193
	v_rcp_f32_e32 v126, v123
	s_nop 0
	v_mul_f32_e32 v123, v190, v126
	v_fmac_f32_e32 v201, v204, v197
	v_rcp_f32_e32 v126, v122
	s_nop 0
	v_mul_f32_e32 v122, v185, v126
	v_fma_f32 v188, -v192, v201, v193
	v_pk_add_f32 v[126:127], v[122:123], v[182:183]
	v_fma_f32 v122, -v194, v198, 1.0
	v_fmac_f32_e32 v198, v122, v198
	v_div_scale_f32 v122, vcc, v129, v124, v129
	v_rcp_f32_e32 v185, v125
	s_nop 0
	v_mul_f32_e32 v123, v189, v185
	v_mul_f32_e32 v125, v122, v198
	v_mul_f32_e32 v120, 0x3fb8aa3b, v120
	v_mul_f32_e32 v121, 0x3fb8aa3b, v121
	v_fma_f32 v182, -v194, v125, v122
	v_exp_f32_e32 v120, v120
	v_exp_f32_e32 v121, v121
	v_fmac_f32_e32 v125, v182, v198
	v_rcp_f32_e32 v122, v124
	s_nop 0
	v_mul_f32_e32 v122, v129, v122
	v_and_b32_e32 v129, 0xffff0000, v134
	v_pk_add_f32 v[190:191], v[120:121], 1.0 op_sel_hi:[1,0]
	v_pk_add_f32 v[182:183], v[122:123], v[186:187]
	v_lshlrev_b32_e32 v192, 16, v130
	v_and_b32_e32 v193, 0xffff0000, v130
	v_lshlrev_b32_e32 v130, 16, v134
	v_lshl_add_u64 v[120:121], s[24:25], 0, v[156:157]
	v_or_b32_e32 v156, 0x100, v156
	v_lshl_add_u64 v[122:123], s[20:21], 0, v[156:157]
	global_load_dwordx4 v[122:125], v[122:123], off
	v_lshl_add_u64 v[186:187], s[16:17], 0, v[156:157]
	global_load_dwordx4 v[186:189], v[186:187], off
	v_rcp_f32_e32 v134, v191
	s_nop 0
	v_mul_f32_e32 v191, v129, v134
	v_mul_f32_e32 v132, 0x3fb8aa3b, v132
	v_mul_f32_e32 v133, 0x3fb8aa3b, v133
	v_exp_f32_e32 v132, v132
	v_exp_f32_e32 v133, v133
	v_rcp_f32_e32 v129, v190
	s_nop 0
	v_mul_f32_e32 v190, v130, v129
	v_and_b32_e32 v129, 0xffff0000, v135
	v_pk_add_f32 v[132:133], v[132:133], 1.0 op_sel_hi:[1,0]
	v_pk_add_f32 v[190:191], v[190:191], v[192:193]
	v_lshlrev_b32_e32 v135, 16, v135
	v_lshlrev_b32_e32 v130, 16, v131
	v_and_b32_e32 v131, 0xffff0000, v131
	v_div_scale_f32 v192, s[8:9], v132, v132, v135
	v_rcp_f32_e32 v194, v192
	v_rcp_f32_e32 v134, v133
	s_nop 0
	v_mul_f32_e32 v133, v129, v134
	v_fma_f32 v129, -v192, v194, 1.0
	v_fmac_f32_e32 v194, v129, v194
	v_div_scale_f32 v129, vcc, v135, v132, v135
	v_mul_f32_e32 v134, v129, v194
	v_fma_f32 v185, -v192, v134, v129
	v_fmac_f32_e32 v134, v185, v194
	v_fma_f32 v129, -v192, v134, v129
	v_div_fmas_f32 v129, v129, v194, v134
	v_pk_mul_f32 v[116:117], v[116:117], v[128:129] op_sel_hi:[1,0]
	v_rcp_f32_e32 v129, v132
	s_nop 0
	v_mul_f32_e32 v132, v135, v129
	v_mul_f32_e32 v116, 0x3fb8aa3b, v116
	v_mul_f32_e32 v117, 0x3fb8aa3b, v117
	v_exp_f32_e32 v116, v116
	v_exp_f32_e32 v117, v117
	v_pk_add_f32 v[134:135], v[132:133], v[130:131]
	v_pk_mul_f32 v[118:119], v[118:119], v[128:129] op_sel_hi:[1,0]
	v_pk_mul_f32 v[114:115], v[114:115], v[128:129] op_sel_hi:[1,0]
	v_pk_add_f32 v[116:117], v[116:117], 1.0 op_sel_hi:[1,0]
	v_pk_mul_f32 v[112:113], v[112:113], v[128:129] op_sel_hi:[1,0]
	v_mul_f32_e32 v118, 0x3fb8aa3b, v118
	v_mul_f32_e32 v119, 0x3fb8aa3b, v119
	v_exp_f32_e32 v118, v118
	v_exp_f32_e32 v119, v119
	v_mul_f32_e32 v112, 0x3fb8aa3b, v112
	v_mul_f32_e32 v113, 0x3fb8aa3b, v113
	v_exp_f32_e32 v112, v112
	v_pk_add_f32 v[118:119], v[118:119], 1.0 op_sel_hi:[1,0]
	v_exp_f32_e32 v113, v113
	s_waitcnt vmcnt(1)
; DI unsigned pk_bf16(float lo, float hi) { typedef float f2 __attribute__((ext_vector_type(2))); typedef __bf16 b2 __attribute__((ext_vector_type(2))); f2 v = {lo, hi}; b2 b = __builtin_convertvector(v, b2); return __builtin_bit_cast(unsigned, b); }
; DI float bf_lo(unsigned w) { return __uint_as_float(w << 16); }
; DI float bf_hi(unsigned w) { return __uint_as_float(w & 0xffff0000u); }
;     DI void operator()(const f32x4 (&acc)[2][2][4][2], const pg8::Unit& u, int wr, int wc, int fr, int fq) const {
;     ...
;                     const u32x4 pw = *(const u32x4*)(pp + o2), bw = *(const u32x4*)(base + o2);
;                     const f32x4 a0 = acc[ai][bj][m][0] * rs, a1 = acc[ai][bj][m][1] * rs;
;                     f32x4 r0, r1;
;                     r0[0] = bf_lo(bw.x) + bf_lo(pw.x) / (1.f + __expf(a0[0])); r0[1] = bf_hi(bw.x) + bf_hi(pw.x) / (1.f + __expf(a0[1]));
;                     r0[2] = bf_lo(bw.y) + bf_lo(pw.y) / (1.f + __expf(a0[2])); r0[3] = bf_hi(bw.y) + bf_hi(pw.y) / (1.f + __expf(a0[3]));
;                     r1[0] = bf_lo(bw.z) + bf_lo(pw.z) / (1.f + __expf(a1[0])); r1[1] = bf_hi(bw.z) + bf_hi(pw.z) / (1.f + __expf(a1[1]));
;                     r1[2] = bf_lo(bw.w) + bf_lo(pw.w) / (1.f + __expf(a1[2])); r1[3] = bf_hi(bw.w) + bf_hi(pw.w) / (1.f + __expf(a1[3]));
;                     u32x4 w; w.x = pk_bf16(r0[0], r0[1]); w.y = pk_bf16(r0[2], r0[3]); w.z = pk_bf16(r1[0], r1[1]); w.w = pk_bf16(r1[2], r1[3]);
;                     *(u32x4*)(hb + o2) = w;
;                     ss += ((r0[0] * r0[0] + r0[1] * r0[1]) + (r0[2] * r0[2] + r0[3] * r0[3])) + ((r1[0] * r1[0] + r1[1] * r1[1]) + (r1[2] * r1[2] + r1[3] * r1[3]));
;                 }
;                 ss += __shfl_xor(ss, 16); ss += __shfl_xor(ss, 32);
;                 if (fq == 0) part[(size_t)row * 16 + u.pn * 4 + wc] = ss;
	v_and_b32_e32 v133, 0xffff0000, v122
	v_div_scale_f32 v185, s[8:9], v117, v117, v133
	v_rcp_f32_e32 v194, v185
	s_waitcnt vmcnt(0)
	v_lshlrev_b32_e32 v128, 16, v186
	v_and_b32_e32 v129, 0xffff0000, v186
	v_lshlrev_b32_e32 v122, 16, v122
	v_fma_f32 v186, -v185, v194, 1.0
	v_fmac_f32_e32 v194, v186, v194
	v_div_scale_f32 v186, vcc, v133, v117, v133
	v_mul_f32_e32 v195, v186, v194
	v_fma_f32 v196, -v185, v195, v186
	v_fmac_f32_e32 v195, v196, v194
	v_div_scale_f32 v186, s[8:9], v116, v116, v122
	v_rcp_f32_e32 v196, v186
	v_rcp_f32_e32 v185, v117
	s_nop 0
	v_mul_f32_e32 v117, v133, v185
	v_pk_add_f32 v[112:113], v[112:113], 1.0 op_sel_hi:[1,0]
	v_fma_f32 v133, -v186, v196, 1.0
	v_fmac_f32_e32 v196, v133, v196
	v_rcp_f32_e32 v133, v116
	s_nop 0
	v_mul_f32_e32 v116, v122, v133
	v_and_b32_e32 v122, 0xffff0000, v123
	v_pk_add_f32 v[116:117], v[116:117], v[128:129]
	v_lshlrev_b32_e32 v128, 16, v187
	v_and_b32_e32 v129, 0xffff0000, v187
	v_lshlrev_b32_e32 v123, 16, v123
	v_div_scale_f32 v186, s[8:9], v118, v118, v123
	v_rcp_f32_e32 v194, v186
	v_rcp_f32_e32 v133, v119
	s_nop 0
	v_mul_f32_e32 v119, v122, v133
	v_mul_f32_e32 v114, 0x3fb8aa3b, v114
	v_fma_f32 v122, -v186, v194, 1.0
	v_fmac_f32_e32 v194, v122, v194
	v_rcp_f32_e32 v122, v118
	s_nop 0
	v_mul_f32_e32 v118, v123, v122
	v_pk_add_f32 v[118:119], v[118:119], v[128:129]
	v_and_b32_e32 v128, 0xffff0000, v124
	v_lshlrev_b32_e32 v124, 16, v124
	v_mul_f32_e32 v115, 0x3fb8aa3b, v115
	v_exp_f32_e32 v114, v114
	v_rcp_f32_e32 v129, v113
	s_nop 0
	v_mul_f32_e32 v113, v128, v129
	v_exp_f32_e32 v115, v115
	v_lshlrev_b32_e32 v122, 16, v188
	v_and_b32_e32 v123, 0xffff0000, v188
	v_rcp_f32_e32 v128, v112
	s_nop 0
	v_mul_f32_e32 v112, v124, v128
	v_pk_add_f32 v[122:123], v[112:113], v[122:123]
	v_and_b32_e32 v124, 0xffff0000, v125
	v_pk_add_f32 v[112:113], v[114:115], 1.0 op_sel_hi:[1,0]
	v_lshlrev_b32_e32 v125, 16, v125
	v_div_scale_f32 v128, s[8:9], v113, v113, v124
	v_rcp_f32_e32 v129, v128
	v_lshlrev_b32_e32 v114, 16, v189
	v_and_b32_e32 v115, 0xffff0000, v189
	v_cvt_pk_bf16_f32 v132, v190, v191
	v_fma_f32 v133, -v128, v129, 1.0
	v_fmac_f32_e32 v129, v133, v129
	v_div_scale_f32 v133, vcc, v124, v113, v124
	v_mul_f32_e32 v185, v133, v129
	v_fma_f32 v186, -v128, v185, v133
	v_fmac_f32_e32 v185, v186, v129
	v_div_scale_f32 v133, s[8:9], v112, v112, v125
	v_rcp_f32_e32 v128, v113
	s_nop 0
	v_mul_f32_e32 v113, v124, v128
	v_pk_mul_f32 v[190:191], v[190:191], v[190:191]
	v_div_scale_f32 v124, vcc, v125, v112, v125
	v_rcp_f32_e32 v124, v112
	s_nop 0
	v_mul_f32_e32 v112, v125, v124
	v_pk_add_f32 v[124:125], v[112:113], v[114:115]
	v_pk_mul_f32 v[112:113], v[116:117], v[116:117]
	v_pk_mul_f32 v[114:115], v[118:119], v[118:119]
	v_pk_mul_f32 v[192:193], v[134:135], v[134:135]
	v_add_f32_e32 v114, v114, v115
	v_add_f32_e32 v112, v112, v113
	v_cvt_pk_bf16_f32 v130, v126, v127
	v_cvt_pk_bf16_f32 v131, v182, v183
	v_pk_mul_f32 v[126:127], v[126:127], v[126:127]
	v_pk_mul_f32 v[182:183], v[182:183], v[182:183]
	v_pk_mul_f32 v[128:129], v[122:123], v[122:123]
	v_pk_mul_f32 v[186:187], v[124:125], v[124:125]
	v_add_f32_e32 v112, v112, v114
	v_add_f32_e32 v113, v192, v193
	v_add_f32_e32 v114, v190, v191
	v_add_f32_e32 v133, v186, v187
	v_add_f32_e32 v128, v128, v129
	v_add_f32_e32 v113, v114, v113
	v_add_f32_e32 v114, v182, v183
	v_add_f32_e32 v115, v126, v127
	v_add_f32_e32 v128, v128, v133
	v_add_f32_e32 v114, v115, v114
	v_add_f32_e32 v112, v112, v128
	v_add_f32_e32 v113, v114, v113
	v_add_f32_e32 v112, v113, v112
	ds_bpermute_b32 v113, v181, v112
	v_cvt_pk_bf16_f32 v133, v134, v135
	v_cvt_pk_bf16_f32 v114, v116, v117
	v_cvt_pk_bf16_f32 v115, v118, v119
	v_cvt_pk_bf16_f32 v116, v122, v123
	s_waitcnt lgkmcnt(0)
	v_add_f32_e32 v112, v112, v113
	ds_bpermute_b32 v113, v180, v112
	v_cvt_pk_bf16_f32 v117, v124, v125
	v_lshl_add_u64 v[118:119], s[24:25], 0, v[156:157]
	global_store_dwordx4 v[120:121], v[130:133], off
	global_store_dwordx4 v[118:119], v[114:117], off
	s_and_saveexec_b64 s[8:9], s[4:5]
	s_cbranch_execz .LBB0_1749
	v_lshlrev_b64 v[114:115], 4, v[154:155]
	s_waitcnt lgkmcnt(0)
	v_add_f32_e32 v116, v112, v113
	v_lshl_add_u64 v[112:113], v[114:115], 2, s[26:27]
	v_lshl_add_u64 v[112:113], s[48:49], 2, v[112:113]
	s_lshl_b32 s34, s61, 2
	v_lshl_add_u64 v[112:113], v[112:113], 0, s[34:35]
	global_store_dword v[112:113], v116, off
; DI unsigned pk_bf16(float lo, float hi) { typedef float f2 __attribute__((ext_vector_type(2))); typedef __bf16 b2 __attribute__((ext_vector_type(2))); f2 v = {lo, hi}; b2 b = __builtin_convertvector(v, b2); return __builtin_bit_cast(unsigned, b); }
; DI float bf_lo(unsigned w) { return __uint_as_float(w << 16); }
; DI float bf_hi(unsigned w) { return __uint_as_float(w & 0xffff0000u); }
;     DI void operator()(const f32x4 (&acc)[2][2][4][2], const pg8::Unit& u, int wr, int wc, int fr, int fq) const {
;     ...
;                 const int row = row0 + ai * 128 + m * 16;
;                 const size_t off = (size_t)row * ldc + col0;
;                 const f32x4* pq = (const f32x4*)(partin + (size_t)row * 16); const f32x4 t4 = (pq[0] + pq[1]) + (pq[2] + pq[3]);
;                 const float rs = -1.0f / sqrtf(((t4.x + t4.y) + (t4.z + t4.w)) * (1.f / DM) + NORM_EPS);
;                 float ss = 0.f;
; #pragma unroll
;                 for (int bj = 0; bj < 2; ++bj) {
;                     const size_t o2 = off + bj * 128;
;                     const u32x4 pw = *(const u32x4*)(pp + o2), bw = *(const u32x4*)(base + o2);
;                     const f32x4 a0 = acc[ai][bj][m][0] * rs, a1 = acc[ai][bj][m][1] * rs;
;                     f32x4 r0, r1;
;                     r0[0] = bf_lo(bw.x) + bf_lo(pw.x) / (1.f + __expf(a0[0])); r0[1] = bf_hi(bw.x) + bf_hi(pw.x) / (1.f + __expf(a0[1]));
;                     r0[2] = bf_lo(bw.y) + bf_lo(pw.y) / (1.f + __expf(a0[2])); r0[3] = bf_hi(bw.y) + bf_hi(pw.y) / (1.f + __expf(a0[3]));
;                     r1[0] = bf_lo(bw.z) + bf_lo(pw.z) / (1.f + __expf(a1[0])); r1[1] = bf_hi(bw.z) + bf_hi(pw.z) / (1.f + __expf(a1[1]));
;                     r1[2] = bf_lo(bw.w) + bf_lo(pw.w) / (1.f + __expf(a1[2])); r1[3] = bf_hi(bw.w) + bf_hi(pw.w) / (1.f + __expf(a1[3]));
;                     u32x4 w; w.x = pk_bf16(r0[0], r0[1]); w.y = pk_bf16(r0[2], r0[3]); w.z = pk_bf16(r1[0], r1[1]); w.w = pk_bf16(r1[2], r1[3]);
;                     *(u32x4*)(hb + o2) = w;
.LBB0_1749:
	s_or_b64 exec, exec, s[8:9]
	v_or_b32_e32 v120, 16, v154
	v_ashrrev_i32_e32 v121, 31, v120
	s_waitcnt lgkmcnt(0)
	v_lshlrev_b64 v[112:113], 6, v[120:121]
	v_lshl_add_u64 v[112:113], s[22:23], 0, v[112:113]
	global_load_dwordx4 v[124:127], v[112:113], off
	global_load_dwordx4 v[128:131], v[112:113], off offset:16
	global_load_dwordx4 v[132:135], v[112:113], off offset:32
	global_load_dwordx4 v[186:189], v[112:113], off offset:48
	v_lshlrev_b64 v[112:113], 10, v[120:121]
	v_lshl_add_u64 v[112:113], v[112:113], 0, v[152:153]
	v_lshlrev_b64 v[122:123], 1, v[112:113]
	v_lshl_add_u64 v[112:113], s[16:17], 0, v[122:123]
	global_load_dwordx4 v[112:115], v[112:113], off
	v_lshl_add_u64 v[116:117], s[20:21], 0, v[122:123]
	global_load_dwordx4 v[116:119], v[116:117], off
	s_waitcnt vmcnt(4)
	v_pk_add_f32 v[126:127], v[126:127], v[130:131]
	v_pk_add_f32 v[124:125], v[124:125], v[128:129]
	s_waitcnt vmcnt(2)
	v_pk_add_f32 v[128:129], v[134:135], v[188:189]
	v_pk_add_f32 v[130:131], v[132:133], v[186:187]
	v_pk_add_f32 v[126:127], v[126:127], v[128:129]
	v_pk_add_f32 v[124:125], v[124:125], v[130:131]
	s_waitcnt vmcnt(0)
	v_lshlrev_b32_e32 v130, 16, v116
	v_pk_mov_b32 v[128:129], v[124:125], v[126:127] op_sel:[1,0]
	v_mov_b32_e32 v125, v127
	v_pk_add_f32 v[124:125], v[128:129], v[124:125]
	v_lshlrev_b32_e32 v126, 16, v112
	v_and_b32_e32 v127, 0xffff0000, v112
	v_add_f32_e32 v112, v124, v125
	v_fmamk_f32 v112, v112, 0x3a800000, v178
	v_and_b32_e32 v131, 0xffff0000, v116
	v_mul_f32_e32 v116, 0x4f800000, v112
	v_cmp_gt_f32_e32 vcc, s72, v112
	v_lshlrev_b32_e32 v124, 16, v113
	v_and_b32_e32 v125, 0xffff0000, v113
	v_cndmask_b32_e32 v112, v112, v116, vcc
	v_sqrt_f32_e32 v116, v112
	v_lshlrev_b32_e32 v113, 16, v117
	s_nop 1
	v_mul_f32_e32 v128, 0x37800000, v116
	v_cndmask_b32_e32 v116, v116, v128, vcc
	v_cmp_class_f32_e32 vcc, v112, v179
	v_and_b32_e32 v129, 0xffff0000, v117
	s_nop 0
	v_cndmask_b32_e32 v112, v116, v112, vcc
	v_rcp_f32_e32 v116, v112
	s_nop 0
	v_mul_f32_e32 v112, -1.0, v116
	v_pk_mul_f32 v[108:109], v[108:109], v[112:113] op_sel_hi:[1,0]
	v_pk_mul_f32 v[110:111], v[110:111], v[112:113] op_sel_hi:[1,0]
	v_pk_mul_f32 v[116:117], v[106:107], v[112:113] op_sel_hi:[1,0]
	v_pk_mul_f32 v[104:105], v[104:105], v[112:113] op_sel_hi:[1,0]
	v_mul_f32_e32 v106, 0x3fb8aa3b, v108
	v_mul_f32_e32 v107, 0x3fb8aa3b, v109
	v_mul_f32_e32 v108, 0x3fb8aa3b, v110
	v_mul_f32_e32 v109, 0x3fb8aa3b, v111
	v_mul_f32_e32 v110, 0x3fb8aa3b, v104
	v_mul_f32_e32 v111, 0x3fb8aa3b, v105
	v_exp_f32_e32 v104, v106
	v_exp_f32_e32 v105, v107
	v_exp_f32_e32 v106, v108
	v_exp_f32_e32 v107, v109
	v_exp_f32_e32 v108, v110
	v_pk_add_f32 v[104:105], v[104:105], 1.0 op_sel_hi:[1,0]
	v_exp_f32_e32 v109, v111
	v_div_scale_f32 v110, s[8:9], v105, v105, v131
	v_pk_add_f32 v[106:107], v[106:107], 1.0 op_sel_hi:[1,0]
	v_div_scale_f32 v128, s[8:9], v104, v104, v130
	v_rcp_f32_e32 v156, v110
	v_div_scale_f32 v133, s[10:11], v107, v107, v129
	v_rcp_f32_e32 v157, v128
	v_div_scale_f32 v135, s[12:13], v106, v106, v113
	v_rcp_f32_e32 v182, v133
	v_rcp_f32_e32 v183, v135
	v_fma_f32 v185, -v110, v156, 1.0
	v_div_scale_f32 v111, vcc, v131, v105, v131
	v_fma_f32 v186, -v128, v157, 1.0
	v_fmac_f32_e32 v156, v185, v156
	v_div_scale_f32 v132, s[8:9], v130, v104, v130
	v_fma_f32 v187, -v133, v182, 1.0
	v_fmac_f32_e32 v157, v186, v157
	v_mul_f32_e32 v185, v111, v156
	v_div_scale_f32 v134, s[10:11], v129, v107, v129
	v_fma_f32 v188, -v135, v183, 1.0
	v_fmac_f32_e32 v182, v187, v182
	v_mul_f32_e32 v186, v132, v157
	v_fma_f32 v189, -v110, v185, v111
	v_div_scale_f32 v155, s[12:13], v113, v106, v113
	v_fmac_f32_e32 v183, v188, v183
	v_mul_f32_e32 v187, v134, v182
	v_fma_f32 v190, -v128, v186, v132
	v_fmac_f32_e32 v185, v189, v156
	v_mul_f32_e32 v188, v155, v183
	v_fma_f32 v191, -v133, v187, v134
	v_fmac_f32_e32 v186, v190, v157
	v_fma_f32 v192, -v135, v188, v155
	v_fmac_f32_e32 v187, v191, v182
	v_fmac_f32_e32 v188, v192, v183
	v_rcp_f32_e32 v110, v105
	s_nop 0
	v_mul_f32_e32 v105, v131, v110
	v_rcp_f32_e32 v110, v104
	s_nop 0
	v_mul_f32_e32 v104, v130, v110
	s_mov_b64 vcc, s[12:13]
	v_pk_add_f32 v[110:111], v[104:105], v[126:127]
	v_rcp_f32_e32 v104, v106
	s_nop 0
	v_mul_f32_e32 v104, v113, v104
	v_and_b32_e32 v113, 0xffff0000, v118
	v_pk_add_f32 v[130:131], v[108:109], 1.0 op_sel_hi:[1,0]
	v_rcp_f32_e32 v128, v107
	s_nop 0
	v_mul_f32_e32 v105, v129, v128
	v_pk_add_f32 v[128:129], v[104:105], v[124:125]
	v_lshlrev_b32_e32 v132, 16, v114
	v_and_b32_e32 v133, 0xffff0000, v114
	v_lshl_add_u64 v[104:105], s[24:25], 0, v[122:123]
	v_or_b32_e32 v122, 0x100, v122
	v_lshl_add_u64 v[106:107], s[20:21], 0, v[122:123]
	global_load_dwordx4 v[106:109], v[106:107], off
	v_lshl_add_u64 v[124:125], s[16:17], 0, v[122:123]
	global_load_dwordx4 v[124:127], v[124:125], off
	v_lshlrev_b32_e32 v114, 16, v118
	v_rcp_f32_e32 v118, v131
	s_nop 0
	v_mul_f32_e32 v131, v113, v118
	v_mul_f32_e32 v116, 0x3fb8aa3b, v116
	v_mul_f32_e32 v117, 0x3fb8aa3b, v117
	v_exp_f32_e32 v116, v116
	v_exp_f32_e32 v117, v117
	v_rcp_f32_e32 v113, v130
	s_nop 0
	v_mul_f32_e32 v130, v114, v113
	v_and_b32_e32 v113, 0xffff0000, v119
	v_pk_add_f32 v[116:117], v[116:117], 1.0 op_sel_hi:[1,0]
	v_pk_add_f32 v[130:131], v[130:131], v[132:133]
	v_lshlrev_b32_e32 v119, 16, v119
	v_lshlrev_b32_e32 v114, 16, v115
	v_and_b32_e32 v115, 0xffff0000, v115
	v_div_scale_f32 v133, s[8:9], v116, v116, v119
	v_rcp_f32_e32 v135, v133
	v_rcp_f32_e32 v118, v117
	s_nop 0
	v_mul_f32_e32 v117, v113, v118
	v_fma_f32 v113, -v133, v135, 1.0
	v_fmac_f32_e32 v135, v113, v135
	v_div_scale_f32 v113, vcc, v119, v116, v119
	v_mul_f32_e32 v118, v113, v135
	v_fma_f32 v132, -v133, v118, v113
	v_fmac_f32_e32 v118, v132, v135
	v_fma_f32 v113, -v133, v118, v113
	v_div_fmas_f32 v113, v113, v135, v118
	v_pk_mul_f32 v[100:101], v[100:101], v[112:113] op_sel_hi:[1,0]
	v_rcp_f32_e32 v113, v116
	s_nop 0
	v_mul_f32_e32 v116, v119, v113
	v_mul_f32_e32 v100, 0x3fb8aa3b, v100
	v_mul_f32_e32 v101, 0x3fb8aa3b, v101
	v_exp_f32_e32 v100, v100
	v_exp_f32_e32 v101, v101
	v_pk_add_f32 v[118:119], v[116:117], v[114:115]
	v_pk_mul_f32 v[102:103], v[102:103], v[112:113] op_sel_hi:[1,0]
	v_pk_mul_f32 v[98:99], v[98:99], v[112:113] op_sel_hi:[1,0]
	v_pk_add_f32 v[100:101], v[100:101], 1.0 op_sel_hi:[1,0]
	v_pk_mul_f32 v[96:97], v[96:97], v[112:113] op_sel_hi:[1,0]
	v_mul_f32_e32 v102, 0x3fb8aa3b, v102
	v_mul_f32_e32 v103, 0x3fb8aa3b, v103
	v_exp_f32_e32 v102, v102
	v_exp_f32_e32 v103, v103
	v_mul_f32_e32 v96, 0x3fb8aa3b, v96
	v_mul_f32_e32 v97, 0x3fb8aa3b, v97
	v_exp_f32_e32 v96, v96
	v_pk_add_f32 v[102:103], v[102:103], 1.0 op_sel_hi:[1,0]
	s_waitcnt vmcnt(1)
; DI unsigned pk_bf16(float lo, float hi) { typedef float f2 __attribute__((ext_vector_type(2))); typedef __bf16 b2 __attribute__((ext_vector_type(2))); f2 v = {lo, hi}; b2 b = __builtin_convertvector(v, b2); return __builtin_bit_cast(unsigned, b); }
; DI float bf_lo(unsigned w) { return __uint_as_float(w << 16); }
; DI float bf_hi(unsigned w) { return __uint_as_float(w & 0xffff0000u); }
;     DI void operator()(const f32x4 (&acc)[2][2][4][2], const pg8::Unit& u, int wr, int wc, int fr, int fq) const {
;     ...
;                     const u32x4 pw = *(const u32x4*)(pp + o2), bw = *(const u32x4*)(base + o2);
;                     const f32x4 a0 = acc[ai][bj][m][0] * rs, a1 = acc[ai][bj][m][1] * rs;
;                     f32x4 r0, r1;
;                     r0[0] = bf_lo(bw.x) + bf_lo(pw.x) / (1.f + __expf(a0[0])); r0[1] = bf_hi(bw.x) + bf_hi(pw.x) / (1.f + __expf(a0[1]));
;                     r0[2] = bf_lo(bw.y) + bf_lo(pw.y) / (1.f + __expf(a0[2])); r0[3] = bf_hi(bw.y) + bf_hi(pw.y) / (1.f + __expf(a0[3]));
;                     r1[0] = bf_lo(bw.z) + bf_lo(pw.z) / (1.f + __expf(a1[0])); r1[1] = bf_hi(bw.z) + bf_hi(pw.z) / (1.f + __expf(a1[1]));
;                     r1[2] = bf_lo(bw.w) + bf_lo(pw.w) / (1.f + __expf(a1[2])); r1[3] = bf_hi(bw.w) + bf_hi(pw.w) / (1.f + __expf(a1[3]));
;                     u32x4 w; w.x = pk_bf16(r0[0], r0[1]); w.y = pk_bf16(r0[2], r0[3]); w.z = pk_bf16(r1[0], r1[1]); w.w = pk_bf16(r1[2], r1[3]);
;                     *(u32x4*)(hb + o2) = w;
;                     ss += ((r0[0] * r0[0] + r0[1] * r0[1]) + (r0[2] * r0[2] + r0[3] * r0[3])) + ((r1[0] * r1[0] + r1[1] * r1[1]) + (r1[2] * r1[2] + r1[3] * r1[3]));
;                 }
;                 ss += __shfl_xor(ss, 16); ss += __shfl_xor(ss, 32);
;                 if (fq == 0) part[(size_t)row * 16 + u.pn * 4 + wc] = ss;
	v_and_b32_e32 v117, 0xffff0000, v106
	v_div_scale_f32 v134, s[8:9], v101, v101, v117
	v_rcp_f32_e32 v135, v134
	s_waitcnt vmcnt(0)
	v_lshlrev_b32_e32 v112, 16, v124
	v_and_b32_e32 v113, 0xffff0000, v124
	v_lshlrev_b32_e32 v106, 16, v106
	v_fma_f32 v124, -v134, v135, 1.0
	v_fmac_f32_e32 v135, v124, v135
	v_div_scale_f32 v124, vcc, v117, v101, v117
	v_mul_f32_e32 v155, v124, v135
	v_fma_f32 v156, -v134, v155, v124
	v_fmac_f32_e32 v155, v156, v135
	v_div_scale_f32 v134, s[8:9], v100, v100, v106
	v_rcp_f32_e32 v156, v134
	v_rcp_f32_e32 v124, v101
	s_nop 0
	v_mul_f32_e32 v101, v117, v124
	v_exp_f32_e32 v97, v97
	v_fma_f32 v117, -v134, v156, 1.0
	v_fmac_f32_e32 v156, v117, v156
	v_rcp_f32_e32 v117, v100
	s_nop 0
	v_mul_f32_e32 v100, v106, v117
	v_and_b32_e32 v106, 0xffff0000, v107
	v_div_scale_f32 v117, s[8:9], v103, v103, v106
	v_rcp_f32_e32 v124, v117
	v_pk_add_f32 v[100:101], v[100:101], v[112:113]
	v_lshlrev_b32_e32 v112, 16, v125
	v_and_b32_e32 v113, 0xffff0000, v125
	v_fma_f32 v125, -v117, v124, 1.0
	v_fmac_f32_e32 v124, v125, v124
	v_div_scale_f32 v125, vcc, v106, v103, v106
	v_mul_f32_e32 v134, v125, v124
	v_fma_f32 v135, -v117, v134, v125
	v_lshlrev_b32_e32 v107, 16, v107
	v_fmac_f32_e32 v134, v135, v124
	v_div_scale_f32 v125, s[8:9], v102, v102, v107
	v_rcp_f32_e32 v135, v125
	v_rcp_f32_e32 v117, v103
	s_nop 0
	v_mul_f32_e32 v103, v106, v117
	v_pk_add_f32 v[96:97], v[96:97], 1.0 op_sel_hi:[1,0]
	v_fma_f32 v106, -v125, v135, 1.0
	v_fmac_f32_e32 v135, v106, v135
	v_rcp_f32_e32 v106, v102
	s_nop 0
	v_mul_f32_e32 v102, v107, v106
	v_pk_add_f32 v[102:103], v[102:103], v[112:113]
	v_and_b32_e32 v112, 0xffff0000, v108
	v_lshlrev_b32_e32 v106, 16, v126
	v_and_b32_e32 v107, 0xffff0000, v126
	v_lshlrev_b32_e32 v108, 16, v108
	v_div_scale_f32 v124, s[8:9], v96, v96, v108
	v_rcp_f32_e32 v126, v124
	v_rcp_f32_e32 v113, v97
	s_nop 0
	v_mul_f32_e32 v97, v112, v113
	v_mul_f32_e32 v98, 0x3fb8aa3b, v98
	v_fma_f32 v112, -v124, v126, 1.0
	v_fmac_f32_e32 v126, v112, v126
	v_mul_f32_e32 v99, 0x3fb8aa3b, v99
	v_exp_f32_e32 v98, v98
	v_exp_f32_e32 v99, v99
	v_rcp_f32_e32 v112, v96
	s_nop 0
	v_mul_f32_e32 v96, v108, v112
	v_pk_add_f32 v[106:107], v[96:97], v[106:107]
	v_and_b32_e32 v108, 0xffff0000, v109
	v_pk_add_f32 v[96:97], v[98:99], 1.0 op_sel_hi:[1,0]
	v_lshlrev_b32_e32 v109, 16, v109
	v_lshlrev_b32_e32 v98, 16, v127
	v_and_b32_e32 v99, 0xffff0000, v127
	v_cvt_pk_bf16_f32 v116, v130, v131
	v_div_scale_f32 v117, s[8:9], v96, v96, v109
	v_rcp_f32_e32 v112, v97
	s_nop 0
	v_mul_f32_e32 v97, v108, v112
	v_pk_mul_f32 v[130:131], v[130:131], v[130:131]
	v_div_scale_f32 v108, vcc, v109, v96, v109
	v_rcp_f32_e32 v108, v96
	s_nop 0
	v_mul_f32_e32 v96, v109, v108
	v_pk_add_f32 v[108:109], v[96:97], v[98:99]
	v_pk_mul_f32 v[96:97], v[100:101], v[100:101]
	v_pk_mul_f32 v[98:99], v[102:103], v[102:103]
	v_pk_mul_f32 v[132:133], v[118:119], v[118:119]
	v_add_f32_e32 v98, v98, v99
	v_add_f32_e32 v96, v96, v97
	v_cvt_pk_bf16_f32 v114, v110, v111
	v_cvt_pk_bf16_f32 v115, v128, v129
	v_pk_mul_f32 v[110:111], v[110:111], v[110:111]
	v_pk_mul_f32 v[128:129], v[128:129], v[128:129]
	v_pk_mul_f32 v[112:113], v[106:107], v[106:107]
	v_pk_mul_f32 v[124:125], v[108:109], v[108:109]
	v_add_f32_e32 v96, v96, v98
	v_add_f32_e32 v97, v132, v133
	v_add_f32_e32 v98, v130, v131
	v_add_f32_e32 v117, v124, v125
	v_add_f32_e32 v112, v112, v113
	v_add_f32_e32 v97, v98, v97
	v_add_f32_e32 v98, v128, v129
	v_add_f32_e32 v99, v110, v111
	v_add_f32_e32 v112, v112, v117
	v_add_f32_e32 v98, v99, v98
	v_add_f32_e32 v96, v96, v112
	v_add_f32_e32 v97, v98, v97
	v_add_f32_e32 v96, v97, v96
	ds_bpermute_b32 v97, v181, v96
	v_cvt_pk_bf16_f32 v117, v118, v119
	v_cvt_pk_bf16_f32 v98, v100, v101
	v_cvt_pk_bf16_f32 v99, v102, v103
	v_cvt_pk_bf16_f32 v100, v106, v107
	s_waitcnt lgkmcnt(0)
	v_add_f32_e32 v96, v96, v97
	ds_bpermute_b32 v97, v180, v96
	v_cvt_pk_bf16_f32 v101, v108, v109
	v_lshl_add_u64 v[102:103], s[24:25], 0, v[122:123]
	global_store_dwordx4 v[104:105], v[114:117], off
	global_store_dwordx4 v[102:103], v[98:101], off
	s_and_saveexec_b64 s[8:9], s[4:5]
	s_cbranch_execz .LBB0_1751
	v_lshlrev_b64 v[98:99], 4, v[120:121]
	s_waitcnt lgkmcnt(0)
	v_add_f32_e32 v100, v96, v97
	v_lshl_add_u64 v[96:97], v[98:99], 2, s[26:27]
	v_lshl_add_u64 v[96:97], s[48:49], 2, v[96:97]
	s_lshl_b32 s34, s61, 2
	v_lshl_add_u64 v[96:97], v[96:97], 0, s[34:35]
	global_store_dword v[96:97], v100, off
; DI unsigned pk_bf16(float lo, float hi) { typedef float f2 __attribute__((ext_vector_type(2))); typedef __bf16 b2 __attribute__((ext_vector_type(2))); f2 v = {lo, hi}; b2 b = __builtin_convertvector(v, b2); return __builtin_bit_cast(unsigned, b); }
; DI float bf_lo(unsigned w) { return __uint_as_float(w << 16); }
; DI float bf_hi(unsigned w) { return __uint_as_float(w & 0xffff0000u); }
;     DI void operator()(const f32x4 (&acc)[2][2][4][2], const pg8::Unit& u, int wr, int wc, int fr, int fq) const {
;     ...
;                 const int row = row0 + ai * 128 + m * 16;
;                 const size_t off = (size_t)row * ldc + col0;
;                 const f32x4* pq = (const f32x4*)(partin + (size_t)row * 16); const f32x4 t4 = (pq[0] + pq[1]) + (pq[2] + pq[3]);
;                 const float rs = -1.0f / sqrtf(((t4.x + t4.y) + (t4.z + t4.w)) * (1.f / DM) + NORM_EPS);
;                 float ss = 0.f;
; #pragma unroll
;                 for (int bj = 0; bj < 2; ++bj) {
;                     const size_t o2 = off + bj * 128;
;                     const u32x4 pw = *(const u32x4*)(pp + o2), bw = *(const u32x4*)(base + o2);
;                     const f32x4 a0 = acc[ai][bj][m][0] * rs, a1 = acc[ai][bj][m][1] * rs;
;                     f32x4 r0, r1;
;                     r0[0] = bf_lo(bw.x) + bf_lo(pw.x) / (1.f + __expf(a0[0])); r0[1] = bf_hi(bw.x) + bf_hi(pw.x) / (1.f + __expf(a0[1]));
;                     r0[2] = bf_lo(bw.y) + bf_lo(pw.y) / (1.f + __expf(a0[2])); r0[3] = bf_hi(bw.y) + bf_hi(pw.y) / (1.f + __expf(a0[3]));
;                     r1[0] = bf_lo(bw.z) + bf_lo(pw.z) / (1.f + __expf(a1[0])); r1[1] = bf_hi(bw.z) + bf_hi(pw.z) / (1.f + __expf(a1[1]));
;                     r1[2] = bf_lo(bw.w) + bf_lo(pw.w) / (1.f + __expf(a1[2])); r1[3] = bf_hi(bw.w) + bf_hi(pw.w) / (1.f + __expf(a1[3]));
;                     u32x4 w; w.x = pk_bf16(r0[0], r0[1]); w.y = pk_bf16(r0[2], r0[3]); w.z = pk_bf16(r1[0], r1[1]); w.w = pk_bf16(r1[2], r1[3]);
;                     *(u32x4*)(hb + o2) = w;
.LBB0_1751:
	s_or_b64 exec, exec, s[8:9]
	v_or_b32_e32 v104, 32, v154
	v_ashrrev_i32_e32 v105, 31, v104
	s_waitcnt lgkmcnt(0)
	v_lshlrev_b64 v[96:97], 6, v[104:105]
	v_lshl_add_u64 v[96:97], s[22:23], 0, v[96:97]
	global_load_dwordx4 v[108:111], v[96:97], off
	global_load_dwordx4 v[112:115], v[96:97], off offset:16
	global_load_dwordx4 v[116:119], v[96:97], off offset:32
	global_load_dwordx4 v[120:123], v[96:97], off offset:48
	v_lshlrev_b64 v[96:97], 10, v[104:105]
	v_lshl_add_u64 v[96:97], v[96:97], 0, v[152:153]
	v_lshlrev_b64 v[106:107], 1, v[96:97]
	v_lshl_add_u64 v[96:97], s[16:17], 0, v[106:107]
	global_load_dwordx4 v[96:99], v[96:97], off
	v_lshl_add_u64 v[100:101], s[20:21], 0, v[106:107]
	global_load_dwordx4 v[100:103], v[100:101], off
	s_waitcnt vmcnt(4)
	v_pk_add_f32 v[110:111], v[110:111], v[114:115]
	v_pk_add_f32 v[108:109], v[108:109], v[112:113]
	s_waitcnt vmcnt(2)
	v_pk_add_f32 v[112:113], v[118:119], v[122:123]
	v_pk_add_f32 v[114:115], v[116:117], v[120:121]
	v_pk_add_f32 v[110:111], v[110:111], v[112:113]
	v_pk_add_f32 v[108:109], v[108:109], v[114:115]
	s_waitcnt vmcnt(0)
	v_lshlrev_b32_e32 v114, 16, v100
	v_pk_mov_b32 v[112:113], v[108:109], v[110:111] op_sel:[1,0]
	v_mov_b32_e32 v109, v111
	v_pk_add_f32 v[108:109], v[112:113], v[108:109]
	v_lshlrev_b32_e32 v110, 16, v96
	v_and_b32_e32 v111, 0xffff0000, v96
	v_add_f32_e32 v96, v108, v109
	v_fmamk_f32 v96, v96, 0x3a800000, v178
	v_and_b32_e32 v115, 0xffff0000, v100
	v_mul_f32_e32 v100, 0x4f800000, v96
	v_cmp_gt_f32_e32 vcc, s72, v96
	v_lshlrev_b32_e32 v108, 16, v97
	v_and_b32_e32 v109, 0xffff0000, v97
	v_cndmask_b32_e32 v96, v96, v100, vcc
	v_sqrt_f32_e32 v100, v96
	v_lshlrev_b32_e32 v97, 16, v101
	s_nop 1
	v_mul_f32_e32 v112, 0x37800000, v100
	v_cndmask_b32_e32 v100, v100, v112, vcc
	v_cmp_class_f32_e32 vcc, v96, v179
	v_and_b32_e32 v113, 0xffff0000, v101
	s_nop 0
	v_cndmask_b32_e32 v96, v100, v96, vcc
	v_rcp_f32_e32 v100, v96
	s_nop 0
	v_mul_f32_e32 v96, -1.0, v100
	v_pk_mul_f32 v[92:93], v[92:93], v[96:97] op_sel_hi:[1,0]
	v_pk_mul_f32 v[94:95], v[94:95], v[96:97] op_sel_hi:[1,0]
	v_pk_mul_f32 v[100:101], v[90:91], v[96:97] op_sel_hi:[1,0]
	v_pk_mul_f32 v[88:89], v[88:89], v[96:97] op_sel_hi:[1,0]
	v_mul_f32_e32 v90, 0x3fb8aa3b, v92
	v_mul_f32_e32 v91, 0x3fb8aa3b, v93
	v_mul_f32_e32 v92, 0x3fb8aa3b, v94
	v_mul_f32_e32 v93, 0x3fb8aa3b, v95
	v_mul_f32_e32 v94, 0x3fb8aa3b, v88
	v_mul_f32_e32 v95, 0x3fb8aa3b, v89
	v_exp_f32_e32 v88, v90
	v_exp_f32_e32 v89, v91
	v_exp_f32_e32 v90, v92
	v_exp_f32_e32 v91, v93
	v_exp_f32_e32 v92, v94
	v_pk_add_f32 v[88:89], v[88:89], 1.0 op_sel_hi:[1,0]
	v_exp_f32_e32 v93, v95
	v_div_scale_f32 v94, s[8:9], v89, v89, v115
	v_pk_add_f32 v[90:91], v[90:91], 1.0 op_sel_hi:[1,0]
	v_div_scale_f32 v112, s[8:9], v88, v88, v114
	v_rcp_f32_e32 v121, v94
	v_div_scale_f32 v117, s[10:11], v91, v91, v113
	v_rcp_f32_e32 v122, v112
	v_div_scale_f32 v119, s[12:13], v90, v90, v97
	v_rcp_f32_e32 v123, v117
	v_rcp_f32_e32 v124, v119
	v_fma_f32 v125, -v94, v121, 1.0
	v_div_scale_f32 v95, vcc, v115, v89, v115
	v_fma_f32 v126, -v112, v122, 1.0
	v_fmac_f32_e32 v121, v125, v121
	v_div_scale_f32 v116, s[8:9], v114, v88, v114
	v_fma_f32 v127, -v117, v123, 1.0
	v_fmac_f32_e32 v122, v126, v122
	v_mul_f32_e32 v125, v95, v121
	v_div_scale_f32 v118, s[10:11], v113, v91, v113
	v_fma_f32 v128, -v119, v124, 1.0
	v_fmac_f32_e32 v123, v127, v123
	v_mul_f32_e32 v126, v116, v122
	v_fma_f32 v129, -v94, v125, v95
	v_div_scale_f32 v120, s[12:13], v97, v90, v97
	v_fmac_f32_e32 v124, v128, v124
	v_mul_f32_e32 v127, v118, v123
	v_fma_f32 v130, -v112, v126, v116
	v_fmac_f32_e32 v125, v129, v121
	v_mul_f32_e32 v128, v120, v124
	v_fma_f32 v131, -v117, v127, v118
	v_fmac_f32_e32 v126, v130, v122
	v_fma_f32 v132, -v119, v128, v120
	v_fmac_f32_e32 v127, v131, v123
	v_fmac_f32_e32 v128, v132, v124
	v_rcp_f32_e32 v94, v89
	s_nop 0
	v_mul_f32_e32 v89, v115, v94
	v_rcp_f32_e32 v94, v88
	s_nop 0
	v_mul_f32_e32 v88, v114, v94
	s_mov_b64 vcc, s[12:13]
	v_pk_add_f32 v[94:95], v[88:89], v[110:111]
	v_rcp_f32_e32 v88, v90
	s_nop 0
	v_mul_f32_e32 v88, v97, v88
	v_and_b32_e32 v97, 0xffff0000, v102
	v_pk_add_f32 v[114:115], v[92:93], 1.0 op_sel_hi:[1,0]
	v_rcp_f32_e32 v112, v91
	s_nop 0
	v_mul_f32_e32 v89, v113, v112
	v_pk_add_f32 v[112:113], v[88:89], v[108:109]
	v_lshlrev_b32_e32 v116, 16, v98
	v_and_b32_e32 v117, 0xffff0000, v98
	v_lshl_add_u64 v[88:89], s[24:25], 0, v[106:107]
	v_or_b32_e32 v106, 0x100, v106
	v_lshl_add_u64 v[90:91], s[20:21], 0, v[106:107]
	global_load_dwordx4 v[90:93], v[90:91], off
	v_lshl_add_u64 v[108:109], s[16:17], 0, v[106:107]
	global_load_dwordx4 v[108:111], v[108:109], off
	v_lshlrev_b32_e32 v98, 16, v102
	v_rcp_f32_e32 v102, v115
	s_nop 0
	v_mul_f32_e32 v115, v97, v102
	v_mul_f32_e32 v100, 0x3fb8aa3b, v100
	v_mul_f32_e32 v101, 0x3fb8aa3b, v101
	v_exp_f32_e32 v100, v100
	v_exp_f32_e32 v101, v101
	v_rcp_f32_e32 v97, v114
	s_nop 0
	v_mul_f32_e32 v114, v98, v97
	v_and_b32_e32 v97, 0xffff0000, v103
	v_pk_add_f32 v[100:101], v[100:101], 1.0 op_sel_hi:[1,0]
	v_pk_add_f32 v[114:115], v[114:115], v[116:117]
	v_lshlrev_b32_e32 v103, 16, v103
	v_lshlrev_b32_e32 v98, 16, v99
	v_and_b32_e32 v99, 0xffff0000, v99
	v_div_scale_f32 v117, s[8:9], v100, v100, v103
	v_rcp_f32_e32 v119, v117
	v_rcp_f32_e32 v102, v101
	s_nop 0
	v_mul_f32_e32 v101, v97, v102
	v_fma_f32 v97, -v117, v119, 1.0
	v_fmac_f32_e32 v119, v97, v119
	v_div_scale_f32 v97, vcc, v103, v100, v103
	v_mul_f32_e32 v102, v97, v119
	v_fma_f32 v116, -v117, v102, v97
	v_fmac_f32_e32 v102, v116, v119
	v_fma_f32 v97, -v117, v102, v97
	v_div_fmas_f32 v97, v97, v119, v102
	v_pk_mul_f32 v[84:85], v[84:85], v[96:97] op_sel_hi:[1,0]
	v_rcp_f32_e32 v97, v100
	s_nop 0
	v_mul_f32_e32 v100, v103, v97
	v_mul_f32_e32 v84, 0x3fb8aa3b, v84
	v_mul_f32_e32 v85, 0x3fb8aa3b, v85
	v_exp_f32_e32 v84, v84
	v_exp_f32_e32 v85, v85
	v_pk_add_f32 v[102:103], v[100:101], v[98:99]
	v_pk_mul_f32 v[86:87], v[86:87], v[96:97] op_sel_hi:[1,0]
	v_pk_mul_f32 v[82:83], v[82:83], v[96:97] op_sel_hi:[1,0]
	v_pk_add_f32 v[84:85], v[84:85], 1.0 op_sel_hi:[1,0]
	v_pk_mul_f32 v[80:81], v[80:81], v[96:97] op_sel_hi:[1,0]
	v_mul_f32_e32 v86, 0x3fb8aa3b, v86
	v_mul_f32_e32 v87, 0x3fb8aa3b, v87
	v_exp_f32_e32 v86, v86
	v_exp_f32_e32 v87, v87
	v_mul_f32_e32 v80, 0x3fb8aa3b, v80
	v_mul_f32_e32 v81, 0x3fb8aa3b, v81
	v_exp_f32_e32 v80, v80
	v_pk_add_f32 v[86:87], v[86:87], 1.0 op_sel_hi:[1,0]
	s_waitcnt vmcnt(1)
; DI unsigned pk_bf16(float lo, float hi) { typedef float f2 __attribute__((ext_vector_type(2))); typedef __bf16 b2 __attribute__((ext_vector_type(2))); f2 v = {lo, hi}; b2 b = __builtin_convertvector(v, b2); return __builtin_bit_cast(unsigned, b); }
; DI float bf_lo(unsigned w) { return __uint_as_float(w << 16); }
; DI float bf_hi(unsigned w) { return __uint_as_float(w & 0xffff0000u); }
;     DI void operator()(const f32x4 (&acc)[2][2][4][2], const pg8::Unit& u, int wr, int wc, int fr, int fq) const {
;     ...
;                     const u32x4 pw = *(const u32x4*)(pp + o2), bw = *(const u32x4*)(base + o2);
;                     const f32x4 a0 = acc[ai][bj][m][0] * rs, a1 = acc[ai][bj][m][1] * rs;
;                     f32x4 r0, r1;
;                     r0[0] = bf_lo(bw.x) + bf_lo(pw.x) / (1.f + __expf(a0[0])); r0[1] = bf_hi(bw.x) + bf_hi(pw.x) / (1.f + __expf(a0[1]));
;                     r0[2] = bf_lo(bw.y) + bf_lo(pw.y) / (1.f + __expf(a0[2])); r0[3] = bf_hi(bw.y) + bf_hi(pw.y) / (1.f + __expf(a0[3]));
;                     r1[0] = bf_lo(bw.z) + bf_lo(pw.z) / (1.f + __expf(a1[0])); r1[1] = bf_hi(bw.z) + bf_hi(pw.z) / (1.f + __expf(a1[1]));
;                     r1[2] = bf_lo(bw.w) + bf_lo(pw.w) / (1.f + __expf(a1[2])); r1[3] = bf_hi(bw.w) + bf_hi(pw.w) / (1.f + __expf(a1[3]));
;                     u32x4 w; w.x = pk_bf16(r0[0], r0[1]); w.y = pk_bf16(r0[2], r0[3]); w.z = pk_bf16(r1[0], r1[1]); w.w = pk_bf16(r1[2], r1[3]);
;                     *(u32x4*)(hb + o2) = w;
;                     ss += ((r0[0] * r0[0] + r0[1] * r0[1]) + (r0[2] * r0[2] + r0[3] * r0[3])) + ((r1[0] * r1[0] + r1[1] * r1[1]) + (r1[2] * r1[2] + r1[3] * r1[3]));
;                 }
;                 ss += __shfl_xor(ss, 16); ss += __shfl_xor(ss, 32);
;                 if (fq == 0) part[(size_t)row * 16 + u.pn * 4 + wc] = ss;
	v_and_b32_e32 v101, 0xffff0000, v90
	v_div_scale_f32 v118, s[8:9], v85, v85, v101
	v_rcp_f32_e32 v119, v118
	s_waitcnt vmcnt(0)
	v_lshlrev_b32_e32 v96, 16, v108
	v_and_b32_e32 v97, 0xffff0000, v108
	v_lshlrev_b32_e32 v90, 16, v90
	v_fma_f32 v108, -v118, v119, 1.0
	v_fmac_f32_e32 v119, v108, v119
	v_div_scale_f32 v108, vcc, v101, v85, v101
	v_mul_f32_e32 v120, v108, v119
	v_fma_f32 v121, -v118, v120, v108
	v_fmac_f32_e32 v120, v121, v119
	v_div_scale_f32 v118, s[8:9], v84, v84, v90
	v_rcp_f32_e32 v121, v118
	v_rcp_f32_e32 v108, v85
	s_nop 0
	v_mul_f32_e32 v85, v101, v108
	v_exp_f32_e32 v81, v81
	v_fma_f32 v101, -v118, v121, 1.0
	v_fmac_f32_e32 v121, v101, v121
	v_rcp_f32_e32 v101, v84
	s_nop 0
	v_mul_f32_e32 v84, v90, v101
	v_and_b32_e32 v90, 0xffff0000, v91
	v_div_scale_f32 v101, s[8:9], v87, v87, v90
	v_rcp_f32_e32 v108, v101
	v_pk_add_f32 v[84:85], v[84:85], v[96:97]
	v_lshlrev_b32_e32 v96, 16, v109
	v_and_b32_e32 v97, 0xffff0000, v109
	v_fma_f32 v109, -v101, v108, 1.0
	v_fmac_f32_e32 v108, v109, v108
	v_div_scale_f32 v109, vcc, v90, v87, v90
	v_mul_f32_e32 v118, v109, v108
	v_fma_f32 v119, -v101, v118, v109
	v_lshlrev_b32_e32 v91, 16, v91
	v_fmac_f32_e32 v118, v119, v108
	v_div_scale_f32 v109, s[8:9], v86, v86, v91
	v_rcp_f32_e32 v119, v109
	v_rcp_f32_e32 v101, v87
	s_nop 0
	v_mul_f32_e32 v87, v90, v101
	v_pk_add_f32 v[80:81], v[80:81], 1.0 op_sel_hi:[1,0]
	v_fma_f32 v90, -v109, v119, 1.0
	v_fmac_f32_e32 v119, v90, v119
	v_rcp_f32_e32 v90, v86
	s_nop 0
	v_mul_f32_e32 v86, v91, v90
	v_pk_add_f32 v[86:87], v[86:87], v[96:97]
	v_and_b32_e32 v96, 0xffff0000, v92
	v_lshlrev_b32_e32 v90, 16, v110
	v_and_b32_e32 v91, 0xffff0000, v110
	v_lshlrev_b32_e32 v92, 16, v92
	v_div_scale_f32 v108, s[8:9], v80, v80, v92
	v_rcp_f32_e32 v110, v108
	v_rcp_f32_e32 v97, v81
	s_nop 0
	v_mul_f32_e32 v81, v96, v97
	v_mul_f32_e32 v82, 0x3fb8aa3b, v82
	v_fma_f32 v96, -v108, v110, 1.0
	v_fmac_f32_e32 v110, v96, v110
	v_mul_f32_e32 v83, 0x3fb8aa3b, v83
	v_exp_f32_e32 v82, v82
	v_exp_f32_e32 v83, v83
	v_rcp_f32_e32 v96, v80
	s_nop 0
	v_mul_f32_e32 v80, v92, v96
	v_pk_add_f32 v[90:91], v[80:81], v[90:91]
	v_and_b32_e32 v92, 0xffff0000, v93
	v_pk_add_f32 v[80:81], v[82:83], 1.0 op_sel_hi:[1,0]
	v_lshlrev_b32_e32 v93, 16, v93
	v_lshlrev_b32_e32 v82, 16, v111
	v_and_b32_e32 v83, 0xffff0000, v111
	v_cvt_pk_bf16_f32 v100, v114, v115
	v_div_scale_f32 v101, s[8:9], v80, v80, v93
	v_rcp_f32_e32 v96, v81
	s_nop 0
	v_mul_f32_e32 v81, v92, v96
	v_pk_mul_f32 v[114:115], v[114:115], v[114:115]
	v_div_scale_f32 v92, vcc, v93, v80, v93
	v_rcp_f32_e32 v92, v80
	s_nop 0
	v_mul_f32_e32 v80, v93, v92
	v_pk_add_f32 v[92:93], v[80:81], v[82:83]
	v_pk_mul_f32 v[80:81], v[84:85], v[84:85]
	v_pk_mul_f32 v[82:83], v[86:87], v[86:87]
	v_pk_mul_f32 v[116:117], v[102:103], v[102:103]
	v_add_f32_e32 v82, v82, v83
	v_add_f32_e32 v80, v80, v81
	v_cvt_pk_bf16_f32 v98, v94, v95
	v_cvt_pk_bf16_f32 v99, v112, v113
	v_pk_mul_f32 v[94:95], v[94:95], v[94:95]
	v_pk_mul_f32 v[112:113], v[112:113], v[112:113]
	v_pk_mul_f32 v[96:97], v[90:91], v[90:91]
	v_pk_mul_f32 v[108:109], v[92:93], v[92:93]
	v_add_f32_e32 v80, v80, v82
	v_add_f32_e32 v81, v116, v117
	v_add_f32_e32 v82, v114, v115
	v_add_f32_e32 v101, v108, v109
	v_add_f32_e32 v96, v96, v97
	v_add_f32_e32 v81, v82, v81
	v_add_f32_e32 v82, v112, v113
	v_add_f32_e32 v83, v94, v95
	v_add_f32_e32 v96, v96, v101
	v_add_f32_e32 v82, v83, v82
	v_add_f32_e32 v80, v80, v96
	v_add_f32_e32 v81, v82, v81
	v_add_f32_e32 v80, v81, v80
	ds_bpermute_b32 v81, v181, v80
	v_cvt_pk_bf16_f32 v101, v102, v103
	v_cvt_pk_bf16_f32 v82, v84, v85
	v_cvt_pk_bf16_f32 v83, v86, v87
	v_cvt_pk_bf16_f32 v84, v90, v91
	s_waitcnt lgkmcnt(0)
	v_add_f32_e32 v80, v80, v81
	ds_bpermute_b32 v81, v180, v80
	v_cvt_pk_bf16_f32 v85, v92, v93
	v_lshl_add_u64 v[86:87], s[24:25], 0, v[106:107]
	global_store_dwordx4 v[88:89], v[98:101], off
	global_store_dwordx4 v[86:87], v[82:85], off
	s_and_saveexec_b64 s[8:9], s[4:5]
	s_cbranch_execz .LBB0_1753
	v_lshlrev_b64 v[82:83], 4, v[104:105]
	s_waitcnt lgkmcnt(0)
	v_add_f32_e32 v84, v80, v81
	v_lshl_add_u64 v[80:81], v[82:83], 2, s[26:27]
	v_lshl_add_u64 v[80:81], s[48:49], 2, v[80:81]
	s_lshl_b32 s34, s61, 2
	v_lshl_add_u64 v[80:81], v[80:81], 0, s[34:35]
	global_store_dword v[80:81], v84, off
; DI unsigned pk_bf16(float lo, float hi) { typedef float f2 __attribute__((ext_vector_type(2))); typedef __bf16 b2 __attribute__((ext_vector_type(2))); f2 v = {lo, hi}; b2 b = __builtin_convertvector(v, b2); return __builtin_bit_cast(unsigned, b); }
; DI float bf_lo(unsigned w) { return __uint_as_float(w << 16); }
; DI float bf_hi(unsigned w) { return __uint_as_float(w & 0xffff0000u); }
;     DI void operator()(const f32x4 (&acc)[2][2][4][2], const pg8::Unit& u, int wr, int wc, int fr, int fq) const {
;     ...
;                 const int row = row0 + ai * 128 + m * 16;
;                 const size_t off = (size_t)row * ldc + col0;
;                 const f32x4* pq = (const f32x4*)(partin + (size_t)row * 16); const f32x4 t4 = (pq[0] + pq[1]) + (pq[2] + pq[3]);
;                 const float rs = -1.0f / sqrtf(((t4.x + t4.y) + (t4.z + t4.w)) * (1.f / DM) + NORM_EPS);
;                 float ss = 0.f;
; #pragma unroll
;                 for (int bj = 0; bj < 2; ++bj) {
;                     const size_t o2 = off + bj * 128;
;                     const u32x4 pw = *(const u32x4*)(pp + o2), bw = *(const u32x4*)(base + o2);
;                     const f32x4 a0 = acc[ai][bj][m][0] * rs, a1 = acc[ai][bj][m][1] * rs;
;                     f32x4 r0, r1;
;                     r0[0] = bf_lo(bw.x) + bf_lo(pw.x) / (1.f + __expf(a0[0])); r0[1] = bf_hi(bw.x) + bf_hi(pw.x) / (1.f + __expf(a0[1]));
;                     r0[2] = bf_lo(bw.y) + bf_lo(pw.y) / (1.f + __expf(a0[2])); r0[3] = bf_hi(bw.y) + bf_hi(pw.y) / (1.f + __expf(a0[3]));
;                     r1[0] = bf_lo(bw.z) + bf_lo(pw.z) / (1.f + __expf(a1[0])); r1[1] = bf_hi(bw.z) + bf_hi(pw.z) / (1.f + __expf(a1[1]));
;                     r1[2] = bf_lo(bw.w) + bf_lo(pw.w) / (1.f + __expf(a1[2])); r1[3] = bf_hi(bw.w) + bf_hi(pw.w) / (1.f + __expf(a1[3]));
;                     u32x4 w; w.x = pk_bf16(r0[0], r0[1]); w.y = pk_bf16(r0[2], r0[3]); w.z = pk_bf16(r1[0], r1[1]); w.w = pk_bf16(r1[2], r1[3]);
;                     *(u32x4*)(hb + o2) = w;
.LBB0_1753:
	s_or_b64 exec, exec, s[8:9]
	v_or_b32_e32 v88, 48, v154
	v_ashrrev_i32_e32 v89, 31, v88
	s_waitcnt lgkmcnt(0)
	v_lshlrev_b64 v[80:81], 6, v[88:89]
	v_lshl_add_u64 v[80:81], s[22:23], 0, v[80:81]
	global_load_dwordx4 v[92:95], v[80:81], off
	global_load_dwordx4 v[96:99], v[80:81], off offset:16
	global_load_dwordx4 v[100:103], v[80:81], off offset:32
	global_load_dwordx4 v[104:107], v[80:81], off offset:48
	v_lshlrev_b64 v[80:81], 10, v[88:89]
	v_lshl_add_u64 v[80:81], v[80:81], 0, v[152:153]
	v_lshlrev_b64 v[90:91], 1, v[80:81]
	v_lshl_add_u64 v[80:81], s[16:17], 0, v[90:91]
	global_load_dwordx4 v[80:83], v[80:81], off
	v_lshl_add_u64 v[84:85], s[20:21], 0, v[90:91]
	global_load_dwordx4 v[84:87], v[84:85], off
	s_waitcnt vmcnt(4)
	v_pk_add_f32 v[94:95], v[94:95], v[98:99]
	v_pk_add_f32 v[92:93], v[92:93], v[96:97]
	s_waitcnt vmcnt(2)
	v_pk_add_f32 v[96:97], v[102:103], v[106:107]
	v_pk_add_f32 v[98:99], v[100:101], v[104:105]
	v_pk_add_f32 v[94:95], v[94:95], v[96:97]
	v_pk_add_f32 v[92:93], v[92:93], v[98:99]
	s_waitcnt vmcnt(0)
	v_lshlrev_b32_e32 v98, 16, v84
	v_pk_mov_b32 v[96:97], v[92:93], v[94:95] op_sel:[1,0]
	v_mov_b32_e32 v93, v95
	v_pk_add_f32 v[92:93], v[96:97], v[92:93]
	v_lshlrev_b32_e32 v94, 16, v80
	v_and_b32_e32 v95, 0xffff0000, v80
	v_add_f32_e32 v80, v92, v93
	v_fmamk_f32 v80, v80, 0x3a800000, v178
	v_and_b32_e32 v99, 0xffff0000, v84
	v_mul_f32_e32 v84, 0x4f800000, v80
	v_cmp_gt_f32_e32 vcc, s72, v80
	v_lshlrev_b32_e32 v92, 16, v81
	v_and_b32_e32 v93, 0xffff0000, v81
	v_cndmask_b32_e32 v80, v80, v84, vcc
	v_sqrt_f32_e32 v84, v80
	v_lshlrev_b32_e32 v81, 16, v85
	s_nop 1
	v_mul_f32_e32 v96, 0x37800000, v84
	v_cndmask_b32_e32 v84, v84, v96, vcc
	v_cmp_class_f32_e32 vcc, v80, v179
	v_and_b32_e32 v97, 0xffff0000, v85
	s_nop 0
	v_cndmask_b32_e32 v80, v84, v80, vcc
	v_rcp_f32_e32 v84, v80
	s_nop 0
	v_mul_f32_e32 v80, -1.0, v84
	v_pk_mul_f32 v[76:77], v[76:77], v[80:81] op_sel_hi:[1,0]
	v_pk_mul_f32 v[78:79], v[78:79], v[80:81] op_sel_hi:[1,0]
	v_pk_mul_f32 v[84:85], v[74:75], v[80:81] op_sel_hi:[1,0]
	v_pk_mul_f32 v[72:73], v[72:73], v[80:81] op_sel_hi:[1,0]
	v_mul_f32_e32 v74, 0x3fb8aa3b, v76
	v_mul_f32_e32 v75, 0x3fb8aa3b, v77
	v_mul_f32_e32 v76, 0x3fb8aa3b, v78
	v_mul_f32_e32 v77, 0x3fb8aa3b, v79
	v_mul_f32_e32 v78, 0x3fb8aa3b, v72
	v_mul_f32_e32 v79, 0x3fb8aa3b, v73
	v_exp_f32_e32 v72, v74
	v_exp_f32_e32 v73, v75
	v_exp_f32_e32 v74, v76
	v_exp_f32_e32 v75, v77
	v_exp_f32_e32 v76, v78
	v_pk_add_f32 v[72:73], v[72:73], 1.0 op_sel_hi:[1,0]
	v_exp_f32_e32 v77, v79
	v_div_scale_f32 v78, s[8:9], v73, v73, v99
	v_pk_add_f32 v[74:75], v[74:75], 1.0 op_sel_hi:[1,0]
	v_div_scale_f32 v96, s[8:9], v72, v72, v98
	v_rcp_f32_e32 v105, v78
	v_div_scale_f32 v101, s[10:11], v75, v75, v97
	v_rcp_f32_e32 v106, v96
	v_div_scale_f32 v103, s[12:13], v74, v74, v81
	v_rcp_f32_e32 v107, v101
	v_rcp_f32_e32 v108, v103
	v_fma_f32 v109, -v78, v105, 1.0
	v_div_scale_f32 v79, vcc, v99, v73, v99
	v_fma_f32 v110, -v96, v106, 1.0
	v_fmac_f32_e32 v105, v109, v105
	v_div_scale_f32 v100, s[8:9], v98, v72, v98
	v_fma_f32 v111, -v101, v107, 1.0
	v_fmac_f32_e32 v106, v110, v106
	v_mul_f32_e32 v109, v79, v105
	v_div_scale_f32 v102, s[10:11], v97, v75, v97
	v_fma_f32 v112, -v103, v108, 1.0
	v_fmac_f32_e32 v107, v111, v107
	v_mul_f32_e32 v110, v100, v106
	v_fma_f32 v113, -v78, v109, v79
	v_div_scale_f32 v104, s[12:13], v81, v74, v81
	v_fmac_f32_e32 v108, v112, v108
	v_mul_f32_e32 v111, v102, v107
	v_fma_f32 v114, -v96, v110, v100
	v_fmac_f32_e32 v109, v113, v105
	v_mul_f32_e32 v112, v104, v108
	v_fma_f32 v115, -v101, v111, v102
	v_fmac_f32_e32 v110, v114, v106
	v_fma_f32 v116, -v103, v112, v104
	v_fmac_f32_e32 v111, v115, v107
	v_fmac_f32_e32 v112, v116, v108
	v_rcp_f32_e32 v78, v73
	s_nop 0
	v_mul_f32_e32 v73, v99, v78
	v_rcp_f32_e32 v78, v72
	s_nop 0
	v_mul_f32_e32 v72, v98, v78
	s_mov_b64 vcc, s[12:13]
	v_pk_add_f32 v[78:79], v[72:73], v[94:95]
	v_rcp_f32_e32 v72, v74
	s_nop 0
	v_mul_f32_e32 v72, v81, v72
	v_and_b32_e32 v81, 0xffff0000, v86
	v_pk_add_f32 v[98:99], v[76:77], 1.0 op_sel_hi:[1,0]
	v_rcp_f32_e32 v96, v75
	s_nop 0
	v_mul_f32_e32 v73, v97, v96
	v_pk_add_f32 v[96:97], v[72:73], v[92:93]
	v_lshlrev_b32_e32 v100, 16, v82
	v_and_b32_e32 v101, 0xffff0000, v82
	v_lshl_add_u64 v[72:73], s[24:25], 0, v[90:91]
	v_or_b32_e32 v90, 0x100, v90
	v_lshl_add_u64 v[74:75], s[20:21], 0, v[90:91]
	global_load_dwordx4 v[74:77], v[74:75], off
	v_lshl_add_u64 v[92:93], s[16:17], 0, v[90:91]
	global_load_dwordx4 v[92:95], v[92:93], off
	v_lshlrev_b32_e32 v82, 16, v86
	v_rcp_f32_e32 v86, v99
	s_nop 0
	v_mul_f32_e32 v99, v81, v86
	v_mul_f32_e32 v84, 0x3fb8aa3b, v84
	v_mul_f32_e32 v85, 0x3fb8aa3b, v85
	v_exp_f32_e32 v84, v84
	v_exp_f32_e32 v85, v85
	v_rcp_f32_e32 v81, v98
	s_nop 0
	v_mul_f32_e32 v98, v82, v81
	v_and_b32_e32 v81, 0xffff0000, v87
	v_pk_add_f32 v[84:85], v[84:85], 1.0 op_sel_hi:[1,0]
	v_pk_add_f32 v[98:99], v[98:99], v[100:101]
	v_lshlrev_b32_e32 v87, 16, v87
	v_lshlrev_b32_e32 v82, 16, v83
	v_and_b32_e32 v83, 0xffff0000, v83
	v_div_scale_f32 v101, s[8:9], v84, v84, v87
	v_rcp_f32_e32 v103, v101
	v_rcp_f32_e32 v86, v85
	s_nop 0
	v_mul_f32_e32 v85, v81, v86
	v_fma_f32 v81, -v101, v103, 1.0
	v_fmac_f32_e32 v103, v81, v103
	v_div_scale_f32 v81, vcc, v87, v84, v87
	v_mul_f32_e32 v86, v81, v103
	v_fma_f32 v100, -v101, v86, v81
	v_fmac_f32_e32 v86, v100, v103
	v_fma_f32 v81, -v101, v86, v81
	v_div_fmas_f32 v81, v81, v103, v86
	v_pk_mul_f32 v[68:69], v[68:69], v[80:81] op_sel_hi:[1,0]
	v_rcp_f32_e32 v81, v84
	s_nop 0
	v_mul_f32_e32 v84, v87, v81
	v_mul_f32_e32 v68, 0x3fb8aa3b, v68
	v_mul_f32_e32 v69, 0x3fb8aa3b, v69
	v_exp_f32_e32 v68, v68
	v_exp_f32_e32 v69, v69
	v_pk_add_f32 v[86:87], v[84:85], v[82:83]
	v_pk_mul_f32 v[70:71], v[70:71], v[80:81] op_sel_hi:[1,0]
	v_pk_mul_f32 v[66:67], v[66:67], v[80:81] op_sel_hi:[1,0]
	v_pk_add_f32 v[68:69], v[68:69], 1.0 op_sel_hi:[1,0]
	v_pk_mul_f32 v[64:65], v[64:65], v[80:81] op_sel_hi:[1,0]
	v_mul_f32_e32 v70, 0x3fb8aa3b, v70
	v_mul_f32_e32 v71, 0x3fb8aa3b, v71
	v_exp_f32_e32 v70, v70
	v_exp_f32_e32 v71, v71
	v_mul_f32_e32 v64, 0x3fb8aa3b, v64
	v_mul_f32_e32 v65, 0x3fb8aa3b, v65
	v_exp_f32_e32 v64, v64
	v_pk_add_f32 v[70:71], v[70:71], 1.0 op_sel_hi:[1,0]
	s_waitcnt vmcnt(1)
; DI unsigned pk_bf16(float lo, float hi) { typedef float f2 __attribute__((ext_vector_type(2))); typedef __bf16 b2 __attribute__((ext_vector_type(2))); f2 v = {lo, hi}; b2 b = __builtin_convertvector(v, b2); return __builtin_bit_cast(unsigned, b); }
; DI float bf_lo(unsigned w) { return __uint_as_float(w << 16); }
; DI float bf_hi(unsigned w) { return __uint_as_float(w & 0xffff0000u); }
;     DI void operator()(const f32x4 (&acc)[2][2][4][2], const pg8::Unit& u, int wr, int wc, int fr, int fq) const {
;     ...
;                 for (int bj = 0; bj < 2; ++bj) {
;                     const size_t o2 = off + bj * 128;
;                     const u32x4 pw = *(const u32x4*)(pp + o2), bw = *(const u32x4*)(base + o2);
;                     const f32x4 a0 = acc[ai][bj][m][0] * rs, a1 = acc[ai][bj][m][1] * rs;
;                     f32x4 r0, r1;
;                     r0[0] = bf_lo(bw.x) + bf_lo(pw.x) / (1.f + __expf(a0[0])); r0[1] = bf_hi(bw.x) + bf_hi(pw.x) / (1.f + __expf(a0[1]));
;                     r0[2] = bf_lo(bw.y) + bf_lo(pw.y) / (1.f + __expf(a0[2])); r0[3] = bf_hi(bw.y) + bf_hi(pw.y) / (1.f + __expf(a0[3]));
;                     r1[0] = bf_lo(bw.z) + bf_lo(pw.z) / (1.f + __expf(a1[0])); r1[1] = bf_hi(bw.z) + bf_hi(pw.z) / (1.f + __expf(a1[1]));
;                     r1[2] = bf_lo(bw.w) + bf_lo(pw.w) / (1.f + __expf(a1[2])); r1[3] = bf_hi(bw.w) + bf_hi(pw.w) / (1.f + __expf(a1[3]));
;                     u32x4 w; w.x = pk_bf16(r0[0], r0[1]); w.y = pk_bf16(r0[2], r0[3]); w.z = pk_bf16(r1[0], r1[1]); w.w = pk_bf16(r1[2], r1[3]);
;                     *(u32x4*)(hb + o2) = w;
;                     ss += ((r0[0] * r0[0] + r0[1] * r0[1]) + (r0[2] * r0[2] + r0[3] * r0[3])) + ((r1[0] * r1[0] + r1[1] * r1[1]) + (r1[2] * r1[2] + r1[3] * r1[3]));
;                 }
;                 ss += __shfl_xor(ss, 16); ss += __shfl_xor(ss, 32);
;                 if (fq == 0) part[(size_t)row * 16 + u.pn * 4 + wc] = ss;
	v_and_b32_e32 v85, 0xffff0000, v74
	v_div_scale_f32 v102, s[8:9], v69, v69, v85
	v_rcp_f32_e32 v103, v102
	s_waitcnt vmcnt(0)
	v_lshlrev_b32_e32 v80, 16, v92
	v_and_b32_e32 v81, 0xffff0000, v92
	v_lshlrev_b32_e32 v74, 16, v74
	v_fma_f32 v92, -v102, v103, 1.0
	v_fmac_f32_e32 v103, v92, v103
	v_div_scale_f32 v92, vcc, v85, v69, v85
	v_mul_f32_e32 v104, v92, v103
	v_fma_f32 v105, -v102, v104, v92
	v_fmac_f32_e32 v104, v105, v103
	v_div_scale_f32 v102, s[8:9], v68, v68, v74
	v_rcp_f32_e32 v105, v102
	v_rcp_f32_e32 v92, v69
	s_nop 0
	v_mul_f32_e32 v69, v85, v92
	v_exp_f32_e32 v65, v65
	v_fma_f32 v85, -v102, v105, 1.0
	v_fmac_f32_e32 v105, v85, v105
	v_rcp_f32_e32 v85, v68
	s_nop 0
	v_mul_f32_e32 v68, v74, v85
	v_and_b32_e32 v74, 0xffff0000, v75
	v_div_scale_f32 v85, s[8:9], v71, v71, v74
	v_rcp_f32_e32 v92, v85
	v_pk_add_f32 v[68:69], v[68:69], v[80:81]
	v_lshlrev_b32_e32 v80, 16, v93
	v_and_b32_e32 v81, 0xffff0000, v93
	v_fma_f32 v93, -v85, v92, 1.0
	v_fmac_f32_e32 v92, v93, v92
	v_div_scale_f32 v93, vcc, v74, v71, v74
	v_mul_f32_e32 v102, v93, v92
	v_fma_f32 v103, -v85, v102, v93
	v_lshlrev_b32_e32 v75, 16, v75
	v_fmac_f32_e32 v102, v103, v92
	v_div_scale_f32 v93, s[8:9], v70, v70, v75
	v_rcp_f32_e32 v103, v93
	v_rcp_f32_e32 v85, v71
	s_nop 0
	v_mul_f32_e32 v71, v74, v85
	v_pk_add_f32 v[64:65], v[64:65], 1.0 op_sel_hi:[1,0]
	v_fma_f32 v74, -v93, v103, 1.0
	v_fmac_f32_e32 v103, v74, v103
	v_rcp_f32_e32 v74, v70
	s_nop 0
	v_mul_f32_e32 v70, v75, v74
	v_pk_add_f32 v[70:71], v[70:71], v[80:81]
	v_and_b32_e32 v80, 0xffff0000, v76
	v_lshlrev_b32_e32 v74, 16, v94
	v_and_b32_e32 v75, 0xffff0000, v94
	v_lshlrev_b32_e32 v76, 16, v76
	v_div_scale_f32 v92, s[8:9], v64, v64, v76
	v_rcp_f32_e32 v94, v92
	v_rcp_f32_e32 v81, v65
	s_nop 0
	v_mul_f32_e32 v65, v80, v81
	v_mul_f32_e32 v66, 0x3fb8aa3b, v66
	v_fma_f32 v80, -v92, v94, 1.0
	v_fmac_f32_e32 v94, v80, v94
	v_mul_f32_e32 v67, 0x3fb8aa3b, v67
	v_exp_f32_e32 v66, v66
	v_exp_f32_e32 v67, v67
	v_rcp_f32_e32 v80, v64
	s_nop 0
	v_mul_f32_e32 v64, v76, v80
	v_pk_add_f32 v[74:75], v[64:65], v[74:75]
	v_and_b32_e32 v76, 0xffff0000, v77
	v_pk_add_f32 v[64:65], v[66:67], 1.0 op_sel_hi:[1,0]
	v_lshlrev_b32_e32 v77, 16, v77
	v_lshlrev_b32_e32 v66, 16, v95
	v_and_b32_e32 v67, 0xffff0000, v95
	v_cvt_pk_bf16_f32 v84, v98, v99
	v_div_scale_f32 v85, s[8:9], v64, v64, v77
	v_rcp_f32_e32 v80, v65
	s_nop 0
	v_mul_f32_e32 v65, v76, v80
	v_pk_mul_f32 v[98:99], v[98:99], v[98:99]
	v_div_scale_f32 v76, vcc, v77, v64, v77
	v_rcp_f32_e32 v76, v64
	s_nop 0
	v_mul_f32_e32 v64, v77, v76
	v_pk_add_f32 v[76:77], v[64:65], v[66:67]
	v_pk_mul_f32 v[64:65], v[68:69], v[68:69]
	v_pk_mul_f32 v[66:67], v[70:71], v[70:71]
	v_pk_mul_f32 v[100:101], v[86:87], v[86:87]
	v_add_f32_e32 v66, v66, v67
	v_add_f32_e32 v64, v64, v65
	v_cvt_pk_bf16_f32 v82, v78, v79
	v_cvt_pk_bf16_f32 v83, v96, v97
	v_pk_mul_f32 v[78:79], v[78:79], v[78:79]
	v_pk_mul_f32 v[96:97], v[96:97], v[96:97]
	v_pk_mul_f32 v[80:81], v[74:75], v[74:75]
	v_pk_mul_f32 v[92:93], v[76:77], v[76:77]
	v_add_f32_e32 v64, v64, v66
	v_add_f32_e32 v65, v100, v101
	v_add_f32_e32 v66, v98, v99
	v_add_f32_e32 v85, v92, v93
	v_add_f32_e32 v80, v80, v81
	v_add_f32_e32 v65, v66, v65
	v_add_f32_e32 v66, v96, v97
	v_add_f32_e32 v67, v78, v79
	v_add_f32_e32 v80, v80, v85
	v_add_f32_e32 v66, v67, v66
	v_add_f32_e32 v64, v64, v80
	v_add_f32_e32 v65, v66, v65
	v_add_f32_e32 v64, v65, v64
	ds_bpermute_b32 v65, v181, v64
	v_cvt_pk_bf16_f32 v85, v86, v87
	v_cvt_pk_bf16_f32 v66, v68, v69
	v_cvt_pk_bf16_f32 v67, v70, v71
	v_cvt_pk_bf16_f32 v68, v74, v75
	s_waitcnt lgkmcnt(0)
	v_add_f32_e32 v64, v64, v65
	ds_bpermute_b32 v65, v180, v64
	v_cvt_pk_bf16_f32 v69, v76, v77
	v_lshl_add_u64 v[70:71], s[24:25], 0, v[90:91]
	global_store_dwordx4 v[72:73], v[82:85], off
	global_store_dwordx4 v[70:71], v[66:69], off
	s_and_saveexec_b64 s[8:9], s[4:5]
	s_cbranch_execz .LBB0_1755
	v_lshlrev_b64 v[66:67], 4, v[88:89]
	s_waitcnt lgkmcnt(0)
	v_add_f32_e32 v68, v64, v65
	v_lshl_add_u64 v[64:65], v[66:67], 2, s[26:27]
	v_lshl_add_u64 v[64:65], s[48:49], 2, v[64:65]
	s_lshl_b32 s34, s61, 2
	v_lshl_add_u64 v[64:65], v[64:65], 0, s[34:35]
	global_store_dword v[64:65], v68, off
.LBB0_1755:
	s_or_b64 exec, exec, s[8:9]
	v_add_u32_e32 v72, 0x80, v154
	v_ashrrev_i32_e32 v73, 31, v72
	s_waitcnt lgkmcnt(0)
	v_lshlrev_b64 v[64:65], 6, v[72:73]
	v_lshl_add_u64 v[64:65], s[22:23], 0, v[64:65]
	global_load_dwordx4 v[76:79], v[64:65], off
	global_load_dwordx4 v[80:83], v[64:65], off offset:16
	global_load_dwordx4 v[84:87], v[64:65], off offset:32
	global_load_dwordx4 v[88:91], v[64:65], off offset:48
	v_lshlrev_b64 v[64:65], 10, v[72:73]
	v_lshl_add_u64 v[64:65], v[64:65], 0, v[152:153]
	v_lshlrev_b64 v[74:75], 1, v[64:65]
	v_lshl_add_u64 v[64:65], s[16:17], 0, v[74:75]
	global_load_dwordx4 v[64:67], v[64:65], off
	v_lshl_add_u64 v[68:69], s[20:21], 0, v[74:75]
	global_load_dwordx4 v[68:71], v[68:69], off
	s_waitcnt vmcnt(4)
	v_pk_add_f32 v[78:79], v[78:79], v[82:83]
	v_pk_add_f32 v[76:77], v[76:77], v[80:81]
	s_waitcnt vmcnt(2)
	v_pk_add_f32 v[80:81], v[86:87], v[90:91]
	v_pk_add_f32 v[82:83], v[84:85], v[88:89]
	v_pk_add_f32 v[78:79], v[78:79], v[80:81]
	v_pk_add_f32 v[76:77], v[76:77], v[82:83]
	s_waitcnt vmcnt(0)
; DI unsigned pk_bf16(float lo, float hi) { typedef float f2 __attribute__((ext_vector_type(2))); typedef __bf16 b2 __attribute__((ext_vector_type(2))); f2 v = {lo, hi}; b2 b = __builtin_convertvector(v, b2); return __builtin_bit_cast(unsigned, b); }
; DI float bf_lo(unsigned w) { return __uint_as_float(w << 16); }
; DI float bf_hi(unsigned w) { return __uint_as_float(w & 0xffff0000u); }
;     DI void operator()(const f32x4 (&acc)[2][2][4][2], const pg8::Unit& u, int wr, int wc, int fr, int fq) const {
;     ...
;                 const int row = row0 + ai * 128 + m * 16;
;                 const size_t off = (size_t)row * ldc + col0;
;                 const f32x4* pq = (const f32x4*)(partin + (size_t)row * 16); const f32x4 t4 = (pq[0] + pq[1]) + (pq[2] + pq[3]);
;                 const float rs = -1.0f / sqrtf(((t4.x + t4.y) + (t4.z + t4.w)) * (1.f / DM) + NORM_EPS);
;                 float ss = 0.f;
; #pragma unroll
;                 for (int bj = 0; bj < 2; ++bj) {
;                     const size_t o2 = off + bj * 128;
;                     const u32x4 pw = *(const u32x4*)(pp + o2), bw = *(const u32x4*)(base + o2);
;                     const f32x4 a0 = acc[ai][bj][m][0] * rs, a1 = acc[ai][bj][m][1] * rs;
;                     f32x4 r0, r1;
;                     r0[0] = bf_lo(bw.x) + bf_lo(pw.x) / (1.f + __expf(a0[0])); r0[1] = bf_hi(bw.x) + bf_hi(pw.x) / (1.f + __expf(a0[1]));
;                     r0[2] = bf_lo(bw.y) + bf_lo(pw.y) / (1.f + __expf(a0[2])); r0[3] = bf_hi(bw.y) + bf_hi(pw.y) / (1.f + __expf(a0[3]));
;                     r1[0] = bf_lo(bw.z) + bf_lo(pw.z) / (1.f + __expf(a1[0])); r1[1] = bf_hi(bw.z) + bf_hi(pw.z) / (1.f + __expf(a1[1]));
;                     r1[2] = bf_lo(bw.w) + bf_lo(pw.w) / (1.f + __expf(a1[2])); r1[3] = bf_hi(bw.w) + bf_hi(pw.w) / (1.f + __expf(a1[3]));
;                     u32x4 w; w.x = pk_bf16(r0[0], r0[1]); w.y = pk_bf16(r0[2], r0[3]); w.z = pk_bf16(r1[0], r1[1]); w.w = pk_bf16(r1[2], r1[3]);
;                     *(u32x4*)(hb + o2) = w;
	v_lshlrev_b32_e32 v82, 16, v68
	v_pk_mov_b32 v[80:81], v[76:77], v[78:79] op_sel:[1,0]
	v_mov_b32_e32 v77, v79
	v_pk_add_f32 v[76:77], v[80:81], v[76:77]
	v_lshlrev_b32_e32 v78, 16, v64
	v_and_b32_e32 v79, 0xffff0000, v64
	v_add_f32_e32 v64, v76, v77
	v_fmamk_f32 v64, v64, 0x3a800000, v178
	v_and_b32_e32 v83, 0xffff0000, v68
	v_mul_f32_e32 v68, 0x4f800000, v64
	v_cmp_gt_f32_e32 vcc, s72, v64
	v_lshlrev_b32_e32 v76, 16, v65
	v_and_b32_e32 v77, 0xffff0000, v65
	v_cndmask_b32_e32 v64, v64, v68, vcc
	v_sqrt_f32_e32 v68, v64
	v_lshlrev_b32_e32 v65, 16, v69
	s_nop 1
	v_mul_f32_e32 v80, 0x37800000, v68
	v_cndmask_b32_e32 v68, v68, v80, vcc
	v_cmp_class_f32_e32 vcc, v64, v179
	v_and_b32_e32 v81, 0xffff0000, v69
	s_nop 0
	v_cndmask_b32_e32 v64, v68, v64, vcc
	v_rcp_f32_e32 v68, v64
	s_nop 0
	v_mul_f32_e32 v64, -1.0, v68
	v_pk_mul_f32 v[60:61], v[60:61], v[64:65] op_sel_hi:[1,0]
	v_pk_mul_f32 v[62:63], v[62:63], v[64:65] op_sel_hi:[1,0]
	v_pk_mul_f32 v[68:69], v[58:59], v[64:65] op_sel_hi:[1,0]
	v_pk_mul_f32 v[56:57], v[56:57], v[64:65] op_sel_hi:[1,0]
	v_mul_f32_e32 v58, 0x3fb8aa3b, v60
	v_mul_f32_e32 v59, 0x3fb8aa3b, v61
	v_mul_f32_e32 v60, 0x3fb8aa3b, v62
	v_mul_f32_e32 v61, 0x3fb8aa3b, v63
	v_mul_f32_e32 v62, 0x3fb8aa3b, v56
	v_mul_f32_e32 v63, 0x3fb8aa3b, v57
	v_exp_f32_e32 v56, v58
	v_exp_f32_e32 v57, v59
	v_exp_f32_e32 v58, v60
	v_exp_f32_e32 v59, v61
	v_exp_f32_e32 v60, v62
	v_pk_add_f32 v[56:57], v[56:57], 1.0 op_sel_hi:[1,0]
	v_exp_f32_e32 v61, v63
	v_div_scale_f32 v62, s[8:9], v57, v57, v83
	v_pk_add_f32 v[58:59], v[58:59], 1.0 op_sel_hi:[1,0]
	v_div_scale_f32 v80, s[8:9], v56, v56, v82
	v_rcp_f32_e32 v89, v62
	v_div_scale_f32 v85, s[10:11], v59, v59, v81
	v_rcp_f32_e32 v90, v80
	v_div_scale_f32 v87, s[12:13], v58, v58, v65
	v_rcp_f32_e32 v91, v85
	v_rcp_f32_e32 v92, v87
	v_fma_f32 v93, -v62, v89, 1.0
	v_div_scale_f32 v63, vcc, v83, v57, v83
	v_fma_f32 v94, -v80, v90, 1.0
	v_fmac_f32_e32 v89, v93, v89
	v_div_scale_f32 v84, s[8:9], v82, v56, v82
	v_fma_f32 v95, -v85, v91, 1.0
	v_fmac_f32_e32 v90, v94, v90
	v_mul_f32_e32 v93, v63, v89
	v_div_scale_f32 v86, s[10:11], v81, v59, v81
	v_fma_f32 v96, -v87, v92, 1.0
	v_fmac_f32_e32 v91, v95, v91
	v_mul_f32_e32 v94, v84, v90
	v_fma_f32 v97, -v62, v93, v63
	v_div_scale_f32 v88, s[12:13], v65, v58, v65
	v_fmac_f32_e32 v92, v96, v92
	v_mul_f32_e32 v95, v86, v91
	v_fma_f32 v98, -v80, v94, v84
	v_fmac_f32_e32 v93, v97, v89
	v_mul_f32_e32 v96, v88, v92
	v_fma_f32 v99, -v85, v95, v86
	v_fmac_f32_e32 v94, v98, v90
	v_fma_f32 v100, -v87, v96, v88
	v_fmac_f32_e32 v95, v99, v91
	v_fmac_f32_e32 v96, v100, v92
	v_rcp_f32_e32 v62, v57
	s_nop 0
	v_mul_f32_e32 v57, v83, v62
	v_rcp_f32_e32 v62, v56
	s_nop 0
	v_mul_f32_e32 v56, v82, v62
	s_mov_b64 vcc, s[12:13]
	v_pk_add_f32 v[62:63], v[56:57], v[78:79]
	v_rcp_f32_e32 v56, v58
	s_nop 0
	v_mul_f32_e32 v56, v65, v56
	v_and_b32_e32 v65, 0xffff0000, v70
	v_pk_add_f32 v[82:83], v[60:61], 1.0 op_sel_hi:[1,0]
	v_rcp_f32_e32 v80, v59
	s_nop 0
	v_mul_f32_e32 v57, v81, v80
	v_pk_add_f32 v[80:81], v[56:57], v[76:77]
	v_lshlrev_b32_e32 v84, 16, v66
	v_and_b32_e32 v85, 0xffff0000, v66
	v_lshl_add_u64 v[56:57], s[24:25], 0, v[74:75]
	v_or_b32_e32 v74, 0x100, v74
	v_lshl_add_u64 v[58:59], s[20:21], 0, v[74:75]
	global_load_dwordx4 v[58:61], v[58:59], off
	v_lshl_add_u64 v[76:77], s[16:17], 0, v[74:75]
	global_load_dwordx4 v[76:79], v[76:77], off
	v_lshlrev_b32_e32 v66, 16, v70
	v_rcp_f32_e32 v70, v83
	s_nop 0
	v_mul_f32_e32 v83, v65, v70
	v_mul_f32_e32 v68, 0x3fb8aa3b, v68
	v_mul_f32_e32 v69, 0x3fb8aa3b, v69
	v_exp_f32_e32 v68, v68
	v_exp_f32_e32 v69, v69
	v_rcp_f32_e32 v65, v82
	s_nop 0
	v_mul_f32_e32 v82, v66, v65
	v_and_b32_e32 v65, 0xffff0000, v71
	v_pk_add_f32 v[68:69], v[68:69], 1.0 op_sel_hi:[1,0]
	v_pk_add_f32 v[82:83], v[82:83], v[84:85]
	v_lshlrev_b32_e32 v71, 16, v71
	v_lshlrev_b32_e32 v66, 16, v67
	v_and_b32_e32 v67, 0xffff0000, v67
	v_div_scale_f32 v85, s[8:9], v68, v68, v71
	v_rcp_f32_e32 v87, v85
	v_rcp_f32_e32 v70, v69
	s_nop 0
	v_mul_f32_e32 v69, v65, v70
	v_fma_f32 v65, -v85, v87, 1.0
	v_fmac_f32_e32 v87, v65, v87
	v_div_scale_f32 v65, vcc, v71, v68, v71
	v_mul_f32_e32 v70, v65, v87
	v_fma_f32 v84, -v85, v70, v65
	v_fmac_f32_e32 v70, v84, v87
	v_fma_f32 v65, -v85, v70, v65
	v_div_fmas_f32 v65, v65, v87, v70
	v_pk_mul_f32 v[52:53], v[52:53], v[64:65] op_sel_hi:[1,0]
	v_rcp_f32_e32 v65, v68
	s_nop 0
	v_mul_f32_e32 v68, v71, v65
	v_mul_f32_e32 v52, 0x3fb8aa3b, v52
	v_mul_f32_e32 v53, 0x3fb8aa3b, v53
	v_exp_f32_e32 v52, v52
	v_exp_f32_e32 v53, v53
	v_pk_add_f32 v[70:71], v[68:69], v[66:67]
	v_pk_mul_f32 v[54:55], v[54:55], v[64:65] op_sel_hi:[1,0]
	v_pk_mul_f32 v[50:51], v[50:51], v[64:65] op_sel_hi:[1,0]
	v_pk_add_f32 v[52:53], v[52:53], 1.0 op_sel_hi:[1,0]
	v_pk_mul_f32 v[48:49], v[48:49], v[64:65] op_sel_hi:[1,0]
	v_mul_f32_e32 v54, 0x3fb8aa3b, v54
	v_mul_f32_e32 v55, 0x3fb8aa3b, v55
	v_exp_f32_e32 v54, v54
	v_exp_f32_e32 v55, v55
	v_mul_f32_e32 v48, 0x3fb8aa3b, v48
	v_mul_f32_e32 v49, 0x3fb8aa3b, v49
	v_exp_f32_e32 v48, v48
	v_pk_add_f32 v[54:55], v[54:55], 1.0 op_sel_hi:[1,0]
	s_waitcnt vmcnt(1)
	v_and_b32_e32 v69, 0xffff0000, v58
	v_div_scale_f32 v86, s[8:9], v53, v53, v69
	v_rcp_f32_e32 v87, v86
	s_waitcnt vmcnt(0)
; DI unsigned pk_bf16(float lo, float hi) { typedef float f2 __attribute__((ext_vector_type(2))); typedef __bf16 b2 __attribute__((ext_vector_type(2))); f2 v = {lo, hi}; b2 b = __builtin_convertvector(v, b2); return __builtin_bit_cast(unsigned, b); }
; DI float bf_lo(unsigned w) { return __uint_as_float(w << 16); }
; DI float bf_hi(unsigned w) { return __uint_as_float(w & 0xffff0000u); }
;     DI void operator()(const f32x4 (&acc)[2][2][4][2], const pg8::Unit& u, int wr, int wc, int fr, int fq) const {
;     ...
;                 for (int bj = 0; bj < 2; ++bj) {
;                     const size_t o2 = off + bj * 128;
;                     const u32x4 pw = *(const u32x4*)(pp + o2), bw = *(const u32x4*)(base + o2);
;                     const f32x4 a0 = acc[ai][bj][m][0] * rs, a1 = acc[ai][bj][m][1] * rs;
;                     f32x4 r0, r1;
;                     r0[0] = bf_lo(bw.x) + bf_lo(pw.x) / (1.f + __expf(a0[0])); r0[1] = bf_hi(bw.x) + bf_hi(pw.x) / (1.f + __expf(a0[1]));
;                     r0[2] = bf_lo(bw.y) + bf_lo(pw.y) / (1.f + __expf(a0[2])); r0[3] = bf_hi(bw.y) + bf_hi(pw.y) / (1.f + __expf(a0[3]));
;                     r1[0] = bf_lo(bw.z) + bf_lo(pw.z) / (1.f + __expf(a1[0])); r1[1] = bf_hi(bw.z) + bf_hi(pw.z) / (1.f + __expf(a1[1]));
;                     r1[2] = bf_lo(bw.w) + bf_lo(pw.w) / (1.f + __expf(a1[2])); r1[3] = bf_hi(bw.w) + bf_hi(pw.w) / (1.f + __expf(a1[3]));
;                     u32x4 w; w.x = pk_bf16(r0[0], r0[1]); w.y = pk_bf16(r0[2], r0[3]); w.z = pk_bf16(r1[0], r1[1]); w.w = pk_bf16(r1[2], r1[3]);
;                     *(u32x4*)(hb + o2) = w;
;                     ss += ((r0[0] * r0[0] + r0[1] * r0[1]) + (r0[2] * r0[2] + r0[3] * r0[3])) + ((r1[0] * r1[0] + r1[1] * r1[1]) + (r1[2] * r1[2] + r1[3] * r1[3]));
;                 }
;                 ss += __shfl_xor(ss, 16); ss += __shfl_xor(ss, 32);
;                 if (fq == 0) part[(size_t)row * 16 + u.pn * 4 + wc] = ss;
	v_lshlrev_b32_e32 v64, 16, v76
	v_and_b32_e32 v65, 0xffff0000, v76
	v_lshlrev_b32_e32 v58, 16, v58
	v_fma_f32 v76, -v86, v87, 1.0
	v_fmac_f32_e32 v87, v76, v87
	v_div_scale_f32 v76, vcc, v69, v53, v69
	v_mul_f32_e32 v88, v76, v87
	v_fma_f32 v89, -v86, v88, v76
	v_fmac_f32_e32 v88, v89, v87
	v_div_scale_f32 v86, s[8:9], v52, v52, v58
	v_rcp_f32_e32 v89, v86
	v_rcp_f32_e32 v76, v53
	s_nop 0
	v_mul_f32_e32 v53, v69, v76
	v_exp_f32_e32 v49, v49
	v_fma_f32 v69, -v86, v89, 1.0
	v_fmac_f32_e32 v89, v69, v89
	v_rcp_f32_e32 v69, v52
	s_nop 0
	v_mul_f32_e32 v52, v58, v69
	v_and_b32_e32 v58, 0xffff0000, v59
	v_div_scale_f32 v69, s[8:9], v55, v55, v58
	v_rcp_f32_e32 v76, v69
	v_pk_add_f32 v[52:53], v[52:53], v[64:65]
	v_lshlrev_b32_e32 v64, 16, v77
	v_and_b32_e32 v65, 0xffff0000, v77
	v_fma_f32 v77, -v69, v76, 1.0
	v_fmac_f32_e32 v76, v77, v76
	v_div_scale_f32 v77, vcc, v58, v55, v58
	v_mul_f32_e32 v86, v77, v76
	v_fma_f32 v87, -v69, v86, v77
	v_lshlrev_b32_e32 v59, 16, v59
	v_fmac_f32_e32 v86, v87, v76
	v_div_scale_f32 v77, s[8:9], v54, v54, v59
	v_rcp_f32_e32 v87, v77
	v_rcp_f32_e32 v69, v55
	s_nop 0
	v_mul_f32_e32 v55, v58, v69
	v_pk_add_f32 v[48:49], v[48:49], 1.0 op_sel_hi:[1,0]
	v_fma_f32 v58, -v77, v87, 1.0
	v_fmac_f32_e32 v87, v58, v87
	v_rcp_f32_e32 v58, v54
	s_nop 0
	v_mul_f32_e32 v54, v59, v58
	v_pk_add_f32 v[54:55], v[54:55], v[64:65]
	v_and_b32_e32 v64, 0xffff0000, v60
	v_lshlrev_b32_e32 v58, 16, v78
	v_and_b32_e32 v59, 0xffff0000, v78
	v_lshlrev_b32_e32 v60, 16, v60
	v_div_scale_f32 v76, s[8:9], v48, v48, v60
	v_rcp_f32_e32 v78, v76
	v_rcp_f32_e32 v65, v49
	s_nop 0
	v_mul_f32_e32 v49, v64, v65
	v_mul_f32_e32 v50, 0x3fb8aa3b, v50
	v_fma_f32 v64, -v76, v78, 1.0
	v_fmac_f32_e32 v78, v64, v78
	v_mul_f32_e32 v51, 0x3fb8aa3b, v51
	v_exp_f32_e32 v50, v50
	v_exp_f32_e32 v51, v51
	v_rcp_f32_e32 v64, v48
	s_nop 0
	v_mul_f32_e32 v48, v60, v64
	v_pk_add_f32 v[58:59], v[48:49], v[58:59]
	v_and_b32_e32 v60, 0xffff0000, v61
	v_pk_add_f32 v[48:49], v[50:51], 1.0 op_sel_hi:[1,0]
	v_lshlrev_b32_e32 v61, 16, v61
	v_lshlrev_b32_e32 v50, 16, v79
	v_and_b32_e32 v51, 0xffff0000, v79
	v_cvt_pk_bf16_f32 v68, v82, v83
	v_div_scale_f32 v69, s[8:9], v48, v48, v61
	v_rcp_f32_e32 v64, v49
	s_nop 0
	v_mul_f32_e32 v49, v60, v64
	v_pk_mul_f32 v[82:83], v[82:83], v[82:83]
	v_div_scale_f32 v60, vcc, v61, v48, v61
	v_rcp_f32_e32 v60, v48
	s_nop 0
	v_mul_f32_e32 v48, v61, v60
	v_pk_add_f32 v[60:61], v[48:49], v[50:51]
	v_pk_mul_f32 v[48:49], v[52:53], v[52:53]
	v_pk_mul_f32 v[50:51], v[54:55], v[54:55]
	v_pk_mul_f32 v[84:85], v[70:71], v[70:71]
	v_add_f32_e32 v50, v50, v51
	v_add_f32_e32 v48, v48, v49
	v_cvt_pk_bf16_f32 v66, v62, v63
	v_cvt_pk_bf16_f32 v67, v80, v81
	v_pk_mul_f32 v[62:63], v[62:63], v[62:63]
	v_pk_mul_f32 v[80:81], v[80:81], v[80:81]
	v_pk_mul_f32 v[64:65], v[58:59], v[58:59]
	v_pk_mul_f32 v[76:77], v[60:61], v[60:61]
	v_add_f32_e32 v48, v48, v50
	v_add_f32_e32 v49, v84, v85
	v_add_f32_e32 v50, v82, v83
	v_add_f32_e32 v69, v76, v77
	v_add_f32_e32 v64, v64, v65
	v_add_f32_e32 v49, v50, v49
	v_add_f32_e32 v50, v80, v81
	v_add_f32_e32 v51, v62, v63
	v_add_f32_e32 v64, v64, v69
	v_add_f32_e32 v50, v51, v50
	v_add_f32_e32 v48, v48, v64
	v_add_f32_e32 v49, v50, v49
	v_add_f32_e32 v48, v49, v48
	ds_bpermute_b32 v49, v181, v48
	v_cvt_pk_bf16_f32 v69, v70, v71
	v_cvt_pk_bf16_f32 v50, v52, v53
	v_cvt_pk_bf16_f32 v51, v54, v55
	v_cvt_pk_bf16_f32 v52, v58, v59
	s_waitcnt lgkmcnt(0)
	v_add_f32_e32 v48, v48, v49
	ds_bpermute_b32 v49, v180, v48
	v_cvt_pk_bf16_f32 v53, v60, v61
	v_lshl_add_u64 v[54:55], s[24:25], 0, v[74:75]
	global_store_dwordx4 v[56:57], v[66:69], off
	global_store_dwordx4 v[54:55], v[50:53], off
	s_and_saveexec_b64 s[8:9], s[4:5]
	s_cbranch_execz .LBB0_1757
	v_lshlrev_b64 v[50:51], 4, v[72:73]
	s_waitcnt lgkmcnt(0)
	v_add_f32_e32 v52, v48, v49
	v_lshl_add_u64 v[48:49], v[50:51], 2, s[26:27]
	v_lshl_add_u64 v[48:49], s[48:49], 2, v[48:49]
	s_lshl_b32 s34, s61, 2
	v_lshl_add_u64 v[48:49], v[48:49], 0, s[34:35]
	global_store_dword v[48:49], v52, off
.LBB0_1757:
	s_or_b64 exec, exec, s[8:9]
	v_add_u32_e32 v56, 0x90, v154
	v_ashrrev_i32_e32 v57, 31, v56
	s_waitcnt lgkmcnt(0)
	v_lshlrev_b64 v[48:49], 6, v[56:57]
	v_lshl_add_u64 v[48:49], s[22:23], 0, v[48:49]
	global_load_dwordx4 v[60:63], v[48:49], off
	global_load_dwordx4 v[64:67], v[48:49], off offset:16
	global_load_dwordx4 v[68:71], v[48:49], off offset:32
	global_load_dwordx4 v[72:75], v[48:49], off offset:48
	v_lshlrev_b64 v[48:49], 10, v[56:57]
	v_lshl_add_u64 v[48:49], v[48:49], 0, v[152:153]
	v_lshlrev_b64 v[58:59], 1, v[48:49]
	v_lshl_add_u64 v[48:49], s[16:17], 0, v[58:59]
	global_load_dwordx4 v[48:51], v[48:49], off
	v_lshl_add_u64 v[52:53], s[20:21], 0, v[58:59]
	global_load_dwordx4 v[52:55], v[52:53], off
	s_waitcnt vmcnt(4)
	v_pk_add_f32 v[62:63], v[62:63], v[66:67]
	v_pk_add_f32 v[60:61], v[60:61], v[64:65]
	s_waitcnt vmcnt(2)
	v_pk_add_f32 v[64:65], v[70:71], v[74:75]
	v_pk_add_f32 v[66:67], v[68:69], v[72:73]
	v_pk_add_f32 v[62:63], v[62:63], v[64:65]
	v_pk_add_f32 v[60:61], v[60:61], v[66:67]
	s_waitcnt vmcnt(0)
; DI unsigned pk_bf16(float lo, float hi) { typedef float f2 __attribute__((ext_vector_type(2))); typedef __bf16 b2 __attribute__((ext_vector_type(2))); f2 v = {lo, hi}; b2 b = __builtin_convertvector(v, b2); return __builtin_bit_cast(unsigned, b); }
; DI float bf_lo(unsigned w) { return __uint_as_float(w << 16); }
; DI float bf_hi(unsigned w) { return __uint_as_float(w & 0xffff0000u); }
;     DI void operator()(const f32x4 (&acc)[2][2][4][2], const pg8::Unit& u, int wr, int wc, int fr, int fq) const {
;     ...
;                 const int row = row0 + ai * 128 + m * 16;
;                 const size_t off = (size_t)row * ldc + col0;
;                 const f32x4* pq = (const f32x4*)(partin + (size_t)row * 16); const f32x4 t4 = (pq[0] + pq[1]) + (pq[2] + pq[3]);
;                 const float rs = -1.0f / sqrtf(((t4.x + t4.y) + (t4.z + t4.w)) * (1.f / DM) + NORM_EPS);
;                 float ss = 0.f;
; #pragma unroll
;                 for (int bj = 0; bj < 2; ++bj) {
;                     const size_t o2 = off + bj * 128;
;                     const u32x4 pw = *(const u32x4*)(pp + o2), bw = *(const u32x4*)(base + o2);
;                     const f32x4 a0 = acc[ai][bj][m][0] * rs, a1 = acc[ai][bj][m][1] * rs;
;                     f32x4 r0, r1;
;                     r0[0] = bf_lo(bw.x) + bf_lo(pw.x) / (1.f + __expf(a0[0])); r0[1] = bf_hi(bw.x) + bf_hi(pw.x) / (1.f + __expf(a0[1]));
;                     r0[2] = bf_lo(bw.y) + bf_lo(pw.y) / (1.f + __expf(a0[2])); r0[3] = bf_hi(bw.y) + bf_hi(pw.y) / (1.f + __expf(a0[3]));
;                     r1[0] = bf_lo(bw.z) + bf_lo(pw.z) / (1.f + __expf(a1[0])); r1[1] = bf_hi(bw.z) + bf_hi(pw.z) / (1.f + __expf(a1[1]));
;                     r1[2] = bf_lo(bw.w) + bf_lo(pw.w) / (1.f + __expf(a1[2])); r1[3] = bf_hi(bw.w) + bf_hi(pw.w) / (1.f + __expf(a1[3]));
;                     u32x4 w; w.x = pk_bf16(r0[0], r0[1]); w.y = pk_bf16(r0[2], r0[3]); w.z = pk_bf16(r1[0], r1[1]); w.w = pk_bf16(r1[2], r1[3]);
;                     *(u32x4*)(hb + o2) = w;
	v_lshlrev_b32_e32 v66, 16, v52
	v_pk_mov_b32 v[64:65], v[60:61], v[62:63] op_sel:[1,0]
	v_mov_b32_e32 v61, v63
	v_pk_add_f32 v[60:61], v[64:65], v[60:61]
	v_lshlrev_b32_e32 v62, 16, v48
	v_and_b32_e32 v63, 0xffff0000, v48
	v_add_f32_e32 v48, v60, v61
	v_fmamk_f32 v48, v48, 0x3a800000, v178
	v_and_b32_e32 v67, 0xffff0000, v52
	v_mul_f32_e32 v52, 0x4f800000, v48
	v_cmp_gt_f32_e32 vcc, s72, v48
	v_lshlrev_b32_e32 v60, 16, v49
	v_and_b32_e32 v61, 0xffff0000, v49
	v_cndmask_b32_e32 v48, v48, v52, vcc
	v_sqrt_f32_e32 v52, v48
	v_lshlrev_b32_e32 v49, 16, v53
	s_nop 1
	v_mul_f32_e32 v64, 0x37800000, v52
	v_cndmask_b32_e32 v52, v52, v64, vcc
	v_cmp_class_f32_e32 vcc, v48, v179
	v_and_b32_e32 v65, 0xffff0000, v53
	s_nop 0
	v_cndmask_b32_e32 v48, v52, v48, vcc
	v_rcp_f32_e32 v52, v48
	s_nop 0
	v_mul_f32_e32 v48, -1.0, v52
	v_pk_mul_f32 v[44:45], v[44:45], v[48:49] op_sel_hi:[1,0]
	v_pk_mul_f32 v[46:47], v[46:47], v[48:49] op_sel_hi:[1,0]
	v_pk_mul_f32 v[52:53], v[42:43], v[48:49] op_sel_hi:[1,0]
	v_pk_mul_f32 v[40:41], v[40:41], v[48:49] op_sel_hi:[1,0]
	v_mul_f32_e32 v42, 0x3fb8aa3b, v44
	v_mul_f32_e32 v43, 0x3fb8aa3b, v45
	v_mul_f32_e32 v44, 0x3fb8aa3b, v46
	v_mul_f32_e32 v45, 0x3fb8aa3b, v47
	v_mul_f32_e32 v46, 0x3fb8aa3b, v40
	v_mul_f32_e32 v47, 0x3fb8aa3b, v41
	v_exp_f32_e32 v40, v42
	v_exp_f32_e32 v41, v43
	v_exp_f32_e32 v42, v44
	v_exp_f32_e32 v43, v45
	v_exp_f32_e32 v44, v46
	v_pk_add_f32 v[40:41], v[40:41], 1.0 op_sel_hi:[1,0]
	v_exp_f32_e32 v45, v47
	v_div_scale_f32 v46, s[8:9], v41, v41, v67
	v_pk_add_f32 v[42:43], v[42:43], 1.0 op_sel_hi:[1,0]
	v_div_scale_f32 v64, s[8:9], v40, v40, v66
	v_rcp_f32_e32 v73, v46
	v_div_scale_f32 v69, s[10:11], v43, v43, v65
	v_rcp_f32_e32 v74, v64
	v_div_scale_f32 v71, s[12:13], v42, v42, v49
	v_rcp_f32_e32 v75, v69
	v_rcp_f32_e32 v76, v71
	v_fma_f32 v77, -v46, v73, 1.0
	v_div_scale_f32 v47, vcc, v67, v41, v67
	v_fma_f32 v78, -v64, v74, 1.0
	v_fmac_f32_e32 v73, v77, v73
	v_div_scale_f32 v68, s[8:9], v66, v40, v66
	v_fma_f32 v79, -v69, v75, 1.0
	v_fmac_f32_e32 v74, v78, v74
	v_mul_f32_e32 v77, v47, v73
	v_div_scale_f32 v70, s[10:11], v65, v43, v65
	v_fma_f32 v80, -v71, v76, 1.0
	v_fmac_f32_e32 v75, v79, v75
	v_mul_f32_e32 v78, v68, v74
	v_fma_f32 v81, -v46, v77, v47
	v_div_scale_f32 v72, s[12:13], v49, v42, v49
	v_fmac_f32_e32 v76, v80, v76
	v_mul_f32_e32 v79, v70, v75
	v_fma_f32 v82, -v64, v78, v68
	v_fmac_f32_e32 v77, v81, v73
	v_mul_f32_e32 v80, v72, v76
	v_fma_f32 v83, -v69, v79, v70
	v_fmac_f32_e32 v78, v82, v74
	v_fma_f32 v84, -v71, v80, v72
	v_fmac_f32_e32 v79, v83, v75
	v_fmac_f32_e32 v80, v84, v76
	v_rcp_f32_e32 v46, v41
	s_nop 0
	v_mul_f32_e32 v41, v67, v46
	v_rcp_f32_e32 v46, v40
	s_nop 0
	v_mul_f32_e32 v40, v66, v46
	s_mov_b64 vcc, s[12:13]
	v_pk_add_f32 v[46:47], v[40:41], v[62:63]
	v_rcp_f32_e32 v40, v42
	s_nop 0
	v_mul_f32_e32 v40, v49, v40
	v_and_b32_e32 v49, 0xffff0000, v54
	v_pk_add_f32 v[66:67], v[44:45], 1.0 op_sel_hi:[1,0]
	v_rcp_f32_e32 v64, v43
	s_nop 0
	v_mul_f32_e32 v41, v65, v64
	v_pk_add_f32 v[64:65], v[40:41], v[60:61]
	v_lshlrev_b32_e32 v68, 16, v50
	v_and_b32_e32 v69, 0xffff0000, v50
	v_lshl_add_u64 v[40:41], s[24:25], 0, v[58:59]
	v_or_b32_e32 v58, 0x100, v58
	v_lshl_add_u64 v[42:43], s[20:21], 0, v[58:59]
	global_load_dwordx4 v[42:45], v[42:43], off
	v_lshl_add_u64 v[60:61], s[16:17], 0, v[58:59]
	global_load_dwordx4 v[60:63], v[60:61], off
	v_lshlrev_b32_e32 v50, 16, v54
	v_rcp_f32_e32 v54, v67
	s_nop 0
	v_mul_f32_e32 v67, v49, v54
	v_mul_f32_e32 v52, 0x3fb8aa3b, v52
	v_mul_f32_e32 v53, 0x3fb8aa3b, v53
	v_exp_f32_e32 v52, v52
	v_exp_f32_e32 v53, v53
	v_rcp_f32_e32 v49, v66
	s_nop 0
	v_mul_f32_e32 v66, v50, v49
	v_and_b32_e32 v49, 0xffff0000, v55
	v_pk_add_f32 v[52:53], v[52:53], 1.0 op_sel_hi:[1,0]
	v_pk_add_f32 v[66:67], v[66:67], v[68:69]
	v_lshlrev_b32_e32 v55, 16, v55
	v_lshlrev_b32_e32 v50, 16, v51
	v_and_b32_e32 v51, 0xffff0000, v51
	v_div_scale_f32 v69, s[8:9], v52, v52, v55
	v_rcp_f32_e32 v71, v69
	v_rcp_f32_e32 v54, v53
	s_nop 0
	v_mul_f32_e32 v53, v49, v54
	v_fma_f32 v49, -v69, v71, 1.0
	v_fmac_f32_e32 v71, v49, v71
	v_div_scale_f32 v49, vcc, v55, v52, v55
	v_mul_f32_e32 v54, v49, v71
	v_fma_f32 v68, -v69, v54, v49
	v_fmac_f32_e32 v54, v68, v71
	v_fma_f32 v49, -v69, v54, v49
	v_div_fmas_f32 v49, v49, v71, v54
	v_pk_mul_f32 v[36:37], v[36:37], v[48:49] op_sel_hi:[1,0]
	v_rcp_f32_e32 v49, v52
	s_nop 0
	v_mul_f32_e32 v52, v55, v49
	v_mul_f32_e32 v36, 0x3fb8aa3b, v36
	v_mul_f32_e32 v37, 0x3fb8aa3b, v37
	v_exp_f32_e32 v36, v36
	v_exp_f32_e32 v37, v37
	v_pk_add_f32 v[54:55], v[52:53], v[50:51]
	v_pk_mul_f32 v[38:39], v[38:39], v[48:49] op_sel_hi:[1,0]
	v_pk_mul_f32 v[34:35], v[34:35], v[48:49] op_sel_hi:[1,0]
	v_pk_add_f32 v[36:37], v[36:37], 1.0 op_sel_hi:[1,0]
	v_pk_mul_f32 v[32:33], v[32:33], v[48:49] op_sel_hi:[1,0]
	v_mul_f32_e32 v38, 0x3fb8aa3b, v38
	v_mul_f32_e32 v39, 0x3fb8aa3b, v39
	v_exp_f32_e32 v38, v38
	v_exp_f32_e32 v39, v39
	v_mul_f32_e32 v32, 0x3fb8aa3b, v32
	v_mul_f32_e32 v33, 0x3fb8aa3b, v33
	v_exp_f32_e32 v32, v32
	v_pk_add_f32 v[38:39], v[38:39], 1.0 op_sel_hi:[1,0]
	s_waitcnt vmcnt(1)
	v_and_b32_e32 v53, 0xffff0000, v42
	v_div_scale_f32 v70, s[8:9], v37, v37, v53
	v_rcp_f32_e32 v71, v70
	s_waitcnt vmcnt(0)
; DI unsigned pk_bf16(float lo, float hi) { typedef float f2 __attribute__((ext_vector_type(2))); typedef __bf16 b2 __attribute__((ext_vector_type(2))); f2 v = {lo, hi}; b2 b = __builtin_convertvector(v, b2); return __builtin_bit_cast(unsigned, b); }
; DI float bf_lo(unsigned w) { return __uint_as_float(w << 16); }
; DI float bf_hi(unsigned w) { return __uint_as_float(w & 0xffff0000u); }
;     DI void operator()(const f32x4 (&acc)[2][2][4][2], const pg8::Unit& u, int wr, int wc, int fr, int fq) const {
;     ...
;                 for (int bj = 0; bj < 2; ++bj) {
;                     const size_t o2 = off + bj * 128;
;                     const u32x4 pw = *(const u32x4*)(pp + o2), bw = *(const u32x4*)(base + o2);
;                     const f32x4 a0 = acc[ai][bj][m][0] * rs, a1 = acc[ai][bj][m][1] * rs;
;                     f32x4 r0, r1;
;                     r0[0] = bf_lo(bw.x) + bf_lo(pw.x) / (1.f + __expf(a0[0])); r0[1] = bf_hi(bw.x) + bf_hi(pw.x) / (1.f + __expf(a0[1]));
;                     r0[2] = bf_lo(bw.y) + bf_lo(pw.y) / (1.f + __expf(a0[2])); r0[3] = bf_hi(bw.y) + bf_hi(pw.y) / (1.f + __expf(a0[3]));
;                     r1[0] = bf_lo(bw.z) + bf_lo(pw.z) / (1.f + __expf(a1[0])); r1[1] = bf_hi(bw.z) + bf_hi(pw.z) / (1.f + __expf(a1[1]));
;                     r1[2] = bf_lo(bw.w) + bf_lo(pw.w) / (1.f + __expf(a1[2])); r1[3] = bf_hi(bw.w) + bf_hi(pw.w) / (1.f + __expf(a1[3]));
;                     u32x4 w; w.x = pk_bf16(r0[0], r0[1]); w.y = pk_bf16(r0[2], r0[3]); w.z = pk_bf16(r1[0], r1[1]); w.w = pk_bf16(r1[2], r1[3]);
;                     *(u32x4*)(hb + o2) = w;
;                     ss += ((r0[0] * r0[0] + r0[1] * r0[1]) + (r0[2] * r0[2] + r0[3] * r0[3])) + ((r1[0] * r1[0] + r1[1] * r1[1]) + (r1[2] * r1[2] + r1[3] * r1[3]));
;                 }
;                 ss += __shfl_xor(ss, 16); ss += __shfl_xor(ss, 32);
;                 if (fq == 0) part[(size_t)row * 16 + u.pn * 4 + wc] = ss;
	v_lshlrev_b32_e32 v48, 16, v60
	v_and_b32_e32 v49, 0xffff0000, v60
	v_lshlrev_b32_e32 v42, 16, v42
	v_fma_f32 v60, -v70, v71, 1.0
	v_fmac_f32_e32 v71, v60, v71
	v_div_scale_f32 v60, vcc, v53, v37, v53
	v_mul_f32_e32 v72, v60, v71
	v_fma_f32 v73, -v70, v72, v60
	v_fmac_f32_e32 v72, v73, v71
	v_div_scale_f32 v70, s[8:9], v36, v36, v42
	v_rcp_f32_e32 v73, v70
	v_rcp_f32_e32 v60, v37
	s_nop 0
	v_mul_f32_e32 v37, v53, v60
	v_exp_f32_e32 v33, v33
	v_fma_f32 v53, -v70, v73, 1.0
	v_fmac_f32_e32 v73, v53, v73
	v_rcp_f32_e32 v53, v36
	s_nop 0
	v_mul_f32_e32 v36, v42, v53
	v_and_b32_e32 v42, 0xffff0000, v43
	v_div_scale_f32 v53, s[8:9], v39, v39, v42
	v_rcp_f32_e32 v60, v53
	v_pk_add_f32 v[36:37], v[36:37], v[48:49]
	v_lshlrev_b32_e32 v48, 16, v61
	v_and_b32_e32 v49, 0xffff0000, v61
	v_fma_f32 v61, -v53, v60, 1.0
	v_fmac_f32_e32 v60, v61, v60
	v_div_scale_f32 v61, vcc, v42, v39, v42
	v_mul_f32_e32 v70, v61, v60
	v_fma_f32 v71, -v53, v70, v61
	v_lshlrev_b32_e32 v43, 16, v43
	v_fmac_f32_e32 v70, v71, v60
	v_div_scale_f32 v61, s[8:9], v38, v38, v43
	v_rcp_f32_e32 v71, v61
	v_rcp_f32_e32 v53, v39
	s_nop 0
	v_mul_f32_e32 v39, v42, v53
	v_pk_add_f32 v[32:33], v[32:33], 1.0 op_sel_hi:[1,0]
	v_fma_f32 v42, -v61, v71, 1.0
	v_fmac_f32_e32 v71, v42, v71
	v_rcp_f32_e32 v42, v38
	s_nop 0
	v_mul_f32_e32 v38, v43, v42
	v_pk_add_f32 v[38:39], v[38:39], v[48:49]
	v_and_b32_e32 v48, 0xffff0000, v44
	v_lshlrev_b32_e32 v42, 16, v62
	v_and_b32_e32 v43, 0xffff0000, v62
	v_lshlrev_b32_e32 v44, 16, v44
	v_div_scale_f32 v60, s[8:9], v32, v32, v44
	v_rcp_f32_e32 v62, v60
	v_rcp_f32_e32 v49, v33
	s_nop 0
	v_mul_f32_e32 v33, v48, v49
	v_mul_f32_e32 v34, 0x3fb8aa3b, v34
	v_fma_f32 v48, -v60, v62, 1.0
	v_fmac_f32_e32 v62, v48, v62
	v_mul_f32_e32 v35, 0x3fb8aa3b, v35
	v_exp_f32_e32 v34, v34
	v_exp_f32_e32 v35, v35
	v_rcp_f32_e32 v48, v32
	s_nop 0
	v_mul_f32_e32 v32, v44, v48
	v_pk_add_f32 v[42:43], v[32:33], v[42:43]
	v_and_b32_e32 v44, 0xffff0000, v45
	v_pk_add_f32 v[32:33], v[34:35], 1.0 op_sel_hi:[1,0]
	v_lshlrev_b32_e32 v45, 16, v45
	v_lshlrev_b32_e32 v34, 16, v63
	v_and_b32_e32 v35, 0xffff0000, v63
	v_cvt_pk_bf16_f32 v52, v66, v67
	v_div_scale_f32 v53, s[8:9], v32, v32, v45
	v_rcp_f32_e32 v48, v33
	s_nop 0
	v_mul_f32_e32 v33, v44, v48
	v_pk_mul_f32 v[66:67], v[66:67], v[66:67]
	v_div_scale_f32 v44, vcc, v45, v32, v45
	v_rcp_f32_e32 v44, v32
	s_nop 0
	v_mul_f32_e32 v32, v45, v44
	v_pk_add_f32 v[44:45], v[32:33], v[34:35]
	v_pk_mul_f32 v[32:33], v[36:37], v[36:37]
	v_pk_mul_f32 v[34:35], v[38:39], v[38:39]
	v_pk_mul_f32 v[68:69], v[54:55], v[54:55]
	v_add_f32_e32 v34, v34, v35
	v_add_f32_e32 v32, v32, v33
	v_cvt_pk_bf16_f32 v50, v46, v47
	v_cvt_pk_bf16_f32 v51, v64, v65
	v_pk_mul_f32 v[46:47], v[46:47], v[46:47]
	v_pk_mul_f32 v[64:65], v[64:65], v[64:65]
	v_pk_mul_f32 v[48:49], v[42:43], v[42:43]
	v_pk_mul_f32 v[60:61], v[44:45], v[44:45]
	v_add_f32_e32 v32, v32, v34
	v_add_f32_e32 v33, v68, v69
	v_add_f32_e32 v34, v66, v67
	v_add_f32_e32 v53, v60, v61
	v_add_f32_e32 v48, v48, v49
	v_add_f32_e32 v33, v34, v33
	v_add_f32_e32 v34, v64, v65
	v_add_f32_e32 v35, v46, v47
	v_add_f32_e32 v48, v48, v53
	v_add_f32_e32 v34, v35, v34
	v_add_f32_e32 v32, v32, v48
	v_add_f32_e32 v33, v34, v33
	v_add_f32_e32 v32, v33, v32
	ds_bpermute_b32 v33, v181, v32
	v_cvt_pk_bf16_f32 v53, v54, v55
	v_cvt_pk_bf16_f32 v34, v36, v37
	v_cvt_pk_bf16_f32 v35, v38, v39
	v_cvt_pk_bf16_f32 v36, v42, v43
	s_waitcnt lgkmcnt(0)
	v_add_f32_e32 v32, v32, v33
	ds_bpermute_b32 v33, v180, v32
	v_cvt_pk_bf16_f32 v37, v44, v45
	v_lshl_add_u64 v[38:39], s[24:25], 0, v[58:59]
	global_store_dwordx4 v[40:41], v[50:53], off
	global_store_dwordx4 v[38:39], v[34:37], off
	s_and_saveexec_b64 s[8:9], s[4:5]
	s_cbranch_execz .LBB0_1759
	v_lshlrev_b64 v[34:35], 4, v[56:57]
	s_waitcnt lgkmcnt(0)
	v_add_f32_e32 v36, v32, v33
	v_lshl_add_u64 v[32:33], v[34:35], 2, s[26:27]
	v_lshl_add_u64 v[32:33], s[48:49], 2, v[32:33]
	s_lshl_b32 s34, s61, 2
	v_lshl_add_u64 v[32:33], v[32:33], 0, s[34:35]
	global_store_dword v[32:33], v36, off
.LBB0_1759:
	s_or_b64 exec, exec, s[8:9]
	v_add_u32_e32 v40, 0xa0, v154
	v_ashrrev_i32_e32 v41, 31, v40
	s_waitcnt lgkmcnt(0)
	v_lshlrev_b64 v[32:33], 6, v[40:41]
	v_lshl_add_u64 v[32:33], s[22:23], 0, v[32:33]
	global_load_dwordx4 v[44:47], v[32:33], off
	global_load_dwordx4 v[48:51], v[32:33], off offset:16
	global_load_dwordx4 v[52:55], v[32:33], off offset:32
	global_load_dwordx4 v[56:59], v[32:33], off offset:48
	v_lshlrev_b64 v[32:33], 10, v[40:41]
	v_lshl_add_u64 v[32:33], v[32:33], 0, v[152:153]
	v_lshlrev_b64 v[42:43], 1, v[32:33]
	v_lshl_add_u64 v[32:33], s[16:17], 0, v[42:43]
	global_load_dwordx4 v[32:35], v[32:33], off
	v_lshl_add_u64 v[36:37], s[20:21], 0, v[42:43]
	global_load_dwordx4 v[36:39], v[36:37], off
	s_waitcnt vmcnt(4)
	v_pk_add_f32 v[46:47], v[46:47], v[50:51]
	v_pk_add_f32 v[44:45], v[44:45], v[48:49]
	s_waitcnt vmcnt(2)
	v_pk_add_f32 v[48:49], v[54:55], v[58:59]
	v_pk_add_f32 v[50:51], v[52:53], v[56:57]
	v_pk_add_f32 v[46:47], v[46:47], v[48:49]
	v_pk_add_f32 v[44:45], v[44:45], v[50:51]
	s_waitcnt vmcnt(0)
; DI unsigned pk_bf16(float lo, float hi) { typedef float f2 __attribute__((ext_vector_type(2))); typedef __bf16 b2 __attribute__((ext_vector_type(2))); f2 v = {lo, hi}; b2 b = __builtin_convertvector(v, b2); return __builtin_bit_cast(unsigned, b); }
; DI float bf_lo(unsigned w) { return __uint_as_float(w << 16); }
; DI float bf_hi(unsigned w) { return __uint_as_float(w & 0xffff0000u); }
;     DI void operator()(const f32x4 (&acc)[2][2][4][2], const pg8::Unit& u, int wr, int wc, int fr, int fq) const {
;     ...
;                 const int row = row0 + ai * 128 + m * 16;
;                 const size_t off = (size_t)row * ldc + col0;
;                 const f32x4* pq = (const f32x4*)(partin + (size_t)row * 16); const f32x4 t4 = (pq[0] + pq[1]) + (pq[2] + pq[3]);
;                 const float rs = -1.0f / sqrtf(((t4.x + t4.y) + (t4.z + t4.w)) * (1.f / DM) + NORM_EPS);
;                 float ss = 0.f;
; #pragma unroll
;                 for (int bj = 0; bj < 2; ++bj) {
;                     const size_t o2 = off + bj * 128;
;                     const u32x4 pw = *(const u32x4*)(pp + o2), bw = *(const u32x4*)(base + o2);
;                     const f32x4 a0 = acc[ai][bj][m][0] * rs, a1 = acc[ai][bj][m][1] * rs;
;                     f32x4 r0, r1;
;                     r0[0] = bf_lo(bw.x) + bf_lo(pw.x) / (1.f + __expf(a0[0])); r0[1] = bf_hi(bw.x) + bf_hi(pw.x) / (1.f + __expf(a0[1]));
;                     r0[2] = bf_lo(bw.y) + bf_lo(pw.y) / (1.f + __expf(a0[2])); r0[3] = bf_hi(bw.y) + bf_hi(pw.y) / (1.f + __expf(a0[3]));
;                     r1[0] = bf_lo(bw.z) + bf_lo(pw.z) / (1.f + __expf(a1[0])); r1[1] = bf_hi(bw.z) + bf_hi(pw.z) / (1.f + __expf(a1[1]));
;                     r1[2] = bf_lo(bw.w) + bf_lo(pw.w) / (1.f + __expf(a1[2])); r1[3] = bf_hi(bw.w) + bf_hi(pw.w) / (1.f + __expf(a1[3]));
;                     u32x4 w; w.x = pk_bf16(r0[0], r0[1]); w.y = pk_bf16(r0[2], r0[3]); w.z = pk_bf16(r1[0], r1[1]); w.w = pk_bf16(r1[2], r1[3]);
;                     *(u32x4*)(hb + o2) = w;
	v_lshlrev_b32_e32 v50, 16, v36
	v_pk_mov_b32 v[48:49], v[44:45], v[46:47] op_sel:[1,0]
	v_mov_b32_e32 v45, v47
	v_pk_add_f32 v[44:45], v[48:49], v[44:45]
	v_lshlrev_b32_e32 v46, 16, v32
	v_and_b32_e32 v47, 0xffff0000, v32
	v_add_f32_e32 v32, v44, v45
	v_fmamk_f32 v32, v32, 0x3a800000, v178
	v_and_b32_e32 v51, 0xffff0000, v36
	v_mul_f32_e32 v36, 0x4f800000, v32
	v_cmp_gt_f32_e32 vcc, s72, v32
	v_lshlrev_b32_e32 v44, 16, v33
	v_and_b32_e32 v45, 0xffff0000, v33
	v_cndmask_b32_e32 v32, v32, v36, vcc
	v_sqrt_f32_e32 v36, v32
	v_lshlrev_b32_e32 v33, 16, v37
	s_nop 1
	v_mul_f32_e32 v48, 0x37800000, v36
	v_cndmask_b32_e32 v36, v36, v48, vcc
	v_cmp_class_f32_e32 vcc, v32, v179
	v_and_b32_e32 v49, 0xffff0000, v37
	s_nop 0
	v_cndmask_b32_e32 v32, v36, v32, vcc
	v_rcp_f32_e32 v36, v32
	s_nop 0
	v_mul_f32_e32 v32, -1.0, v36
	v_pk_mul_f32 v[28:29], v[28:29], v[32:33] op_sel_hi:[1,0]
	v_pk_mul_f32 v[30:31], v[30:31], v[32:33] op_sel_hi:[1,0]
	v_pk_mul_f32 v[36:37], v[26:27], v[32:33] op_sel_hi:[1,0]
	v_pk_mul_f32 v[24:25], v[24:25], v[32:33] op_sel_hi:[1,0]
	v_mul_f32_e32 v26, 0x3fb8aa3b, v28
	v_mul_f32_e32 v27, 0x3fb8aa3b, v29
	v_mul_f32_e32 v28, 0x3fb8aa3b, v30
	v_mul_f32_e32 v29, 0x3fb8aa3b, v31
	v_mul_f32_e32 v30, 0x3fb8aa3b, v24
	v_mul_f32_e32 v31, 0x3fb8aa3b, v25
	v_exp_f32_e32 v24, v26
	v_exp_f32_e32 v25, v27
	v_exp_f32_e32 v26, v28
	v_exp_f32_e32 v27, v29
	v_exp_f32_e32 v28, v30
	v_pk_add_f32 v[24:25], v[24:25], 1.0 op_sel_hi:[1,0]
	v_exp_f32_e32 v29, v31
	v_div_scale_f32 v30, s[8:9], v25, v25, v51
	v_pk_add_f32 v[26:27], v[26:27], 1.0 op_sel_hi:[1,0]
	v_div_scale_f32 v48, s[8:9], v24, v24, v50
	v_rcp_f32_e32 v57, v30
	v_div_scale_f32 v53, s[10:11], v27, v27, v49
	v_rcp_f32_e32 v58, v48
	v_div_scale_f32 v55, s[12:13], v26, v26, v33
	v_rcp_f32_e32 v59, v53
	v_rcp_f32_e32 v60, v55
	v_fma_f32 v61, -v30, v57, 1.0
	v_div_scale_f32 v31, vcc, v51, v25, v51
	v_fma_f32 v62, -v48, v58, 1.0
	v_fmac_f32_e32 v57, v61, v57
	v_div_scale_f32 v52, s[8:9], v50, v24, v50
	v_fma_f32 v63, -v53, v59, 1.0
	v_fmac_f32_e32 v58, v62, v58
	v_mul_f32_e32 v61, v31, v57
	v_div_scale_f32 v54, s[10:11], v49, v27, v49
	v_fma_f32 v64, -v55, v60, 1.0
	v_fmac_f32_e32 v59, v63, v59
	v_mul_f32_e32 v62, v52, v58
	v_fma_f32 v65, -v30, v61, v31
	v_div_scale_f32 v56, s[12:13], v33, v26, v33
	v_fmac_f32_e32 v60, v64, v60
	v_mul_f32_e32 v63, v54, v59
	v_fma_f32 v66, -v48, v62, v52
	v_fmac_f32_e32 v61, v65, v57
	v_mul_f32_e32 v64, v56, v60
	v_fma_f32 v67, -v53, v63, v54
	v_fmac_f32_e32 v62, v66, v58
	v_fma_f32 v68, -v55, v64, v56
	v_fmac_f32_e32 v63, v67, v59
	v_fmac_f32_e32 v64, v68, v60
	v_rcp_f32_e32 v30, v25
	s_nop 0
	v_mul_f32_e32 v25, v51, v30
	v_rcp_f32_e32 v30, v24
	s_nop 0
	v_mul_f32_e32 v24, v50, v30
	s_mov_b64 vcc, s[12:13]
	v_pk_add_f32 v[30:31], v[24:25], v[46:47]
	v_rcp_f32_e32 v24, v26
	s_nop 0
	v_mul_f32_e32 v24, v33, v24
	v_and_b32_e32 v33, 0xffff0000, v38
	v_pk_add_f32 v[50:51], v[28:29], 1.0 op_sel_hi:[1,0]
	v_rcp_f32_e32 v48, v27
	s_nop 0
	v_mul_f32_e32 v25, v49, v48
	v_pk_add_f32 v[48:49], v[24:25], v[44:45]
	v_lshlrev_b32_e32 v52, 16, v34
	v_and_b32_e32 v53, 0xffff0000, v34
	v_lshl_add_u64 v[24:25], s[24:25], 0, v[42:43]
	v_or_b32_e32 v42, 0x100, v42
	v_lshl_add_u64 v[26:27], s[20:21], 0, v[42:43]
	global_load_dwordx4 v[26:29], v[26:27], off
	v_lshl_add_u64 v[44:45], s[16:17], 0, v[42:43]
	global_load_dwordx4 v[44:47], v[44:45], off
	v_lshlrev_b32_e32 v34, 16, v38
	v_rcp_f32_e32 v38, v51
	s_nop 0
	v_mul_f32_e32 v51, v33, v38
	v_mul_f32_e32 v36, 0x3fb8aa3b, v36
	v_mul_f32_e32 v37, 0x3fb8aa3b, v37
	v_exp_f32_e32 v36, v36
	v_exp_f32_e32 v37, v37
	v_rcp_f32_e32 v33, v50
	s_nop 0
	v_mul_f32_e32 v50, v34, v33
	v_and_b32_e32 v33, 0xffff0000, v39
	v_pk_add_f32 v[36:37], v[36:37], 1.0 op_sel_hi:[1,0]
	v_pk_add_f32 v[50:51], v[50:51], v[52:53]
	v_lshlrev_b32_e32 v39, 16, v39
	v_lshlrev_b32_e32 v34, 16, v35
	v_and_b32_e32 v35, 0xffff0000, v35
	v_div_scale_f32 v53, s[8:9], v36, v36, v39
	v_rcp_f32_e32 v55, v53
	v_rcp_f32_e32 v38, v37
	s_nop 0
	v_mul_f32_e32 v37, v33, v38
	v_fma_f32 v33, -v53, v55, 1.0
	v_fmac_f32_e32 v55, v33, v55
	v_div_scale_f32 v33, vcc, v39, v36, v39
	v_mul_f32_e32 v38, v33, v55
	v_fma_f32 v52, -v53, v38, v33
	v_fmac_f32_e32 v38, v52, v55
	v_fma_f32 v33, -v53, v38, v33
	v_div_fmas_f32 v33, v33, v55, v38
	v_pk_mul_f32 v[20:21], v[20:21], v[32:33] op_sel_hi:[1,0]
	v_rcp_f32_e32 v33, v36
	s_nop 0
	v_mul_f32_e32 v36, v39, v33
	v_mul_f32_e32 v20, 0x3fb8aa3b, v20
	v_mul_f32_e32 v21, 0x3fb8aa3b, v21
	v_exp_f32_e32 v20, v20
	v_exp_f32_e32 v21, v21
	v_pk_add_f32 v[38:39], v[36:37], v[34:35]
	v_pk_mul_f32 v[22:23], v[22:23], v[32:33] op_sel_hi:[1,0]
	v_pk_mul_f32 v[18:19], v[18:19], v[32:33] op_sel_hi:[1,0]
	v_pk_add_f32 v[20:21], v[20:21], 1.0 op_sel_hi:[1,0]
	v_pk_mul_f32 v[16:17], v[16:17], v[32:33] op_sel_hi:[1,0]
	v_mul_f32_e32 v22, 0x3fb8aa3b, v22
	v_mul_f32_e32 v23, 0x3fb8aa3b, v23
	v_exp_f32_e32 v22, v22
	v_exp_f32_e32 v23, v23
	v_mul_f32_e32 v16, 0x3fb8aa3b, v16
	v_mul_f32_e32 v17, 0x3fb8aa3b, v17
	v_exp_f32_e32 v16, v16
	v_pk_add_f32 v[22:23], v[22:23], 1.0 op_sel_hi:[1,0]
	s_waitcnt vmcnt(1)
	v_and_b32_e32 v37, 0xffff0000, v26
	v_div_scale_f32 v54, s[8:9], v21, v21, v37
	v_rcp_f32_e32 v55, v54
	s_waitcnt vmcnt(0)
; DI unsigned pk_bf16(float lo, float hi) { typedef float f2 __attribute__((ext_vector_type(2))); typedef __bf16 b2 __attribute__((ext_vector_type(2))); f2 v = {lo, hi}; b2 b = __builtin_convertvector(v, b2); return __builtin_bit_cast(unsigned, b); }
; DI float bf_lo(unsigned w) { return __uint_as_float(w << 16); }
; DI float bf_hi(unsigned w) { return __uint_as_float(w & 0xffff0000u); }
;     DI void operator()(const f32x4 (&acc)[2][2][4][2], const pg8::Unit& u, int wr, int wc, int fr, int fq) const {
;     ...
;                 for (int bj = 0; bj < 2; ++bj) {
;                     const size_t o2 = off + bj * 128;
;                     const u32x4 pw = *(const u32x4*)(pp + o2), bw = *(const u32x4*)(base + o2);
;                     const f32x4 a0 = acc[ai][bj][m][0] * rs, a1 = acc[ai][bj][m][1] * rs;
;                     f32x4 r0, r1;
;                     r0[0] = bf_lo(bw.x) + bf_lo(pw.x) / (1.f + __expf(a0[0])); r0[1] = bf_hi(bw.x) + bf_hi(pw.x) / (1.f + __expf(a0[1]));
;                     r0[2] = bf_lo(bw.y) + bf_lo(pw.y) / (1.f + __expf(a0[2])); r0[3] = bf_hi(bw.y) + bf_hi(pw.y) / (1.f + __expf(a0[3]));
;                     r1[0] = bf_lo(bw.z) + bf_lo(pw.z) / (1.f + __expf(a1[0])); r1[1] = bf_hi(bw.z) + bf_hi(pw.z) / (1.f + __expf(a1[1]));
;                     r1[2] = bf_lo(bw.w) + bf_lo(pw.w) / (1.f + __expf(a1[2])); r1[3] = bf_hi(bw.w) + bf_hi(pw.w) / (1.f + __expf(a1[3]));
;                     u32x4 w; w.x = pk_bf16(r0[0], r0[1]); w.y = pk_bf16(r0[2], r0[3]); w.z = pk_bf16(r1[0], r1[1]); w.w = pk_bf16(r1[2], r1[3]);
;                     *(u32x4*)(hb + o2) = w;
;                     ss += ((r0[0] * r0[0] + r0[1] * r0[1]) + (r0[2] * r0[2] + r0[3] * r0[3])) + ((r1[0] * r1[0] + r1[1] * r1[1]) + (r1[2] * r1[2] + r1[3] * r1[3]));
;                 }
;                 ss += __shfl_xor(ss, 16); ss += __shfl_xor(ss, 32);
;                 if (fq == 0) part[(size_t)row * 16 + u.pn * 4 + wc] = ss;
	v_lshlrev_b32_e32 v32, 16, v44
	v_and_b32_e32 v33, 0xffff0000, v44
	v_lshlrev_b32_e32 v26, 16, v26
	v_fma_f32 v44, -v54, v55, 1.0
	v_fmac_f32_e32 v55, v44, v55
	v_div_scale_f32 v44, vcc, v37, v21, v37
	v_mul_f32_e32 v56, v44, v55
	v_fma_f32 v57, -v54, v56, v44
	v_fmac_f32_e32 v56, v57, v55
	v_div_scale_f32 v54, s[8:9], v20, v20, v26
	v_rcp_f32_e32 v57, v54
	v_rcp_f32_e32 v44, v21
	s_nop 0
	v_mul_f32_e32 v21, v37, v44
	v_exp_f32_e32 v17, v17
	v_fma_f32 v37, -v54, v57, 1.0
	v_fmac_f32_e32 v57, v37, v57
	v_rcp_f32_e32 v37, v20
	s_nop 0
	v_mul_f32_e32 v20, v26, v37
	v_and_b32_e32 v26, 0xffff0000, v27
	v_div_scale_f32 v37, s[8:9], v23, v23, v26
	v_rcp_f32_e32 v44, v37
	v_pk_add_f32 v[20:21], v[20:21], v[32:33]
	v_lshlrev_b32_e32 v32, 16, v45
	v_and_b32_e32 v33, 0xffff0000, v45
	v_fma_f32 v45, -v37, v44, 1.0
	v_fmac_f32_e32 v44, v45, v44
	v_div_scale_f32 v45, vcc, v26, v23, v26
	v_mul_f32_e32 v54, v45, v44
	v_fma_f32 v55, -v37, v54, v45
	v_lshlrev_b32_e32 v27, 16, v27
	v_fmac_f32_e32 v54, v55, v44
	v_div_scale_f32 v45, s[8:9], v22, v22, v27
	v_rcp_f32_e32 v55, v45
	v_rcp_f32_e32 v37, v23
	s_nop 0
	v_mul_f32_e32 v23, v26, v37
	v_pk_add_f32 v[16:17], v[16:17], 1.0 op_sel_hi:[1,0]
	v_fma_f32 v26, -v45, v55, 1.0
	v_fmac_f32_e32 v55, v26, v55
	v_rcp_f32_e32 v26, v22
	s_nop 0
	v_mul_f32_e32 v22, v27, v26
	v_pk_add_f32 v[22:23], v[22:23], v[32:33]
	v_and_b32_e32 v32, 0xffff0000, v28
	v_lshlrev_b32_e32 v26, 16, v46
	v_and_b32_e32 v27, 0xffff0000, v46
	v_lshlrev_b32_e32 v28, 16, v28
	v_div_scale_f32 v44, s[8:9], v16, v16, v28
	v_rcp_f32_e32 v46, v44
	v_rcp_f32_e32 v33, v17
	s_nop 0
	v_mul_f32_e32 v17, v32, v33
	v_mul_f32_e32 v18, 0x3fb8aa3b, v18
	v_fma_f32 v32, -v44, v46, 1.0
	v_fmac_f32_e32 v46, v32, v46
	v_mul_f32_e32 v19, 0x3fb8aa3b, v19
	v_exp_f32_e32 v18, v18
	v_exp_f32_e32 v19, v19
	v_rcp_f32_e32 v32, v16
	s_nop 0
	v_mul_f32_e32 v16, v28, v32
	v_pk_add_f32 v[26:27], v[16:17], v[26:27]
	v_and_b32_e32 v28, 0xffff0000, v29
	v_pk_add_f32 v[16:17], v[18:19], 1.0 op_sel_hi:[1,0]
	v_lshlrev_b32_e32 v29, 16, v29
	v_lshlrev_b32_e32 v18, 16, v47
	v_and_b32_e32 v19, 0xffff0000, v47
	v_cvt_pk_bf16_f32 v36, v50, v51
	v_div_scale_f32 v37, s[8:9], v16, v16, v29
	v_rcp_f32_e32 v32, v17
	s_nop 0
	v_mul_f32_e32 v17, v28, v32
	v_pk_mul_f32 v[50:51], v[50:51], v[50:51]
	v_div_scale_f32 v28, vcc, v29, v16, v29
	v_rcp_f32_e32 v28, v16
	s_nop 0
	v_mul_f32_e32 v16, v29, v28
	v_pk_add_f32 v[28:29], v[16:17], v[18:19]
	v_pk_mul_f32 v[16:17], v[20:21], v[20:21]
	v_pk_mul_f32 v[18:19], v[22:23], v[22:23]
	v_pk_mul_f32 v[52:53], v[38:39], v[38:39]
	v_add_f32_e32 v18, v18, v19
	v_add_f32_e32 v16, v16, v17
	v_cvt_pk_bf16_f32 v34, v30, v31
	v_cvt_pk_bf16_f32 v35, v48, v49
	v_pk_mul_f32 v[30:31], v[30:31], v[30:31]
	v_pk_mul_f32 v[48:49], v[48:49], v[48:49]
	v_pk_mul_f32 v[32:33], v[26:27], v[26:27]
	v_pk_mul_f32 v[44:45], v[28:29], v[28:29]
	v_add_f32_e32 v16, v16, v18
	v_add_f32_e32 v17, v52, v53
	v_add_f32_e32 v18, v50, v51
	v_add_f32_e32 v37, v44, v45
	v_add_f32_e32 v32, v32, v33
	v_add_f32_e32 v17, v18, v17
	v_add_f32_e32 v18, v48, v49
	v_add_f32_e32 v19, v30, v31
	v_add_f32_e32 v32, v32, v37
	v_add_f32_e32 v18, v19, v18
	v_add_f32_e32 v16, v16, v32
	v_add_f32_e32 v17, v18, v17
	v_add_f32_e32 v16, v17, v16
	ds_bpermute_b32 v17, v181, v16
	v_cvt_pk_bf16_f32 v37, v38, v39
	v_cvt_pk_bf16_f32 v18, v20, v21
	v_cvt_pk_bf16_f32 v19, v22, v23
	v_cvt_pk_bf16_f32 v20, v26, v27
	s_waitcnt lgkmcnt(0)
	v_add_f32_e32 v16, v16, v17
	ds_bpermute_b32 v17, v180, v16
	v_cvt_pk_bf16_f32 v21, v28, v29
	v_lshl_add_u64 v[22:23], s[24:25], 0, v[42:43]
	global_store_dwordx4 v[24:25], v[34:37], off
	global_store_dwordx4 v[22:23], v[18:21], off
	s_and_saveexec_b64 s[8:9], s[4:5]
	s_cbranch_execz .LBB0_1761
	v_lshlrev_b64 v[18:19], 4, v[40:41]
	s_waitcnt lgkmcnt(0)
	v_add_f32_e32 v20, v16, v17
	v_lshl_add_u64 v[16:17], v[18:19], 2, s[26:27]
	v_lshl_add_u64 v[16:17], s[48:49], 2, v[16:17]
	s_lshl_b32 s34, s61, 2
	v_lshl_add_u64 v[16:17], v[16:17], 0, s[34:35]
	global_store_dword v[16:17], v20, off
.LBB0_1761:
	s_or_b64 exec, exec, s[8:9]
	v_add_u32_e32 v24, 0xb0, v154
	v_ashrrev_i32_e32 v25, 31, v24
	s_waitcnt lgkmcnt(0)
	v_lshlrev_b64 v[16:17], 6, v[24:25]
	v_lshl_add_u64 v[16:17], s[22:23], 0, v[16:17]
	global_load_dwordx4 v[28:31], v[16:17], off
	global_load_dwordx4 v[32:35], v[16:17], off offset:16
	global_load_dwordx4 v[36:39], v[16:17], off offset:32
	global_load_dwordx4 v[40:43], v[16:17], off offset:48
	v_lshlrev_b64 v[16:17], 10, v[24:25]
	v_lshl_add_u64 v[16:17], v[16:17], 0, v[152:153]
	v_lshlrev_b64 v[26:27], 1, v[16:17]
	v_lshl_add_u64 v[16:17], s[16:17], 0, v[26:27]
	global_load_dwordx4 v[16:19], v[16:17], off
	v_lshl_add_u64 v[20:21], s[20:21], 0, v[26:27]
	global_load_dwordx4 v[20:23], v[20:21], off
	s_waitcnt vmcnt(4)
	v_pk_add_f32 v[30:31], v[30:31], v[34:35]
	v_pk_add_f32 v[28:29], v[28:29], v[32:33]
	s_waitcnt vmcnt(2)
	v_pk_add_f32 v[32:33], v[38:39], v[42:43]
	v_pk_add_f32 v[34:35], v[36:37], v[40:41]
	v_pk_add_f32 v[30:31], v[30:31], v[32:33]
	v_pk_add_f32 v[28:29], v[28:29], v[34:35]
	s_waitcnt vmcnt(0)
; DI unsigned pk_bf16(float lo, float hi) { typedef float f2 __attribute__((ext_vector_type(2))); typedef __bf16 b2 __attribute__((ext_vector_type(2))); f2 v = {lo, hi}; b2 b = __builtin_convertvector(v, b2); return __builtin_bit_cast(unsigned, b); }
; DI float bf_lo(unsigned w) { return __uint_as_float(w << 16); }
; DI float bf_hi(unsigned w) { return __uint_as_float(w & 0xffff0000u); }
;     DI void operator()(const f32x4 (&acc)[2][2][4][2], const pg8::Unit& u, int wr, int wc, int fr, int fq) const {
;     ...
;                 const int row = row0 + ai * 128 + m * 16;
;                 const size_t off = (size_t)row * ldc + col0;
;                 const f32x4* pq = (const f32x4*)(partin + (size_t)row * 16); const f32x4 t4 = (pq[0] + pq[1]) + (pq[2] + pq[3]);
;                 const float rs = -1.0f / sqrtf(((t4.x + t4.y) + (t4.z + t4.w)) * (1.f / DM) + NORM_EPS);
;                 float ss = 0.f;
; #pragma unroll
;                 for (int bj = 0; bj < 2; ++bj) {
;                     const size_t o2 = off + bj * 128;
;                     const u32x4 pw = *(const u32x4*)(pp + o2), bw = *(const u32x4*)(base + o2);
;                     const f32x4 a0 = acc[ai][bj][m][0] * rs, a1 = acc[ai][bj][m][1] * rs;
;                     f32x4 r0, r1;
;                     r0[0] = bf_lo(bw.x) + bf_lo(pw.x) / (1.f + __expf(a0[0])); r0[1] = bf_hi(bw.x) + bf_hi(pw.x) / (1.f + __expf(a0[1]));
;                     r0[2] = bf_lo(bw.y) + bf_lo(pw.y) / (1.f + __expf(a0[2])); r0[3] = bf_hi(bw.y) + bf_hi(pw.y) / (1.f + __expf(a0[3]));
;                     r1[0] = bf_lo(bw.z) + bf_lo(pw.z) / (1.f + __expf(a1[0])); r1[1] = bf_hi(bw.z) + bf_hi(pw.z) / (1.f + __expf(a1[1]));
;                     r1[2] = bf_lo(bw.w) + bf_lo(pw.w) / (1.f + __expf(a1[2])); r1[3] = bf_hi(bw.w) + bf_hi(pw.w) / (1.f + __expf(a1[3]));
;                     u32x4 w; w.x = pk_bf16(r0[0], r0[1]); w.y = pk_bf16(r0[2], r0[3]); w.z = pk_bf16(r1[0], r1[1]); w.w = pk_bf16(r1[2], r1[3]);
;                     *(u32x4*)(hb + o2) = w;
	v_lshlrev_b32_e32 v34, 16, v20
	v_pk_mov_b32 v[32:33], v[28:29], v[30:31] op_sel:[1,0]
	v_mov_b32_e32 v29, v31
	v_pk_add_f32 v[28:29], v[32:33], v[28:29]
	v_lshlrev_b32_e32 v30, 16, v16
	v_and_b32_e32 v31, 0xffff0000, v16
	v_add_f32_e32 v16, v28, v29
	v_fmamk_f32 v16, v16, 0x3a800000, v178
	v_and_b32_e32 v35, 0xffff0000, v20
	v_mul_f32_e32 v20, 0x4f800000, v16
	v_cmp_gt_f32_e32 vcc, s72, v16
	v_lshlrev_b32_e32 v28, 16, v17
	v_and_b32_e32 v29, 0xffff0000, v17
	v_cndmask_b32_e32 v16, v16, v20, vcc
	v_sqrt_f32_e32 v20, v16
	v_lshlrev_b32_e32 v17, 16, v21
	s_nop 1
	v_mul_f32_e32 v32, 0x37800000, v20
	v_cndmask_b32_e32 v20, v20, v32, vcc
	v_cmp_class_f32_e32 vcc, v16, v179
	v_and_b32_e32 v33, 0xffff0000, v21
	s_nop 0
	v_cndmask_b32_e32 v16, v20, v16, vcc
	v_rcp_f32_e32 v20, v16
	s_nop 0
	v_mul_f32_e32 v16, -1.0, v20
	v_pk_mul_f32 v[12:13], v[12:13], v[16:17] op_sel_hi:[1,0]
	v_pk_mul_f32 v[14:15], v[14:15], v[16:17] op_sel_hi:[1,0]
	v_pk_mul_f32 v[20:21], v[10:11], v[16:17] op_sel_hi:[1,0]
	v_pk_mul_f32 v[8:9], v[8:9], v[16:17] op_sel_hi:[1,0]
	v_mul_f32_e32 v10, 0x3fb8aa3b, v12
	v_mul_f32_e32 v11, 0x3fb8aa3b, v13
	v_mul_f32_e32 v12, 0x3fb8aa3b, v14
	v_mul_f32_e32 v13, 0x3fb8aa3b, v15
	v_mul_f32_e32 v14, 0x3fb8aa3b, v8
	v_mul_f32_e32 v15, 0x3fb8aa3b, v9
	v_exp_f32_e32 v8, v10
	v_exp_f32_e32 v9, v11
	v_exp_f32_e32 v10, v12
	v_exp_f32_e32 v11, v13
	v_exp_f32_e32 v12, v14
	v_pk_add_f32 v[8:9], v[8:9], 1.0 op_sel_hi:[1,0]
	v_exp_f32_e32 v13, v15
	v_div_scale_f32 v14, s[8:9], v9, v9, v35
	v_pk_add_f32 v[10:11], v[10:11], 1.0 op_sel_hi:[1,0]
	v_div_scale_f32 v32, s[8:9], v8, v8, v34
	v_rcp_f32_e32 v41, v14
	v_div_scale_f32 v37, s[10:11], v11, v11, v33
	v_rcp_f32_e32 v42, v32
	v_div_scale_f32 v39, s[12:13], v10, v10, v17
	v_rcp_f32_e32 v43, v37
	v_rcp_f32_e32 v44, v39
	v_fma_f32 v45, -v14, v41, 1.0
	v_div_scale_f32 v15, vcc, v35, v9, v35
	v_fma_f32 v46, -v32, v42, 1.0
	v_fmac_f32_e32 v41, v45, v41
	v_div_scale_f32 v36, s[8:9], v34, v8, v34
	v_fma_f32 v47, -v37, v43, 1.0
	v_fmac_f32_e32 v42, v46, v42
	v_mul_f32_e32 v45, v15, v41
	v_div_scale_f32 v38, s[10:11], v33, v11, v33
	v_fma_f32 v48, -v39, v44, 1.0
	v_fmac_f32_e32 v43, v47, v43
	v_mul_f32_e32 v46, v36, v42
	v_fma_f32 v49, -v14, v45, v15
	v_div_scale_f32 v40, s[12:13], v17, v10, v17
	v_fmac_f32_e32 v44, v48, v44
	v_mul_f32_e32 v47, v38, v43
	v_fma_f32 v50, -v32, v46, v36
	v_fmac_f32_e32 v45, v49, v41
	v_mul_f32_e32 v48, v40, v44
	v_fma_f32 v51, -v37, v47, v38
	v_fmac_f32_e32 v46, v50, v42
	v_fma_f32 v52, -v39, v48, v40
	v_fmac_f32_e32 v47, v51, v43
	v_fmac_f32_e32 v48, v52, v44
	v_rcp_f32_e32 v14, v9
	s_nop 0
	v_mul_f32_e32 v9, v35, v14
	v_rcp_f32_e32 v14, v8
	s_nop 0
	v_mul_f32_e32 v8, v34, v14
	s_mov_b64 vcc, s[12:13]
	v_pk_add_f32 v[14:15], v[8:9], v[30:31]
	v_rcp_f32_e32 v8, v10
	s_nop 0
	v_mul_f32_e32 v8, v17, v8
	v_and_b32_e32 v17, 0xffff0000, v22
	v_pk_add_f32 v[34:35], v[12:13], 1.0 op_sel_hi:[1,0]
	v_rcp_f32_e32 v32, v11
	s_nop 0
	v_mul_f32_e32 v9, v33, v32
	v_pk_add_f32 v[32:33], v[8:9], v[28:29]
	v_lshlrev_b32_e32 v36, 16, v18
	v_and_b32_e32 v37, 0xffff0000, v18
	v_lshl_add_u64 v[8:9], s[24:25], 0, v[26:27]
	v_or_b32_e32 v26, 0x100, v26
	v_lshl_add_u64 v[10:11], s[20:21], 0, v[26:27]
	global_load_dwordx4 v[10:13], v[10:11], off
	v_lshl_add_u64 v[28:29], s[16:17], 0, v[26:27]
	global_load_dwordx4 v[28:31], v[28:29], off
	v_lshlrev_b32_e32 v18, 16, v22
	v_rcp_f32_e32 v22, v35
	s_nop 0
	v_mul_f32_e32 v35, v17, v22
	v_mul_f32_e32 v20, 0x3fb8aa3b, v20
	v_mul_f32_e32 v21, 0x3fb8aa3b, v21
	v_exp_f32_e32 v20, v20
	v_exp_f32_e32 v21, v21
	v_rcp_f32_e32 v17, v34
	s_nop 0
	v_mul_f32_e32 v34, v18, v17
	v_and_b32_e32 v17, 0xffff0000, v23
	v_pk_add_f32 v[20:21], v[20:21], 1.0 op_sel_hi:[1,0]
	v_pk_add_f32 v[34:35], v[34:35], v[36:37]
	v_lshlrev_b32_e32 v23, 16, v23
	v_lshlrev_b32_e32 v18, 16, v19
	v_and_b32_e32 v19, 0xffff0000, v19
	v_div_scale_f32 v37, s[8:9], v20, v20, v23
	v_rcp_f32_e32 v39, v37
	v_rcp_f32_e32 v22, v21
	s_nop 0
	v_mul_f32_e32 v21, v17, v22
	v_fma_f32 v17, -v37, v39, 1.0
	v_fmac_f32_e32 v39, v17, v39
	v_div_scale_f32 v17, vcc, v23, v20, v23
	v_mul_f32_e32 v22, v17, v39
	v_fma_f32 v36, -v37, v22, v17
	v_fmac_f32_e32 v22, v36, v39
	v_fma_f32 v17, -v37, v22, v17
	v_div_fmas_f32 v17, v17, v39, v22
	v_pk_mul_f32 v[4:5], v[4:5], v[16:17] op_sel_hi:[1,0]
	v_rcp_f32_e32 v17, v20
	s_nop 0
	v_mul_f32_e32 v20, v23, v17
	v_mul_f32_e32 v4, 0x3fb8aa3b, v4
	v_mul_f32_e32 v5, 0x3fb8aa3b, v5
	v_exp_f32_e32 v4, v4
	v_exp_f32_e32 v5, v5
	v_pk_add_f32 v[22:23], v[20:21], v[18:19]
	v_pk_mul_f32 v[6:7], v[6:7], v[16:17] op_sel_hi:[1,0]
	v_pk_mul_f32 v[2:3], v[2:3], v[16:17] op_sel_hi:[1,0]
	v_pk_add_f32 v[4:5], v[4:5], 1.0 op_sel_hi:[1,0]
	v_pk_mul_f32 v[0:1], v[0:1], v[16:17] op_sel_hi:[1,0]
	v_mul_f32_e32 v6, 0x3fb8aa3b, v6
	v_mul_f32_e32 v7, 0x3fb8aa3b, v7
	v_exp_f32_e32 v6, v6
	v_exp_f32_e32 v7, v7
	v_mul_f32_e32 v0, 0x3fb8aa3b, v0
	v_mul_f32_e32 v1, 0x3fb8aa3b, v1
	v_exp_f32_e32 v0, v0
	v_pk_add_f32 v[6:7], v[6:7], 1.0 op_sel_hi:[1,0]
	s_waitcnt vmcnt(1)
; DI unsigned pk_bf16(float lo, float hi) { typedef float f2 __attribute__((ext_vector_type(2))); typedef __bf16 b2 __attribute__((ext_vector_type(2))); f2 v = {lo, hi}; b2 b = __builtin_convertvector(v, b2); return __builtin_bit_cast(unsigned, b); }
; DI float bf_lo(unsigned w) { return __uint_as_float(w << 16); }
; DI float bf_hi(unsigned w) { return __uint_as_float(w & 0xffff0000u); }
;     DI void operator()(const f32x4 (&acc)[2][2][4][2], const pg8::Unit& u, int wr, int wc, int fr, int fq) const {
;     ...
;                 for (int bj = 0; bj < 2; ++bj) {
;                     const size_t o2 = off + bj * 128;
;                     const u32x4 pw = *(const u32x4*)(pp + o2), bw = *(const u32x4*)(base + o2);
;                     const f32x4 a0 = acc[ai][bj][m][0] * rs, a1 = acc[ai][bj][m][1] * rs;
;                     f32x4 r0, r1;
;                     r0[0] = bf_lo(bw.x) + bf_lo(pw.x) / (1.f + __expf(a0[0])); r0[1] = bf_hi(bw.x) + bf_hi(pw.x) / (1.f + __expf(a0[1]));
;                     r0[2] = bf_lo(bw.y) + bf_lo(pw.y) / (1.f + __expf(a0[2])); r0[3] = bf_hi(bw.y) + bf_hi(pw.y) / (1.f + __expf(a0[3]));
;                     r1[0] = bf_lo(bw.z) + bf_lo(pw.z) / (1.f + __expf(a1[0])); r1[1] = bf_hi(bw.z) + bf_hi(pw.z) / (1.f + __expf(a1[1]));
;                     r1[2] = bf_lo(bw.w) + bf_lo(pw.w) / (1.f + __expf(a1[2])); r1[3] = bf_hi(bw.w) + bf_hi(pw.w) / (1.f + __expf(a1[3]));
;                     u32x4 w; w.x = pk_bf16(r0[0], r0[1]); w.y = pk_bf16(r0[2], r0[3]); w.z = pk_bf16(r1[0], r1[1]); w.w = pk_bf16(r1[2], r1[3]);
;                     *(u32x4*)(hb + o2) = w;
;                     ss += ((r0[0] * r0[0] + r0[1] * r0[1]) + (r0[2] * r0[2] + r0[3] * r0[3])) + ((r1[0] * r1[0] + r1[1] * r1[1]) + (r1[2] * r1[2] + r1[3] * r1[3]));
;                 }
;                 ss += __shfl_xor(ss, 16); ss += __shfl_xor(ss, 32);
;                 if (fq == 0) part[(size_t)row * 16 + u.pn * 4 + wc] = ss;
	v_and_b32_e32 v21, 0xffff0000, v10
	v_div_scale_f32 v38, s[8:9], v5, v5, v21
	v_rcp_f32_e32 v39, v38
	s_waitcnt vmcnt(0)
	v_lshlrev_b32_e32 v16, 16, v28
	v_and_b32_e32 v17, 0xffff0000, v28
	v_lshlrev_b32_e32 v10, 16, v10
	v_fma_f32 v28, -v38, v39, 1.0
	v_fmac_f32_e32 v39, v28, v39
	v_div_scale_f32 v28, vcc, v21, v5, v21
	v_mul_f32_e32 v40, v28, v39
	v_fma_f32 v41, -v38, v40, v28
	v_fmac_f32_e32 v40, v41, v39
	v_div_scale_f32 v38, s[8:9], v4, v4, v10
	v_rcp_f32_e32 v41, v38
	v_rcp_f32_e32 v28, v5
	s_nop 0
	v_mul_f32_e32 v5, v21, v28
	v_exp_f32_e32 v1, v1
	v_fma_f32 v21, -v38, v41, 1.0
	v_fmac_f32_e32 v41, v21, v41
	v_rcp_f32_e32 v21, v4
	s_nop 0
	v_mul_f32_e32 v4, v10, v21
	v_and_b32_e32 v10, 0xffff0000, v11
	v_div_scale_f32 v21, s[8:9], v7, v7, v10
	v_rcp_f32_e32 v28, v21
	v_pk_add_f32 v[4:5], v[4:5], v[16:17]
	v_lshlrev_b32_e32 v16, 16, v29
	v_and_b32_e32 v17, 0xffff0000, v29
	v_fma_f32 v29, -v21, v28, 1.0
	v_fmac_f32_e32 v28, v29, v28
	v_div_scale_f32 v29, vcc, v10, v7, v10
	v_mul_f32_e32 v38, v29, v28
	v_fma_f32 v39, -v21, v38, v29
	v_lshlrev_b32_e32 v11, 16, v11
	v_fmac_f32_e32 v38, v39, v28
	v_div_scale_f32 v29, s[8:9], v6, v6, v11
	v_rcp_f32_e32 v39, v29
	v_rcp_f32_e32 v21, v7
	s_nop 0
	v_mul_f32_e32 v7, v10, v21
	v_pk_add_f32 v[0:1], v[0:1], 1.0 op_sel_hi:[1,0]
	v_fma_f32 v10, -v29, v39, 1.0
	v_fmac_f32_e32 v39, v10, v39
	v_rcp_f32_e32 v10, v6
	s_nop 0
	v_mul_f32_e32 v6, v11, v10
	v_pk_add_f32 v[6:7], v[6:7], v[16:17]
	v_and_b32_e32 v16, 0xffff0000, v12
	v_lshlrev_b32_e32 v10, 16, v30
	v_and_b32_e32 v11, 0xffff0000, v30
	v_lshlrev_b32_e32 v12, 16, v12
	v_div_scale_f32 v28, s[8:9], v0, v0, v12
	v_rcp_f32_e32 v30, v28
	v_rcp_f32_e32 v17, v1
	s_nop 0
	v_mul_f32_e32 v1, v16, v17
	v_mul_f32_e32 v2, 0x3fb8aa3b, v2
	v_fma_f32 v16, -v28, v30, 1.0
	v_fmac_f32_e32 v30, v16, v30
	v_mul_f32_e32 v3, 0x3fb8aa3b, v3
	v_exp_f32_e32 v2, v2
	v_exp_f32_e32 v3, v3
	v_rcp_f32_e32 v16, v0
	s_nop 0
	v_mul_f32_e32 v0, v12, v16
	v_pk_add_f32 v[10:11], v[0:1], v[10:11]
	v_and_b32_e32 v12, 0xffff0000, v13
	v_pk_add_f32 v[0:1], v[2:3], 1.0 op_sel_hi:[1,0]
	v_lshlrev_b32_e32 v13, 16, v13
	v_lshlrev_b32_e32 v2, 16, v31
	v_and_b32_e32 v3, 0xffff0000, v31
	v_cvt_pk_bf16_f32 v20, v34, v35
	v_div_scale_f32 v21, s[8:9], v0, v0, v13
	v_rcp_f32_e32 v16, v1
	s_nop 0
	v_mul_f32_e32 v1, v12, v16
	v_pk_mul_f32 v[34:35], v[34:35], v[34:35]
	v_div_scale_f32 v12, vcc, v13, v0, v13
	v_rcp_f32_e32 v12, v0
	s_nop 0
	v_mul_f32_e32 v0, v13, v12
	v_pk_add_f32 v[12:13], v[0:1], v[2:3]
	v_pk_mul_f32 v[0:1], v[4:5], v[4:5]
	v_pk_mul_f32 v[2:3], v[6:7], v[6:7]
	v_pk_mul_f32 v[36:37], v[22:23], v[22:23]
	v_add_f32_e32 v2, v2, v3
	v_add_f32_e32 v0, v0, v1
	v_cvt_pk_bf16_f32 v18, v14, v15
	v_cvt_pk_bf16_f32 v19, v32, v33
	v_pk_mul_f32 v[14:15], v[14:15], v[14:15]
	v_pk_mul_f32 v[32:33], v[32:33], v[32:33]
	v_pk_mul_f32 v[16:17], v[10:11], v[10:11]
	v_pk_mul_f32 v[28:29], v[12:13], v[12:13]
	v_add_f32_e32 v0, v0, v2
	v_add_f32_e32 v1, v36, v37
	v_add_f32_e32 v2, v34, v35
	v_add_f32_e32 v21, v28, v29
	v_add_f32_e32 v16, v16, v17
	v_add_f32_e32 v1, v2, v1
	v_add_f32_e32 v2, v32, v33
	v_add_f32_e32 v3, v14, v15
	v_add_f32_e32 v16, v16, v21
	v_add_f32_e32 v2, v3, v2
	v_add_f32_e32 v0, v0, v16
	v_add_f32_e32 v1, v2, v1
	v_add_f32_e32 v0, v1, v0
	ds_bpermute_b32 v1, v181, v0
	v_cvt_pk_bf16_f32 v21, v22, v23
	v_cvt_pk_bf16_f32 v2, v4, v5
	v_cvt_pk_bf16_f32 v3, v6, v7
	v_cvt_pk_bf16_f32 v4, v10, v11
	s_waitcnt lgkmcnt(0)
	v_add_f32_e32 v0, v0, v1
	ds_bpermute_b32 v1, v180, v0
	v_cvt_pk_bf16_f32 v5, v12, v13
	v_lshl_add_u64 v[6:7], s[24:25], 0, v[26:27]
	global_store_dwordx4 v[8:9], v[18:21], off
	global_store_dwordx4 v[6:7], v[2:5], off
	s_and_saveexec_b64 s[8:9], s[4:5]
	s_cbranch_execz .LBB0_1763
	v_lshlrev_b64 v[2:3], 4, v[24:25]
	s_waitcnt lgkmcnt(0)
	v_add_f32_e32 v4, v0, v1
	v_lshl_add_u64 v[0:1], v[2:3], 2, s[26:27]
	v_lshl_add_u64 v[0:1], s[48:49], 2, v[0:1]
	s_lshl_b32 s34, s61, 2
	v_lshl_add_u64 v[0:1], v[0:1], 0, s[34:35]
	global_store_dword v[0:1], v4, off
